# speedup vs baseline: 1.0229x; 1.0229x over previous
.LBB0_101:
	ds_read_b128 v[168:171], v163
	ds_read_b128 v[172:175], v164
	ds_read_b128 v[176:179], v165
	ds_read_b128 v[180:183], v166
	v_lshl_add_u64 v[210:211], v[148:149], 0, v[142:143]
	s_mov_b32 m0, s12
	v_lshl_add_u64 v[214:215], v[210:211], 0, s[50:51]
	ds_read_b128 v[184:187], v150
	ds_read_b128 v[188:191], v150 offset:2048
	ds_read_b128 v[192:195], v151
	ds_read_b128 v[196:199], v151 offset:2048
	ds_read_b128 v[200:203], v150 offset:4096
	ds_read_b128 v[206:209], v150 offset:6144
	ds_read_b128 v[218:221], v151 offset:4096
	ds_read_b128 v[222:225], v151 offset:6144
	global_load_lds_dwordx4 v[214:215], off
	v_lshl_add_u64 v[214:215], v[148:149], 0, v[140:141]
	v_lshl_add_u64 v[226:227], v[214:215], 0, s[50:51]
	s_mov_b32 m0, s4
	s_nop 0
	global_load_lds_dwordx4 v[226:227], off
	s_waitcnt lgkmcnt(8)
	s_waitcnt vmcnt(10)
	s_barrier
	s_waitcnt lgkmcnt(0)
	s_setprio 1
	s_waitcnt lgkmcnt(0)
	v_mfma_f32_16x16x32_bf16 v[126:129], v[184:187], v[168:171], v[126:129]
	v_mfma_f32_16x16x32_bf16 v[122:125], v[184:187], v[176:179], v[122:125]
	v_mfma_f32_16x16x32_bf16 v[118:121], v[188:191], v[168:171], v[118:121]
	v_mfma_f32_16x16x32_bf16 v[114:117], v[188:191], v[176:179], v[114:117]
	v_mfma_f32_16x16x32_bf16 v[110:113], v[200:203], v[168:171], v[110:113]
	v_mfma_f32_16x16x32_bf16 v[106:109], v[200:203], v[176:179], v[106:109]
	v_mfma_f32_16x16x32_bf16 v[102:105], v[206:209], v[168:171], v[102:105]
	v_mfma_f32_16x16x32_bf16 v[98:101], v[206:209], v[176:179], v[98:101]
	v_mfma_f32_16x16x32_bf16 v[126:129], v[192:195], v[172:175], v[126:129]
	v_mfma_f32_16x16x32_bf16 v[122:125], v[192:195], v[180:183], v[122:125]
	v_mfma_f32_16x16x32_bf16 v[118:121], v[196:199], v[172:175], v[118:121]
	v_mfma_f32_16x16x32_bf16 v[114:117], v[196:199], v[180:183], v[114:117]
	v_mfma_f32_16x16x32_bf16 v[110:113], v[218:221], v[172:175], v[110:113]
	v_mfma_f32_16x16x32_bf16 v[106:109], v[218:221], v[180:183], v[106:109]
	v_mfma_f32_16x16x32_bf16 v[102:105], v[222:225], v[172:175], v[102:105]
	v_mfma_f32_16x16x32_bf16 v[98:101], v[222:225], v[180:183], v[98:101]
	s_setprio 0
	s_barrier
	v_lshl_add_u64 v[242:243], v[148:149], 0, v[146:147]
	s_mov_b32 m0, s2
	v_lshl_add_u64 v[244:245], v[242:243], 0, s[70:71]
	ds_read_b128 v[226:229], v159
	ds_read_b128 v[230:233], v160
	ds_read_b128 v[234:237], v161
	ds_read_b128 v[238:241], v162
	global_load_lds_dwordx4 v[244:245], off
	v_lshl_add_u64 v[244:245], v[148:149], 0, v[144:145]
	v_lshl_add_u64 v[246:247], v[244:245], 0, s[70:71]
	s_mov_b32 m0, s3
	s_nop 0
	global_load_lds_dwordx4 v[246:247], off
	s_waitcnt vmcnt(10)
	s_waitcnt lgkmcnt(0)
	s_barrier
	s_waitcnt lgkmcnt(0)
	s_setprio 1
	s_waitcnt lgkmcnt(0)
	v_mfma_f32_16x16x32_bf16 v[94:97], v[184:187], v[226:229], v[94:97]
	v_mfma_f32_16x16x32_bf16 v[90:93], v[184:187], v[234:237], v[90:93]
	v_mfma_f32_16x16x32_bf16 v[86:89], v[188:191], v[226:229], v[86:89]
	v_mfma_f32_16x16x32_bf16 v[82:85], v[188:191], v[234:237], v[82:85]
	v_mfma_f32_16x16x32_bf16 v[78:81], v[200:203], v[226:229], v[78:81]
	v_mfma_f32_16x16x32_bf16 v[74:77], v[200:203], v[234:237], v[74:77]
	v_mfma_f32_16x16x32_bf16 v[70:73], v[206:209], v[226:229], v[70:73]
	v_mfma_f32_16x16x32_bf16 v[66:69], v[206:209], v[234:237], v[66:69]
	v_mfma_f32_16x16x32_bf16 v[94:97], v[192:195], v[230:233], v[94:97]
	v_mfma_f32_16x16x32_bf16 v[90:93], v[192:195], v[238:241], v[90:93]
	v_mfma_f32_16x16x32_bf16 v[86:89], v[196:199], v[230:233], v[86:89]
	v_mfma_f32_16x16x32_bf16 v[82:85], v[196:199], v[238:241], v[82:85]
	v_mfma_f32_16x16x32_bf16 v[78:81], v[218:221], v[230:233], v[78:81]
	v_mfma_f32_16x16x32_bf16 v[74:77], v[218:221], v[238:241], v[74:77]
	v_mfma_f32_16x16x32_bf16 v[70:73], v[222:225], v[230:233], v[70:73]
	v_mfma_f32_16x16x32_bf16 v[66:69], v[222:225], v[238:241], v[66:69]
	s_setprio 0
	s_mov_b32 m0, s1
	v_lshl_add_u64 v[246:247], v[210:211], 0, s[54:55]
	s_barrier
	ds_read_b128 v[184:187], v150 offset:16384
	ds_read_b128 v[188:191], v150 offset:18432
	ds_read_b128 v[192:195], v151 offset:16384
	ds_read_b128 v[196:199], v151 offset:18432
	ds_read_b128 v[200:203], v150 offset:20480
	ds_read_b128 v[206:209], v150 offset:22528
	ds_read_b128 v[218:221], v151 offset:20480
	ds_read_b128 v[222:225], v151 offset:22528
	global_load_lds_dwordx4 v[246:247], off
	v_lshl_add_u64 v[246:247], v[214:215], 0, s[54:55]
	s_mov_b32 m0, s9
	s_nop 0
	global_load_lds_dwordx4 v[246:247], off
	v_lshl_add_u64 v[246:247], v[242:243], 0, s[36:37]
	s_mov_b32 m0, s11
	s_nop 0
	global_load_lds_dwordx4 v[246:247], off
	v_lshl_add_u64 v[246:247], v[244:245], 0, s[36:37]
	s_mov_b32 m0, s24
	s_nop 0
	global_load_lds_dwordx4 v[246:247], off
	s_waitcnt vmcnt(10)
	s_waitcnt lgkmcnt(0)
	s_barrier
	s_waitcnt lgkmcnt(0)
	s_setprio 1
	s_waitcnt lgkmcnt(0)
	v_mfma_f32_16x16x32_bf16 v[62:65], v[184:187], v[168:171], v[62:65]
	v_mfma_f32_16x16x32_bf16 v[58:61], v[184:187], v[176:179], v[58:61]
	v_mfma_f32_16x16x32_bf16 v[54:57], v[188:191], v[168:171], v[54:57]
	v_mfma_f32_16x16x32_bf16 v[50:53], v[188:191], v[176:179], v[50:53]
	v_mfma_f32_16x16x32_bf16 v[46:49], v[200:203], v[168:171], v[46:49]
	v_mfma_f32_16x16x32_bf16 v[42:45], v[200:203], v[176:179], v[42:45]
	v_mfma_f32_16x16x32_bf16 v[38:41], v[206:209], v[168:171], v[38:41]
	v_mfma_f32_16x16x32_bf16 v[34:37], v[206:209], v[176:179], v[34:37]
	v_mfma_f32_16x16x32_bf16 v[62:65], v[192:195], v[172:175], v[62:65]
	v_mfma_f32_16x16x32_bf16 v[58:61], v[192:195], v[180:183], v[58:61]
	v_mfma_f32_16x16x32_bf16 v[54:57], v[196:199], v[172:175], v[54:57]
	v_mfma_f32_16x16x32_bf16 v[50:53], v[196:199], v[180:183], v[50:53]
	v_mfma_f32_16x16x32_bf16 v[46:49], v[218:221], v[172:175], v[46:49]
	v_mfma_f32_16x16x32_bf16 v[42:45], v[218:221], v[180:183], v[42:45]
	v_mfma_f32_16x16x32_bf16 v[38:41], v[222:225], v[172:175], v[38:41]
	v_mfma_f32_16x16x32_bf16 v[34:37], v[222:225], v[180:183], v[34:37]
	v_mfma_f32_16x16x32_bf16 v[30:33], v[184:187], v[226:229], v[30:33]
	v_mfma_f32_16x16x32_bf16 v[26:29], v[184:187], v[234:237], v[26:29]
	v_mfma_f32_16x16x32_bf16 v[22:25], v[188:191], v[226:229], v[22:25]
	v_mfma_f32_16x16x32_bf16 v[18:21], v[188:191], v[234:237], v[18:21]
	v_mfma_f32_16x16x32_bf16 v[14:17], v[200:203], v[226:229], v[14:17]
	v_mfma_f32_16x16x32_bf16 v[10:13], v[200:203], v[234:237], v[10:13]
	v_mfma_f32_16x16x32_bf16 v[6:9], v[206:209], v[226:229], v[6:9]
	v_mfma_f32_16x16x32_bf16 v[2:5], v[206:209], v[234:237], v[2:5]
	v_mfma_f32_16x16x32_bf16 v[30:33], v[192:195], v[230:233], v[30:33]
	v_mfma_f32_16x16x32_bf16 v[26:29], v[192:195], v[238:241], v[26:29]
	v_mfma_f32_16x16x32_bf16 v[22:25], v[196:199], v[230:233], v[22:25]
	v_mfma_f32_16x16x32_bf16 v[18:21], v[196:199], v[238:241], v[18:21]
	v_mfma_f32_16x16x32_bf16 v[14:17], v[218:221], v[230:233], v[14:17]
	v_mfma_f32_16x16x32_bf16 v[10:13], v[218:221], v[238:241], v[10:13]
	v_mfma_f32_16x16x32_bf16 v[6:9], v[222:225], v[230:233], v[6:9]
	v_mfma_f32_16x16x32_bf16 v[2:5], v[222:225], v[238:241], v[2:5]
	s_setprio 0
	s_barrier
	ds_read_b128 v[168:171], v155
	ds_read_b128 v[172:175], v156
	ds_read_b128 v[176:179], v157
	ds_read_b128 v[180:183], v158
	s_mov_b32 m0, s25
	v_lshl_add_u64 v[226:227], v[210:211], 0, s[58:59]
	ds_read_b128 v[184:187], v150 offset:32768
	ds_read_b128 v[188:191], v150 offset:34816
	ds_read_b128 v[192:195], v151 offset:32768
	ds_read_b128 v[196:199], v151 offset:34816
	ds_read_b128 v[200:203], v150 offset:36864
	ds_read_b128 v[206:209], v150 offset:38912
	ds_read_b128 v[218:221], v151 offset:36864
	ds_read_b128 v[222:225], v151 offset:38912
	global_load_lds_dwordx4 v[226:227], off
	v_lshl_add_u64 v[226:227], v[214:215], 0, s[58:59]
	s_mov_b32 m0, s26
	s_nop 0
	global_load_lds_dwordx4 v[226:227], off
	s_waitcnt lgkmcnt(8)
	s_waitcnt vmcnt(10)
	s_barrier
	s_waitcnt lgkmcnt(0)
	s_setprio 1
	s_waitcnt lgkmcnt(0)
	v_mfma_f32_16x16x32_bf16 v[126:129], v[184:187], v[168:171], v[126:129]
	v_mfma_f32_16x16x32_bf16 v[122:125], v[184:187], v[176:179], v[122:125]
	v_mfma_f32_16x16x32_bf16 v[118:121], v[188:191], v[168:171], v[118:121]
	v_mfma_f32_16x16x32_bf16 v[114:117], v[188:191], v[176:179], v[114:117]
	v_mfma_f32_16x16x32_bf16 v[110:113], v[200:203], v[168:171], v[110:113]
	v_mfma_f32_16x16x32_bf16 v[106:109], v[200:203], v[176:179], v[106:109]
	v_mfma_f32_16x16x32_bf16 v[102:105], v[206:209], v[168:171], v[102:105]
	v_mfma_f32_16x16x32_bf16 v[98:101], v[206:209], v[176:179], v[98:101]
	v_mfma_f32_16x16x32_bf16 v[126:129], v[192:195], v[172:175], v[126:129]
	v_mfma_f32_16x16x32_bf16 v[122:125], v[192:195], v[180:183], v[122:125]
	v_mfma_f32_16x16x32_bf16 v[118:121], v[196:199], v[172:175], v[118:121]
	v_mfma_f32_16x16x32_bf16 v[114:117], v[196:199], v[180:183], v[114:117]
	v_mfma_f32_16x16x32_bf16 v[110:113], v[218:221], v[172:175], v[110:113]
	v_mfma_f32_16x16x32_bf16 v[106:109], v[218:221], v[180:183], v[106:109]
	v_mfma_f32_16x16x32_bf16 v[102:105], v[222:225], v[172:175], v[102:105]
	v_mfma_f32_16x16x32_bf16 v[98:101], v[222:225], v[180:183], v[98:101]
	s_setprio 0
	s_barrier
	s_mov_b32 m0, s27
	v_lshl_add_u64 v[246:247], v[242:243], 0, s[38:39]
	ds_read_b128 v[226:229], v0
	ds_read_b128 v[230:233], v152
	ds_read_b128 v[234:237], v153
	ds_read_b128 v[238:241], v154
	global_load_lds_dwordx4 v[246:247], off
	v_lshl_add_u64 v[246:247], v[244:245], 0, s[38:39]
	s_mov_b32 m0, s28
	s_nop 0
	global_load_lds_dwordx4 v[246:247], off
	s_waitcnt vmcnt(10)
	s_waitcnt lgkmcnt(0)
	s_barrier
	s_waitcnt lgkmcnt(0)
	s_setprio 1
	s_waitcnt lgkmcnt(0)
	v_mfma_f32_16x16x32_bf16 v[94:97], v[184:187], v[226:229], v[94:97]
	v_mfma_f32_16x16x32_bf16 v[90:93], v[184:187], v[234:237], v[90:93]
	v_mfma_f32_16x16x32_bf16 v[86:89], v[188:191], v[226:229], v[86:89]
	v_mfma_f32_16x16x32_bf16 v[82:85], v[188:191], v[234:237], v[82:85]
	v_mfma_f32_16x16x32_bf16 v[78:81], v[200:203], v[226:229], v[78:81]
	v_mfma_f32_16x16x32_bf16 v[74:77], v[200:203], v[234:237], v[74:77]
	v_mfma_f32_16x16x32_bf16 v[70:73], v[206:209], v[226:229], v[70:73]
	v_mfma_f32_16x16x32_bf16 v[66:69], v[206:209], v[234:237], v[66:69]
	v_mfma_f32_16x16x32_bf16 v[94:97], v[192:195], v[230:233], v[94:97]
	v_mfma_f32_16x16x32_bf16 v[90:93], v[192:195], v[238:241], v[90:93]
	v_mfma_f32_16x16x32_bf16 v[86:89], v[196:199], v[230:233], v[86:89]
	v_mfma_f32_16x16x32_bf16 v[82:85], v[196:199], v[238:241], v[82:85]
	v_mfma_f32_16x16x32_bf16 v[78:81], v[218:221], v[230:233], v[78:81]
	v_mfma_f32_16x16x32_bf16 v[74:77], v[218:221], v[238:241], v[74:77]
	v_mfma_f32_16x16x32_bf16 v[70:73], v[222:225], v[230:233], v[70:73]
	v_mfma_f32_16x16x32_bf16 v[66:69], v[222:225], v[238:241], v[66:69]
	s_setprio 0
	s_mov_b32 m0, s29
	v_lshl_add_u64 v[210:211], v[210:211], 0, s[62:63]
	s_barrier
	ds_read_b128 v[184:187], v150 offset:49152
	ds_read_b128 v[188:191], v150 offset:51200
	ds_read_b128 v[192:195], v151 offset:49152
	ds_read_b128 v[196:199], v151 offset:51200
	ds_read_b128 v[200:203], v150 offset:53248
	ds_read_b128 v[206:209], v150 offset:55296
	ds_read_b128 v[218:221], v151 offset:53248
	ds_read_b128 v[222:225], v151 offset:55296
	global_load_lds_dwordx4 v[210:211], off
	v_lshl_add_u64 v[210:211], v[214:215], 0, s[62:63]
	s_mov_b32 m0, s30
	s_nop 0
	global_load_lds_dwordx4 v[210:211], off
	v_lshl_add_u64 v[210:211], v[242:243], 0, s[40:41]
	s_mov_b32 m0, s31
	s_nop 0
	global_load_lds_dwordx4 v[210:211], off
	v_lshl_add_u64 v[210:211], v[244:245], 0, s[40:41]
	s_mov_b32 m0, s34
	s_nop 0
	global_load_lds_dwordx4 v[210:211], off
	s_waitcnt vmcnt(10)
	s_waitcnt lgkmcnt(0)
	s_barrier
	s_waitcnt lgkmcnt(0)
	s_setprio 1
	s_waitcnt lgkmcnt(0)
	v_mfma_f32_16x16x32_bf16 v[62:65], v[184:187], v[168:171], v[62:65]
	v_mfma_f32_16x16x32_bf16 v[58:61], v[184:187], v[176:179], v[58:61]
	v_mfma_f32_16x16x32_bf16 v[54:57], v[188:191], v[168:171], v[54:57]
	v_mfma_f32_16x16x32_bf16 v[50:53], v[188:191], v[176:179], v[50:53]
	v_mfma_f32_16x16x32_bf16 v[46:49], v[200:203], v[168:171], v[46:49]
	v_mfma_f32_16x16x32_bf16 v[42:45], v[200:203], v[176:179], v[42:45]
	v_mfma_f32_16x16x32_bf16 v[38:41], v[206:209], v[168:171], v[38:41]
	v_mfma_f32_16x16x32_bf16 v[34:37], v[206:209], v[176:179], v[34:37]
	v_mfma_f32_16x16x32_bf16 v[62:65], v[192:195], v[172:175], v[62:65]
	v_mfma_f32_16x16x32_bf16 v[58:61], v[192:195], v[180:183], v[58:61]
	v_mfma_f32_16x16x32_bf16 v[54:57], v[196:199], v[172:175], v[54:57]
	v_mfma_f32_16x16x32_bf16 v[50:53], v[196:199], v[180:183], v[50:53]
	v_mfma_f32_16x16x32_bf16 v[46:49], v[218:221], v[172:175], v[46:49]
	v_mfma_f32_16x16x32_bf16 v[42:45], v[218:221], v[180:183], v[42:45]
	v_mfma_f32_16x16x32_bf16 v[38:41], v[222:225], v[172:175], v[38:41]
	v_mfma_f32_16x16x32_bf16 v[34:37], v[222:225], v[180:183], v[34:37]
	v_mfma_f32_16x16x32_bf16 v[30:33], v[184:187], v[226:229], v[30:33]
	v_mfma_f32_16x16x32_bf16 v[26:29], v[184:187], v[234:237], v[26:29]
	v_mfma_f32_16x16x32_bf16 v[22:25], v[188:191], v[226:229], v[22:25]
	v_mfma_f32_16x16x32_bf16 v[18:21], v[188:191], v[234:237], v[18:21]
	v_mfma_f32_16x16x32_bf16 v[14:17], v[200:203], v[226:229], v[14:17]
	v_mfma_f32_16x16x32_bf16 v[10:13], v[200:203], v[234:237], v[10:13]
	v_mfma_f32_16x16x32_bf16 v[6:9], v[206:209], v[226:229], v[6:9]
	v_mfma_f32_16x16x32_bf16 v[2:5], v[206:209], v[234:237], v[2:5]
	v_mfma_f32_16x16x32_bf16 v[30:33], v[192:195], v[230:233], v[30:33]
	v_mfma_f32_16x16x32_bf16 v[26:29], v[192:195], v[238:241], v[26:29]
	v_mfma_f32_16x16x32_bf16 v[22:25], v[196:199], v[230:233], v[22:25]
	v_mfma_f32_16x16x32_bf16 v[18:21], v[196:199], v[238:241], v[18:21]
	v_mfma_f32_16x16x32_bf16 v[14:17], v[218:221], v[230:233], v[14:17]
	v_mfma_f32_16x16x32_bf16 v[10:13], v[218:221], v[238:241], v[10:13]
	v_mfma_f32_16x16x32_bf16 v[6:9], v[222:225], v[230:233], v[6:9]
	v_mfma_f32_16x16x32_bf16 v[2:5], v[222:225], v[238:241], v[2:5]
	s_setprio 0
	s_add_i32 s5, s5, 2
	s_cmp_lt_u32 s5, 28
	v_lshl_add_u64 v[148:149], v[148:149], 0, s[54:55]
	s_barrier
	s_cbranch_scc1 .LBB0_101
	s_waitcnt vmcnt(6)
	s_mov_b64 s[2:3], 0xf80
	s_mov_b32 m0, s12
	v_lshl_add_u64 v[138:139], v[138:139], 0, s[2:3]
	ds_read_b128 v[140:143], v163
	ds_read_b128 v[144:147], v164
	ds_read_b128 v[168:171], v165
	ds_read_b128 v[164:167], v166
	ds_read_b128 v[172:175], v150
	ds_read_b128 v[176:179], v150 offset:2048
	ds_read_b128 v[180:183], v151
	ds_read_b128 v[184:187], v151 offset:2048
	ds_read_b128 v[188:191], v150 offset:4096
	ds_read_b128 v[192:195], v150 offset:6144
	ds_read_b128 v[196:199], v151 offset:4096
	ds_read_b128 v[200:203], v151 offset:6144
	global_load_lds_dwordx4 v[138:139], off
	v_lshl_add_u64 v[136:137], v[136:137], 0, s[2:3]
	s_mov_b32 m0, s4
	s_nop 0
	global_load_lds_dwordx4 v[136:137], off
	s_barrier
	s_waitcnt lgkmcnt(0)
	s_setprio 1
	s_waitcnt lgkmcnt(0)
	v_mfma_f32_16x16x32_bf16 v[126:129], v[172:175], v[140:143], v[126:129]
	v_mfma_f32_16x16x32_bf16 v[114:117], v[176:179], v[168:171], v[114:117]
	v_mfma_f32_16x16x32_bf16 v[110:113], v[188:191], v[140:143], v[110:113]
	v_mfma_f32_16x16x32_bf16 v[106:109], v[188:191], v[168:171], v[106:109]
	v_mfma_f32_16x16x32_bf16 v[126:129], v[180:183], v[144:147], v[126:129]
	v_mfma_f32_16x16x32_bf16 v[122:125], v[172:175], v[168:171], v[122:125]
	v_mfma_f32_16x16x32_bf16 v[118:121], v[176:179], v[140:143], v[118:121]
	v_mfma_f32_16x16x32_bf16 v[114:117], v[184:187], v[164:167], v[114:117]
	v_mfma_f32_16x16x32_bf16 v[110:113], v[196:199], v[144:147], v[110:113]
	v_mfma_f32_16x16x32_bf16 v[106:109], v[196:199], v[164:167], v[106:109]
	v_mfma_f32_16x16x32_bf16 v[102:105], v[192:195], v[140:143], v[102:105]
	v_mfma_f32_16x16x32_bf16 v[98:101], v[192:195], v[168:171], v[98:101]
	v_mfma_f32_16x16x32_bf16 v[136:139], v[180:183], v[164:167], v[122:125]
	v_mfma_f32_16x16x32_bf16 v[206:209], v[184:187], v[144:147], v[118:121]
	v_mfma_f32_16x16x32_bf16 v[218:221], v[200:203], v[144:147], v[102:105]
	v_mfma_f32_16x16x32_bf16 v[222:225], v[200:203], v[164:167], v[98:101]
	s_setprio 0
	s_barrier
	s_nop 1
	ds_read_b128 v[98:101], v159
	ds_read_b128 v[102:105], v160
	ds_read_b128 v[118:121], v161
	ds_read_b128 v[122:125], v162
	s_barrier
	s_waitcnt lgkmcnt(0)
	s_setprio 1
	s_waitcnt lgkmcnt(0)
	v_mfma_f32_16x16x32_bf16 v[94:97], v[172:175], v[98:101], v[94:97]
	v_mfma_f32_16x16x32_bf16 v[90:93], v[172:175], v[118:121], v[90:93]
	v_mfma_f32_16x16x32_bf16 v[78:81], v[188:191], v[98:101], v[78:81]
	v_mfma_f32_16x16x32_bf16 v[74:77], v[188:191], v[118:121], v[74:77]
	v_mfma_f32_16x16x32_bf16 v[94:97], v[180:183], v[102:105], v[94:97]
	v_mfma_f32_16x16x32_bf16 v[90:93], v[180:183], v[122:125], v[90:93]
	v_mfma_f32_16x16x32_bf16 v[86:89], v[176:179], v[98:101], v[86:89]
	v_mfma_f32_16x16x32_bf16 v[82:85], v[176:179], v[118:121], v[82:85]
	v_mfma_f32_16x16x32_bf16 v[78:81], v[196:199], v[102:105], v[78:81]
	v_mfma_f32_16x16x32_bf16 v[74:77], v[196:199], v[122:125], v[74:77]
	v_mfma_f32_16x16x32_bf16 v[70:73], v[192:195], v[98:101], v[70:73]
	v_mfma_f32_16x16x32_bf16 v[66:69], v[192:195], v[118:121], v[66:69]
	v_mfma_f32_16x16x32_bf16 v[160:163], v[184:187], v[102:105], v[86:89]
	v_mfma_f32_16x16x32_bf16 v[172:175], v[184:187], v[122:125], v[82:85]
	v_mfma_f32_16x16x32_bf16 v[176:179], v[200:203], v[102:105], v[70:73]
	v_mfma_f32_16x16x32_bf16 v[180:183], v[200:203], v[122:125], v[66:69]
	s_setprio 0
	s_barrier
	s_nop 1
	ds_read_b128 v[66:69], v150 offset:16384
	ds_read_b128 v[70:73], v150 offset:18432
	ds_read_b128 v[82:85], v151 offset:16384
	ds_read_b128 v[86:89], v151 offset:18432
	ds_read_b128 v[184:187], v150 offset:20480
	ds_read_b128 v[188:191], v150 offset:22528
	ds_read_b128 v[192:195], v151 offset:20480
	ds_read_b128 v[196:199], v151 offset:22528
	s_waitcnt vmcnt(4)
	s_barrier
	s_waitcnt lgkmcnt(0)
	s_setprio 1
	s_waitcnt lgkmcnt(0)
	v_mfma_f32_16x16x32_bf16 v[62:65], v[66:69], v[140:143], v[62:65]
	v_mfma_f32_16x16x32_bf16 v[54:57], v[70:73], v[140:143], v[54:57]
	v_mfma_f32_16x16x32_bf16 v[46:49], v[184:187], v[140:143], v[46:49]
	v_mfma_f32_16x16x32_bf16 v[38:41], v[188:191], v[140:143], v[38:41]
	v_mfma_f32_16x16x32_bf16 v[62:65], v[82:85], v[144:147], v[62:65]
	v_mfma_f32_16x16x32_bf16 v[58:61], v[66:69], v[168:171], v[58:61]
	v_mfma_f32_16x16x32_bf16 v[54:57], v[86:89], v[144:147], v[54:57]
	v_mfma_f32_16x16x32_bf16 v[50:53], v[70:73], v[168:171], v[50:53]
	v_mfma_f32_16x16x32_bf16 v[46:49], v[192:195], v[144:147], v[46:49]
	v_mfma_f32_16x16x32_bf16 v[42:45], v[184:187], v[168:171], v[42:45]
	v_mfma_f32_16x16x32_bf16 v[38:41], v[196:199], v[144:147], v[38:41]
	v_mfma_f32_16x16x32_bf16 v[34:37], v[188:191], v[168:171], v[34:37]
	v_mfma_f32_16x16x32_bf16 v[200:203], v[82:85], v[164:167], v[58:61]
	v_mfma_f32_16x16x32_bf16 v[226:229], v[86:89], v[164:167], v[50:53]
	v_mfma_f32_16x16x32_bf16 v[230:233], v[192:195], v[164:167], v[42:45]
	v_mfma_f32_16x16x32_bf16 v[140:143], v[196:199], v[164:167], v[34:37]
	s_setprio 0
	s_setprio 1
	v_mfma_f32_16x16x32_bf16 v[30:33], v[66:69], v[98:101], v[30:33]
	v_mfma_f32_16x16x32_bf16 v[22:25], v[70:73], v[98:101], v[22:25]
	v_mfma_f32_16x16x32_bf16 v[14:17], v[184:187], v[98:101], v[14:17]
	v_mfma_f32_16x16x32_bf16 v[6:9], v[188:191], v[98:101], v[6:9]
	v_mfma_f32_16x16x32_bf16 v[30:33], v[82:85], v[102:105], v[30:33]
	v_mfma_f32_16x16x32_bf16 v[26:29], v[66:69], v[118:121], v[26:29]
	v_mfma_f32_16x16x32_bf16 v[22:25], v[86:89], v[102:105], v[22:25]
	v_mfma_f32_16x16x32_bf16 v[18:21], v[70:73], v[118:121], v[18:21]
	v_mfma_f32_16x16x32_bf16 v[14:17], v[192:195], v[102:105], v[14:17]
	v_mfma_f32_16x16x32_bf16 v[10:13], v[184:187], v[118:121], v[10:13]
	v_mfma_f32_16x16x32_bf16 v[6:9], v[196:199], v[102:105], v[6:9]
	v_mfma_f32_16x16x32_bf16 v[2:5], v[188:191], v[118:121], v[2:5]
	v_mfma_f32_16x16x32_bf16 v[144:147], v[82:85], v[122:125], v[26:29]
	v_mfma_f32_16x16x32_bf16 v[164:167], v[86:89], v[122:125], v[18:21]
	v_mfma_f32_16x16x32_bf16 v[168:171], v[192:195], v[122:125], v[10:13]
	v_mfma_f32_16x16x32_bf16 v[184:187], v[196:199], v[122:125], v[2:5]
	s_setprio 0
	s_barrier
	s_nop 1
	ds_read_b128 v[2:5], v155
	ds_read_b128 v[10:13], v156
	ds_read_b128 v[188:191], v157
	ds_read_b128 v[156:159], v158
	ds_read_b128 v[18:21], v150 offset:32768
	ds_read_b128 v[26:29], v150 offset:34816
	ds_read_b128 v[34:37], v151 offset:32768
	ds_read_b128 v[42:45], v151 offset:34816
	ds_read_b128 v[50:53], v150 offset:36864
	ds_read_b128 v[58:61], v150 offset:38912
	ds_read_b128 v[192:195], v151 offset:36864
	ds_read_b128 v[196:199], v151 offset:38912
	s_waitcnt vmcnt(2)
	s_barrier
	s_waitcnt lgkmcnt(0)
	s_setprio 1
	s_waitcnt lgkmcnt(0)
	v_mfma_f32_16x16x32_bf16 v[66:69], v[18:21], v[2:5], v[126:129]
	v_mfma_f32_16x16x32_bf16 v[122:125], v[34:37], v[10:13], v[66:69]
	v_mfma_f32_16x16x32_bf16 v[66:69], v[18:21], v[188:191], v[136:139]
	v_mfma_f32_16x16x32_bf16 v[118:121], v[34:37], v[156:159], v[66:69]
	v_mfma_f32_16x16x32_bf16 v[66:69], v[26:29], v[2:5], v[206:209]
	v_mfma_f32_16x16x32_bf16 v[102:105], v[42:45], v[10:13], v[66:69]
	v_mfma_f32_16x16x32_bf16 v[66:69], v[26:29], v[188:191], v[114:117]
	v_mfma_f32_16x16x32_bf16 v[98:101], v[42:45], v[156:159], v[66:69]
	v_mfma_f32_16x16x32_bf16 v[66:69], v[50:53], v[2:5], v[110:113]
	v_mfma_f32_16x16x32_bf16 v[86:89], v[192:195], v[10:13], v[66:69]
	v_mfma_f32_16x16x32_bf16 v[66:69], v[50:53], v[188:191], v[106:109]
	v_mfma_f32_16x16x32_bf16 v[82:85], v[192:195], v[156:159], v[66:69]
	v_mfma_f32_16x16x32_bf16 v[66:69], v[58:61], v[2:5], v[218:221]
	v_mfma_f32_16x16x32_bf16 v[70:73], v[196:199], v[10:13], v[66:69]
	v_mfma_f32_16x16x32_bf16 v[66:69], v[58:61], v[188:191], v[222:225]
	v_mfma_f32_16x16x32_bf16 v[66:69], v[196:199], v[156:159], v[66:69]
	s_setprio 0
	s_barrier
	ds_read_b128 v[136:139], v0
	ds_read_b128 v[206:209], v152
	ds_read_b128 v[218:221], v153
	ds_read_b128 v[152:155], v154
	s_waitcnt vmcnt(0)
	s_barrier
	s_waitcnt lgkmcnt(0)
	s_setprio 1
	s_waitcnt lgkmcnt(0)
	v_mfma_f32_16x16x32_bf16 v[94:97], v[18:21], v[136:139], v[94:97]
	v_mfma_f32_16x16x32_bf16 v[18:21], v[18:21], v[218:221], v[90:93]
	v_mfma_f32_16x16x32_bf16 v[114:117], v[34:37], v[152:155], v[18:21]
	v_mfma_f32_16x16x32_bf16 v[18:21], v[26:29], v[136:139], v[160:163]
	v_mfma_f32_16x16x32_bf16 v[110:113], v[42:45], v[206:209], v[18:21]
	v_mfma_f32_16x16x32_bf16 v[18:21], v[26:29], v[218:221], v[172:175]
	v_mfma_f32_16x16x32_bf16 v[106:109], v[42:45], v[152:155], v[18:21]
	v_mfma_f32_16x16x32_bf16 v[18:21], v[50:53], v[136:139], v[78:81]
	v_mfma_f32_16x16x32_bf16 v[126:129], v[34:37], v[206:209], v[94:97]
	v_mfma_f32_16x16x32_bf16 v[94:97], v[192:195], v[206:209], v[18:21]
	v_mfma_f32_16x16x32_bf16 v[18:21], v[50:53], v[218:221], v[74:77]
	v_mfma_f32_16x16x32_bf16 v[90:93], v[192:195], v[152:155], v[18:21]
	v_mfma_f32_16x16x32_bf16 v[18:21], v[58:61], v[136:139], v[176:179]
	v_mfma_f32_16x16x32_bf16 v[78:81], v[196:199], v[206:209], v[18:21]
	v_mfma_f32_16x16x32_bf16 v[18:21], v[58:61], v[218:221], v[180:183]
	v_mfma_f32_16x16x32_bf16 v[74:77], v[196:199], v[152:155], v[18:21]
	s_setprio 0
	s_barrier
	ds_read_b128 v[160:163], v150 offset:49152
	ds_read_b128 v[172:175], v150 offset:51200
	ds_read_b128 v[176:179], v151 offset:49152
	ds_read_b128 v[180:183], v151 offset:51200
	ds_read_b128 v[192:195], v150 offset:53248
	ds_read_b128 v[196:199], v150 offset:55296
	ds_read_b128 v[222:225], v151 offset:53248
	ds_read_b128 v[148:151], v151 offset:55296
	s_barrier
	s_waitcnt lgkmcnt(0)
	s_setprio 1
	s_waitcnt lgkmcnt(0)
	v_mfma_f32_16x16x32_bf16 v[18:21], v[160:163], v[2:5], v[62:65]
	v_mfma_f32_16x16x32_bf16 v[58:61], v[176:179], v[10:13], v[18:21]
	v_mfma_f32_16x16x32_bf16 v[18:21], v[160:163], v[188:191], v[200:203]
	v_mfma_f32_16x16x32_bf16 v[50:53], v[176:179], v[156:159], v[18:21]
	v_mfma_f32_16x16x32_bf16 v[18:21], v[172:175], v[2:5], v[54:57]
	v_mfma_f32_16x16x32_bf16 v[42:45], v[180:183], v[10:13], v[18:21]
	v_mfma_f32_16x16x32_bf16 v[18:21], v[172:175], v[188:191], v[226:229]
	v_mfma_f32_16x16x32_bf16 v[34:37], v[180:183], v[156:159], v[18:21]
	v_mfma_f32_16x16x32_bf16 v[18:21], v[192:195], v[2:5], v[46:49]
	v_mfma_f32_16x16x32_bf16 v[2:5], v[196:199], v[2:5], v[38:41]
	v_mfma_f32_16x16x32_bf16 v[26:29], v[222:225], v[10:13], v[18:21]
	v_mfma_f32_16x16x32_bf16 v[18:21], v[192:195], v[188:191], v[230:233]
	v_mfma_f32_16x16x32_bf16 v[10:13], v[148:151], v[10:13], v[2:5]
	v_mfma_f32_16x16x32_bf16 v[2:5], v[196:199], v[188:191], v[140:143]
	v_mfma_f32_16x16x32_bf16 v[18:21], v[222:225], v[156:159], v[18:21]
	v_mfma_f32_16x16x32_bf16 v[2:5], v[148:151], v[156:159], v[2:5]
	s_setprio 0
	s_setprio 1
	v_mfma_f32_16x16x32_bf16 v[30:33], v[160:163], v[136:139], v[30:33]
	v_mfma_f32_16x16x32_bf16 v[62:65], v[176:179], v[206:209], v[30:33]
	v_mfma_f32_16x16x32_bf16 v[30:33], v[160:163], v[218:221], v[144:147]
	v_mfma_f32_16x16x32_bf16 v[22:25], v[172:175], v[136:139], v[22:25]
	v_mfma_f32_16x16x32_bf16 v[14:17], v[192:195], v[136:139], v[14:17]
	v_mfma_f32_16x16x32_bf16 v[54:57], v[176:179], v[152:155], v[30:33]
	v_mfma_f32_16x16x32_bf16 v[46:49], v[180:183], v[206:209], v[22:25]
	v_mfma_f32_16x16x32_bf16 v[22:25], v[172:175], v[218:221], v[164:167]
	v_mfma_f32_16x16x32_bf16 v[30:33], v[222:225], v[206:209], v[14:17]
	v_mfma_f32_16x16x32_bf16 v[14:17], v[192:195], v[218:221], v[168:171]
	v_mfma_f32_16x16x32_bf16 v[6:9], v[196:199], v[136:139], v[6:9]
	v_mfma_f32_16x16x32_bf16 v[38:41], v[180:183], v[152:155], v[22:25]
	v_mfma_f32_16x16x32_bf16 v[22:25], v[222:225], v[152:155], v[14:17]
	v_mfma_f32_16x16x32_bf16 v[14:17], v[148:151], v[206:209], v[6:9]
	v_mfma_f32_16x16x32_bf16 v[6:9], v[196:199], v[218:221], v[184:187]
	v_mfma_f32_16x16x32_bf16 v[6:9], v[148:151], v[152:155], v[6:9]
	s_setprio 0
	s_cmpk_gt_u32 s0, 0xff
	s_barrier
	s_cbranch_scc1 .LBB0_104
	s_barrier

.LBB0_109:
	v_or_b32_e32 v0, 0x10000, v150
	v_add_u32_e32 v153, 0x10800, v150
	v_or_b32_e32 v152, 0x10000, v151
	ds_read_b128 v[160:163], v0
	ds_read_b128 v[164:167], v152
	v_add_u32_e32 v154, 0x10800, v151
	ds_read_b128 v[168:171], v153
	ds_read_b128 v[172:175], v154
	v_lshl_add_u64 v[210:211], v[132:133], 0, v[142:143]
	s_add_i32 s30, s1, 0xc000
	v_lshl_add_u64 v[156:157], v[210:211], 0, s[50:51]
	s_mov_b32 m0, s30
	v_lshl_add_u64 v[214:215], v[132:133], 0, v[140:141]
	s_add_i32 s5, s1, 0xe000
	ds_read_b128 v[176:179], v148
	ds_read_b128 v[180:183], v148 offset:2048
	ds_read_b128 v[184:187], v149
	ds_read_b128 v[188:191], v149 offset:2048
	ds_read_b128 v[192:195], v148 offset:4096
	ds_read_b128 v[196:199], v148 offset:6144
	ds_read_b128 v[200:203], v149 offset:4096
	ds_read_b128 v[206:209], v149 offset:6144
	global_load_lds_dwordx4 v[156:157], off
	v_lshl_add_u64 v[156:157], v[214:215], 0, s[50:51]
	s_mov_b32 m0, s5
	s_nop 0
	global_load_lds_dwordx4 v[156:157], off
	s_waitcnt lgkmcnt(8)
	s_waitcnt vmcnt(10)
	s_barrier
	s_waitcnt lgkmcnt(0)
	s_setprio 1
	s_waitcnt lgkmcnt(0)
	v_mfma_f32_16x16x32_bf16 v[126:129], v[160:163], v[176:179], v[126:129]
	v_mfma_f32_16x16x32_bf16 v[122:125], v[168:171], v[176:179], v[122:125]
	v_mfma_f32_16x16x32_bf16 v[118:121], v[160:163], v[180:183], v[118:121]
	v_mfma_f32_16x16x32_bf16 v[114:117], v[168:171], v[180:183], v[114:117]
	v_mfma_f32_16x16x32_bf16 v[110:113], v[160:163], v[192:195], v[110:113]
	v_mfma_f32_16x16x32_bf16 v[106:109], v[168:171], v[192:195], v[106:109]
	v_mfma_f32_16x16x32_bf16 v[102:105], v[160:163], v[196:199], v[102:105]
	v_mfma_f32_16x16x32_bf16 v[98:101], v[168:171], v[196:199], v[98:101]
	v_mfma_f32_16x16x32_bf16 v[126:129], v[164:167], v[184:187], v[126:129]
	v_mfma_f32_16x16x32_bf16 v[122:125], v[172:175], v[184:187], v[122:125]
	v_mfma_f32_16x16x32_bf16 v[118:121], v[164:167], v[188:191], v[118:121]
	v_mfma_f32_16x16x32_bf16 v[114:117], v[172:175], v[188:191], v[114:117]
	v_mfma_f32_16x16x32_bf16 v[110:113], v[164:167], v[200:203], v[110:113]
	v_mfma_f32_16x16x32_bf16 v[106:109], v[172:175], v[200:203], v[106:109]
	v_mfma_f32_16x16x32_bf16 v[102:105], v[164:167], v[206:209], v[102:105]
	v_mfma_f32_16x16x32_bf16 v[98:101], v[172:175], v[206:209], v[98:101]
	s_setprio 0
	s_barrier
	v_lshl_add_u64 v[242:243], v[132:133], 0, v[146:147]
	s_mov_b32 m0, s2
	v_or_b32_e32 v155, 0x14000, v150
	v_add_u32_e32 v157, 0x14800, v150
	v_lshl_add_u64 v[234:235], v[242:243], 0, s[70:71]
	v_lshl_add_u64 v[244:245], v[132:133], 0, v[144:145]
	v_or_b32_e32 v156, 0x14000, v151
	ds_read_b128 v[218:221], v155
	ds_read_b128 v[222:225], v156
	v_add_u32_e32 v158, 0x14800, v151
	ds_read_b128 v[226:229], v157
	ds_read_b128 v[230:233], v158
	global_load_lds_dwordx4 v[234:235], off
	v_lshl_add_u64 v[234:235], v[244:245], 0, s[70:71]
	s_mov_b32 m0, s3
	s_nop 0
	global_load_lds_dwordx4 v[234:235], off
	s_waitcnt vmcnt(10)
	s_waitcnt lgkmcnt(0)
	s_barrier
	s_waitcnt lgkmcnt(0)
	s_setprio 1
	s_waitcnt lgkmcnt(0)
	v_mfma_f32_16x16x32_bf16 v[94:97], v[218:221], v[176:179], v[94:97]
	v_mfma_f32_16x16x32_bf16 v[90:93], v[226:229], v[176:179], v[90:93]
	v_mfma_f32_16x16x32_bf16 v[86:89], v[218:221], v[180:183], v[86:89]
	v_mfma_f32_16x16x32_bf16 v[82:85], v[226:229], v[180:183], v[82:85]
	v_mfma_f32_16x16x32_bf16 v[78:81], v[218:221], v[192:195], v[78:81]
	v_mfma_f32_16x16x32_bf16 v[74:77], v[226:229], v[192:195], v[74:77]
	v_mfma_f32_16x16x32_bf16 v[70:73], v[218:221], v[196:199], v[70:73]
	v_mfma_f32_16x16x32_bf16 v[66:69], v[226:229], v[196:199], v[66:69]
	v_mfma_f32_16x16x32_bf16 v[94:97], v[222:225], v[184:187], v[94:97]
	v_mfma_f32_16x16x32_bf16 v[90:93], v[230:233], v[184:187], v[90:93]
	v_mfma_f32_16x16x32_bf16 v[86:89], v[222:225], v[188:191], v[86:89]
	v_mfma_f32_16x16x32_bf16 v[82:85], v[230:233], v[188:191], v[82:85]
	v_mfma_f32_16x16x32_bf16 v[78:81], v[222:225], v[200:203], v[78:81]
	v_mfma_f32_16x16x32_bf16 v[74:77], v[230:233], v[200:203], v[74:77]
	v_mfma_f32_16x16x32_bf16 v[70:73], v[222:225], v[206:209], v[70:73]
	v_mfma_f32_16x16x32_bf16 v[66:69], v[230:233], v[206:209], v[66:69]
	s_setprio 0
	s_mov_b32 m0, s1
	v_lshl_add_u64 v[234:235], v[210:211], 0, s[54:55]
	s_barrier
	ds_read_b128 v[176:179], v148 offset:16384
	ds_read_b128 v[180:183], v148 offset:18432
	ds_read_b128 v[184:187], v149 offset:16384
	ds_read_b128 v[188:191], v149 offset:18432
	ds_read_b128 v[192:195], v148 offset:20480
	ds_read_b128 v[196:199], v148 offset:22528
	ds_read_b128 v[200:203], v149 offset:20480
	ds_read_b128 v[206:209], v149 offset:22528
	global_load_lds_dwordx4 v[234:235], off
	v_lshl_add_u64 v[234:235], v[214:215], 0, s[54:55]
	s_mov_b32 m0, s9
	s_nop 0
	global_load_lds_dwordx4 v[234:235], off
	v_lshl_add_u64 v[234:235], v[242:243], 0, s[34:35]
	s_mov_b32 m0, s11
	s_nop 0
	global_load_lds_dwordx4 v[234:235], off
	v_lshl_add_u64 v[234:235], v[244:245], 0, s[34:35]
	s_mov_b32 m0, s12
	s_nop 0
	global_load_lds_dwordx4 v[234:235], off
	s_waitcnt vmcnt(10)
	s_waitcnt lgkmcnt(0)
	s_barrier
	s_waitcnt lgkmcnt(0)
	s_setprio 1
	s_waitcnt lgkmcnt(0)
	v_mfma_f32_16x16x32_bf16 v[62:65], v[160:163], v[176:179], v[62:65]
	v_mfma_f32_16x16x32_bf16 v[58:61], v[168:171], v[176:179], v[58:61]
	v_mfma_f32_16x16x32_bf16 v[54:57], v[160:163], v[180:183], v[54:57]
	v_mfma_f32_16x16x32_bf16 v[50:53], v[168:171], v[180:183], v[50:53]
	v_mfma_f32_16x16x32_bf16 v[46:49], v[160:163], v[192:195], v[46:49]
	v_mfma_f32_16x16x32_bf16 v[42:45], v[168:171], v[192:195], v[42:45]
	v_mfma_f32_16x16x32_bf16 v[38:41], v[160:163], v[196:199], v[38:41]
	v_mfma_f32_16x16x32_bf16 v[34:37], v[168:171], v[196:199], v[34:37]
	v_mfma_f32_16x16x32_bf16 v[62:65], v[164:167], v[184:187], v[62:65]
	v_mfma_f32_16x16x32_bf16 v[58:61], v[172:175], v[184:187], v[58:61]
	v_mfma_f32_16x16x32_bf16 v[54:57], v[164:167], v[188:191], v[54:57]
	v_mfma_f32_16x16x32_bf16 v[50:53], v[172:175], v[188:191], v[50:53]
	v_mfma_f32_16x16x32_bf16 v[46:49], v[164:167], v[200:203], v[46:49]
	v_mfma_f32_16x16x32_bf16 v[42:45], v[172:175], v[200:203], v[42:45]
	v_mfma_f32_16x16x32_bf16 v[38:41], v[164:167], v[206:209], v[38:41]
	v_mfma_f32_16x16x32_bf16 v[34:37], v[172:175], v[206:209], v[34:37]
	v_mfma_f32_16x16x32_bf16 v[30:33], v[218:221], v[176:179], v[30:33]
	v_mfma_f32_16x16x32_bf16 v[26:29], v[226:229], v[176:179], v[26:29]
	v_mfma_f32_16x16x32_bf16 v[22:25], v[218:221], v[180:183], v[22:25]
	v_mfma_f32_16x16x32_bf16 v[18:21], v[226:229], v[180:183], v[18:21]
	v_mfma_f32_16x16x32_bf16 v[14:17], v[218:221], v[192:195], v[14:17]
	v_mfma_f32_16x16x32_bf16 v[10:13], v[226:229], v[192:195], v[10:13]
	v_mfma_f32_16x16x32_bf16 v[6:9], v[218:221], v[196:199], v[6:9]
	v_mfma_f32_16x16x32_bf16 v[2:5], v[226:229], v[196:199], v[2:5]
	v_mfma_f32_16x16x32_bf16 v[30:33], v[222:225], v[184:187], v[30:33]
	v_mfma_f32_16x16x32_bf16 v[26:29], v[230:233], v[184:187], v[26:29]
	v_mfma_f32_16x16x32_bf16 v[22:25], v[222:225], v[188:191], v[22:25]
	v_mfma_f32_16x16x32_bf16 v[18:21], v[230:233], v[188:191], v[18:21]
	v_mfma_f32_16x16x32_bf16 v[14:17], v[222:225], v[200:203], v[14:17]
	v_mfma_f32_16x16x32_bf16 v[10:13], v[230:233], v[200:203], v[10:13]
	v_mfma_f32_16x16x32_bf16 v[6:9], v[222:225], v[206:209], v[6:9]
	v_mfma_f32_16x16x32_bf16 v[2:5], v[230:233], v[206:209], v[2:5]
	s_setprio 0
	v_or_b32_e32 v159, 0x18000, v150
	v_add_u32_e32 v161, 0x18800, v150
	s_barrier
	v_or_b32_e32 v160, 0x18000, v151
	ds_read_b128 v[168:171], v159
	ds_read_b128 v[172:175], v160
	v_add_u32_e32 v162, 0x18800, v151
	ds_read_b128 v[176:179], v161
	ds_read_b128 v[180:183], v162
	s_mov_b32 m0, s13
	v_lshl_add_u64 v[164:165], v[210:211], 0, s[58:59]
	ds_read_b128 v[184:187], v148 offset:32768
	ds_read_b128 v[188:191], v148 offset:34816
	ds_read_b128 v[192:195], v149 offset:32768
	ds_read_b128 v[196:199], v149 offset:34816
	ds_read_b128 v[200:203], v148 offset:36864
	ds_read_b128 v[206:209], v148 offset:38912
	ds_read_b128 v[218:221], v149 offset:36864
	ds_read_b128 v[222:225], v149 offset:38912
	global_load_lds_dwordx4 v[164:165], off
	v_lshl_add_u64 v[164:165], v[214:215], 0, s[58:59]
	s_mov_b32 m0, s23
	s_nop 0
	global_load_lds_dwordx4 v[164:165], off
	s_waitcnt lgkmcnt(8)
	s_waitcnt vmcnt(10)
	s_barrier
	s_waitcnt lgkmcnt(0)
	s_setprio 1
	s_waitcnt lgkmcnt(0)
	v_mfma_f32_16x16x32_bf16 v[126:129], v[168:171], v[184:187], v[126:129]
	v_mfma_f32_16x16x32_bf16 v[122:125], v[176:179], v[184:187], v[122:125]
	v_mfma_f32_16x16x32_bf16 v[118:121], v[168:171], v[188:191], v[118:121]
	v_mfma_f32_16x16x32_bf16 v[114:117], v[176:179], v[188:191], v[114:117]
	v_mfma_f32_16x16x32_bf16 v[110:113], v[168:171], v[200:203], v[110:113]
	v_mfma_f32_16x16x32_bf16 v[106:109], v[176:179], v[200:203], v[106:109]
	v_mfma_f32_16x16x32_bf16 v[102:105], v[168:171], v[206:209], v[102:105]
	v_mfma_f32_16x16x32_bf16 v[98:101], v[176:179], v[206:209], v[98:101]
	v_mfma_f32_16x16x32_bf16 v[126:129], v[172:175], v[192:195], v[126:129]
	v_mfma_f32_16x16x32_bf16 v[122:125], v[180:183], v[192:195], v[122:125]
	v_mfma_f32_16x16x32_bf16 v[118:121], v[172:175], v[196:199], v[118:121]
	v_mfma_f32_16x16x32_bf16 v[114:117], v[180:183], v[196:199], v[114:117]
	v_mfma_f32_16x16x32_bf16 v[110:113], v[172:175], v[218:221], v[110:113]
	v_mfma_f32_16x16x32_bf16 v[106:109], v[180:183], v[218:221], v[106:109]
	v_mfma_f32_16x16x32_bf16 v[102:105], v[172:175], v[222:225], v[102:105]
	v_mfma_f32_16x16x32_bf16 v[98:101], v[180:183], v[222:225], v[98:101]
	s_setprio 0
	s_barrier
	s_mov_b32 m0, s24
	v_or_b32_e32 v163, 0x1c000, v150
	v_add_u32_e32 v165, 0x1c800, v150
	v_lshl_add_u64 v[246:247], v[242:243], 0, s[36:37]
	v_or_b32_e32 v164, 0x1c000, v151
	ds_read_b128 v[226:229], v163
	ds_read_b128 v[230:233], v164
	v_add_u32_e32 v166, 0x1c800, v151
	ds_read_b128 v[234:237], v165
	ds_read_b128 v[238:241], v166
	global_load_lds_dwordx4 v[246:247], off
	v_lshl_add_u64 v[246:247], v[244:245], 0, s[36:37]
	s_mov_b32 m0, s25
	s_nop 0
	global_load_lds_dwordx4 v[246:247], off
	s_waitcnt vmcnt(10)
	s_waitcnt lgkmcnt(0)
	s_barrier
	s_waitcnt lgkmcnt(0)
	s_setprio 1
	s_waitcnt lgkmcnt(0)
	v_mfma_f32_16x16x32_bf16 v[94:97], v[226:229], v[184:187], v[94:97]
	v_mfma_f32_16x16x32_bf16 v[90:93], v[234:237], v[184:187], v[90:93]
	v_mfma_f32_16x16x32_bf16 v[86:89], v[226:229], v[188:191], v[86:89]
	v_mfma_f32_16x16x32_bf16 v[82:85], v[234:237], v[188:191], v[82:85]
	v_mfma_f32_16x16x32_bf16 v[78:81], v[226:229], v[200:203], v[78:81]
	v_mfma_f32_16x16x32_bf16 v[74:77], v[234:237], v[200:203], v[74:77]
	v_mfma_f32_16x16x32_bf16 v[70:73], v[226:229], v[206:209], v[70:73]
	v_mfma_f32_16x16x32_bf16 v[66:69], v[234:237], v[206:209], v[66:69]
	v_mfma_f32_16x16x32_bf16 v[94:97], v[230:233], v[192:195], v[94:97]
	v_mfma_f32_16x16x32_bf16 v[90:93], v[238:241], v[192:195], v[90:93]
	v_mfma_f32_16x16x32_bf16 v[86:89], v[230:233], v[196:199], v[86:89]
	v_mfma_f32_16x16x32_bf16 v[82:85], v[238:241], v[196:199], v[82:85]
	v_mfma_f32_16x16x32_bf16 v[78:81], v[230:233], v[218:221], v[78:81]
	v_mfma_f32_16x16x32_bf16 v[74:77], v[238:241], v[218:221], v[74:77]
	v_mfma_f32_16x16x32_bf16 v[70:73], v[230:233], v[222:225], v[70:73]
	v_mfma_f32_16x16x32_bf16 v[66:69], v[238:241], v[222:225], v[66:69]
	s_setprio 0
	s_mov_b32 m0, s26
	v_lshl_add_u64 v[210:211], v[210:211], 0, s[62:63]
	s_barrier
	ds_read_b128 v[184:187], v148 offset:49152
	ds_read_b128 v[188:191], v148 offset:51200
	ds_read_b128 v[192:195], v149 offset:49152
	ds_read_b128 v[196:199], v149 offset:51200
	ds_read_b128 v[200:203], v148 offset:53248
	ds_read_b128 v[206:209], v148 offset:55296
	ds_read_b128 v[218:221], v149 offset:53248
	ds_read_b128 v[222:225], v149 offset:55296
	global_load_lds_dwordx4 v[210:211], off
	v_lshl_add_u64 v[210:211], v[214:215], 0, s[62:63]
	s_mov_b32 m0, s27
	s_nop 0
	global_load_lds_dwordx4 v[210:211], off
	v_lshl_add_u64 v[210:211], v[242:243], 0, s[38:39]
	s_mov_b32 m0, s28
	s_nop 0
	global_load_lds_dwordx4 v[210:211], off
	v_lshl_add_u64 v[210:211], v[244:245], 0, s[38:39]
	s_mov_b32 m0, s29
	s_nop 0
	global_load_lds_dwordx4 v[210:211], off
	s_waitcnt vmcnt(10)
	s_waitcnt lgkmcnt(0)
	s_barrier
	s_waitcnt lgkmcnt(0)
	s_setprio 1
	s_waitcnt lgkmcnt(0)
	v_mfma_f32_16x16x32_bf16 v[62:65], v[168:171], v[184:187], v[62:65]
	v_mfma_f32_16x16x32_bf16 v[58:61], v[176:179], v[184:187], v[58:61]
	v_mfma_f32_16x16x32_bf16 v[54:57], v[168:171], v[188:191], v[54:57]
	v_mfma_f32_16x16x32_bf16 v[50:53], v[176:179], v[188:191], v[50:53]
	v_mfma_f32_16x16x32_bf16 v[46:49], v[168:171], v[200:203], v[46:49]
	v_mfma_f32_16x16x32_bf16 v[42:45], v[176:179], v[200:203], v[42:45]
	v_mfma_f32_16x16x32_bf16 v[38:41], v[168:171], v[206:209], v[38:41]
	v_mfma_f32_16x16x32_bf16 v[34:37], v[176:179], v[206:209], v[34:37]
	v_mfma_f32_16x16x32_bf16 v[62:65], v[172:175], v[192:195], v[62:65]
	v_mfma_f32_16x16x32_bf16 v[58:61], v[180:183], v[192:195], v[58:61]
	v_mfma_f32_16x16x32_bf16 v[54:57], v[172:175], v[196:199], v[54:57]
	v_mfma_f32_16x16x32_bf16 v[50:53], v[180:183], v[196:199], v[50:53]
	v_mfma_f32_16x16x32_bf16 v[46:49], v[172:175], v[218:221], v[46:49]
	v_mfma_f32_16x16x32_bf16 v[42:45], v[180:183], v[218:221], v[42:45]
	v_mfma_f32_16x16x32_bf16 v[38:41], v[172:175], v[222:225], v[38:41]
	v_mfma_f32_16x16x32_bf16 v[34:37], v[180:183], v[222:225], v[34:37]
	v_mfma_f32_16x16x32_bf16 v[30:33], v[226:229], v[184:187], v[30:33]
	v_mfma_f32_16x16x32_bf16 v[26:29], v[234:237], v[184:187], v[26:29]
	v_mfma_f32_16x16x32_bf16 v[22:25], v[226:229], v[188:191], v[22:25]
	v_mfma_f32_16x16x32_bf16 v[18:21], v[234:237], v[188:191], v[18:21]
	v_mfma_f32_16x16x32_bf16 v[14:17], v[226:229], v[200:203], v[14:17]
	v_mfma_f32_16x16x32_bf16 v[10:13], v[234:237], v[200:203], v[10:13]
	v_mfma_f32_16x16x32_bf16 v[6:9], v[226:229], v[206:209], v[6:9]
	v_mfma_f32_16x16x32_bf16 v[2:5], v[234:237], v[206:209], v[2:5]
	v_mfma_f32_16x16x32_bf16 v[30:33], v[230:233], v[192:195], v[30:33]
	v_mfma_f32_16x16x32_bf16 v[26:29], v[238:241], v[192:195], v[26:29]
	v_mfma_f32_16x16x32_bf16 v[22:25], v[230:233], v[196:199], v[22:25]
	v_mfma_f32_16x16x32_bf16 v[18:21], v[238:241], v[196:199], v[18:21]
	v_mfma_f32_16x16x32_bf16 v[14:17], v[230:233], v[218:221], v[14:17]
	v_mfma_f32_16x16x32_bf16 v[10:13], v[238:241], v[218:221], v[10:13]
	v_mfma_f32_16x16x32_bf16 v[6:9], v[230:233], v[222:225], v[6:9]
	v_mfma_f32_16x16x32_bf16 v[2:5], v[238:241], v[222:225], v[2:5]
	s_setprio 0
	s_add_i32 s4, s4, 2
	s_cmp_lt_u32 s4, 28
	v_lshl_add_u64 v[132:133], v[132:133], 0, s[54:55]
	s_barrier
	s_cbranch_scc1 .LBB0_109
	s_waitcnt vmcnt(6)
	s_mov_b64 s[2:3], 0xf80
	s_mov_b32 m0, s30
	v_lshl_add_u64 v[132:133], v[138:139], 0, s[2:3]
	ds_read_b128 v[140:143], v0
	ds_read_b128 v[144:147], v152
	ds_read_b128 v[150:153], v153
	ds_read_b128 v[168:171], v154
	ds_read_b128 v[172:175], v148
	ds_read_b128 v[176:179], v148 offset:2048
	ds_read_b128 v[180:183], v149
	ds_read_b128 v[184:187], v149 offset:2048
	ds_read_b128 v[188:191], v148 offset:4096
	ds_read_b128 v[192:195], v148 offset:6144
	ds_read_b128 v[196:199], v149 offset:4096
	ds_read_b128 v[200:203], v149 offset:6144
	global_load_lds_dwordx4 v[132:133], off
	v_lshl_add_u64 v[132:133], v[136:137], 0, s[2:3]
	s_mov_b32 m0, s5
	s_nop 0
	global_load_lds_dwordx4 v[132:133], off
	s_barrier
	s_waitcnt lgkmcnt(0)
	s_setprio 1
	s_waitcnt lgkmcnt(0)
	v_mfma_f32_16x16x32_bf16 v[126:129], v[140:143], v[172:175], v[126:129]
	v_mfma_f32_16x16x32_bf16 v[122:125], v[150:153], v[172:175], v[122:125]
	v_mfma_f32_16x16x32_bf16 v[118:121], v[140:143], v[176:179], v[118:121]
	v_mfma_f32_16x16x32_bf16 v[110:113], v[140:143], v[188:191], v[110:113]
	v_mfma_f32_16x16x32_bf16 v[106:109], v[150:153], v[188:191], v[106:109]
	v_mfma_f32_16x16x32_bf16 v[126:129], v[144:147], v[180:183], v[126:129]
	v_mfma_f32_16x16x32_bf16 v[122:125], v[168:171], v[180:183], v[122:125]
	v_mfma_f32_16x16x32_bf16 v[118:121], v[144:147], v[184:187], v[118:121]
	v_mfma_f32_16x16x32_bf16 v[114:117], v[150:153], v[176:179], v[114:117]
	v_mfma_f32_16x16x32_bf16 v[110:113], v[144:147], v[196:199], v[110:113]
	v_mfma_f32_16x16x32_bf16 v[106:109], v[168:171], v[196:199], v[106:109]
	v_mfma_f32_16x16x32_bf16 v[102:105], v[140:143], v[192:195], v[102:105]
	v_mfma_f32_16x16x32_bf16 v[98:101], v[150:153], v[192:195], v[98:101]
	v_mfma_f32_16x16x32_bf16 v[136:139], v[168:171], v[184:187], v[114:117]
	v_mfma_f32_16x16x32_bf16 v[206:209], v[144:147], v[200:203], v[102:105]
	v_mfma_f32_16x16x32_bf16 v[218:221], v[168:171], v[200:203], v[98:101]
	s_setprio 0
	s_barrier
	s_nop 2
	ds_read_b128 v[98:101], v155
	ds_read_b128 v[102:105], v156
	ds_read_b128 v[114:117], v157
	ds_read_b128 v[154:157], v158
	s_barrier
	s_waitcnt lgkmcnt(0)
	s_setprio 1
	s_waitcnt lgkmcnt(0)
	v_mfma_f32_16x16x32_bf16 v[94:97], v[98:101], v[172:175], v[94:97]
	v_mfma_f32_16x16x32_bf16 v[90:93], v[114:117], v[172:175], v[90:93]
	v_mfma_f32_16x16x32_bf16 v[78:81], v[98:101], v[188:191], v[78:81]
	v_mfma_f32_16x16x32_bf16 v[74:77], v[114:117], v[188:191], v[74:77]
	v_mfma_f32_16x16x32_bf16 v[94:97], v[102:105], v[180:183], v[94:97]
	v_mfma_f32_16x16x32_bf16 v[90:93], v[154:157], v[180:183], v[90:93]
	v_mfma_f32_16x16x32_bf16 v[86:89], v[98:101], v[176:179], v[86:89]
	v_mfma_f32_16x16x32_bf16 v[82:85], v[114:117], v[176:179], v[82:85]
	v_mfma_f32_16x16x32_bf16 v[78:81], v[102:105], v[196:199], v[78:81]
	v_mfma_f32_16x16x32_bf16 v[74:77], v[154:157], v[196:199], v[74:77]
	v_mfma_f32_16x16x32_bf16 v[70:73], v[98:101], v[192:195], v[70:73]
	v_mfma_f32_16x16x32_bf16 v[66:69], v[114:117], v[192:195], v[66:69]
	v_mfma_f32_16x16x32_bf16 v[172:175], v[102:105], v[184:187], v[86:89]
	v_mfma_f32_16x16x32_bf16 v[176:179], v[154:157], v[184:187], v[82:85]
	v_mfma_f32_16x16x32_bf16 v[180:183], v[102:105], v[200:203], v[70:73]
	v_mfma_f32_16x16x32_bf16 v[184:187], v[154:157], v[200:203], v[66:69]
	s_setprio 0
	s_barrier
	s_nop 1
	ds_read_b128 v[66:69], v148 offset:16384
	ds_read_b128 v[70:73], v148 offset:18432
	ds_read_b128 v[82:85], v149 offset:16384
	ds_read_b128 v[86:89], v149 offset:18432
	ds_read_b128 v[188:191], v148 offset:20480
	ds_read_b128 v[192:195], v148 offset:22528
	ds_read_b128 v[196:199], v149 offset:20480
	ds_read_b128 v[200:203], v149 offset:22528
	s_waitcnt vmcnt(4)
	s_barrier
	s_waitcnt lgkmcnt(0)
	s_setprio 1
	s_waitcnt lgkmcnt(0)
	v_mfma_f32_16x16x32_bf16 v[62:65], v[140:143], v[66:69], v[62:65]
	v_mfma_f32_16x16x32_bf16 v[58:61], v[150:153], v[66:69], v[58:61]
	v_mfma_f32_16x16x32_bf16 v[46:49], v[140:143], v[188:191], v[46:49]
	v_mfma_f32_16x16x32_bf16 v[42:45], v[150:153], v[188:191], v[42:45]
	v_mfma_f32_16x16x32_bf16 v[62:65], v[144:147], v[82:85], v[62:65]
	v_mfma_f32_16x16x32_bf16 v[58:61], v[168:171], v[82:85], v[58:61]
	v_mfma_f32_16x16x32_bf16 v[54:57], v[140:143], v[70:73], v[54:57]
	v_mfma_f32_16x16x32_bf16 v[50:53], v[150:153], v[70:73], v[50:53]
	v_mfma_f32_16x16x32_bf16 v[46:49], v[144:147], v[196:199], v[46:49]
	v_mfma_f32_16x16x32_bf16 v[42:45], v[168:171], v[196:199], v[42:45]
	v_mfma_f32_16x16x32_bf16 v[38:41], v[140:143], v[192:195], v[38:41]
	v_mfma_f32_16x16x32_bf16 v[34:37], v[150:153], v[192:195], v[34:37]
	v_mfma_f32_16x16x32_bf16 v[222:225], v[144:147], v[86:89], v[54:57]
	v_mfma_f32_16x16x32_bf16 v[226:229], v[168:171], v[86:89], v[50:53]
	v_mfma_f32_16x16x32_bf16 v[140:143], v[144:147], v[200:203], v[38:41]
	v_mfma_f32_16x16x32_bf16 v[144:147], v[168:171], v[200:203], v[34:37]
	s_setprio 0
	s_setprio 1
	v_mfma_f32_16x16x32_bf16 v[30:33], v[98:101], v[66:69], v[30:33]
	v_mfma_f32_16x16x32_bf16 v[26:29], v[114:117], v[66:69], v[26:29]
	v_mfma_f32_16x16x32_bf16 v[14:17], v[98:101], v[188:191], v[14:17]
	v_mfma_f32_16x16x32_bf16 v[10:13], v[114:117], v[188:191], v[10:13]
	v_mfma_f32_16x16x32_bf16 v[30:33], v[102:105], v[82:85], v[30:33]
	v_mfma_f32_16x16x32_bf16 v[26:29], v[154:157], v[82:85], v[26:29]
	v_mfma_f32_16x16x32_bf16 v[22:25], v[98:101], v[70:73], v[22:25]
	v_mfma_f32_16x16x32_bf16 v[18:21], v[114:117], v[70:73], v[18:21]
	v_mfma_f32_16x16x32_bf16 v[14:17], v[102:105], v[196:199], v[14:17]
	v_mfma_f32_16x16x32_bf16 v[10:13], v[154:157], v[196:199], v[10:13]
	v_mfma_f32_16x16x32_bf16 v[6:9], v[98:101], v[192:195], v[6:9]
	v_mfma_f32_16x16x32_bf16 v[2:5], v[114:117], v[192:195], v[2:5]
	v_mfma_f32_16x16x32_bf16 v[150:153], v[102:105], v[86:89], v[22:25]
	v_mfma_f32_16x16x32_bf16 v[168:171], v[154:157], v[86:89], v[18:21]
	v_mfma_f32_16x16x32_bf16 v[188:191], v[102:105], v[200:203], v[6:9]
	v_mfma_f32_16x16x32_bf16 v[154:157], v[154:157], v[200:203], v[2:5]
	s_setprio 0
	s_barrier
	s_nop 1
	ds_read_b128 v[2:5], v159
	ds_read_b128 v[6:9], v160
	ds_read_b128 v[158:161], v161
	ds_read_b128 v[192:195], v162
	ds_read_b128 v[18:21], v148 offset:32768
	ds_read_b128 v[22:25], v148 offset:34816
	ds_read_b128 v[34:37], v149 offset:32768
	ds_read_b128 v[38:41], v149 offset:34816
	ds_read_b128 v[50:53], v148 offset:36864
	ds_read_b128 v[54:57], v148 offset:38912
	ds_read_b128 v[196:199], v149 offset:36864
	ds_read_b128 v[200:203], v149 offset:38912
	s_waitcnt vmcnt(2)
	s_barrier
	s_waitcnt lgkmcnt(0)
	s_setprio 1
	s_waitcnt lgkmcnt(0)
	v_mfma_f32_16x16x32_bf16 v[66:69], v[2:5], v[18:21], v[126:129]
	v_mfma_f32_16x16x32_bf16 v[126:129], v[6:9], v[34:37], v[66:69]
	v_mfma_f32_16x16x32_bf16 v[66:69], v[158:161], v[18:21], v[122:125]
	v_mfma_f32_16x16x32_bf16 v[114:117], v[192:195], v[34:37], v[66:69]
	v_mfma_f32_16x16x32_bf16 v[66:69], v[2:5], v[22:25], v[118:121]
	v_mfma_f32_16x16x32_bf16 v[102:105], v[6:9], v[38:41], v[66:69]
	v_mfma_f32_16x16x32_bf16 v[66:69], v[158:161], v[22:25], v[136:139]
	v_mfma_f32_16x16x32_bf16 v[98:101], v[192:195], v[38:41], v[66:69]
	v_mfma_f32_16x16x32_bf16 v[66:69], v[2:5], v[50:53], v[110:113]
	v_mfma_f32_16x16x32_bf16 v[86:89], v[6:9], v[196:199], v[66:69]
	v_mfma_f32_16x16x32_bf16 v[66:69], v[158:161], v[50:53], v[106:109]
	v_mfma_f32_16x16x32_bf16 v[82:85], v[192:195], v[196:199], v[66:69]
	v_mfma_f32_16x16x32_bf16 v[66:69], v[2:5], v[54:57], v[206:209]
	v_mfma_f32_16x16x32_bf16 v[70:73], v[6:9], v[200:203], v[66:69]
	v_mfma_f32_16x16x32_bf16 v[66:69], v[158:161], v[54:57], v[218:221]
	v_mfma_f32_16x16x32_bf16 v[66:69], v[192:195], v[200:203], v[66:69]
	s_setprio 0
	s_barrier
	ds_read_b128 v[136:139], v163
	ds_read_b128 v[206:209], v164
	ds_read_b128 v[162:165], v165
	ds_read_b128 v[218:221], v166
	s_waitcnt vmcnt(0)
	s_barrier
	s_waitcnt lgkmcnt(0)
	s_setprio 1
	s_waitcnt lgkmcnt(0)
	v_mfma_f32_16x16x32_bf16 v[94:97], v[136:139], v[18:21], v[94:97]
	v_mfma_f32_16x16x32_bf16 v[18:21], v[162:165], v[18:21], v[90:93]
	v_mfma_f32_16x16x32_bf16 v[118:121], v[218:221], v[34:37], v[18:21]
	v_mfma_f32_16x16x32_bf16 v[18:21], v[136:139], v[22:25], v[172:175]
	v_mfma_f32_16x16x32_bf16 v[110:113], v[206:209], v[38:41], v[18:21]
	v_mfma_f32_16x16x32_bf16 v[18:21], v[162:165], v[22:25], v[176:179]
	v_mfma_f32_16x16x32_bf16 v[106:109], v[218:221], v[38:41], v[18:21]
	v_mfma_f32_16x16x32_bf16 v[18:21], v[136:139], v[50:53], v[78:81]
	v_mfma_f32_16x16x32_bf16 v[122:125], v[206:209], v[34:37], v[94:97]
	v_mfma_f32_16x16x32_bf16 v[94:97], v[206:209], v[196:199], v[18:21]
	v_mfma_f32_16x16x32_bf16 v[18:21], v[162:165], v[50:53], v[74:77]
	v_mfma_f32_16x16x32_bf16 v[90:93], v[218:221], v[196:199], v[18:21]
	v_mfma_f32_16x16x32_bf16 v[18:21], v[136:139], v[54:57], v[180:183]
	v_mfma_f32_16x16x32_bf16 v[78:81], v[206:209], v[200:203], v[18:21]
	v_mfma_f32_16x16x32_bf16 v[18:21], v[162:165], v[54:57], v[184:187]
	v_mfma_f32_16x16x32_bf16 v[74:77], v[218:221], v[200:203], v[18:21]
	s_setprio 0
	s_barrier
	ds_read_b128 v[172:175], v148 offset:49152
	ds_read_b128 v[176:179], v148 offset:51200
	ds_read_b128 v[180:183], v149 offset:49152
	ds_read_b128 v[184:187], v149 offset:51200
	ds_read_b128 v[196:199], v148 offset:53248
	ds_read_b128 v[200:203], v148 offset:55296
	ds_read_b128 v[230:233], v149 offset:53248
	ds_read_b128 v[234:237], v149 offset:55296
	s_barrier
	s_waitcnt lgkmcnt(0)
	s_setprio 1
	s_waitcnt lgkmcnt(0)
	v_mfma_f32_16x16x32_bf16 v[18:21], v[2:5], v[172:175], v[62:65]
	v_mfma_f32_16x16x32_bf16 v[54:57], v[6:9], v[180:183], v[18:21]
	v_mfma_f32_16x16x32_bf16 v[18:21], v[158:161], v[172:175], v[58:61]
	v_mfma_f32_16x16x32_bf16 v[50:53], v[192:195], v[180:183], v[18:21]
	v_mfma_f32_16x16x32_bf16 v[18:21], v[2:5], v[176:179], v[222:225]
	v_mfma_f32_16x16x32_bf16 v[38:41], v[6:9], v[184:187], v[18:21]
	v_mfma_f32_16x16x32_bf16 v[18:21], v[158:161], v[176:179], v[226:229]
	v_mfma_f32_16x16x32_bf16 v[34:37], v[192:195], v[184:187], v[18:21]
	v_mfma_f32_16x16x32_bf16 v[18:21], v[2:5], v[196:199], v[46:49]
	v_mfma_f32_16x16x32_bf16 v[2:5], v[2:5], v[200:203], v[140:143]
	v_mfma_f32_16x16x32_bf16 v[22:25], v[6:9], v[230:233], v[18:21]
	v_mfma_f32_16x16x32_bf16 v[18:21], v[158:161], v[196:199], v[42:45]
	v_mfma_f32_16x16x32_bf16 v[6:9], v[6:9], v[234:237], v[2:5]
	v_mfma_f32_16x16x32_bf16 v[2:5], v[158:161], v[200:203], v[144:147]
	v_mfma_f32_16x16x32_bf16 v[18:21], v[192:195], v[230:233], v[18:21]
	v_mfma_f32_16x16x32_bf16 v[2:5], v[192:195], v[234:237], v[2:5]
	s_setprio 0
	s_setprio 1
	v_mfma_f32_16x16x32_bf16 v[26:29], v[162:165], v[172:175], v[26:29]
	v_mfma_f32_16x16x32_bf16 v[58:61], v[218:221], v[180:183], v[26:29]
	v_mfma_f32_16x16x32_bf16 v[26:29], v[136:139], v[176:179], v[150:153]
	v_mfma_f32_16x16x32_bf16 v[46:49], v[206:209], v[184:187], v[26:29]
	v_mfma_f32_16x16x32_bf16 v[26:29], v[162:165], v[176:179], v[168:171]
	v_mfma_f32_16x16x32_bf16 v[10:13], v[162:165], v[196:199], v[10:13]
	v_mfma_f32_16x16x32_bf16 v[30:33], v[136:139], v[172:175], v[30:33]
	v_mfma_f32_16x16x32_bf16 v[42:45], v[218:221], v[184:187], v[26:29]
	v_mfma_f32_16x16x32_bf16 v[14:17], v[136:139], v[196:199], v[14:17]
	v_mfma_f32_16x16x32_bf16 v[26:29], v[218:221], v[230:233], v[10:13]
	v_mfma_f32_16x16x32_bf16 v[10:13], v[136:139], v[200:203], v[188:191]
	v_mfma_f32_16x16x32_bf16 v[62:65], v[206:209], v[180:183], v[30:33]
	v_mfma_f32_16x16x32_bf16 v[30:33], v[206:209], v[230:233], v[14:17]
	v_mfma_f32_16x16x32_bf16 v[14:17], v[206:209], v[234:237], v[10:13]
	v_mfma_f32_16x16x32_bf16 v[10:13], v[162:165], v[200:203], v[154:157]
	v_mfma_f32_16x16x32_bf16 v[10:13], v[218:221], v[234:237], v[10:13]
	s_setprio 0
	s_cmpk_gt_u32 s0, 0xff
	s_barrier
	s_cbranch_scc1 .LBB0_112
	s_barrier

.LBB0_117:
	v_or_b32_e32 v0, 0x10000, v150
	v_add_u32_e32 v153, 0x10800, v150
	v_or_b32_e32 v152, 0x10000, v151
	ds_read_b128 v[160:163], v0
	ds_read_b128 v[164:167], v152
	v_add_u32_e32 v154, 0x10800, v151
	ds_read_b128 v[168:171], v153
	ds_read_b128 v[172:175], v154
	v_lshl_add_u64 v[210:211], v[134:135], 0, v[142:143]
	s_add_i32 s12, s1, 0xc000
	v_lshl_add_u64 v[156:157], v[210:211], 0, s[50:51]
	s_mov_b32 m0, s12
	v_lshl_add_u64 v[214:215], v[134:135], 0, v[140:141]
	s_add_i32 s5, s1, 0xe000
	ds_read_b128 v[176:179], v148
	ds_read_b128 v[180:183], v148 offset:2048
	ds_read_b128 v[184:187], v149
	ds_read_b128 v[188:191], v149 offset:2048
	ds_read_b128 v[192:195], v148 offset:4096
	ds_read_b128 v[196:199], v148 offset:6144
	ds_read_b128 v[200:203], v149 offset:4096
	ds_read_b128 v[206:209], v149 offset:6144
	global_load_lds_dwordx4 v[156:157], off
	v_lshl_add_u64 v[156:157], v[214:215], 0, s[50:51]
	s_mov_b32 m0, s5
	s_nop 0
	global_load_lds_dwordx4 v[156:157], off
	s_waitcnt lgkmcnt(8)
	s_waitcnt vmcnt(10)
	s_barrier
	s_waitcnt lgkmcnt(0)
	s_setprio 1
	s_waitcnt lgkmcnt(0)
	v_mfma_f32_16x16x32_bf16 v[126:129], v[160:163], v[176:179], v[126:129]
	v_mfma_f32_16x16x32_bf16 v[122:125], v[168:171], v[176:179], v[122:125]
	v_mfma_f32_16x16x32_bf16 v[118:121], v[160:163], v[180:183], v[118:121]
	v_mfma_f32_16x16x32_bf16 v[114:117], v[168:171], v[180:183], v[114:117]
	v_mfma_f32_16x16x32_bf16 v[110:113], v[160:163], v[192:195], v[110:113]
	v_mfma_f32_16x16x32_bf16 v[106:109], v[168:171], v[192:195], v[106:109]
	v_mfma_f32_16x16x32_bf16 v[102:105], v[160:163], v[196:199], v[102:105]
	v_mfma_f32_16x16x32_bf16 v[98:101], v[168:171], v[196:199], v[98:101]
	v_mfma_f32_16x16x32_bf16 v[126:129], v[164:167], v[184:187], v[126:129]
	v_mfma_f32_16x16x32_bf16 v[122:125], v[172:175], v[184:187], v[122:125]
	v_mfma_f32_16x16x32_bf16 v[118:121], v[164:167], v[188:191], v[118:121]
	v_mfma_f32_16x16x32_bf16 v[114:117], v[172:175], v[188:191], v[114:117]
	v_mfma_f32_16x16x32_bf16 v[110:113], v[164:167], v[200:203], v[110:113]
	v_mfma_f32_16x16x32_bf16 v[106:109], v[172:175], v[200:203], v[106:109]
	v_mfma_f32_16x16x32_bf16 v[102:105], v[164:167], v[206:209], v[102:105]
	v_mfma_f32_16x16x32_bf16 v[98:101], v[172:175], v[206:209], v[98:101]
	s_setprio 0
	s_barrier
	v_lshl_add_u64 v[242:243], v[134:135], 0, v[146:147]
	s_mov_b32 m0, s2
	v_or_b32_e32 v155, 0x14000, v150
	v_add_u32_e32 v157, 0x14800, v150
	v_lshl_add_u64 v[234:235], v[242:243], 0, s[70:71]
	v_lshl_add_u64 v[244:245], v[134:135], 0, v[144:145]
	v_or_b32_e32 v156, 0x14000, v151
	ds_read_b128 v[218:221], v155
	ds_read_b128 v[222:225], v156
	v_add_u32_e32 v158, 0x14800, v151
	ds_read_b128 v[226:229], v157
	ds_read_b128 v[230:233], v158
	global_load_lds_dwordx4 v[234:235], off
	v_lshl_add_u64 v[234:235], v[244:245], 0, s[70:71]
	s_mov_b32 m0, s3
	s_nop 0
	global_load_lds_dwordx4 v[234:235], off
	s_waitcnt vmcnt(10)
	s_waitcnt lgkmcnt(0)
	s_barrier
	s_waitcnt lgkmcnt(0)
	s_setprio 1
	s_waitcnt lgkmcnt(0)
	v_mfma_f32_16x16x32_bf16 v[94:97], v[218:221], v[176:179], v[94:97]
	v_mfma_f32_16x16x32_bf16 v[90:93], v[226:229], v[176:179], v[90:93]
	v_mfma_f32_16x16x32_bf16 v[86:89], v[218:221], v[180:183], v[86:89]
	v_mfma_f32_16x16x32_bf16 v[82:85], v[226:229], v[180:183], v[82:85]
	v_mfma_f32_16x16x32_bf16 v[78:81], v[218:221], v[192:195], v[78:81]
	v_mfma_f32_16x16x32_bf16 v[74:77], v[226:229], v[192:195], v[74:77]
	v_mfma_f32_16x16x32_bf16 v[70:73], v[218:221], v[196:199], v[70:73]
	v_mfma_f32_16x16x32_bf16 v[66:69], v[226:229], v[196:199], v[66:69]
	v_mfma_f32_16x16x32_bf16 v[94:97], v[222:225], v[184:187], v[94:97]
	v_mfma_f32_16x16x32_bf16 v[90:93], v[230:233], v[184:187], v[90:93]
	v_mfma_f32_16x16x32_bf16 v[86:89], v[222:225], v[188:191], v[86:89]
	v_mfma_f32_16x16x32_bf16 v[82:85], v[230:233], v[188:191], v[82:85]
	v_mfma_f32_16x16x32_bf16 v[78:81], v[222:225], v[200:203], v[78:81]
	v_mfma_f32_16x16x32_bf16 v[74:77], v[230:233], v[200:203], v[74:77]
	v_mfma_f32_16x16x32_bf16 v[70:73], v[222:225], v[206:209], v[70:73]
	v_mfma_f32_16x16x32_bf16 v[66:69], v[230:233], v[206:209], v[66:69]
	s_setprio 0
	s_mov_b32 m0, s1
	v_lshl_add_u64 v[234:235], v[210:211], 0, s[54:55]
	s_barrier
	ds_read_b128 v[176:179], v148 offset:16384
	ds_read_b128 v[180:183], v148 offset:18432
	ds_read_b128 v[184:187], v149 offset:16384
	ds_read_b128 v[188:191], v149 offset:18432
	ds_read_b128 v[192:195], v148 offset:20480
	ds_read_b128 v[196:199], v148 offset:22528
	ds_read_b128 v[200:203], v149 offset:20480
	ds_read_b128 v[206:209], v149 offset:22528
	global_load_lds_dwordx4 v[234:235], off
	v_lshl_add_u64 v[234:235], v[214:215], 0, s[54:55]
	s_mov_b32 m0, s11
	s_nop 0
	global_load_lds_dwordx4 v[234:235], off
	v_lshl_add_u64 v[234:235], v[242:243], 0, s[36:37]
	s_mov_b32 m0, s23
	s_nop 0
	global_load_lds_dwordx4 v[234:235], off
	v_lshl_add_u64 v[234:235], v[244:245], 0, s[36:37]
	s_mov_b32 m0, s24
	s_nop 0
	global_load_lds_dwordx4 v[234:235], off
	s_waitcnt vmcnt(10)
	s_waitcnt lgkmcnt(0)
	s_barrier
	s_waitcnt lgkmcnt(0)
	s_setprio 1
	s_waitcnt lgkmcnt(0)
	v_mfma_f32_16x16x32_bf16 v[62:65], v[160:163], v[176:179], v[62:65]
	v_mfma_f32_16x16x32_bf16 v[58:61], v[168:171], v[176:179], v[58:61]
	v_mfma_f32_16x16x32_bf16 v[54:57], v[160:163], v[180:183], v[54:57]
	v_mfma_f32_16x16x32_bf16 v[50:53], v[168:171], v[180:183], v[50:53]
	v_mfma_f32_16x16x32_bf16 v[46:49], v[160:163], v[192:195], v[46:49]
	v_mfma_f32_16x16x32_bf16 v[42:45], v[168:171], v[192:195], v[42:45]
	v_mfma_f32_16x16x32_bf16 v[38:41], v[160:163], v[196:199], v[38:41]
	v_mfma_f32_16x16x32_bf16 v[34:37], v[168:171], v[196:199], v[34:37]
	v_mfma_f32_16x16x32_bf16 v[62:65], v[164:167], v[184:187], v[62:65]
	v_mfma_f32_16x16x32_bf16 v[58:61], v[172:175], v[184:187], v[58:61]
	v_mfma_f32_16x16x32_bf16 v[54:57], v[164:167], v[188:191], v[54:57]
	v_mfma_f32_16x16x32_bf16 v[50:53], v[172:175], v[188:191], v[50:53]
	v_mfma_f32_16x16x32_bf16 v[46:49], v[164:167], v[200:203], v[46:49]
	v_mfma_f32_16x16x32_bf16 v[42:45], v[172:175], v[200:203], v[42:45]
	v_mfma_f32_16x16x32_bf16 v[38:41], v[164:167], v[206:209], v[38:41]
	v_mfma_f32_16x16x32_bf16 v[34:37], v[172:175], v[206:209], v[34:37]
	v_mfma_f32_16x16x32_bf16 v[30:33], v[218:221], v[176:179], v[30:33]
	v_mfma_f32_16x16x32_bf16 v[26:29], v[226:229], v[176:179], v[26:29]
	v_mfma_f32_16x16x32_bf16 v[22:25], v[218:221], v[180:183], v[22:25]
	v_mfma_f32_16x16x32_bf16 v[18:21], v[226:229], v[180:183], v[18:21]
	v_mfma_f32_16x16x32_bf16 v[14:17], v[218:221], v[192:195], v[14:17]
	v_mfma_f32_16x16x32_bf16 v[10:13], v[226:229], v[192:195], v[10:13]
	v_mfma_f32_16x16x32_bf16 v[6:9], v[218:221], v[196:199], v[6:9]
	v_mfma_f32_16x16x32_bf16 v[2:5], v[226:229], v[196:199], v[2:5]
	v_mfma_f32_16x16x32_bf16 v[30:33], v[222:225], v[184:187], v[30:33]
	v_mfma_f32_16x16x32_bf16 v[26:29], v[230:233], v[184:187], v[26:29]
	v_mfma_f32_16x16x32_bf16 v[22:25], v[222:225], v[188:191], v[22:25]
	v_mfma_f32_16x16x32_bf16 v[18:21], v[230:233], v[188:191], v[18:21]
	v_mfma_f32_16x16x32_bf16 v[14:17], v[222:225], v[200:203], v[14:17]
	v_mfma_f32_16x16x32_bf16 v[10:13], v[230:233], v[200:203], v[10:13]
	v_mfma_f32_16x16x32_bf16 v[6:9], v[222:225], v[206:209], v[6:9]
	v_mfma_f32_16x16x32_bf16 v[2:5], v[230:233], v[206:209], v[2:5]
	s_setprio 0
	v_or_b32_e32 v159, 0x18000, v150
	v_add_u32_e32 v161, 0x18800, v150
	s_barrier
	v_or_b32_e32 v160, 0x18000, v151
	ds_read_b128 v[168:171], v159
	ds_read_b128 v[172:175], v160
	v_add_u32_e32 v162, 0x18800, v151
	ds_read_b128 v[176:179], v161
	ds_read_b128 v[180:183], v162
	s_mov_b32 m0, s25
	v_lshl_add_u64 v[164:165], v[210:211], 0, s[58:59]
	ds_read_b128 v[184:187], v148 offset:32768
	ds_read_b128 v[188:191], v148 offset:34816
	ds_read_b128 v[192:195], v149 offset:32768
	ds_read_b128 v[196:199], v149 offset:34816
	ds_read_b128 v[200:203], v148 offset:36864
	ds_read_b128 v[206:209], v148 offset:38912
	ds_read_b128 v[218:221], v149 offset:36864
	ds_read_b128 v[222:225], v149 offset:38912
	global_load_lds_dwordx4 v[164:165], off
	v_lshl_add_u64 v[164:165], v[214:215], 0, s[58:59]
	s_mov_b32 m0, s26
	s_nop 0
	global_load_lds_dwordx4 v[164:165], off
	s_waitcnt lgkmcnt(8)
	s_waitcnt vmcnt(10)
	s_barrier
	s_waitcnt lgkmcnt(0)
	s_setprio 1
	s_waitcnt lgkmcnt(0)
	v_mfma_f32_16x16x32_bf16 v[126:129], v[168:171], v[184:187], v[126:129]
	v_mfma_f32_16x16x32_bf16 v[122:125], v[176:179], v[184:187], v[122:125]
	v_mfma_f32_16x16x32_bf16 v[118:121], v[168:171], v[188:191], v[118:121]
	v_mfma_f32_16x16x32_bf16 v[114:117], v[176:179], v[188:191], v[114:117]
	v_mfma_f32_16x16x32_bf16 v[110:113], v[168:171], v[200:203], v[110:113]
	v_mfma_f32_16x16x32_bf16 v[106:109], v[176:179], v[200:203], v[106:109]
	v_mfma_f32_16x16x32_bf16 v[102:105], v[168:171], v[206:209], v[102:105]
	v_mfma_f32_16x16x32_bf16 v[98:101], v[176:179], v[206:209], v[98:101]
	v_mfma_f32_16x16x32_bf16 v[126:129], v[172:175], v[192:195], v[126:129]
	v_mfma_f32_16x16x32_bf16 v[122:125], v[180:183], v[192:195], v[122:125]
	v_mfma_f32_16x16x32_bf16 v[118:121], v[172:175], v[196:199], v[118:121]
	v_mfma_f32_16x16x32_bf16 v[114:117], v[180:183], v[196:199], v[114:117]
	v_mfma_f32_16x16x32_bf16 v[110:113], v[172:175], v[218:221], v[110:113]
	v_mfma_f32_16x16x32_bf16 v[106:109], v[180:183], v[218:221], v[106:109]
	v_mfma_f32_16x16x32_bf16 v[102:105], v[172:175], v[222:225], v[102:105]
	v_mfma_f32_16x16x32_bf16 v[98:101], v[180:183], v[222:225], v[98:101]
	s_setprio 0
	s_barrier
	s_mov_b32 m0, s27
	v_or_b32_e32 v163, 0x1c000, v150
	v_add_u32_e32 v165, 0x1c800, v150
	v_lshl_add_u64 v[246:247], v[242:243], 0, s[38:39]
	v_or_b32_e32 v164, 0x1c000, v151
	ds_read_b128 v[226:229], v163
	ds_read_b128 v[230:233], v164
	v_add_u32_e32 v166, 0x1c800, v151
	ds_read_b128 v[234:237], v165
	ds_read_b128 v[238:241], v166
	global_load_lds_dwordx4 v[246:247], off
	v_lshl_add_u64 v[246:247], v[244:245], 0, s[38:39]
	s_mov_b32 m0, s28
	s_nop 0
	global_load_lds_dwordx4 v[246:247], off
	s_waitcnt vmcnt(10)
	s_waitcnt lgkmcnt(0)
	s_barrier
	s_waitcnt lgkmcnt(0)
	s_setprio 1
	s_waitcnt lgkmcnt(0)
	v_mfma_f32_16x16x32_bf16 v[94:97], v[226:229], v[184:187], v[94:97]
	v_mfma_f32_16x16x32_bf16 v[90:93], v[234:237], v[184:187], v[90:93]
	v_mfma_f32_16x16x32_bf16 v[86:89], v[226:229], v[188:191], v[86:89]
	v_mfma_f32_16x16x32_bf16 v[82:85], v[234:237], v[188:191], v[82:85]
	v_mfma_f32_16x16x32_bf16 v[78:81], v[226:229], v[200:203], v[78:81]
	v_mfma_f32_16x16x32_bf16 v[74:77], v[234:237], v[200:203], v[74:77]
	v_mfma_f32_16x16x32_bf16 v[70:73], v[226:229], v[206:209], v[70:73]
	v_mfma_f32_16x16x32_bf16 v[66:69], v[234:237], v[206:209], v[66:69]
	v_mfma_f32_16x16x32_bf16 v[94:97], v[230:233], v[192:195], v[94:97]
	v_mfma_f32_16x16x32_bf16 v[90:93], v[238:241], v[192:195], v[90:93]
	v_mfma_f32_16x16x32_bf16 v[86:89], v[230:233], v[196:199], v[86:89]
	v_mfma_f32_16x16x32_bf16 v[82:85], v[238:241], v[196:199], v[82:85]
	v_mfma_f32_16x16x32_bf16 v[78:81], v[230:233], v[218:221], v[78:81]
	v_mfma_f32_16x16x32_bf16 v[74:77], v[238:241], v[218:221], v[74:77]
	v_mfma_f32_16x16x32_bf16 v[70:73], v[230:233], v[222:225], v[70:73]
	v_mfma_f32_16x16x32_bf16 v[66:69], v[238:241], v[222:225], v[66:69]
	s_setprio 0
	s_mov_b32 m0, s29
	v_lshl_add_u64 v[210:211], v[210:211], 0, s[62:63]
	s_barrier
	ds_read_b128 v[184:187], v148 offset:49152
	ds_read_b128 v[188:191], v148 offset:51200
	ds_read_b128 v[192:195], v149 offset:49152
	ds_read_b128 v[196:199], v149 offset:51200
	ds_read_b128 v[200:203], v148 offset:53248
	ds_read_b128 v[206:209], v148 offset:55296
	ds_read_b128 v[218:221], v149 offset:53248
	ds_read_b128 v[222:225], v149 offset:55296
	global_load_lds_dwordx4 v[210:211], off
	v_lshl_add_u64 v[210:211], v[214:215], 0, s[62:63]
	s_mov_b32 m0, s30
	s_nop 0
	global_load_lds_dwordx4 v[210:211], off
	v_lshl_add_u64 v[210:211], v[242:243], 0, s[40:41]
	s_mov_b32 m0, s31
	s_nop 0
	global_load_lds_dwordx4 v[210:211], off
	v_lshl_add_u64 v[210:211], v[244:245], 0, s[40:41]
	s_mov_b32 m0, s34
	s_nop 0
	global_load_lds_dwordx4 v[210:211], off
	s_waitcnt vmcnt(10)
	s_waitcnt lgkmcnt(0)
	s_barrier
	s_waitcnt lgkmcnt(0)
	s_setprio 1
	s_waitcnt lgkmcnt(0)
	v_mfma_f32_16x16x32_bf16 v[62:65], v[168:171], v[184:187], v[62:65]
	v_mfma_f32_16x16x32_bf16 v[58:61], v[176:179], v[184:187], v[58:61]
	v_mfma_f32_16x16x32_bf16 v[54:57], v[168:171], v[188:191], v[54:57]
	v_mfma_f32_16x16x32_bf16 v[50:53], v[176:179], v[188:191], v[50:53]
	v_mfma_f32_16x16x32_bf16 v[46:49], v[168:171], v[200:203], v[46:49]
	v_mfma_f32_16x16x32_bf16 v[42:45], v[176:179], v[200:203], v[42:45]
	v_mfma_f32_16x16x32_bf16 v[38:41], v[168:171], v[206:209], v[38:41]
	v_mfma_f32_16x16x32_bf16 v[34:37], v[176:179], v[206:209], v[34:37]
	v_mfma_f32_16x16x32_bf16 v[62:65], v[172:175], v[192:195], v[62:65]
	v_mfma_f32_16x16x32_bf16 v[58:61], v[180:183], v[192:195], v[58:61]
	v_mfma_f32_16x16x32_bf16 v[54:57], v[172:175], v[196:199], v[54:57]
	v_mfma_f32_16x16x32_bf16 v[50:53], v[180:183], v[196:199], v[50:53]
	v_mfma_f32_16x16x32_bf16 v[46:49], v[172:175], v[218:221], v[46:49]
	v_mfma_f32_16x16x32_bf16 v[42:45], v[180:183], v[218:221], v[42:45]
	v_mfma_f32_16x16x32_bf16 v[38:41], v[172:175], v[222:225], v[38:41]
	v_mfma_f32_16x16x32_bf16 v[34:37], v[180:183], v[222:225], v[34:37]
	v_mfma_f32_16x16x32_bf16 v[30:33], v[226:229], v[184:187], v[30:33]
	v_mfma_f32_16x16x32_bf16 v[26:29], v[234:237], v[184:187], v[26:29]
	v_mfma_f32_16x16x32_bf16 v[22:25], v[226:229], v[188:191], v[22:25]
	v_mfma_f32_16x16x32_bf16 v[18:21], v[234:237], v[188:191], v[18:21]
	v_mfma_f32_16x16x32_bf16 v[14:17], v[226:229], v[200:203], v[14:17]
	v_mfma_f32_16x16x32_bf16 v[10:13], v[234:237], v[200:203], v[10:13]
	v_mfma_f32_16x16x32_bf16 v[6:9], v[226:229], v[206:209], v[6:9]
	v_mfma_f32_16x16x32_bf16 v[2:5], v[234:237], v[206:209], v[2:5]
	v_mfma_f32_16x16x32_bf16 v[30:33], v[230:233], v[192:195], v[30:33]
	v_mfma_f32_16x16x32_bf16 v[26:29], v[238:241], v[192:195], v[26:29]
	v_mfma_f32_16x16x32_bf16 v[22:25], v[230:233], v[196:199], v[22:25]
	v_mfma_f32_16x16x32_bf16 v[18:21], v[238:241], v[196:199], v[18:21]
	v_mfma_f32_16x16x32_bf16 v[14:17], v[230:233], v[218:221], v[14:17]
	v_mfma_f32_16x16x32_bf16 v[10:13], v[238:241], v[218:221], v[10:13]
	v_mfma_f32_16x16x32_bf16 v[6:9], v[230:233], v[222:225], v[6:9]
	v_mfma_f32_16x16x32_bf16 v[2:5], v[238:241], v[222:225], v[2:5]
	s_setprio 0
	s_add_i32 s4, s4, 2
	s_cmp_lt_u32 s4, 28
	v_lshl_add_u64 v[134:135], v[134:135], 0, s[54:55]
	s_barrier
	s_cbranch_scc1 .LBB0_117
	s_waitcnt vmcnt(6)
	s_mov_b64 s[2:3], 0xf80
	s_mov_b32 m0, s12
	v_lshl_add_u64 v[134:135], v[138:139], 0, s[2:3]
	ds_read_b128 v[140:143], v0
	ds_read_b128 v[144:147], v152
	ds_read_b128 v[150:153], v153
	ds_read_b128 v[168:171], v154
	ds_read_b128 v[172:175], v148
	ds_read_b128 v[176:179], v148 offset:2048
	ds_read_b128 v[180:183], v149
	ds_read_b128 v[184:187], v149 offset:2048
	ds_read_b128 v[188:191], v148 offset:4096
	ds_read_b128 v[192:195], v148 offset:6144
	ds_read_b128 v[196:199], v149 offset:4096
	ds_read_b128 v[200:203], v149 offset:6144
	global_load_lds_dwordx4 v[134:135], off
	v_lshl_add_u64 v[134:135], v[136:137], 0, s[2:3]
	s_mov_b32 m0, s5
	s_nop 0
	global_load_lds_dwordx4 v[134:135], off
	s_barrier
	s_waitcnt lgkmcnt(0)
	s_setprio 1
	s_waitcnt lgkmcnt(0)
	v_mfma_f32_16x16x32_bf16 v[126:129], v[140:143], v[172:175], v[126:129]
	v_mfma_f32_16x16x32_bf16 v[122:125], v[150:153], v[172:175], v[122:125]
	v_mfma_f32_16x16x32_bf16 v[118:121], v[140:143], v[176:179], v[118:121]
	v_mfma_f32_16x16x32_bf16 v[110:113], v[140:143], v[188:191], v[110:113]
	v_mfma_f32_16x16x32_bf16 v[106:109], v[150:153], v[188:191], v[106:109]
	v_mfma_f32_16x16x32_bf16 v[126:129], v[144:147], v[180:183], v[126:129]
	v_mfma_f32_16x16x32_bf16 v[122:125], v[168:171], v[180:183], v[122:125]
	v_mfma_f32_16x16x32_bf16 v[118:121], v[144:147], v[184:187], v[118:121]
	v_mfma_f32_16x16x32_bf16 v[114:117], v[150:153], v[176:179], v[114:117]
	v_mfma_f32_16x16x32_bf16 v[110:113], v[144:147], v[196:199], v[110:113]
	v_mfma_f32_16x16x32_bf16 v[106:109], v[168:171], v[196:199], v[106:109]
	v_mfma_f32_16x16x32_bf16 v[102:105], v[140:143], v[192:195], v[102:105]
	v_mfma_f32_16x16x32_bf16 v[98:101], v[150:153], v[192:195], v[98:101]
	v_mfma_f32_16x16x32_bf16 v[134:137], v[168:171], v[184:187], v[114:117]
	v_mfma_f32_16x16x32_bf16 v[206:209], v[144:147], v[200:203], v[102:105]
	v_mfma_f32_16x16x32_bf16 v[218:221], v[168:171], v[200:203], v[98:101]
	s_setprio 0
	s_barrier
	s_nop 2
	ds_read_b128 v[98:101], v155
	ds_read_b128 v[102:105], v156
	ds_read_b128 v[114:117], v157
	ds_read_b128 v[154:157], v158
	s_barrier
	s_waitcnt lgkmcnt(0)
	s_setprio 1
	s_waitcnt lgkmcnt(0)
	v_mfma_f32_16x16x32_bf16 v[94:97], v[98:101], v[172:175], v[94:97]
	v_mfma_f32_16x16x32_bf16 v[90:93], v[114:117], v[172:175], v[90:93]
	v_mfma_f32_16x16x32_bf16 v[78:81], v[98:101], v[188:191], v[78:81]
	v_mfma_f32_16x16x32_bf16 v[74:77], v[114:117], v[188:191], v[74:77]
	v_mfma_f32_16x16x32_bf16 v[94:97], v[102:105], v[180:183], v[94:97]
	v_mfma_f32_16x16x32_bf16 v[90:93], v[154:157], v[180:183], v[90:93]
	v_mfma_f32_16x16x32_bf16 v[86:89], v[98:101], v[176:179], v[86:89]
	v_mfma_f32_16x16x32_bf16 v[82:85], v[114:117], v[176:179], v[82:85]
	v_mfma_f32_16x16x32_bf16 v[78:81], v[102:105], v[196:199], v[78:81]
	v_mfma_f32_16x16x32_bf16 v[74:77], v[154:157], v[196:199], v[74:77]
	v_mfma_f32_16x16x32_bf16 v[70:73], v[98:101], v[192:195], v[70:73]
	v_mfma_f32_16x16x32_bf16 v[66:69], v[114:117], v[192:195], v[66:69]
	v_mfma_f32_16x16x32_bf16 v[172:175], v[102:105], v[184:187], v[86:89]
	v_mfma_f32_16x16x32_bf16 v[176:179], v[154:157], v[184:187], v[82:85]
	v_mfma_f32_16x16x32_bf16 v[180:183], v[102:105], v[200:203], v[70:73]
	v_mfma_f32_16x16x32_bf16 v[184:187], v[154:157], v[200:203], v[66:69]
	s_setprio 0
	s_barrier
	s_nop 1
	ds_read_b128 v[66:69], v148 offset:16384
	ds_read_b128 v[70:73], v148 offset:18432
	ds_read_b128 v[82:85], v149 offset:16384
	ds_read_b128 v[86:89], v149 offset:18432
	ds_read_b128 v[188:191], v148 offset:20480
	ds_read_b128 v[192:195], v148 offset:22528
	ds_read_b128 v[196:199], v149 offset:20480
	ds_read_b128 v[200:203], v149 offset:22528
	s_waitcnt vmcnt(4)
	s_barrier
	s_waitcnt lgkmcnt(0)
	s_setprio 1
	s_waitcnt lgkmcnt(0)
	v_mfma_f32_16x16x32_bf16 v[62:65], v[140:143], v[66:69], v[62:65]
	v_mfma_f32_16x16x32_bf16 v[58:61], v[150:153], v[66:69], v[58:61]
	v_mfma_f32_16x16x32_bf16 v[46:49], v[140:143], v[188:191], v[46:49]
	v_mfma_f32_16x16x32_bf16 v[42:45], v[150:153], v[188:191], v[42:45]
	v_mfma_f32_16x16x32_bf16 v[62:65], v[144:147], v[82:85], v[62:65]
	v_mfma_f32_16x16x32_bf16 v[58:61], v[168:171], v[82:85], v[58:61]
	v_mfma_f32_16x16x32_bf16 v[54:57], v[140:143], v[70:73], v[54:57]
	v_mfma_f32_16x16x32_bf16 v[50:53], v[150:153], v[70:73], v[50:53]
	v_mfma_f32_16x16x32_bf16 v[46:49], v[144:147], v[196:199], v[46:49]
	v_mfma_f32_16x16x32_bf16 v[42:45], v[168:171], v[196:199], v[42:45]
	v_mfma_f32_16x16x32_bf16 v[38:41], v[140:143], v[192:195], v[38:41]
	v_mfma_f32_16x16x32_bf16 v[34:37], v[150:153], v[192:195], v[34:37]
	v_mfma_f32_16x16x32_bf16 v[222:225], v[144:147], v[86:89], v[54:57]
	v_mfma_f32_16x16x32_bf16 v[226:229], v[168:171], v[86:89], v[50:53]
	v_mfma_f32_16x16x32_bf16 v[138:141], v[144:147], v[200:203], v[38:41]
	v_mfma_f32_16x16x32_bf16 v[142:145], v[168:171], v[200:203], v[34:37]
	s_setprio 0
	s_setprio 1
	v_mfma_f32_16x16x32_bf16 v[30:33], v[98:101], v[66:69], v[30:33]
	v_mfma_f32_16x16x32_bf16 v[26:29], v[114:117], v[66:69], v[26:29]
	v_mfma_f32_16x16x32_bf16 v[14:17], v[98:101], v[188:191], v[14:17]
	v_mfma_f32_16x16x32_bf16 v[10:13], v[114:117], v[188:191], v[10:13]
	v_mfma_f32_16x16x32_bf16 v[30:33], v[102:105], v[82:85], v[30:33]
	v_mfma_f32_16x16x32_bf16 v[26:29], v[154:157], v[82:85], v[26:29]
	v_mfma_f32_16x16x32_bf16 v[22:25], v[98:101], v[70:73], v[22:25]
	v_mfma_f32_16x16x32_bf16 v[18:21], v[114:117], v[70:73], v[18:21]
	v_mfma_f32_16x16x32_bf16 v[14:17], v[102:105], v[196:199], v[14:17]
	v_mfma_f32_16x16x32_bf16 v[10:13], v[154:157], v[196:199], v[10:13]
	v_mfma_f32_16x16x32_bf16 v[6:9], v[98:101], v[192:195], v[6:9]
	v_mfma_f32_16x16x32_bf16 v[2:5], v[114:117], v[192:195], v[2:5]
	v_mfma_f32_16x16x32_bf16 v[150:153], v[102:105], v[86:89], v[22:25]
	v_mfma_f32_16x16x32_bf16 v[168:171], v[154:157], v[86:89], v[18:21]
	v_mfma_f32_16x16x32_bf16 v[188:191], v[102:105], v[200:203], v[6:9]
	v_mfma_f32_16x16x32_bf16 v[154:157], v[154:157], v[200:203], v[2:5]
	s_setprio 0
	s_barrier
	s_nop 1
	ds_read_b128 v[2:5], v159
	ds_read_b128 v[6:9], v160
	ds_read_b128 v[158:161], v161
	ds_read_b128 v[192:195], v162
	ds_read_b128 v[18:21], v148 offset:32768
	ds_read_b128 v[22:25], v148 offset:34816
	ds_read_b128 v[34:37], v149 offset:32768
	ds_read_b128 v[38:41], v149 offset:34816
	ds_read_b128 v[50:53], v148 offset:36864
	ds_read_b128 v[54:57], v148 offset:38912
	ds_read_b128 v[196:199], v149 offset:36864
	ds_read_b128 v[200:203], v149 offset:38912
	s_waitcnt vmcnt(2)
	s_barrier
	s_waitcnt lgkmcnt(0)
	s_setprio 1
	s_waitcnt lgkmcnt(0)
	v_mfma_f32_16x16x32_bf16 v[66:69], v[2:5], v[18:21], v[126:129]
	v_mfma_f32_16x16x32_bf16 v[126:129], v[6:9], v[34:37], v[66:69]
	v_mfma_f32_16x16x32_bf16 v[66:69], v[158:161], v[18:21], v[122:125]
	v_mfma_f32_16x16x32_bf16 v[114:117], v[192:195], v[34:37], v[66:69]
	v_mfma_f32_16x16x32_bf16 v[66:69], v[2:5], v[22:25], v[118:121]
	v_mfma_f32_16x16x32_bf16 v[102:105], v[6:9], v[38:41], v[66:69]
	v_mfma_f32_16x16x32_bf16 v[66:69], v[158:161], v[22:25], v[134:137]
	v_mfma_f32_16x16x32_bf16 v[98:101], v[192:195], v[38:41], v[66:69]
	v_mfma_f32_16x16x32_bf16 v[66:69], v[2:5], v[50:53], v[110:113]
	v_mfma_f32_16x16x32_bf16 v[86:89], v[6:9], v[196:199], v[66:69]
	v_mfma_f32_16x16x32_bf16 v[66:69], v[158:161], v[50:53], v[106:109]
	v_mfma_f32_16x16x32_bf16 v[82:85], v[192:195], v[196:199], v[66:69]
	v_mfma_f32_16x16x32_bf16 v[66:69], v[2:5], v[54:57], v[206:209]
	v_mfma_f32_16x16x32_bf16 v[70:73], v[6:9], v[200:203], v[66:69]
	v_mfma_f32_16x16x32_bf16 v[66:69], v[158:161], v[54:57], v[218:221]
	v_mfma_f32_16x16x32_bf16 v[66:69], v[192:195], v[200:203], v[66:69]
	s_setprio 0
	s_barrier
	ds_read_b128 v[134:137], v163
	ds_read_b128 v[206:209], v164
	ds_read_b128 v[162:165], v165
	ds_read_b128 v[218:221], v166
	s_waitcnt vmcnt(0)
	s_barrier
	s_waitcnt lgkmcnt(0)
	s_setprio 1
	s_waitcnt lgkmcnt(0)
	v_mfma_f32_16x16x32_bf16 v[94:97], v[134:137], v[18:21], v[94:97]
	v_mfma_f32_16x16x32_bf16 v[18:21], v[162:165], v[18:21], v[90:93]
	v_mfma_f32_16x16x32_bf16 v[118:121], v[218:221], v[34:37], v[18:21]
	v_mfma_f32_16x16x32_bf16 v[18:21], v[134:137], v[22:25], v[172:175]
	v_mfma_f32_16x16x32_bf16 v[110:113], v[206:209], v[38:41], v[18:21]
	v_mfma_f32_16x16x32_bf16 v[18:21], v[162:165], v[22:25], v[176:179]
	v_mfma_f32_16x16x32_bf16 v[106:109], v[218:221], v[38:41], v[18:21]
	v_mfma_f32_16x16x32_bf16 v[18:21], v[134:137], v[50:53], v[78:81]
	v_mfma_f32_16x16x32_bf16 v[122:125], v[206:209], v[34:37], v[94:97]
	v_mfma_f32_16x16x32_bf16 v[94:97], v[206:209], v[196:199], v[18:21]
	v_mfma_f32_16x16x32_bf16 v[18:21], v[162:165], v[50:53], v[74:77]
	v_mfma_f32_16x16x32_bf16 v[90:93], v[218:221], v[196:199], v[18:21]
	v_mfma_f32_16x16x32_bf16 v[18:21], v[134:137], v[54:57], v[180:183]
	v_mfma_f32_16x16x32_bf16 v[78:81], v[206:209], v[200:203], v[18:21]
	v_mfma_f32_16x16x32_bf16 v[18:21], v[162:165], v[54:57], v[184:187]
	v_mfma_f32_16x16x32_bf16 v[74:77], v[218:221], v[200:203], v[18:21]
	s_setprio 0
	s_barrier
	ds_read_b128 v[172:175], v148 offset:49152
	ds_read_b128 v[176:179], v148 offset:51200
	ds_read_b128 v[180:183], v149 offset:49152
	ds_read_b128 v[184:187], v149 offset:51200
	ds_read_b128 v[196:199], v148 offset:53248
	ds_read_b128 v[200:203], v148 offset:55296
	ds_read_b128 v[230:233], v149 offset:53248
	ds_read_b128 v[146:149], v149 offset:55296
	s_barrier
	s_waitcnt lgkmcnt(0)
	s_setprio 1
	s_waitcnt lgkmcnt(0)
	v_mfma_f32_16x16x32_bf16 v[18:21], v[2:5], v[172:175], v[62:65]
	v_mfma_f32_16x16x32_bf16 v[54:57], v[6:9], v[180:183], v[18:21]
	v_mfma_f32_16x16x32_bf16 v[18:21], v[158:161], v[172:175], v[58:61]
	v_mfma_f32_16x16x32_bf16 v[50:53], v[192:195], v[180:183], v[18:21]
	v_mfma_f32_16x16x32_bf16 v[18:21], v[2:5], v[176:179], v[222:225]
	v_mfma_f32_16x16x32_bf16 v[38:41], v[6:9], v[184:187], v[18:21]
	v_mfma_f32_16x16x32_bf16 v[18:21], v[158:161], v[176:179], v[226:229]
	v_mfma_f32_16x16x32_bf16 v[34:37], v[192:195], v[184:187], v[18:21]
	v_mfma_f32_16x16x32_bf16 v[18:21], v[2:5], v[196:199], v[46:49]
	v_mfma_f32_16x16x32_bf16 v[2:5], v[2:5], v[200:203], v[138:141]
	v_mfma_f32_16x16x32_bf16 v[22:25], v[6:9], v[230:233], v[18:21]
	v_mfma_f32_16x16x32_bf16 v[18:21], v[158:161], v[196:199], v[42:45]
	v_mfma_f32_16x16x32_bf16 v[6:9], v[6:9], v[146:149], v[2:5]
	v_mfma_f32_16x16x32_bf16 v[2:5], v[158:161], v[200:203], v[142:145]
	v_mfma_f32_16x16x32_bf16 v[18:21], v[192:195], v[230:233], v[18:21]
	v_mfma_f32_16x16x32_bf16 v[2:5], v[192:195], v[146:149], v[2:5]
	s_setprio 0
	s_setprio 1
	v_mfma_f32_16x16x32_bf16 v[26:29], v[162:165], v[172:175], v[26:29]
	v_mfma_f32_16x16x32_bf16 v[58:61], v[218:221], v[180:183], v[26:29]
	v_mfma_f32_16x16x32_bf16 v[26:29], v[134:137], v[176:179], v[150:153]
	v_mfma_f32_16x16x32_bf16 v[46:49], v[206:209], v[184:187], v[26:29]
	v_mfma_f32_16x16x32_bf16 v[26:29], v[162:165], v[176:179], v[168:171]
	v_mfma_f32_16x16x32_bf16 v[10:13], v[162:165], v[196:199], v[10:13]
	v_mfma_f32_16x16x32_bf16 v[30:33], v[134:137], v[172:175], v[30:33]
	v_mfma_f32_16x16x32_bf16 v[42:45], v[218:221], v[184:187], v[26:29]
	v_mfma_f32_16x16x32_bf16 v[14:17], v[134:137], v[196:199], v[14:17]
	v_mfma_f32_16x16x32_bf16 v[26:29], v[218:221], v[230:233], v[10:13]
	v_mfma_f32_16x16x32_bf16 v[10:13], v[134:137], v[200:203], v[188:191]
	v_mfma_f32_16x16x32_bf16 v[62:65], v[206:209], v[180:183], v[30:33]
	v_mfma_f32_16x16x32_bf16 v[30:33], v[206:209], v[230:233], v[14:17]
	v_mfma_f32_16x16x32_bf16 v[14:17], v[206:209], v[146:149], v[10:13]
	v_mfma_f32_16x16x32_bf16 v[10:13], v[162:165], v[200:203], v[154:157]
	v_mfma_f32_16x16x32_bf16 v[10:13], v[218:221], v[146:149], v[10:13]
	s_setprio 0
	s_cmpk_gt_u32 s0, 0xff
	s_barrier
	s_cbranch_scc1 .LBB0_90
	s_barrier
	s_branch .LBB0_90

.LBB0_341:
	v_or_b32_e32 v0, 0x10000, v152
	v_add_u32_e32 v155, 0x10800, v152
	v_or_b32_e32 v154, 0x10000, v153
	ds_read_b128 v[162:165], v0
	ds_read_b128 v[166:169], v154
	v_add_u32_e32 v156, 0x10800, v153
	ds_read_b128 v[170:173], v155
	ds_read_b128 v[174:177], v156
	v_lshl_add_u64 v[202:203], v[148:149], 0, v[142:143]
	s_add_i32 s12, s1, 0xc000
	v_lshl_add_u64 v[158:159], v[202:203], 0, s[50:51]
	s_mov_b32 m0, s12
	v_lshl_add_u64 v[206:207], v[148:149], 0, v[140:141]
	s_add_i32 s5, s1, 0xe000
	ds_read_b128 v[178:181], v150
	ds_read_b128 v[182:185], v150 offset:2048
	ds_read_b128 v[186:189], v151
	ds_read_b128 v[190:193], v151 offset:2048
	ds_read_b128 v[194:197], v150 offset:4096
	ds_read_b128 v[198:201], v150 offset:6144
	ds_read_b128 v[218:221], v151 offset:4096
	ds_read_b128 v[222:225], v151 offset:6144
	global_load_lds_dwordx4 v[158:159], off
	v_lshl_add_u64 v[158:159], v[206:207], 0, s[50:51]
	s_mov_b32 m0, s5
	s_nop 0
	global_load_lds_dwordx4 v[158:159], off
	s_waitcnt lgkmcnt(8)
	s_waitcnt vmcnt(10)
	s_barrier
	s_waitcnt lgkmcnt(0)
	s_setprio 1
	s_waitcnt lgkmcnt(0)
	v_mfma_f32_16x16x32_bf16 v[126:129], v[178:181], v[162:165], v[126:129]
	v_mfma_f32_16x16x32_bf16 v[122:125], v[178:181], v[170:173], v[122:125]
	v_mfma_f32_16x16x32_bf16 v[118:121], v[182:185], v[162:165], v[118:121]
	v_mfma_f32_16x16x32_bf16 v[114:117], v[182:185], v[170:173], v[114:117]
	v_mfma_f32_16x16x32_bf16 v[110:113], v[194:197], v[162:165], v[110:113]
	v_mfma_f32_16x16x32_bf16 v[106:109], v[194:197], v[170:173], v[106:109]
	v_mfma_f32_16x16x32_bf16 v[102:105], v[198:201], v[162:165], v[102:105]
	v_mfma_f32_16x16x32_bf16 v[98:101], v[198:201], v[170:173], v[98:101]
	v_mfma_f32_16x16x32_bf16 v[126:129], v[186:189], v[166:169], v[126:129]
	v_mfma_f32_16x16x32_bf16 v[122:125], v[186:189], v[174:177], v[122:125]
	v_mfma_f32_16x16x32_bf16 v[118:121], v[190:193], v[166:169], v[118:121]
	v_mfma_f32_16x16x32_bf16 v[114:117], v[190:193], v[174:177], v[114:117]
	v_mfma_f32_16x16x32_bf16 v[110:113], v[218:221], v[166:169], v[110:113]
	v_mfma_f32_16x16x32_bf16 v[106:109], v[218:221], v[174:177], v[106:109]
	v_mfma_f32_16x16x32_bf16 v[102:105], v[222:225], v[166:169], v[102:105]
	v_mfma_f32_16x16x32_bf16 v[98:101], v[222:225], v[174:177], v[98:101]
	s_setprio 0
	s_barrier
	v_lshl_add_u64 v[208:209], v[148:149], 0, v[146:147]
	s_mov_b32 m0, s2
	v_or_b32_e32 v157, 0x14000, v152
	v_add_u32_e32 v159, 0x14800, v152
	v_lshl_add_u64 v[210:211], v[208:209], 0, s[70:71]
	v_or_b32_e32 v158, 0x14000, v153
	ds_read_b128 v[226:229], v157
	ds_read_b128 v[230:233], v158
	v_add_u32_e32 v160, 0x14800, v153
	ds_read_b128 v[234:237], v159
	ds_read_b128 v[238:241], v160
	global_load_lds_dwordx4 v[210:211], off
	v_lshl_add_u64 v[210:211], v[148:149], 0, v[144:145]
	v_lshl_add_u64 v[214:215], v[210:211], 0, s[70:71]
	s_mov_b32 m0, s3
	s_nop 0
	global_load_lds_dwordx4 v[214:215], off
	s_waitcnt vmcnt(10)
	s_waitcnt lgkmcnt(0)
	s_barrier
	s_waitcnt lgkmcnt(0)
	s_setprio 1
	s_waitcnt lgkmcnt(0)
	v_mfma_f32_16x16x32_bf16 v[94:97], v[178:181], v[226:229], v[94:97]
	v_mfma_f32_16x16x32_bf16 v[90:93], v[178:181], v[234:237], v[90:93]
	v_mfma_f32_16x16x32_bf16 v[86:89], v[182:185], v[226:229], v[86:89]
	v_mfma_f32_16x16x32_bf16 v[82:85], v[182:185], v[234:237], v[82:85]
	v_mfma_f32_16x16x32_bf16 v[78:81], v[194:197], v[226:229], v[78:81]
	v_mfma_f32_16x16x32_bf16 v[74:77], v[194:197], v[234:237], v[74:77]
	v_mfma_f32_16x16x32_bf16 v[70:73], v[198:201], v[226:229], v[70:73]
	v_mfma_f32_16x16x32_bf16 v[66:69], v[198:201], v[234:237], v[66:69]
	v_mfma_f32_16x16x32_bf16 v[94:97], v[186:189], v[230:233], v[94:97]
	v_mfma_f32_16x16x32_bf16 v[90:93], v[186:189], v[238:241], v[90:93]
	v_mfma_f32_16x16x32_bf16 v[86:89], v[190:193], v[230:233], v[86:89]
	v_mfma_f32_16x16x32_bf16 v[82:85], v[190:193], v[238:241], v[82:85]
	v_mfma_f32_16x16x32_bf16 v[78:81], v[218:221], v[230:233], v[78:81]
	v_mfma_f32_16x16x32_bf16 v[74:77], v[218:221], v[238:241], v[74:77]
	v_mfma_f32_16x16x32_bf16 v[70:73], v[222:225], v[230:233], v[70:73]
	v_mfma_f32_16x16x32_bf16 v[66:69], v[222:225], v[238:241], v[66:69]
	s_setprio 0
	s_mov_b32 m0, s1
	v_lshl_add_u64 v[214:215], v[202:203], 0, s[54:55]
	s_barrier
	ds_read_b128 v[178:181], v150 offset:16384
	ds_read_b128 v[182:185], v150 offset:18432
	ds_read_b128 v[186:189], v151 offset:16384
	ds_read_b128 v[190:193], v151 offset:18432
	ds_read_b128 v[194:197], v150 offset:20480
	ds_read_b128 v[198:201], v150 offset:22528
	ds_read_b128 v[218:221], v151 offset:20480
	ds_read_b128 v[222:225], v151 offset:22528
	global_load_lds_dwordx4 v[214:215], off
	v_lshl_add_u64 v[214:215], v[206:207], 0, s[54:55]
	s_mov_b32 m0, s9
	s_nop 0
	global_load_lds_dwordx4 v[214:215], off
	v_lshl_add_u64 v[214:215], v[208:209], 0, s[26:27]
	s_mov_b32 m0, s11
	s_nop 0
	global_load_lds_dwordx4 v[214:215], off
	v_lshl_add_u64 v[214:215], v[210:211], 0, s[26:27]
	s_mov_b32 m0, s16
	s_nop 0
	global_load_lds_dwordx4 v[214:215], off
	s_waitcnt vmcnt(10)
	s_waitcnt lgkmcnt(0)
	s_barrier
	s_waitcnt lgkmcnt(0)
	s_setprio 1
	s_waitcnt lgkmcnt(0)
	v_mfma_f32_16x16x32_bf16 v[62:65], v[178:181], v[162:165], v[62:65]
	v_mfma_f32_16x16x32_bf16 v[58:61], v[178:181], v[170:173], v[58:61]
	v_mfma_f32_16x16x32_bf16 v[54:57], v[182:185], v[162:165], v[54:57]
	v_mfma_f32_16x16x32_bf16 v[50:53], v[182:185], v[170:173], v[50:53]
	v_mfma_f32_16x16x32_bf16 v[46:49], v[194:197], v[162:165], v[46:49]
	v_mfma_f32_16x16x32_bf16 v[42:45], v[194:197], v[170:173], v[42:45]
	v_mfma_f32_16x16x32_bf16 v[38:41], v[198:201], v[162:165], v[38:41]
	v_mfma_f32_16x16x32_bf16 v[34:37], v[198:201], v[170:173], v[34:37]
	v_mfma_f32_16x16x32_bf16 v[62:65], v[186:189], v[166:169], v[62:65]
	v_mfma_f32_16x16x32_bf16 v[58:61], v[186:189], v[174:177], v[58:61]
	v_mfma_f32_16x16x32_bf16 v[54:57], v[190:193], v[166:169], v[54:57]
	v_mfma_f32_16x16x32_bf16 v[50:53], v[190:193], v[174:177], v[50:53]
	v_mfma_f32_16x16x32_bf16 v[46:49], v[218:221], v[166:169], v[46:49]
	v_mfma_f32_16x16x32_bf16 v[42:45], v[218:221], v[174:177], v[42:45]
	v_mfma_f32_16x16x32_bf16 v[38:41], v[222:225], v[166:169], v[38:41]
	v_mfma_f32_16x16x32_bf16 v[34:37], v[222:225], v[174:177], v[34:37]
	v_mfma_f32_16x16x32_bf16 v[30:33], v[178:181], v[226:229], v[30:33]
	v_mfma_f32_16x16x32_bf16 v[26:29], v[178:181], v[234:237], v[26:29]
	v_mfma_f32_16x16x32_bf16 v[22:25], v[182:185], v[226:229], v[22:25]
	v_mfma_f32_16x16x32_bf16 v[18:21], v[182:185], v[234:237], v[18:21]
	v_mfma_f32_16x16x32_bf16 v[14:17], v[194:197], v[226:229], v[14:17]
	v_mfma_f32_16x16x32_bf16 v[10:13], v[194:197], v[234:237], v[10:13]
	v_mfma_f32_16x16x32_bf16 v[6:9], v[198:201], v[226:229], v[6:9]
	v_mfma_f32_16x16x32_bf16 v[2:5], v[198:201], v[234:237], v[2:5]
	v_mfma_f32_16x16x32_bf16 v[30:33], v[186:189], v[230:233], v[30:33]
	v_mfma_f32_16x16x32_bf16 v[26:29], v[186:189], v[238:241], v[26:29]
	v_mfma_f32_16x16x32_bf16 v[22:25], v[190:193], v[230:233], v[22:25]
	v_mfma_f32_16x16x32_bf16 v[18:21], v[190:193], v[238:241], v[18:21]
	v_mfma_f32_16x16x32_bf16 v[14:17], v[218:221], v[230:233], v[14:17]
	v_mfma_f32_16x16x32_bf16 v[10:13], v[218:221], v[238:241], v[10:13]
	v_mfma_f32_16x16x32_bf16 v[6:9], v[222:225], v[230:233], v[6:9]
	v_mfma_f32_16x16x32_bf16 v[2:5], v[222:225], v[238:241], v[2:5]
	s_setprio 0
	v_or_b32_e32 v161, 0x18000, v152
	v_add_u32_e32 v163, 0x18800, v152
	s_barrier
	v_or_b32_e32 v162, 0x18000, v153
	ds_read_b128 v[170:173], v161
	ds_read_b128 v[174:177], v162
	v_add_u32_e32 v164, 0x18800, v153
	ds_read_b128 v[178:181], v163
	ds_read_b128 v[182:185], v164
	s_mov_b32 m0, s17
	v_lshl_add_u64 v[166:167], v[202:203], 0, s[58:59]
	ds_read_b128 v[186:189], v150 offset:32768
	ds_read_b128 v[190:193], v150 offset:34816
	ds_read_b128 v[194:197], v151 offset:32768
	ds_read_b128 v[198:201], v151 offset:34816
	ds_read_b128 v[218:221], v150 offset:36864
	ds_read_b128 v[222:225], v150 offset:38912
	ds_read_b128 v[226:229], v151 offset:36864
	ds_read_b128 v[230:233], v151 offset:38912
	global_load_lds_dwordx4 v[166:167], off
	v_lshl_add_u64 v[166:167], v[206:207], 0, s[58:59]
	s_mov_b32 m0, s18
	s_nop 0
	global_load_lds_dwordx4 v[166:167], off
	s_waitcnt lgkmcnt(8)
	s_waitcnt vmcnt(10)
	s_barrier
	s_waitcnt lgkmcnt(0)
	s_setprio 1
	s_waitcnt lgkmcnt(0)
	v_mfma_f32_16x16x32_bf16 v[126:129], v[186:189], v[170:173], v[126:129]
	v_mfma_f32_16x16x32_bf16 v[122:125], v[186:189], v[178:181], v[122:125]
	v_mfma_f32_16x16x32_bf16 v[118:121], v[190:193], v[170:173], v[118:121]
	v_mfma_f32_16x16x32_bf16 v[114:117], v[190:193], v[178:181], v[114:117]
	v_mfma_f32_16x16x32_bf16 v[110:113], v[218:221], v[170:173], v[110:113]
	v_mfma_f32_16x16x32_bf16 v[106:109], v[218:221], v[178:181], v[106:109]
	v_mfma_f32_16x16x32_bf16 v[102:105], v[222:225], v[170:173], v[102:105]
	v_mfma_f32_16x16x32_bf16 v[98:101], v[222:225], v[178:181], v[98:101]
	v_mfma_f32_16x16x32_bf16 v[126:129], v[194:197], v[174:177], v[126:129]
	v_mfma_f32_16x16x32_bf16 v[122:125], v[194:197], v[182:185], v[122:125]
	v_mfma_f32_16x16x32_bf16 v[118:121], v[198:201], v[174:177], v[118:121]
	v_mfma_f32_16x16x32_bf16 v[114:117], v[198:201], v[182:185], v[114:117]
	v_mfma_f32_16x16x32_bf16 v[110:113], v[226:229], v[174:177], v[110:113]
	v_mfma_f32_16x16x32_bf16 v[106:109], v[226:229], v[182:185], v[106:109]
	v_mfma_f32_16x16x32_bf16 v[102:105], v[230:233], v[174:177], v[102:105]
	v_mfma_f32_16x16x32_bf16 v[98:101], v[230:233], v[182:185], v[98:101]
	s_setprio 0
	s_barrier
	s_mov_b32 m0, s19
	v_or_b32_e32 v165, 0x1c000, v152
	v_add_u32_e32 v167, 0x1c800, v152
	v_lshl_add_u64 v[214:215], v[208:209], 0, s[28:29]
	v_or_b32_e32 v166, 0x1c000, v153
	ds_read_b128 v[234:237], v165
	ds_read_b128 v[238:241], v166
	v_add_u32_e32 v168, 0x1c800, v153
	ds_read_b128 v[242:245], v167
	ds_read_b128 v[246:249], v168
	global_load_lds_dwordx4 v[214:215], off
	v_lshl_add_u64 v[214:215], v[210:211], 0, s[28:29]
	s_mov_b32 m0, s20
	s_nop 0
	global_load_lds_dwordx4 v[214:215], off
	s_waitcnt vmcnt(10)
	s_waitcnt lgkmcnt(0)
	s_barrier
	s_waitcnt lgkmcnt(0)
	s_setprio 1
	s_waitcnt lgkmcnt(0)
	v_mfma_f32_16x16x32_bf16 v[94:97], v[186:189], v[234:237], v[94:97]
	v_mfma_f32_16x16x32_bf16 v[90:93], v[186:189], v[242:245], v[90:93]
	v_mfma_f32_16x16x32_bf16 v[86:89], v[190:193], v[234:237], v[86:89]
	v_mfma_f32_16x16x32_bf16 v[82:85], v[190:193], v[242:245], v[82:85]
	v_mfma_f32_16x16x32_bf16 v[78:81], v[218:221], v[234:237], v[78:81]
	v_mfma_f32_16x16x32_bf16 v[74:77], v[218:221], v[242:245], v[74:77]
	v_mfma_f32_16x16x32_bf16 v[70:73], v[222:225], v[234:237], v[70:73]
	v_mfma_f32_16x16x32_bf16 v[66:69], v[222:225], v[242:245], v[66:69]
	v_mfma_f32_16x16x32_bf16 v[94:97], v[194:197], v[238:241], v[94:97]
	v_mfma_f32_16x16x32_bf16 v[90:93], v[194:197], v[246:249], v[90:93]
	v_mfma_f32_16x16x32_bf16 v[86:89], v[198:201], v[238:241], v[86:89]
	v_mfma_f32_16x16x32_bf16 v[82:85], v[198:201], v[246:249], v[82:85]
	v_mfma_f32_16x16x32_bf16 v[78:81], v[226:229], v[238:241], v[78:81]
	v_mfma_f32_16x16x32_bf16 v[74:77], v[226:229], v[246:249], v[74:77]
	v_mfma_f32_16x16x32_bf16 v[70:73], v[230:233], v[238:241], v[70:73]
	v_mfma_f32_16x16x32_bf16 v[66:69], v[230:233], v[246:249], v[66:69]
	s_setprio 0
	s_mov_b32 m0, s21
	v_lshl_add_u64 v[202:203], v[202:203], 0, s[62:63]
	s_barrier
	ds_read_b128 v[186:189], v150 offset:49152
	ds_read_b128 v[190:193], v150 offset:51200
	ds_read_b128 v[194:197], v151 offset:49152
	ds_read_b128 v[198:201], v151 offset:51200
	ds_read_b128 v[218:221], v150 offset:53248
	ds_read_b128 v[222:225], v150 offset:55296
	ds_read_b128 v[226:229], v151 offset:53248
	ds_read_b128 v[230:233], v151 offset:55296
	global_load_lds_dwordx4 v[202:203], off
	v_lshl_add_u64 v[202:203], v[206:207], 0, s[62:63]
	s_mov_b32 m0, s22
	s_nop 0
	global_load_lds_dwordx4 v[202:203], off
	v_lshl_add_u64 v[202:203], v[208:209], 0, s[30:31]
	s_mov_b32 m0, s23
	s_nop 0
	global_load_lds_dwordx4 v[202:203], off
	v_lshl_add_u64 v[202:203], v[210:211], 0, s[30:31]
	s_mov_b32 m0, s24
	s_nop 0
	global_load_lds_dwordx4 v[202:203], off
	s_waitcnt vmcnt(10)
	s_waitcnt lgkmcnt(0)
	s_barrier
	s_waitcnt lgkmcnt(0)
	s_setprio 1
	s_waitcnt lgkmcnt(0)
	v_mfma_f32_16x16x32_bf16 v[62:65], v[186:189], v[170:173], v[62:65]
	v_mfma_f32_16x16x32_bf16 v[58:61], v[186:189], v[178:181], v[58:61]
	v_mfma_f32_16x16x32_bf16 v[54:57], v[190:193], v[170:173], v[54:57]
	v_mfma_f32_16x16x32_bf16 v[50:53], v[190:193], v[178:181], v[50:53]
	v_mfma_f32_16x16x32_bf16 v[46:49], v[218:221], v[170:173], v[46:49]
	v_mfma_f32_16x16x32_bf16 v[42:45], v[218:221], v[178:181], v[42:45]
	v_mfma_f32_16x16x32_bf16 v[38:41], v[222:225], v[170:173], v[38:41]
	v_mfma_f32_16x16x32_bf16 v[34:37], v[222:225], v[178:181], v[34:37]
	v_mfma_f32_16x16x32_bf16 v[62:65], v[194:197], v[174:177], v[62:65]
	v_mfma_f32_16x16x32_bf16 v[58:61], v[194:197], v[182:185], v[58:61]
	v_mfma_f32_16x16x32_bf16 v[54:57], v[198:201], v[174:177], v[54:57]
	v_mfma_f32_16x16x32_bf16 v[50:53], v[198:201], v[182:185], v[50:53]
	v_mfma_f32_16x16x32_bf16 v[46:49], v[226:229], v[174:177], v[46:49]
	v_mfma_f32_16x16x32_bf16 v[42:45], v[226:229], v[182:185], v[42:45]
	v_mfma_f32_16x16x32_bf16 v[38:41], v[230:233], v[174:177], v[38:41]
	v_mfma_f32_16x16x32_bf16 v[34:37], v[230:233], v[182:185], v[34:37]
	v_mfma_f32_16x16x32_bf16 v[30:33], v[186:189], v[234:237], v[30:33]
	v_mfma_f32_16x16x32_bf16 v[26:29], v[186:189], v[242:245], v[26:29]
	v_mfma_f32_16x16x32_bf16 v[22:25], v[190:193], v[234:237], v[22:25]
	v_mfma_f32_16x16x32_bf16 v[18:21], v[190:193], v[242:245], v[18:21]
	v_mfma_f32_16x16x32_bf16 v[14:17], v[218:221], v[234:237], v[14:17]
	v_mfma_f32_16x16x32_bf16 v[10:13], v[218:221], v[242:245], v[10:13]
	v_mfma_f32_16x16x32_bf16 v[6:9], v[222:225], v[234:237], v[6:9]
	v_mfma_f32_16x16x32_bf16 v[2:5], v[222:225], v[242:245], v[2:5]
	v_mfma_f32_16x16x32_bf16 v[30:33], v[194:197], v[238:241], v[30:33]
	v_mfma_f32_16x16x32_bf16 v[26:29], v[194:197], v[246:249], v[26:29]
	v_mfma_f32_16x16x32_bf16 v[22:25], v[198:201], v[238:241], v[22:25]
	v_mfma_f32_16x16x32_bf16 v[18:21], v[198:201], v[246:249], v[18:21]
	v_mfma_f32_16x16x32_bf16 v[14:17], v[226:229], v[238:241], v[14:17]
	v_mfma_f32_16x16x32_bf16 v[10:13], v[226:229], v[246:249], v[10:13]
	v_mfma_f32_16x16x32_bf16 v[6:9], v[230:233], v[238:241], v[6:9]
	v_mfma_f32_16x16x32_bf16 v[2:5], v[230:233], v[246:249], v[2:5]
	s_setprio 0
	s_add_i32 s4, s4, 2
	s_cmp_lt_u32 s4, 28
	v_lshl_add_u64 v[148:149], v[148:149], 0, s[54:55]
	s_barrier
	s_cbranch_scc1 .LBB0_341
	s_waitcnt vmcnt(6)
	s_mov_b64 s[2:3], 0xf80
	s_mov_b32 m0, s12
	v_lshl_add_u64 v[138:139], v[138:139], 0, s[2:3]
	ds_read_b128 v[140:143], v0
	ds_read_b128 v[144:147], v154
	ds_read_b128 v[152:155], v155
	ds_read_b128 v[170:173], v156
	ds_read_b128 v[174:177], v150
	ds_read_b128 v[178:181], v150 offset:2048
	ds_read_b128 v[182:185], v151
	ds_read_b128 v[186:189], v151 offset:2048
	ds_read_b128 v[190:193], v150 offset:4096
	ds_read_b128 v[194:197], v150 offset:6144
	ds_read_b128 v[198:201], v151 offset:4096
	ds_read_b128 v[218:221], v151 offset:6144
	global_load_lds_dwordx4 v[138:139], off
	v_lshl_add_u64 v[136:137], v[136:137], 0, s[2:3]
	s_mov_b32 m0, s5
	s_nop 0
	global_load_lds_dwordx4 v[136:137], off
	s_barrier
	s_waitcnt lgkmcnt(0)
	s_setprio 1
	s_waitcnt lgkmcnt(0)
	v_mfma_f32_16x16x32_bf16 v[126:129], v[174:177], v[140:143], v[126:129]
	v_mfma_f32_16x16x32_bf16 v[114:117], v[178:181], v[152:155], v[114:117]
	v_mfma_f32_16x16x32_bf16 v[110:113], v[190:193], v[140:143], v[110:113]
	v_mfma_f32_16x16x32_bf16 v[106:109], v[190:193], v[152:155], v[106:109]
	v_mfma_f32_16x16x32_bf16 v[126:129], v[182:185], v[144:147], v[126:129]
	v_mfma_f32_16x16x32_bf16 v[122:125], v[174:177], v[152:155], v[122:125]
	v_mfma_f32_16x16x32_bf16 v[118:121], v[178:181], v[140:143], v[118:121]
	v_mfma_f32_16x16x32_bf16 v[114:117], v[186:189], v[170:173], v[114:117]
	v_mfma_f32_16x16x32_bf16 v[110:113], v[198:201], v[144:147], v[110:113]
	v_mfma_f32_16x16x32_bf16 v[106:109], v[198:201], v[170:173], v[106:109]
	v_mfma_f32_16x16x32_bf16 v[102:105], v[194:197], v[140:143], v[102:105]
	v_mfma_f32_16x16x32_bf16 v[98:101], v[194:197], v[152:155], v[98:101]
	v_mfma_f32_16x16x32_bf16 v[136:139], v[182:185], v[170:173], v[122:125]
	v_mfma_f32_16x16x32_bf16 v[222:225], v[186:189], v[144:147], v[118:121]
	v_mfma_f32_16x16x32_bf16 v[226:229], v[218:221], v[144:147], v[102:105]
	v_mfma_f32_16x16x32_bf16 v[230:233], v[218:221], v[170:173], v[98:101]
	s_setprio 0
	s_barrier
	s_nop 1
	ds_read_b128 v[98:101], v157
	ds_read_b128 v[102:105], v158
	ds_read_b128 v[118:121], v159
	ds_read_b128 v[122:125], v160
	s_barrier
	s_waitcnt lgkmcnt(0)
	s_setprio 1
	s_waitcnt lgkmcnt(0)
	v_mfma_f32_16x16x32_bf16 v[94:97], v[174:177], v[98:101], v[94:97]
	v_mfma_f32_16x16x32_bf16 v[90:93], v[174:177], v[118:121], v[90:93]
	v_mfma_f32_16x16x32_bf16 v[78:81], v[190:193], v[98:101], v[78:81]
	v_mfma_f32_16x16x32_bf16 v[74:77], v[190:193], v[118:121], v[74:77]
	v_mfma_f32_16x16x32_bf16 v[94:97], v[182:185], v[102:105], v[94:97]
	v_mfma_f32_16x16x32_bf16 v[90:93], v[182:185], v[122:125], v[90:93]
	v_mfma_f32_16x16x32_bf16 v[86:89], v[178:181], v[98:101], v[86:89]
	v_mfma_f32_16x16x32_bf16 v[82:85], v[178:181], v[118:121], v[82:85]
	v_mfma_f32_16x16x32_bf16 v[78:81], v[198:201], v[102:105], v[78:81]
	v_mfma_f32_16x16x32_bf16 v[74:77], v[198:201], v[122:125], v[74:77]
	v_mfma_f32_16x16x32_bf16 v[70:73], v[194:197], v[98:101], v[70:73]
	v_mfma_f32_16x16x32_bf16 v[66:69], v[194:197], v[118:121], v[66:69]
	v_mfma_f32_16x16x32_bf16 v[156:159], v[186:189], v[102:105], v[86:89]
	v_mfma_f32_16x16x32_bf16 v[174:177], v[186:189], v[122:125], v[82:85]
	v_mfma_f32_16x16x32_bf16 v[178:181], v[218:221], v[102:105], v[70:73]
	v_mfma_f32_16x16x32_bf16 v[182:185], v[218:221], v[122:125], v[66:69]
	s_setprio 0
	s_barrier
	s_nop 1
	ds_read_b128 v[66:69], v150 offset:16384
	ds_read_b128 v[70:73], v150 offset:18432
	ds_read_b128 v[82:85], v151 offset:16384
	ds_read_b128 v[86:89], v151 offset:18432
	ds_read_b128 v[186:189], v150 offset:20480
	ds_read_b128 v[190:193], v150 offset:22528
	ds_read_b128 v[194:197], v151 offset:20480
	ds_read_b128 v[198:201], v151 offset:22528
	s_waitcnt vmcnt(4)
	s_barrier
	s_waitcnt lgkmcnt(0)
	s_setprio 1
	s_waitcnt lgkmcnt(0)
	v_mfma_f32_16x16x32_bf16 v[62:65], v[66:69], v[140:143], v[62:65]
	v_mfma_f32_16x16x32_bf16 v[54:57], v[70:73], v[140:143], v[54:57]
	v_mfma_f32_16x16x32_bf16 v[46:49], v[186:189], v[140:143], v[46:49]
	v_mfma_f32_16x16x32_bf16 v[38:41], v[190:193], v[140:143], v[38:41]
	v_mfma_f32_16x16x32_bf16 v[62:65], v[82:85], v[144:147], v[62:65]
	v_mfma_f32_16x16x32_bf16 v[58:61], v[66:69], v[152:155], v[58:61]
	v_mfma_f32_16x16x32_bf16 v[54:57], v[86:89], v[144:147], v[54:57]
	v_mfma_f32_16x16x32_bf16 v[50:53], v[70:73], v[152:155], v[50:53]
	v_mfma_f32_16x16x32_bf16 v[46:49], v[194:197], v[144:147], v[46:49]
	v_mfma_f32_16x16x32_bf16 v[42:45], v[186:189], v[152:155], v[42:45]
	v_mfma_f32_16x16x32_bf16 v[38:41], v[198:201], v[144:147], v[38:41]
	v_mfma_f32_16x16x32_bf16 v[34:37], v[190:193], v[152:155], v[34:37]
	v_mfma_f32_16x16x32_bf16 v[218:221], v[82:85], v[170:173], v[58:61]
	v_mfma_f32_16x16x32_bf16 v[234:237], v[86:89], v[170:173], v[50:53]
	v_mfma_f32_16x16x32_bf16 v[238:241], v[194:197], v[170:173], v[42:45]
	v_mfma_f32_16x16x32_bf16 v[140:143], v[198:201], v[170:173], v[34:37]
	s_setprio 0
	s_setprio 1
	v_mfma_f32_16x16x32_bf16 v[30:33], v[66:69], v[98:101], v[30:33]
	v_mfma_f32_16x16x32_bf16 v[22:25], v[70:73], v[98:101], v[22:25]
	v_mfma_f32_16x16x32_bf16 v[14:17], v[186:189], v[98:101], v[14:17]
	v_mfma_f32_16x16x32_bf16 v[6:9], v[190:193], v[98:101], v[6:9]
	v_mfma_f32_16x16x32_bf16 v[30:33], v[82:85], v[102:105], v[30:33]
	v_mfma_f32_16x16x32_bf16 v[26:29], v[66:69], v[118:121], v[26:29]
	v_mfma_f32_16x16x32_bf16 v[22:25], v[86:89], v[102:105], v[22:25]
	v_mfma_f32_16x16x32_bf16 v[18:21], v[70:73], v[118:121], v[18:21]
	v_mfma_f32_16x16x32_bf16 v[14:17], v[194:197], v[102:105], v[14:17]
	v_mfma_f32_16x16x32_bf16 v[10:13], v[186:189], v[118:121], v[10:13]
	v_mfma_f32_16x16x32_bf16 v[6:9], v[198:201], v[102:105], v[6:9]
	v_mfma_f32_16x16x32_bf16 v[2:5], v[190:193], v[118:121], v[2:5]
	v_mfma_f32_16x16x32_bf16 v[144:147], v[82:85], v[122:125], v[26:29]
	v_mfma_f32_16x16x32_bf16 v[152:155], v[86:89], v[122:125], v[18:21]
	v_mfma_f32_16x16x32_bf16 v[170:173], v[194:197], v[122:125], v[10:13]
	v_mfma_f32_16x16x32_bf16 v[186:189], v[198:201], v[122:125], v[2:5]
	s_setprio 0
	s_barrier
	s_nop 1
	ds_read_b128 v[2:5], v161
	ds_read_b128 v[10:13], v162
	ds_read_b128 v[160:163], v163
	ds_read_b128 v[190:193], v164
	ds_read_b128 v[18:21], v150 offset:32768
	ds_read_b128 v[26:29], v150 offset:34816
	ds_read_b128 v[34:37], v151 offset:32768
	ds_read_b128 v[42:45], v151 offset:34816
	ds_read_b128 v[50:53], v150 offset:36864
	ds_read_b128 v[58:61], v150 offset:38912
	ds_read_b128 v[194:197], v151 offset:36864
	ds_read_b128 v[198:201], v151 offset:38912
	s_waitcnt vmcnt(2)
	s_barrier
	s_waitcnt lgkmcnt(0)
	s_setprio 1
	s_waitcnt lgkmcnt(0)
	v_mfma_f32_16x16x32_bf16 v[66:69], v[18:21], v[2:5], v[126:129]
	v_mfma_f32_16x16x32_bf16 v[122:125], v[34:37], v[10:13], v[66:69]
	v_mfma_f32_16x16x32_bf16 v[66:69], v[18:21], v[160:163], v[136:139]
	v_mfma_f32_16x16x32_bf16 v[118:121], v[34:37], v[190:193], v[66:69]
	v_mfma_f32_16x16x32_bf16 v[66:69], v[26:29], v[2:5], v[222:225]
	v_mfma_f32_16x16x32_bf16 v[102:105], v[42:45], v[10:13], v[66:69]
	v_mfma_f32_16x16x32_bf16 v[66:69], v[26:29], v[160:163], v[114:117]
	v_mfma_f32_16x16x32_bf16 v[98:101], v[42:45], v[190:193], v[66:69]
	v_mfma_f32_16x16x32_bf16 v[66:69], v[50:53], v[2:5], v[110:113]
	v_mfma_f32_16x16x32_bf16 v[86:89], v[194:197], v[10:13], v[66:69]
	v_mfma_f32_16x16x32_bf16 v[66:69], v[50:53], v[160:163], v[106:109]
	v_mfma_f32_16x16x32_bf16 v[82:85], v[194:197], v[190:193], v[66:69]
	v_mfma_f32_16x16x32_bf16 v[66:69], v[58:61], v[2:5], v[226:229]
	v_mfma_f32_16x16x32_bf16 v[70:73], v[198:201], v[10:13], v[66:69]
	v_mfma_f32_16x16x32_bf16 v[66:69], v[58:61], v[160:163], v[230:233]
	v_mfma_f32_16x16x32_bf16 v[66:69], v[198:201], v[190:193], v[66:69]
	s_setprio 0
	s_barrier
	ds_read_b128 v[136:139], v165
	ds_read_b128 v[222:225], v166
	ds_read_b128 v[164:167], v167
	ds_read_b128 v[226:229], v168
	s_waitcnt vmcnt(0)
	s_barrier
	s_waitcnt lgkmcnt(0)
	s_setprio 1
	s_waitcnt lgkmcnt(0)
	v_mfma_f32_16x16x32_bf16 v[94:97], v[18:21], v[136:139], v[94:97]
	v_mfma_f32_16x16x32_bf16 v[18:21], v[18:21], v[164:167], v[90:93]
	v_mfma_f32_16x16x32_bf16 v[114:117], v[34:37], v[226:229], v[18:21]
	v_mfma_f32_16x16x32_bf16 v[18:21], v[26:29], v[136:139], v[156:159]
	v_mfma_f32_16x16x32_bf16 v[110:113], v[42:45], v[222:225], v[18:21]
	v_mfma_f32_16x16x32_bf16 v[18:21], v[26:29], v[164:167], v[174:177]
	v_mfma_f32_16x16x32_bf16 v[106:109], v[42:45], v[226:229], v[18:21]
	v_mfma_f32_16x16x32_bf16 v[18:21], v[50:53], v[136:139], v[78:81]
	v_mfma_f32_16x16x32_bf16 v[126:129], v[34:37], v[222:225], v[94:97]
	v_mfma_f32_16x16x32_bf16 v[94:97], v[194:197], v[222:225], v[18:21]
	v_mfma_f32_16x16x32_bf16 v[18:21], v[50:53], v[164:167], v[74:77]
	v_mfma_f32_16x16x32_bf16 v[90:93], v[194:197], v[226:229], v[18:21]
	v_mfma_f32_16x16x32_bf16 v[18:21], v[58:61], v[136:139], v[178:181]
	v_mfma_f32_16x16x32_bf16 v[78:81], v[198:201], v[222:225], v[18:21]
	v_mfma_f32_16x16x32_bf16 v[18:21], v[58:61], v[164:167], v[182:185]
	v_mfma_f32_16x16x32_bf16 v[74:77], v[198:201], v[226:229], v[18:21]
	s_setprio 0
	s_barrier
	ds_read_b128 v[156:159], v150 offset:49152
	ds_read_b128 v[174:177], v150 offset:51200
	ds_read_b128 v[178:181], v151 offset:49152
	ds_read_b128 v[182:185], v151 offset:51200
	ds_read_b128 v[194:197], v150 offset:53248
	ds_read_b128 v[198:201], v150 offset:55296
	ds_read_b128 v[230:233], v151 offset:53248
	ds_read_b128 v[148:151], v151 offset:55296
	s_barrier
	s_waitcnt lgkmcnt(0)
	s_setprio 1
	s_waitcnt lgkmcnt(0)
	v_mfma_f32_16x16x32_bf16 v[18:21], v[156:159], v[2:5], v[62:65]
	v_mfma_f32_16x16x32_bf16 v[58:61], v[178:181], v[10:13], v[18:21]
	v_mfma_f32_16x16x32_bf16 v[18:21], v[156:159], v[160:163], v[218:221]
	v_mfma_f32_16x16x32_bf16 v[50:53], v[178:181], v[190:193], v[18:21]
	v_mfma_f32_16x16x32_bf16 v[18:21], v[174:177], v[2:5], v[54:57]
	v_mfma_f32_16x16x32_bf16 v[42:45], v[182:185], v[10:13], v[18:21]
	v_mfma_f32_16x16x32_bf16 v[18:21], v[174:177], v[160:163], v[234:237]
	v_mfma_f32_16x16x32_bf16 v[34:37], v[182:185], v[190:193], v[18:21]
	v_mfma_f32_16x16x32_bf16 v[18:21], v[194:197], v[2:5], v[46:49]
	v_mfma_f32_16x16x32_bf16 v[2:5], v[198:201], v[2:5], v[38:41]
	v_mfma_f32_16x16x32_bf16 v[26:29], v[230:233], v[10:13], v[18:21]
	v_mfma_f32_16x16x32_bf16 v[18:21], v[194:197], v[160:163], v[238:241]
	v_mfma_f32_16x16x32_bf16 v[10:13], v[148:151], v[10:13], v[2:5]
	v_mfma_f32_16x16x32_bf16 v[2:5], v[198:201], v[160:163], v[140:143]
	v_mfma_f32_16x16x32_bf16 v[18:21], v[230:233], v[190:193], v[18:21]
	v_mfma_f32_16x16x32_bf16 v[2:5], v[148:151], v[190:193], v[2:5]
	s_setprio 0
	s_setprio 1
	v_mfma_f32_16x16x32_bf16 v[30:33], v[156:159], v[136:139], v[30:33]
	v_mfma_f32_16x16x32_bf16 v[62:65], v[178:181], v[222:225], v[30:33]
	v_mfma_f32_16x16x32_bf16 v[30:33], v[156:159], v[164:167], v[144:147]
	v_mfma_f32_16x16x32_bf16 v[22:25], v[174:177], v[136:139], v[22:25]
	v_mfma_f32_16x16x32_bf16 v[14:17], v[194:197], v[136:139], v[14:17]
	v_mfma_f32_16x16x32_bf16 v[54:57], v[178:181], v[226:229], v[30:33]
	v_mfma_f32_16x16x32_bf16 v[46:49], v[182:185], v[222:225], v[22:25]
	v_mfma_f32_16x16x32_bf16 v[22:25], v[174:177], v[164:167], v[152:155]
	v_mfma_f32_16x16x32_bf16 v[30:33], v[230:233], v[222:225], v[14:17]
	v_mfma_f32_16x16x32_bf16 v[14:17], v[194:197], v[164:167], v[170:173]
	v_mfma_f32_16x16x32_bf16 v[6:9], v[198:201], v[136:139], v[6:9]
	v_mfma_f32_16x16x32_bf16 v[38:41], v[182:185], v[226:229], v[22:25]
	v_mfma_f32_16x16x32_bf16 v[22:25], v[230:233], v[226:229], v[14:17]
	v_mfma_f32_16x16x32_bf16 v[14:17], v[148:151], v[222:225], v[6:9]
	v_mfma_f32_16x16x32_bf16 v[6:9], v[198:201], v[164:167], v[186:189]
	v_mfma_f32_16x16x32_bf16 v[6:9], v[148:151], v[226:229], v[6:9]
	s_setprio 0
	s_cmpk_gt_u32 s0, 0xff
	s_barrier
	s_cbranch_scc1 .LBB0_344
	s_barrier

.LBB0_349:
	v_or_b32_e32 v0, 0x10000, v150
	v_add_u32_e32 v153, 0x10800, v150
	v_or_b32_e32 v152, 0x10000, v151
	ds_read_b128 v[160:163], v0
	ds_read_b128 v[164:167], v152
	v_add_u32_e32 v154, 0x10800, v151
	ds_read_b128 v[168:171], v153
	ds_read_b128 v[172:175], v154
	v_lshl_add_u64 v[206:207], v[132:133], 0, v[142:143]
	s_add_i32 s22, s1, 0xc000
	v_lshl_add_u64 v[156:157], v[206:207], 0, s[50:51]
	s_mov_b32 m0, s22
	v_lshl_add_u64 v[208:209], v[132:133], 0, v[140:141]
	s_add_i32 s5, s1, 0xe000
	ds_read_b128 v[176:179], v148
	ds_read_b128 v[180:183], v148 offset:2048
	ds_read_b128 v[184:187], v149
	ds_read_b128 v[188:191], v149 offset:2048
	ds_read_b128 v[192:195], v148 offset:4096
	ds_read_b128 v[196:199], v148 offset:6144
	ds_read_b128 v[200:203], v149 offset:4096
	ds_read_b128 v[218:221], v149 offset:6144
	global_load_lds_dwordx4 v[156:157], off
	v_lshl_add_u64 v[156:157], v[208:209], 0, s[50:51]
	s_mov_b32 m0, s5
	s_nop 0
	global_load_lds_dwordx4 v[156:157], off
	s_waitcnt lgkmcnt(8)
	s_waitcnt vmcnt(10)
	s_barrier
	s_waitcnt lgkmcnt(0)
	s_setprio 1
	s_waitcnt lgkmcnt(0)
	v_mfma_f32_16x16x32_bf16 v[126:129], v[160:163], v[176:179], v[126:129]
	v_mfma_f32_16x16x32_bf16 v[122:125], v[168:171], v[176:179], v[122:125]
	v_mfma_f32_16x16x32_bf16 v[118:121], v[160:163], v[180:183], v[118:121]
	v_mfma_f32_16x16x32_bf16 v[114:117], v[168:171], v[180:183], v[114:117]
	v_mfma_f32_16x16x32_bf16 v[110:113], v[160:163], v[192:195], v[110:113]
	v_mfma_f32_16x16x32_bf16 v[106:109], v[168:171], v[192:195], v[106:109]
	v_mfma_f32_16x16x32_bf16 v[102:105], v[160:163], v[196:199], v[102:105]
	v_mfma_f32_16x16x32_bf16 v[98:101], v[168:171], v[196:199], v[98:101]
	v_mfma_f32_16x16x32_bf16 v[126:129], v[164:167], v[184:187], v[126:129]
	v_mfma_f32_16x16x32_bf16 v[122:125], v[172:175], v[184:187], v[122:125]
	v_mfma_f32_16x16x32_bf16 v[118:121], v[164:167], v[188:191], v[118:121]
	v_mfma_f32_16x16x32_bf16 v[114:117], v[172:175], v[188:191], v[114:117]
	v_mfma_f32_16x16x32_bf16 v[110:113], v[164:167], v[200:203], v[110:113]
	v_mfma_f32_16x16x32_bf16 v[106:109], v[172:175], v[200:203], v[106:109]
	v_mfma_f32_16x16x32_bf16 v[102:105], v[164:167], v[218:221], v[102:105]
	v_mfma_f32_16x16x32_bf16 v[98:101], v[172:175], v[218:221], v[98:101]
	s_setprio 0
	s_barrier
	v_lshl_add_u64 v[210:211], v[132:133], 0, v[146:147]
	s_mov_b32 m0, s2
	v_or_b32_e32 v155, 0x14000, v150
	v_add_u32_e32 v157, 0x14800, v150
	v_lshl_add_u64 v[214:215], v[210:211], 0, s[70:71]
	v_or_b32_e32 v156, 0x14000, v151
	ds_read_b128 v[222:225], v155
	ds_read_b128 v[226:229], v156
	v_add_u32_e32 v158, 0x14800, v151
	ds_read_b128 v[230:233], v157
	ds_read_b128 v[234:237], v158
	global_load_lds_dwordx4 v[214:215], off
	v_lshl_add_u64 v[214:215], v[132:133], 0, v[144:145]
	v_lshl_add_u64 v[238:239], v[214:215], 0, s[70:71]
	s_mov_b32 m0, s3
	s_nop 0
	global_load_lds_dwordx4 v[238:239], off
	s_waitcnt vmcnt(10)
	s_waitcnt lgkmcnt(0)
	s_barrier
	s_waitcnt lgkmcnt(0)
	s_setprio 1
	s_waitcnt lgkmcnt(0)
	v_mfma_f32_16x16x32_bf16 v[94:97], v[222:225], v[176:179], v[94:97]
	v_mfma_f32_16x16x32_bf16 v[90:93], v[230:233], v[176:179], v[90:93]
	v_mfma_f32_16x16x32_bf16 v[86:89], v[222:225], v[180:183], v[86:89]
	v_mfma_f32_16x16x32_bf16 v[82:85], v[230:233], v[180:183], v[82:85]
	v_mfma_f32_16x16x32_bf16 v[78:81], v[222:225], v[192:195], v[78:81]
	v_mfma_f32_16x16x32_bf16 v[74:77], v[230:233], v[192:195], v[74:77]
	v_mfma_f32_16x16x32_bf16 v[70:73], v[222:225], v[196:199], v[70:73]
	v_mfma_f32_16x16x32_bf16 v[66:69], v[230:233], v[196:199], v[66:69]
	v_mfma_f32_16x16x32_bf16 v[94:97], v[226:229], v[184:187], v[94:97]
	v_mfma_f32_16x16x32_bf16 v[90:93], v[234:237], v[184:187], v[90:93]
	v_mfma_f32_16x16x32_bf16 v[86:89], v[226:229], v[188:191], v[86:89]
	v_mfma_f32_16x16x32_bf16 v[82:85], v[234:237], v[188:191], v[82:85]
	v_mfma_f32_16x16x32_bf16 v[78:81], v[226:229], v[200:203], v[78:81]
	v_mfma_f32_16x16x32_bf16 v[74:77], v[234:237], v[200:203], v[74:77]
	v_mfma_f32_16x16x32_bf16 v[70:73], v[226:229], v[218:221], v[70:73]
	v_mfma_f32_16x16x32_bf16 v[66:69], v[234:237], v[218:221], v[66:69]
	s_setprio 0
	s_mov_b32 m0, s1
	v_lshl_add_u64 v[238:239], v[206:207], 0, s[54:55]
	s_barrier
	ds_read_b128 v[176:179], v148 offset:16384
	ds_read_b128 v[180:183], v148 offset:18432
	ds_read_b128 v[184:187], v149 offset:16384
	ds_read_b128 v[188:191], v149 offset:18432
	ds_read_b128 v[192:195], v148 offset:20480
	ds_read_b128 v[196:199], v148 offset:22528
	ds_read_b128 v[200:203], v149 offset:20480
	ds_read_b128 v[218:221], v149 offset:22528
	global_load_lds_dwordx4 v[238:239], off
	v_lshl_add_u64 v[238:239], v[208:209], 0, s[54:55]
	s_mov_b32 m0, s9
	s_nop 0
	global_load_lds_dwordx4 v[238:239], off
	v_lshl_add_u64 v[238:239], v[210:211], 0, s[24:25]
	s_mov_b32 m0, s11
	s_nop 0
	global_load_lds_dwordx4 v[238:239], off
	v_lshl_add_u64 v[238:239], v[214:215], 0, s[24:25]
	s_mov_b32 m0, s12
	s_nop 0
	global_load_lds_dwordx4 v[238:239], off
	s_waitcnt vmcnt(10)
	s_waitcnt lgkmcnt(0)
	s_barrier
	s_waitcnt lgkmcnt(0)
	s_setprio 1
	s_waitcnt lgkmcnt(0)
	v_mfma_f32_16x16x32_bf16 v[62:65], v[160:163], v[176:179], v[62:65]
	v_mfma_f32_16x16x32_bf16 v[58:61], v[168:171], v[176:179], v[58:61]
	v_mfma_f32_16x16x32_bf16 v[54:57], v[160:163], v[180:183], v[54:57]
	v_mfma_f32_16x16x32_bf16 v[50:53], v[168:171], v[180:183], v[50:53]
	v_mfma_f32_16x16x32_bf16 v[46:49], v[160:163], v[192:195], v[46:49]
	v_mfma_f32_16x16x32_bf16 v[42:45], v[168:171], v[192:195], v[42:45]
	v_mfma_f32_16x16x32_bf16 v[38:41], v[160:163], v[196:199], v[38:41]
	v_mfma_f32_16x16x32_bf16 v[34:37], v[168:171], v[196:199], v[34:37]
	v_mfma_f32_16x16x32_bf16 v[62:65], v[164:167], v[184:187], v[62:65]
	v_mfma_f32_16x16x32_bf16 v[58:61], v[172:175], v[184:187], v[58:61]
	v_mfma_f32_16x16x32_bf16 v[54:57], v[164:167], v[188:191], v[54:57]
	v_mfma_f32_16x16x32_bf16 v[50:53], v[172:175], v[188:191], v[50:53]
	v_mfma_f32_16x16x32_bf16 v[46:49], v[164:167], v[200:203], v[46:49]
	v_mfma_f32_16x16x32_bf16 v[42:45], v[172:175], v[200:203], v[42:45]
	v_mfma_f32_16x16x32_bf16 v[38:41], v[164:167], v[218:221], v[38:41]
	v_mfma_f32_16x16x32_bf16 v[34:37], v[172:175], v[218:221], v[34:37]
	v_mfma_f32_16x16x32_bf16 v[30:33], v[222:225], v[176:179], v[30:33]
	v_mfma_f32_16x16x32_bf16 v[26:29], v[230:233], v[176:179], v[26:29]
	v_mfma_f32_16x16x32_bf16 v[22:25], v[222:225], v[180:183], v[22:25]
	v_mfma_f32_16x16x32_bf16 v[18:21], v[230:233], v[180:183], v[18:21]
	v_mfma_f32_16x16x32_bf16 v[14:17], v[222:225], v[192:195], v[14:17]
	v_mfma_f32_16x16x32_bf16 v[10:13], v[230:233], v[192:195], v[10:13]
	v_mfma_f32_16x16x32_bf16 v[6:9], v[222:225], v[196:199], v[6:9]
	v_mfma_f32_16x16x32_bf16 v[2:5], v[230:233], v[196:199], v[2:5]
	v_mfma_f32_16x16x32_bf16 v[30:33], v[226:229], v[184:187], v[30:33]
	v_mfma_f32_16x16x32_bf16 v[26:29], v[234:237], v[184:187], v[26:29]
	v_mfma_f32_16x16x32_bf16 v[22:25], v[226:229], v[188:191], v[22:25]
	v_mfma_f32_16x16x32_bf16 v[18:21], v[234:237], v[188:191], v[18:21]
	v_mfma_f32_16x16x32_bf16 v[14:17], v[226:229], v[200:203], v[14:17]
	v_mfma_f32_16x16x32_bf16 v[10:13], v[234:237], v[200:203], v[10:13]
	v_mfma_f32_16x16x32_bf16 v[6:9], v[226:229], v[218:221], v[6:9]
	v_mfma_f32_16x16x32_bf16 v[2:5], v[234:237], v[218:221], v[2:5]
	s_setprio 0
	v_or_b32_e32 v159, 0x18000, v150
	v_add_u32_e32 v161, 0x18800, v150
	s_barrier
	v_or_b32_e32 v160, 0x18000, v151
	ds_read_b128 v[168:171], v159
	ds_read_b128 v[172:175], v160
	v_add_u32_e32 v162, 0x18800, v151
	ds_read_b128 v[176:179], v161
	ds_read_b128 v[180:183], v162
	s_mov_b32 m0, s13
	v_lshl_add_u64 v[164:165], v[206:207], 0, s[58:59]
	ds_read_b128 v[184:187], v148 offset:32768
	ds_read_b128 v[188:191], v148 offset:34816
	ds_read_b128 v[192:195], v149 offset:32768
	ds_read_b128 v[196:199], v149 offset:34816
	ds_read_b128 v[200:203], v148 offset:36864
	ds_read_b128 v[218:221], v148 offset:38912
	ds_read_b128 v[222:225], v149 offset:36864
	ds_read_b128 v[226:229], v149 offset:38912
	global_load_lds_dwordx4 v[164:165], off
	v_lshl_add_u64 v[164:165], v[208:209], 0, s[58:59]
	s_mov_b32 m0, s15
	s_nop 0
	global_load_lds_dwordx4 v[164:165], off
	s_waitcnt lgkmcnt(8)
	s_waitcnt vmcnt(10)
	s_barrier
	s_waitcnt lgkmcnt(0)
	s_setprio 1
	s_waitcnt lgkmcnt(0)
	v_mfma_f32_16x16x32_bf16 v[126:129], v[168:171], v[184:187], v[126:129]
	v_mfma_f32_16x16x32_bf16 v[122:125], v[176:179], v[184:187], v[122:125]
	v_mfma_f32_16x16x32_bf16 v[118:121], v[168:171], v[188:191], v[118:121]
	v_mfma_f32_16x16x32_bf16 v[114:117], v[176:179], v[188:191], v[114:117]
	v_mfma_f32_16x16x32_bf16 v[110:113], v[168:171], v[200:203], v[110:113]
	v_mfma_f32_16x16x32_bf16 v[106:109], v[176:179], v[200:203], v[106:109]
	v_mfma_f32_16x16x32_bf16 v[102:105], v[168:171], v[218:221], v[102:105]
	v_mfma_f32_16x16x32_bf16 v[98:101], v[176:179], v[218:221], v[98:101]
	v_mfma_f32_16x16x32_bf16 v[126:129], v[172:175], v[192:195], v[126:129]
	v_mfma_f32_16x16x32_bf16 v[122:125], v[180:183], v[192:195], v[122:125]
	v_mfma_f32_16x16x32_bf16 v[118:121], v[172:175], v[196:199], v[118:121]
	v_mfma_f32_16x16x32_bf16 v[114:117], v[180:183], v[196:199], v[114:117]
	v_mfma_f32_16x16x32_bf16 v[110:113], v[172:175], v[222:225], v[110:113]
	v_mfma_f32_16x16x32_bf16 v[106:109], v[180:183], v[222:225], v[106:109]
	v_mfma_f32_16x16x32_bf16 v[102:105], v[172:175], v[226:229], v[102:105]
	v_mfma_f32_16x16x32_bf16 v[98:101], v[180:183], v[226:229], v[98:101]
	s_setprio 0
	s_barrier
	s_mov_b32 m0, s16
	v_or_b32_e32 v163, 0x1c000, v150
	v_add_u32_e32 v165, 0x1c800, v150
	v_lshl_add_u64 v[246:247], v[210:211], 0, s[26:27]
	v_or_b32_e32 v164, 0x1c000, v151
	ds_read_b128 v[230:233], v163
	ds_read_b128 v[234:237], v164
	v_add_u32_e32 v166, 0x1c800, v151
	ds_read_b128 v[238:241], v165
	ds_read_b128 v[242:245], v166
	global_load_lds_dwordx4 v[246:247], off
	v_lshl_add_u64 v[246:247], v[214:215], 0, s[26:27]
	s_mov_b32 m0, s17
	s_nop 0
	global_load_lds_dwordx4 v[246:247], off
	s_waitcnt vmcnt(10)
	s_waitcnt lgkmcnt(0)
	s_barrier
	s_waitcnt lgkmcnt(0)
	s_setprio 1
	s_waitcnt lgkmcnt(0)
	v_mfma_f32_16x16x32_bf16 v[94:97], v[230:233], v[184:187], v[94:97]
	v_mfma_f32_16x16x32_bf16 v[90:93], v[238:241], v[184:187], v[90:93]
	v_mfma_f32_16x16x32_bf16 v[86:89], v[230:233], v[188:191], v[86:89]
	v_mfma_f32_16x16x32_bf16 v[82:85], v[238:241], v[188:191], v[82:85]
	v_mfma_f32_16x16x32_bf16 v[78:81], v[230:233], v[200:203], v[78:81]
	v_mfma_f32_16x16x32_bf16 v[74:77], v[238:241], v[200:203], v[74:77]
	v_mfma_f32_16x16x32_bf16 v[70:73], v[230:233], v[218:221], v[70:73]
	v_mfma_f32_16x16x32_bf16 v[66:69], v[238:241], v[218:221], v[66:69]
	v_mfma_f32_16x16x32_bf16 v[94:97], v[234:237], v[192:195], v[94:97]
	v_mfma_f32_16x16x32_bf16 v[90:93], v[242:245], v[192:195], v[90:93]
	v_mfma_f32_16x16x32_bf16 v[86:89], v[234:237], v[196:199], v[86:89]
	v_mfma_f32_16x16x32_bf16 v[82:85], v[242:245], v[196:199], v[82:85]
	v_mfma_f32_16x16x32_bf16 v[78:81], v[234:237], v[222:225], v[78:81]
	v_mfma_f32_16x16x32_bf16 v[74:77], v[242:245], v[222:225], v[74:77]
	v_mfma_f32_16x16x32_bf16 v[70:73], v[234:237], v[226:229], v[70:73]
	v_mfma_f32_16x16x32_bf16 v[66:69], v[242:245], v[226:229], v[66:69]
	s_setprio 0
	s_mov_b32 m0, s18
	v_lshl_add_u64 v[206:207], v[206:207], 0, s[62:63]
	s_barrier
	ds_read_b128 v[184:187], v148 offset:49152
	ds_read_b128 v[188:191], v148 offset:51200
	ds_read_b128 v[192:195], v149 offset:49152
	ds_read_b128 v[196:199], v149 offset:51200
	ds_read_b128 v[200:203], v148 offset:53248
	ds_read_b128 v[218:221], v148 offset:55296
	ds_read_b128 v[222:225], v149 offset:53248
	ds_read_b128 v[226:229], v149 offset:55296
	global_load_lds_dwordx4 v[206:207], off
	v_lshl_add_u64 v[206:207], v[208:209], 0, s[62:63]
	s_mov_b32 m0, s19
	s_nop 0
	global_load_lds_dwordx4 v[206:207], off
	v_lshl_add_u64 v[206:207], v[210:211], 0, s[28:29]
	s_mov_b32 m0, s20
	s_nop 0
	global_load_lds_dwordx4 v[206:207], off
	v_lshl_add_u64 v[206:207], v[214:215], 0, s[28:29]
	s_mov_b32 m0, s21
	s_nop 0
	global_load_lds_dwordx4 v[206:207], off
	s_waitcnt vmcnt(10)
	s_waitcnt lgkmcnt(0)
	s_barrier
	s_waitcnt lgkmcnt(0)
	s_setprio 1
	s_waitcnt lgkmcnt(0)
	v_mfma_f32_16x16x32_bf16 v[62:65], v[168:171], v[184:187], v[62:65]
	v_mfma_f32_16x16x32_bf16 v[58:61], v[176:179], v[184:187], v[58:61]
	v_mfma_f32_16x16x32_bf16 v[54:57], v[168:171], v[188:191], v[54:57]
	v_mfma_f32_16x16x32_bf16 v[50:53], v[176:179], v[188:191], v[50:53]
	v_mfma_f32_16x16x32_bf16 v[46:49], v[168:171], v[200:203], v[46:49]
	v_mfma_f32_16x16x32_bf16 v[42:45], v[176:179], v[200:203], v[42:45]
	v_mfma_f32_16x16x32_bf16 v[38:41], v[168:171], v[218:221], v[38:41]
	v_mfma_f32_16x16x32_bf16 v[34:37], v[176:179], v[218:221], v[34:37]
	v_mfma_f32_16x16x32_bf16 v[62:65], v[172:175], v[192:195], v[62:65]
	v_mfma_f32_16x16x32_bf16 v[58:61], v[180:183], v[192:195], v[58:61]
	v_mfma_f32_16x16x32_bf16 v[54:57], v[172:175], v[196:199], v[54:57]
	v_mfma_f32_16x16x32_bf16 v[50:53], v[180:183], v[196:199], v[50:53]
	v_mfma_f32_16x16x32_bf16 v[46:49], v[172:175], v[222:225], v[46:49]
	v_mfma_f32_16x16x32_bf16 v[42:45], v[180:183], v[222:225], v[42:45]
	v_mfma_f32_16x16x32_bf16 v[38:41], v[172:175], v[226:229], v[38:41]
	v_mfma_f32_16x16x32_bf16 v[34:37], v[180:183], v[226:229], v[34:37]
	v_mfma_f32_16x16x32_bf16 v[30:33], v[230:233], v[184:187], v[30:33]
	v_mfma_f32_16x16x32_bf16 v[26:29], v[238:241], v[184:187], v[26:29]
	v_mfma_f32_16x16x32_bf16 v[22:25], v[230:233], v[188:191], v[22:25]
	v_mfma_f32_16x16x32_bf16 v[18:21], v[238:241], v[188:191], v[18:21]
	v_mfma_f32_16x16x32_bf16 v[14:17], v[230:233], v[200:203], v[14:17]
	v_mfma_f32_16x16x32_bf16 v[10:13], v[238:241], v[200:203], v[10:13]
	v_mfma_f32_16x16x32_bf16 v[6:9], v[230:233], v[218:221], v[6:9]
	v_mfma_f32_16x16x32_bf16 v[2:5], v[238:241], v[218:221], v[2:5]
	v_mfma_f32_16x16x32_bf16 v[30:33], v[234:237], v[192:195], v[30:33]
	v_mfma_f32_16x16x32_bf16 v[26:29], v[242:245], v[192:195], v[26:29]
	v_mfma_f32_16x16x32_bf16 v[22:25], v[234:237], v[196:199], v[22:25]
	v_mfma_f32_16x16x32_bf16 v[18:21], v[242:245], v[196:199], v[18:21]
	v_mfma_f32_16x16x32_bf16 v[14:17], v[234:237], v[222:225], v[14:17]
	v_mfma_f32_16x16x32_bf16 v[10:13], v[242:245], v[222:225], v[10:13]
	v_mfma_f32_16x16x32_bf16 v[6:9], v[234:237], v[226:229], v[6:9]
	v_mfma_f32_16x16x32_bf16 v[2:5], v[242:245], v[226:229], v[2:5]
	s_setprio 0
	s_add_i32 s4, s4, 2
	s_cmp_lt_u32 s4, 28
	v_lshl_add_u64 v[132:133], v[132:133], 0, s[54:55]
	s_barrier
	s_cbranch_scc1 .LBB0_349
	s_waitcnt vmcnt(6)
	s_mov_b64 s[2:3], 0xf80
	s_mov_b32 m0, s22
	v_lshl_add_u64 v[132:133], v[138:139], 0, s[2:3]
	ds_read_b128 v[140:143], v0
	ds_read_b128 v[144:147], v152
	ds_read_b128 v[150:153], v153
	ds_read_b128 v[168:171], v154
	ds_read_b128 v[172:175], v148
	ds_read_b128 v[176:179], v148 offset:2048
	ds_read_b128 v[180:183], v149
	ds_read_b128 v[184:187], v149 offset:2048
	ds_read_b128 v[188:191], v148 offset:4096
	ds_read_b128 v[192:195], v148 offset:6144
	ds_read_b128 v[196:199], v149 offset:4096
	ds_read_b128 v[200:203], v149 offset:6144
	global_load_lds_dwordx4 v[132:133], off
	v_lshl_add_u64 v[132:133], v[136:137], 0, s[2:3]
	s_mov_b32 m0, s5
	s_nop 0
	global_load_lds_dwordx4 v[132:133], off
	s_barrier
	s_waitcnt lgkmcnt(0)
	s_setprio 1
	s_waitcnt lgkmcnt(0)
	v_mfma_f32_16x16x32_bf16 v[126:129], v[140:143], v[172:175], v[126:129]
	v_mfma_f32_16x16x32_bf16 v[122:125], v[150:153], v[172:175], v[122:125]
	v_mfma_f32_16x16x32_bf16 v[118:121], v[140:143], v[176:179], v[118:121]
	v_mfma_f32_16x16x32_bf16 v[110:113], v[140:143], v[188:191], v[110:113]
	v_mfma_f32_16x16x32_bf16 v[106:109], v[150:153], v[188:191], v[106:109]
	v_mfma_f32_16x16x32_bf16 v[126:129], v[144:147], v[180:183], v[126:129]
	v_mfma_f32_16x16x32_bf16 v[122:125], v[168:171], v[180:183], v[122:125]
	v_mfma_f32_16x16x32_bf16 v[118:121], v[144:147], v[184:187], v[118:121]
	v_mfma_f32_16x16x32_bf16 v[114:117], v[150:153], v[176:179], v[114:117]
	v_mfma_f32_16x16x32_bf16 v[110:113], v[144:147], v[196:199], v[110:113]
	v_mfma_f32_16x16x32_bf16 v[106:109], v[168:171], v[196:199], v[106:109]
	v_mfma_f32_16x16x32_bf16 v[102:105], v[140:143], v[192:195], v[102:105]
	v_mfma_f32_16x16x32_bf16 v[98:101], v[150:153], v[192:195], v[98:101]
	v_mfma_f32_16x16x32_bf16 v[136:139], v[168:171], v[184:187], v[114:117]
	v_mfma_f32_16x16x32_bf16 v[218:221], v[144:147], v[200:203], v[102:105]
	v_mfma_f32_16x16x32_bf16 v[222:225], v[168:171], v[200:203], v[98:101]
	s_setprio 0
	s_barrier
	s_nop 2
	ds_read_b128 v[98:101], v155
	ds_read_b128 v[102:105], v156
	ds_read_b128 v[114:117], v157
	ds_read_b128 v[154:157], v158
	s_barrier
	s_waitcnt lgkmcnt(0)
	s_setprio 1
	s_waitcnt lgkmcnt(0)
	v_mfma_f32_16x16x32_bf16 v[94:97], v[98:101], v[172:175], v[94:97]
	v_mfma_f32_16x16x32_bf16 v[90:93], v[114:117], v[172:175], v[90:93]
	v_mfma_f32_16x16x32_bf16 v[78:81], v[98:101], v[188:191], v[78:81]
	v_mfma_f32_16x16x32_bf16 v[74:77], v[114:117], v[188:191], v[74:77]
	v_mfma_f32_16x16x32_bf16 v[94:97], v[102:105], v[180:183], v[94:97]
	v_mfma_f32_16x16x32_bf16 v[90:93], v[154:157], v[180:183], v[90:93]
	v_mfma_f32_16x16x32_bf16 v[86:89], v[98:101], v[176:179], v[86:89]
	v_mfma_f32_16x16x32_bf16 v[82:85], v[114:117], v[176:179], v[82:85]
	v_mfma_f32_16x16x32_bf16 v[78:81], v[102:105], v[196:199], v[78:81]
	v_mfma_f32_16x16x32_bf16 v[74:77], v[154:157], v[196:199], v[74:77]
	v_mfma_f32_16x16x32_bf16 v[70:73], v[98:101], v[192:195], v[70:73]
	v_mfma_f32_16x16x32_bf16 v[66:69], v[114:117], v[192:195], v[66:69]
	v_mfma_f32_16x16x32_bf16 v[172:175], v[102:105], v[184:187], v[86:89]
	v_mfma_f32_16x16x32_bf16 v[176:179], v[154:157], v[184:187], v[82:85]
	v_mfma_f32_16x16x32_bf16 v[180:183], v[102:105], v[200:203], v[70:73]
	v_mfma_f32_16x16x32_bf16 v[184:187], v[154:157], v[200:203], v[66:69]
	s_setprio 0
	s_barrier
	s_nop 1
	ds_read_b128 v[66:69], v148 offset:16384
	ds_read_b128 v[70:73], v148 offset:18432
	ds_read_b128 v[82:85], v149 offset:16384
	ds_read_b128 v[86:89], v149 offset:18432
	ds_read_b128 v[188:191], v148 offset:20480
	ds_read_b128 v[192:195], v148 offset:22528
	ds_read_b128 v[196:199], v149 offset:20480
	ds_read_b128 v[200:203], v149 offset:22528
	s_waitcnt vmcnt(4)
	s_barrier
	s_waitcnt lgkmcnt(0)
	s_setprio 1
	s_waitcnt lgkmcnt(0)
	v_mfma_f32_16x16x32_bf16 v[62:65], v[140:143], v[66:69], v[62:65]
	v_mfma_f32_16x16x32_bf16 v[58:61], v[150:153], v[66:69], v[58:61]
	v_mfma_f32_16x16x32_bf16 v[46:49], v[140:143], v[188:191], v[46:49]
	v_mfma_f32_16x16x32_bf16 v[42:45], v[150:153], v[188:191], v[42:45]
	v_mfma_f32_16x16x32_bf16 v[62:65], v[144:147], v[82:85], v[62:65]
	v_mfma_f32_16x16x32_bf16 v[58:61], v[168:171], v[82:85], v[58:61]
	v_mfma_f32_16x16x32_bf16 v[54:57], v[140:143], v[70:73], v[54:57]
	v_mfma_f32_16x16x32_bf16 v[50:53], v[150:153], v[70:73], v[50:53]
	v_mfma_f32_16x16x32_bf16 v[46:49], v[144:147], v[196:199], v[46:49]
	v_mfma_f32_16x16x32_bf16 v[42:45], v[168:171], v[196:199], v[42:45]
	v_mfma_f32_16x16x32_bf16 v[38:41], v[140:143], v[192:195], v[38:41]
	v_mfma_f32_16x16x32_bf16 v[34:37], v[150:153], v[192:195], v[34:37]
	v_mfma_f32_16x16x32_bf16 v[226:229], v[144:147], v[86:89], v[54:57]
	v_mfma_f32_16x16x32_bf16 v[230:233], v[168:171], v[86:89], v[50:53]
	v_mfma_f32_16x16x32_bf16 v[140:143], v[144:147], v[200:203], v[38:41]
	v_mfma_f32_16x16x32_bf16 v[144:147], v[168:171], v[200:203], v[34:37]
	s_setprio 0
	s_setprio 1
	v_mfma_f32_16x16x32_bf16 v[30:33], v[98:101], v[66:69], v[30:33]
	v_mfma_f32_16x16x32_bf16 v[26:29], v[114:117], v[66:69], v[26:29]
	v_mfma_f32_16x16x32_bf16 v[14:17], v[98:101], v[188:191], v[14:17]
	v_mfma_f32_16x16x32_bf16 v[10:13], v[114:117], v[188:191], v[10:13]
	v_mfma_f32_16x16x32_bf16 v[30:33], v[102:105], v[82:85], v[30:33]
	v_mfma_f32_16x16x32_bf16 v[26:29], v[154:157], v[82:85], v[26:29]
	v_mfma_f32_16x16x32_bf16 v[22:25], v[98:101], v[70:73], v[22:25]
	v_mfma_f32_16x16x32_bf16 v[18:21], v[114:117], v[70:73], v[18:21]
	v_mfma_f32_16x16x32_bf16 v[14:17], v[102:105], v[196:199], v[14:17]
	v_mfma_f32_16x16x32_bf16 v[10:13], v[154:157], v[196:199], v[10:13]
	v_mfma_f32_16x16x32_bf16 v[6:9], v[98:101], v[192:195], v[6:9]
	v_mfma_f32_16x16x32_bf16 v[2:5], v[114:117], v[192:195], v[2:5]
	v_mfma_f32_16x16x32_bf16 v[150:153], v[102:105], v[86:89], v[22:25]
	v_mfma_f32_16x16x32_bf16 v[168:171], v[154:157], v[86:89], v[18:21]
	v_mfma_f32_16x16x32_bf16 v[188:191], v[102:105], v[200:203], v[6:9]
	v_mfma_f32_16x16x32_bf16 v[154:157], v[154:157], v[200:203], v[2:5]
	s_setprio 0
	s_barrier
	s_nop 1
	ds_read_b128 v[2:5], v159
	ds_read_b128 v[6:9], v160
	ds_read_b128 v[158:161], v161
	ds_read_b128 v[192:195], v162
	ds_read_b128 v[18:21], v148 offset:32768
	ds_read_b128 v[22:25], v148 offset:34816
	ds_read_b128 v[34:37], v149 offset:32768
	ds_read_b128 v[38:41], v149 offset:34816
	ds_read_b128 v[50:53], v148 offset:36864
	ds_read_b128 v[54:57], v148 offset:38912
	ds_read_b128 v[196:199], v149 offset:36864
	ds_read_b128 v[200:203], v149 offset:38912
	s_waitcnt vmcnt(2)
	s_barrier
	s_waitcnt lgkmcnt(0)
	s_setprio 1
	s_waitcnt lgkmcnt(0)
	v_mfma_f32_16x16x32_bf16 v[66:69], v[2:5], v[18:21], v[126:129]
	v_mfma_f32_16x16x32_bf16 v[126:129], v[6:9], v[34:37], v[66:69]
	v_mfma_f32_16x16x32_bf16 v[66:69], v[158:161], v[18:21], v[122:125]
	v_mfma_f32_16x16x32_bf16 v[114:117], v[192:195], v[34:37], v[66:69]
	v_mfma_f32_16x16x32_bf16 v[66:69], v[2:5], v[22:25], v[118:121]
	v_mfma_f32_16x16x32_bf16 v[102:105], v[6:9], v[38:41], v[66:69]
	v_mfma_f32_16x16x32_bf16 v[66:69], v[158:161], v[22:25], v[136:139]
	v_mfma_f32_16x16x32_bf16 v[98:101], v[192:195], v[38:41], v[66:69]
	v_mfma_f32_16x16x32_bf16 v[66:69], v[2:5], v[50:53], v[110:113]
	v_mfma_f32_16x16x32_bf16 v[86:89], v[6:9], v[196:199], v[66:69]
	v_mfma_f32_16x16x32_bf16 v[66:69], v[158:161], v[50:53], v[106:109]
	v_mfma_f32_16x16x32_bf16 v[82:85], v[192:195], v[196:199], v[66:69]
	v_mfma_f32_16x16x32_bf16 v[66:69], v[2:5], v[54:57], v[218:221]
	v_mfma_f32_16x16x32_bf16 v[70:73], v[6:9], v[200:203], v[66:69]
	v_mfma_f32_16x16x32_bf16 v[66:69], v[158:161], v[54:57], v[222:225]
	v_mfma_f32_16x16x32_bf16 v[66:69], v[192:195], v[200:203], v[66:69]
	s_setprio 0
	s_barrier
	ds_read_b128 v[136:139], v163
	ds_read_b128 v[218:221], v164
	ds_read_b128 v[162:165], v165
	ds_read_b128 v[222:225], v166
	s_waitcnt vmcnt(0)
	s_barrier
	s_waitcnt lgkmcnt(0)
	s_setprio 1
	s_waitcnt lgkmcnt(0)
	v_mfma_f32_16x16x32_bf16 v[94:97], v[136:139], v[18:21], v[94:97]
	v_mfma_f32_16x16x32_bf16 v[18:21], v[162:165], v[18:21], v[90:93]
	v_mfma_f32_16x16x32_bf16 v[118:121], v[222:225], v[34:37], v[18:21]
	v_mfma_f32_16x16x32_bf16 v[18:21], v[136:139], v[22:25], v[172:175]
	v_mfma_f32_16x16x32_bf16 v[110:113], v[218:221], v[38:41], v[18:21]
	v_mfma_f32_16x16x32_bf16 v[18:21], v[162:165], v[22:25], v[176:179]
	v_mfma_f32_16x16x32_bf16 v[106:109], v[222:225], v[38:41], v[18:21]
	v_mfma_f32_16x16x32_bf16 v[18:21], v[136:139], v[50:53], v[78:81]
	v_mfma_f32_16x16x32_bf16 v[122:125], v[218:221], v[34:37], v[94:97]
	v_mfma_f32_16x16x32_bf16 v[94:97], v[218:221], v[196:199], v[18:21]
	v_mfma_f32_16x16x32_bf16 v[18:21], v[162:165], v[50:53], v[74:77]
	v_mfma_f32_16x16x32_bf16 v[90:93], v[222:225], v[196:199], v[18:21]
	v_mfma_f32_16x16x32_bf16 v[18:21], v[136:139], v[54:57], v[180:183]
	v_mfma_f32_16x16x32_bf16 v[78:81], v[218:221], v[200:203], v[18:21]
	v_mfma_f32_16x16x32_bf16 v[18:21], v[162:165], v[54:57], v[184:187]
	v_mfma_f32_16x16x32_bf16 v[74:77], v[222:225], v[200:203], v[18:21]
	s_setprio 0
	s_barrier
	ds_read_b128 v[172:175], v148 offset:49152
	ds_read_b128 v[176:179], v148 offset:51200
	ds_read_b128 v[180:183], v149 offset:49152
	ds_read_b128 v[184:187], v149 offset:51200
	ds_read_b128 v[196:199], v148 offset:53248
	ds_read_b128 v[200:203], v148 offset:55296
	ds_read_b128 v[234:237], v149 offset:53248
	ds_read_b128 v[238:241], v149 offset:55296
	s_barrier
	s_waitcnt lgkmcnt(0)
	s_setprio 1
	s_waitcnt lgkmcnt(0)
	v_mfma_f32_16x16x32_bf16 v[18:21], v[2:5], v[172:175], v[62:65]
	v_mfma_f32_16x16x32_bf16 v[54:57], v[6:9], v[180:183], v[18:21]
	v_mfma_f32_16x16x32_bf16 v[18:21], v[158:161], v[172:175], v[58:61]
	v_mfma_f32_16x16x32_bf16 v[50:53], v[192:195], v[180:183], v[18:21]
	v_mfma_f32_16x16x32_bf16 v[18:21], v[2:5], v[176:179], v[226:229]
	v_mfma_f32_16x16x32_bf16 v[38:41], v[6:9], v[184:187], v[18:21]
	v_mfma_f32_16x16x32_bf16 v[18:21], v[158:161], v[176:179], v[230:233]
	v_mfma_f32_16x16x32_bf16 v[34:37], v[192:195], v[184:187], v[18:21]
	v_mfma_f32_16x16x32_bf16 v[18:21], v[2:5], v[196:199], v[46:49]
	v_mfma_f32_16x16x32_bf16 v[2:5], v[2:5], v[200:203], v[140:143]
	v_mfma_f32_16x16x32_bf16 v[22:25], v[6:9], v[234:237], v[18:21]
	v_mfma_f32_16x16x32_bf16 v[18:21], v[158:161], v[196:199], v[42:45]
	v_mfma_f32_16x16x32_bf16 v[6:9], v[6:9], v[238:241], v[2:5]
	v_mfma_f32_16x16x32_bf16 v[2:5], v[158:161], v[200:203], v[144:147]
	v_mfma_f32_16x16x32_bf16 v[18:21], v[192:195], v[234:237], v[18:21]
	v_mfma_f32_16x16x32_bf16 v[2:5], v[192:195], v[238:241], v[2:5]
	s_setprio 0
	s_setprio 1
	v_mfma_f32_16x16x32_bf16 v[26:29], v[162:165], v[172:175], v[26:29]
	v_mfma_f32_16x16x32_bf16 v[58:61], v[222:225], v[180:183], v[26:29]
	v_mfma_f32_16x16x32_bf16 v[26:29], v[136:139], v[176:179], v[150:153]
	v_mfma_f32_16x16x32_bf16 v[46:49], v[218:221], v[184:187], v[26:29]
	v_mfma_f32_16x16x32_bf16 v[26:29], v[162:165], v[176:179], v[168:171]
	v_mfma_f32_16x16x32_bf16 v[10:13], v[162:165], v[196:199], v[10:13]
	v_mfma_f32_16x16x32_bf16 v[30:33], v[136:139], v[172:175], v[30:33]
	v_mfma_f32_16x16x32_bf16 v[42:45], v[222:225], v[184:187], v[26:29]
	v_mfma_f32_16x16x32_bf16 v[14:17], v[136:139], v[196:199], v[14:17]
	v_mfma_f32_16x16x32_bf16 v[26:29], v[222:225], v[234:237], v[10:13]
	v_mfma_f32_16x16x32_bf16 v[10:13], v[136:139], v[200:203], v[188:191]
	v_mfma_f32_16x16x32_bf16 v[62:65], v[218:221], v[180:183], v[30:33]
	v_mfma_f32_16x16x32_bf16 v[30:33], v[218:221], v[234:237], v[14:17]
	v_mfma_f32_16x16x32_bf16 v[14:17], v[218:221], v[238:241], v[10:13]
	v_mfma_f32_16x16x32_bf16 v[10:13], v[162:165], v[200:203], v[154:157]
	v_mfma_f32_16x16x32_bf16 v[10:13], v[222:225], v[238:241], v[10:13]
	s_setprio 0
	s_cmpk_gt_u32 s0, 0xff
	s_barrier
	s_cbranch_scc1 .LBB0_352
	s_barrier

.LBB0_357:
	v_or_b32_e32 v0, 0x10000, v150
	v_add_u32_e32 v153, 0x10800, v150
	v_or_b32_e32 v152, 0x10000, v151
	ds_read_b128 v[160:163], v0
	ds_read_b128 v[164:167], v152
	v_add_u32_e32 v154, 0x10800, v151
	ds_read_b128 v[168:171], v153
	ds_read_b128 v[172:175], v154
	v_lshl_add_u64 v[206:207], v[134:135], 0, v[142:143]
	s_add_i32 s12, s1, 0xc000
	v_lshl_add_u64 v[156:157], v[206:207], 0, s[50:51]
	s_mov_b32 m0, s12
	v_lshl_add_u64 v[208:209], v[134:135], 0, v[140:141]
	s_add_i32 s5, s1, 0xe000
	ds_read_b128 v[176:179], v148
	ds_read_b128 v[180:183], v148 offset:2048
	ds_read_b128 v[184:187], v149
	ds_read_b128 v[188:191], v149 offset:2048
	ds_read_b128 v[192:195], v148 offset:4096
	ds_read_b128 v[196:199], v148 offset:6144
	ds_read_b128 v[200:203], v149 offset:4096
	ds_read_b128 v[218:221], v149 offset:6144
	global_load_lds_dwordx4 v[156:157], off
	v_lshl_add_u64 v[156:157], v[208:209], 0, s[50:51]
	s_mov_b32 m0, s5
	s_nop 0
	global_load_lds_dwordx4 v[156:157], off
	s_waitcnt lgkmcnt(8)
	s_waitcnt vmcnt(10)
	s_barrier
	s_waitcnt lgkmcnt(0)
	s_setprio 1
	s_waitcnt lgkmcnt(0)
	v_mfma_f32_16x16x32_bf16 v[126:129], v[160:163], v[176:179], v[126:129]
	v_mfma_f32_16x16x32_bf16 v[122:125], v[168:171], v[176:179], v[122:125]
	v_mfma_f32_16x16x32_bf16 v[118:121], v[160:163], v[180:183], v[118:121]
	v_mfma_f32_16x16x32_bf16 v[114:117], v[168:171], v[180:183], v[114:117]
	v_mfma_f32_16x16x32_bf16 v[110:113], v[160:163], v[192:195], v[110:113]
	v_mfma_f32_16x16x32_bf16 v[106:109], v[168:171], v[192:195], v[106:109]
	v_mfma_f32_16x16x32_bf16 v[102:105], v[160:163], v[196:199], v[102:105]
	v_mfma_f32_16x16x32_bf16 v[98:101], v[168:171], v[196:199], v[98:101]
	v_mfma_f32_16x16x32_bf16 v[126:129], v[164:167], v[184:187], v[126:129]
	v_mfma_f32_16x16x32_bf16 v[122:125], v[172:175], v[184:187], v[122:125]
	v_mfma_f32_16x16x32_bf16 v[118:121], v[164:167], v[188:191], v[118:121]
	v_mfma_f32_16x16x32_bf16 v[114:117], v[172:175], v[188:191], v[114:117]
	v_mfma_f32_16x16x32_bf16 v[110:113], v[164:167], v[200:203], v[110:113]
	v_mfma_f32_16x16x32_bf16 v[106:109], v[172:175], v[200:203], v[106:109]
	v_mfma_f32_16x16x32_bf16 v[102:105], v[164:167], v[218:221], v[102:105]
	v_mfma_f32_16x16x32_bf16 v[98:101], v[172:175], v[218:221], v[98:101]
	s_setprio 0
	s_barrier
	v_lshl_add_u64 v[210:211], v[134:135], 0, v[146:147]
	s_mov_b32 m0, s2
	v_or_b32_e32 v155, 0x14000, v150
	v_add_u32_e32 v157, 0x14800, v150
	v_lshl_add_u64 v[214:215], v[210:211], 0, s[70:71]
	v_or_b32_e32 v156, 0x14000, v151
	ds_read_b128 v[222:225], v155
	ds_read_b128 v[226:229], v156
	v_add_u32_e32 v158, 0x14800, v151
	ds_read_b128 v[230:233], v157
	ds_read_b128 v[234:237], v158
	global_load_lds_dwordx4 v[214:215], off
	v_lshl_add_u64 v[214:215], v[134:135], 0, v[144:145]
	v_lshl_add_u64 v[238:239], v[214:215], 0, s[70:71]
	s_mov_b32 m0, s3
	s_nop 0
	global_load_lds_dwordx4 v[238:239], off
	s_waitcnt vmcnt(10)
	s_waitcnt lgkmcnt(0)
	s_barrier
	s_waitcnt lgkmcnt(0)
	s_setprio 1
	s_waitcnt lgkmcnt(0)
	v_mfma_f32_16x16x32_bf16 v[94:97], v[222:225], v[176:179], v[94:97]
	v_mfma_f32_16x16x32_bf16 v[90:93], v[230:233], v[176:179], v[90:93]
	v_mfma_f32_16x16x32_bf16 v[86:89], v[222:225], v[180:183], v[86:89]
	v_mfma_f32_16x16x32_bf16 v[82:85], v[230:233], v[180:183], v[82:85]
	v_mfma_f32_16x16x32_bf16 v[78:81], v[222:225], v[192:195], v[78:81]
	v_mfma_f32_16x16x32_bf16 v[74:77], v[230:233], v[192:195], v[74:77]
	v_mfma_f32_16x16x32_bf16 v[70:73], v[222:225], v[196:199], v[70:73]
	v_mfma_f32_16x16x32_bf16 v[66:69], v[230:233], v[196:199], v[66:69]
	v_mfma_f32_16x16x32_bf16 v[94:97], v[226:229], v[184:187], v[94:97]
	v_mfma_f32_16x16x32_bf16 v[90:93], v[234:237], v[184:187], v[90:93]
	v_mfma_f32_16x16x32_bf16 v[86:89], v[226:229], v[188:191], v[86:89]
	v_mfma_f32_16x16x32_bf16 v[82:85], v[234:237], v[188:191], v[82:85]
	v_mfma_f32_16x16x32_bf16 v[78:81], v[226:229], v[200:203], v[78:81]
	v_mfma_f32_16x16x32_bf16 v[74:77], v[234:237], v[200:203], v[74:77]
	v_mfma_f32_16x16x32_bf16 v[70:73], v[226:229], v[218:221], v[70:73]
	v_mfma_f32_16x16x32_bf16 v[66:69], v[234:237], v[218:221], v[66:69]
	s_setprio 0
	s_mov_b32 m0, s1
	v_lshl_add_u64 v[238:239], v[206:207], 0, s[54:55]
	s_barrier
	ds_read_b128 v[176:179], v148 offset:16384
	ds_read_b128 v[180:183], v148 offset:18432
	ds_read_b128 v[184:187], v149 offset:16384
	ds_read_b128 v[188:191], v149 offset:18432
	ds_read_b128 v[192:195], v148 offset:20480
	ds_read_b128 v[196:199], v148 offset:22528
	ds_read_b128 v[200:203], v149 offset:20480
	ds_read_b128 v[218:221], v149 offset:22528
	global_load_lds_dwordx4 v[238:239], off
	v_lshl_add_u64 v[238:239], v[208:209], 0, s[54:55]
	s_mov_b32 m0, s11
	s_nop 0
	global_load_lds_dwordx4 v[238:239], off
	v_lshl_add_u64 v[238:239], v[210:211], 0, s[26:27]
	s_mov_b32 m0, s15
	s_nop 0
	global_load_lds_dwordx4 v[238:239], off
	v_lshl_add_u64 v[238:239], v[214:215], 0, s[26:27]
	s_mov_b32 m0, s16
	s_nop 0
	global_load_lds_dwordx4 v[238:239], off
	s_waitcnt vmcnt(10)
	s_waitcnt lgkmcnt(0)
	s_barrier
	s_waitcnt lgkmcnt(0)
	s_setprio 1
	s_waitcnt lgkmcnt(0)
	v_mfma_f32_16x16x32_bf16 v[62:65], v[160:163], v[176:179], v[62:65]
	v_mfma_f32_16x16x32_bf16 v[58:61], v[168:171], v[176:179], v[58:61]
	v_mfma_f32_16x16x32_bf16 v[54:57], v[160:163], v[180:183], v[54:57]
	v_mfma_f32_16x16x32_bf16 v[50:53], v[168:171], v[180:183], v[50:53]
	v_mfma_f32_16x16x32_bf16 v[46:49], v[160:163], v[192:195], v[46:49]
	v_mfma_f32_16x16x32_bf16 v[42:45], v[168:171], v[192:195], v[42:45]
	v_mfma_f32_16x16x32_bf16 v[38:41], v[160:163], v[196:199], v[38:41]
	v_mfma_f32_16x16x32_bf16 v[34:37], v[168:171], v[196:199], v[34:37]
	v_mfma_f32_16x16x32_bf16 v[62:65], v[164:167], v[184:187], v[62:65]
	v_mfma_f32_16x16x32_bf16 v[58:61], v[172:175], v[184:187], v[58:61]
	v_mfma_f32_16x16x32_bf16 v[54:57], v[164:167], v[188:191], v[54:57]
	v_mfma_f32_16x16x32_bf16 v[50:53], v[172:175], v[188:191], v[50:53]
	v_mfma_f32_16x16x32_bf16 v[46:49], v[164:167], v[200:203], v[46:49]
	v_mfma_f32_16x16x32_bf16 v[42:45], v[172:175], v[200:203], v[42:45]
	v_mfma_f32_16x16x32_bf16 v[38:41], v[164:167], v[218:221], v[38:41]
	v_mfma_f32_16x16x32_bf16 v[34:37], v[172:175], v[218:221], v[34:37]
	v_mfma_f32_16x16x32_bf16 v[30:33], v[222:225], v[176:179], v[30:33]
	v_mfma_f32_16x16x32_bf16 v[26:29], v[230:233], v[176:179], v[26:29]
	v_mfma_f32_16x16x32_bf16 v[22:25], v[222:225], v[180:183], v[22:25]
	v_mfma_f32_16x16x32_bf16 v[18:21], v[230:233], v[180:183], v[18:21]
	v_mfma_f32_16x16x32_bf16 v[14:17], v[222:225], v[192:195], v[14:17]
	v_mfma_f32_16x16x32_bf16 v[10:13], v[230:233], v[192:195], v[10:13]
	v_mfma_f32_16x16x32_bf16 v[6:9], v[222:225], v[196:199], v[6:9]
	v_mfma_f32_16x16x32_bf16 v[2:5], v[230:233], v[196:199], v[2:5]
	v_mfma_f32_16x16x32_bf16 v[30:33], v[226:229], v[184:187], v[30:33]
	v_mfma_f32_16x16x32_bf16 v[26:29], v[234:237], v[184:187], v[26:29]
	v_mfma_f32_16x16x32_bf16 v[22:25], v[226:229], v[188:191], v[22:25]
	v_mfma_f32_16x16x32_bf16 v[18:21], v[234:237], v[188:191], v[18:21]
	v_mfma_f32_16x16x32_bf16 v[14:17], v[226:229], v[200:203], v[14:17]
	v_mfma_f32_16x16x32_bf16 v[10:13], v[234:237], v[200:203], v[10:13]
	v_mfma_f32_16x16x32_bf16 v[6:9], v[226:229], v[218:221], v[6:9]
	v_mfma_f32_16x16x32_bf16 v[2:5], v[234:237], v[218:221], v[2:5]
	s_setprio 0
	v_or_b32_e32 v159, 0x18000, v150
	v_add_u32_e32 v161, 0x18800, v150
	s_barrier
	v_or_b32_e32 v160, 0x18000, v151
	ds_read_b128 v[168:171], v159
	ds_read_b128 v[172:175], v160
	v_add_u32_e32 v162, 0x18800, v151
	ds_read_b128 v[176:179], v161
	ds_read_b128 v[180:183], v162
	s_mov_b32 m0, s17
	v_lshl_add_u64 v[164:165], v[206:207], 0, s[58:59]
	ds_read_b128 v[184:187], v148 offset:32768
	ds_read_b128 v[188:191], v148 offset:34816
	ds_read_b128 v[192:195], v149 offset:32768
	ds_read_b128 v[196:199], v149 offset:34816
	ds_read_b128 v[200:203], v148 offset:36864
	ds_read_b128 v[218:221], v148 offset:38912
	ds_read_b128 v[222:225], v149 offset:36864
	ds_read_b128 v[226:229], v149 offset:38912
	global_load_lds_dwordx4 v[164:165], off
	v_lshl_add_u64 v[164:165], v[208:209], 0, s[58:59]
	s_mov_b32 m0, s18
	s_nop 0
	global_load_lds_dwordx4 v[164:165], off
	s_waitcnt lgkmcnt(8)
	s_waitcnt vmcnt(10)
	s_barrier
	s_waitcnt lgkmcnt(0)
	s_setprio 1
	s_waitcnt lgkmcnt(0)
	v_mfma_f32_16x16x32_bf16 v[126:129], v[168:171], v[184:187], v[126:129]
	v_mfma_f32_16x16x32_bf16 v[122:125], v[176:179], v[184:187], v[122:125]
	v_mfma_f32_16x16x32_bf16 v[118:121], v[168:171], v[188:191], v[118:121]
	v_mfma_f32_16x16x32_bf16 v[114:117], v[176:179], v[188:191], v[114:117]
	v_mfma_f32_16x16x32_bf16 v[110:113], v[168:171], v[200:203], v[110:113]
	v_mfma_f32_16x16x32_bf16 v[106:109], v[176:179], v[200:203], v[106:109]
	v_mfma_f32_16x16x32_bf16 v[102:105], v[168:171], v[218:221], v[102:105]
	v_mfma_f32_16x16x32_bf16 v[98:101], v[176:179], v[218:221], v[98:101]
	v_mfma_f32_16x16x32_bf16 v[126:129], v[172:175], v[192:195], v[126:129]
	v_mfma_f32_16x16x32_bf16 v[122:125], v[180:183], v[192:195], v[122:125]
	v_mfma_f32_16x16x32_bf16 v[118:121], v[172:175], v[196:199], v[118:121]
	v_mfma_f32_16x16x32_bf16 v[114:117], v[180:183], v[196:199], v[114:117]
	v_mfma_f32_16x16x32_bf16 v[110:113], v[172:175], v[222:225], v[110:113]
	v_mfma_f32_16x16x32_bf16 v[106:109], v[180:183], v[222:225], v[106:109]
	v_mfma_f32_16x16x32_bf16 v[102:105], v[172:175], v[226:229], v[102:105]
	v_mfma_f32_16x16x32_bf16 v[98:101], v[180:183], v[226:229], v[98:101]
	s_setprio 0
	s_barrier
	s_mov_b32 m0, s19
	v_or_b32_e32 v163, 0x1c000, v150
	v_add_u32_e32 v165, 0x1c800, v150
	v_lshl_add_u64 v[246:247], v[210:211], 0, s[28:29]
	v_or_b32_e32 v164, 0x1c000, v151
	ds_read_b128 v[230:233], v163
	ds_read_b128 v[234:237], v164
	v_add_u32_e32 v166, 0x1c800, v151
	ds_read_b128 v[238:241], v165
	ds_read_b128 v[242:245], v166
	global_load_lds_dwordx4 v[246:247], off
	v_lshl_add_u64 v[246:247], v[214:215], 0, s[28:29]
	s_mov_b32 m0, s20
	s_nop 0
	global_load_lds_dwordx4 v[246:247], off
	s_waitcnt vmcnt(10)
	s_waitcnt lgkmcnt(0)
	s_barrier
	s_waitcnt lgkmcnt(0)
	s_setprio 1
	s_waitcnt lgkmcnt(0)
	v_mfma_f32_16x16x32_bf16 v[94:97], v[230:233], v[184:187], v[94:97]
	v_mfma_f32_16x16x32_bf16 v[90:93], v[238:241], v[184:187], v[90:93]
	v_mfma_f32_16x16x32_bf16 v[86:89], v[230:233], v[188:191], v[86:89]
	v_mfma_f32_16x16x32_bf16 v[82:85], v[238:241], v[188:191], v[82:85]
	v_mfma_f32_16x16x32_bf16 v[78:81], v[230:233], v[200:203], v[78:81]
	v_mfma_f32_16x16x32_bf16 v[74:77], v[238:241], v[200:203], v[74:77]
	v_mfma_f32_16x16x32_bf16 v[70:73], v[230:233], v[218:221], v[70:73]
	v_mfma_f32_16x16x32_bf16 v[66:69], v[238:241], v[218:221], v[66:69]
	v_mfma_f32_16x16x32_bf16 v[94:97], v[234:237], v[192:195], v[94:97]
	v_mfma_f32_16x16x32_bf16 v[90:93], v[242:245], v[192:195], v[90:93]
	v_mfma_f32_16x16x32_bf16 v[86:89], v[234:237], v[196:199], v[86:89]
	v_mfma_f32_16x16x32_bf16 v[82:85], v[242:245], v[196:199], v[82:85]
	v_mfma_f32_16x16x32_bf16 v[78:81], v[234:237], v[222:225], v[78:81]
	v_mfma_f32_16x16x32_bf16 v[74:77], v[242:245], v[222:225], v[74:77]
	v_mfma_f32_16x16x32_bf16 v[70:73], v[234:237], v[226:229], v[70:73]
	v_mfma_f32_16x16x32_bf16 v[66:69], v[242:245], v[226:229], v[66:69]
	s_setprio 0
	s_mov_b32 m0, s21
	v_lshl_add_u64 v[206:207], v[206:207], 0, s[62:63]
	s_barrier
	ds_read_b128 v[184:187], v148 offset:49152
	ds_read_b128 v[188:191], v148 offset:51200
	ds_read_b128 v[192:195], v149 offset:49152
	ds_read_b128 v[196:199], v149 offset:51200
	ds_read_b128 v[200:203], v148 offset:53248
	ds_read_b128 v[218:221], v148 offset:55296
	ds_read_b128 v[222:225], v149 offset:53248
	ds_read_b128 v[226:229], v149 offset:55296
	global_load_lds_dwordx4 v[206:207], off
	v_lshl_add_u64 v[206:207], v[208:209], 0, s[62:63]
	s_mov_b32 m0, s22
	s_nop 0
	global_load_lds_dwordx4 v[206:207], off
	v_lshl_add_u64 v[206:207], v[210:211], 0, s[30:31]
	s_mov_b32 m0, s23
	s_nop 0
	global_load_lds_dwordx4 v[206:207], off
	v_lshl_add_u64 v[206:207], v[214:215], 0, s[30:31]
	s_mov_b32 m0, s24
	s_nop 0
	global_load_lds_dwordx4 v[206:207], off
	s_waitcnt vmcnt(10)
	s_waitcnt lgkmcnt(0)
	s_barrier
	s_waitcnt lgkmcnt(0)
	s_setprio 1
	s_waitcnt lgkmcnt(0)
	v_mfma_f32_16x16x32_bf16 v[62:65], v[168:171], v[184:187], v[62:65]
	v_mfma_f32_16x16x32_bf16 v[58:61], v[176:179], v[184:187], v[58:61]
	v_mfma_f32_16x16x32_bf16 v[54:57], v[168:171], v[188:191], v[54:57]
	v_mfma_f32_16x16x32_bf16 v[50:53], v[176:179], v[188:191], v[50:53]
	v_mfma_f32_16x16x32_bf16 v[46:49], v[168:171], v[200:203], v[46:49]
	v_mfma_f32_16x16x32_bf16 v[42:45], v[176:179], v[200:203], v[42:45]
	v_mfma_f32_16x16x32_bf16 v[38:41], v[168:171], v[218:221], v[38:41]
	v_mfma_f32_16x16x32_bf16 v[34:37], v[176:179], v[218:221], v[34:37]
	v_mfma_f32_16x16x32_bf16 v[62:65], v[172:175], v[192:195], v[62:65]
	v_mfma_f32_16x16x32_bf16 v[58:61], v[180:183], v[192:195], v[58:61]
	v_mfma_f32_16x16x32_bf16 v[54:57], v[172:175], v[196:199], v[54:57]
	v_mfma_f32_16x16x32_bf16 v[50:53], v[180:183], v[196:199], v[50:53]
	v_mfma_f32_16x16x32_bf16 v[46:49], v[172:175], v[222:225], v[46:49]
	v_mfma_f32_16x16x32_bf16 v[42:45], v[180:183], v[222:225], v[42:45]
	v_mfma_f32_16x16x32_bf16 v[38:41], v[172:175], v[226:229], v[38:41]
	v_mfma_f32_16x16x32_bf16 v[34:37], v[180:183], v[226:229], v[34:37]
	v_mfma_f32_16x16x32_bf16 v[30:33], v[230:233], v[184:187], v[30:33]
	v_mfma_f32_16x16x32_bf16 v[26:29], v[238:241], v[184:187], v[26:29]
	v_mfma_f32_16x16x32_bf16 v[22:25], v[230:233], v[188:191], v[22:25]
	v_mfma_f32_16x16x32_bf16 v[18:21], v[238:241], v[188:191], v[18:21]
	v_mfma_f32_16x16x32_bf16 v[14:17], v[230:233], v[200:203], v[14:17]
	v_mfma_f32_16x16x32_bf16 v[10:13], v[238:241], v[200:203], v[10:13]
	v_mfma_f32_16x16x32_bf16 v[6:9], v[230:233], v[218:221], v[6:9]
	v_mfma_f32_16x16x32_bf16 v[2:5], v[238:241], v[218:221], v[2:5]
	v_mfma_f32_16x16x32_bf16 v[30:33], v[234:237], v[192:195], v[30:33]
	v_mfma_f32_16x16x32_bf16 v[26:29], v[242:245], v[192:195], v[26:29]
	v_mfma_f32_16x16x32_bf16 v[22:25], v[234:237], v[196:199], v[22:25]
	v_mfma_f32_16x16x32_bf16 v[18:21], v[242:245], v[196:199], v[18:21]
	v_mfma_f32_16x16x32_bf16 v[14:17], v[234:237], v[222:225], v[14:17]
	v_mfma_f32_16x16x32_bf16 v[10:13], v[242:245], v[222:225], v[10:13]
	v_mfma_f32_16x16x32_bf16 v[6:9], v[234:237], v[226:229], v[6:9]
	v_mfma_f32_16x16x32_bf16 v[2:5], v[242:245], v[226:229], v[2:5]
	s_setprio 0
	s_add_i32 s4, s4, 2
	s_cmp_lt_u32 s4, 28
	v_lshl_add_u64 v[134:135], v[134:135], 0, s[54:55]
	s_barrier
	s_cbranch_scc1 .LBB0_357
	s_waitcnt vmcnt(6)
	s_mov_b64 s[2:3], 0xf80
	s_mov_b32 m0, s12
	v_lshl_add_u64 v[134:135], v[138:139], 0, s[2:3]
	ds_read_b128 v[140:143], v0
	ds_read_b128 v[144:147], v152
	ds_read_b128 v[150:153], v153
	ds_read_b128 v[168:171], v154
	ds_read_b128 v[172:175], v148
	ds_read_b128 v[176:179], v148 offset:2048
	ds_read_b128 v[180:183], v149
	ds_read_b128 v[184:187], v149 offset:2048
	ds_read_b128 v[188:191], v148 offset:4096
	ds_read_b128 v[192:195], v148 offset:6144
	ds_read_b128 v[196:199], v149 offset:4096
	ds_read_b128 v[200:203], v149 offset:6144
	global_load_lds_dwordx4 v[134:135], off
	v_lshl_add_u64 v[134:135], v[136:137], 0, s[2:3]
	s_mov_b32 m0, s5
	s_nop 0
	global_load_lds_dwordx4 v[134:135], off
	s_barrier
	s_waitcnt lgkmcnt(0)
	s_setprio 1
	s_waitcnt lgkmcnt(0)
	v_mfma_f32_16x16x32_bf16 v[126:129], v[140:143], v[172:175], v[126:129]
	v_mfma_f32_16x16x32_bf16 v[122:125], v[150:153], v[172:175], v[122:125]
	v_mfma_f32_16x16x32_bf16 v[118:121], v[140:143], v[176:179], v[118:121]
	v_mfma_f32_16x16x32_bf16 v[110:113], v[140:143], v[188:191], v[110:113]
	v_mfma_f32_16x16x32_bf16 v[106:109], v[150:153], v[188:191], v[106:109]
	v_mfma_f32_16x16x32_bf16 v[126:129], v[144:147], v[180:183], v[126:129]
	v_mfma_f32_16x16x32_bf16 v[122:125], v[168:171], v[180:183], v[122:125]
	v_mfma_f32_16x16x32_bf16 v[118:121], v[144:147], v[184:187], v[118:121]
	v_mfma_f32_16x16x32_bf16 v[114:117], v[150:153], v[176:179], v[114:117]
	v_mfma_f32_16x16x32_bf16 v[110:113], v[144:147], v[196:199], v[110:113]
	v_mfma_f32_16x16x32_bf16 v[106:109], v[168:171], v[196:199], v[106:109]
	v_mfma_f32_16x16x32_bf16 v[102:105], v[140:143], v[192:195], v[102:105]
	v_mfma_f32_16x16x32_bf16 v[98:101], v[150:153], v[192:195], v[98:101]
	v_mfma_f32_16x16x32_bf16 v[134:137], v[168:171], v[184:187], v[114:117]
	v_mfma_f32_16x16x32_bf16 v[218:221], v[144:147], v[200:203], v[102:105]
	v_mfma_f32_16x16x32_bf16 v[222:225], v[168:171], v[200:203], v[98:101]
	s_setprio 0
	s_barrier
	s_nop 2
	ds_read_b128 v[98:101], v155
	ds_read_b128 v[102:105], v156
	ds_read_b128 v[114:117], v157
	ds_read_b128 v[154:157], v158
	s_barrier
	s_waitcnt lgkmcnt(0)
	s_setprio 1
	s_waitcnt lgkmcnt(0)
	v_mfma_f32_16x16x32_bf16 v[94:97], v[98:101], v[172:175], v[94:97]
	v_mfma_f32_16x16x32_bf16 v[90:93], v[114:117], v[172:175], v[90:93]
	v_mfma_f32_16x16x32_bf16 v[78:81], v[98:101], v[188:191], v[78:81]
	v_mfma_f32_16x16x32_bf16 v[74:77], v[114:117], v[188:191], v[74:77]
	v_mfma_f32_16x16x32_bf16 v[94:97], v[102:105], v[180:183], v[94:97]
	v_mfma_f32_16x16x32_bf16 v[90:93], v[154:157], v[180:183], v[90:93]
	v_mfma_f32_16x16x32_bf16 v[86:89], v[98:101], v[176:179], v[86:89]
	v_mfma_f32_16x16x32_bf16 v[82:85], v[114:117], v[176:179], v[82:85]
	v_mfma_f32_16x16x32_bf16 v[78:81], v[102:105], v[196:199], v[78:81]
	v_mfma_f32_16x16x32_bf16 v[74:77], v[154:157], v[196:199], v[74:77]
	v_mfma_f32_16x16x32_bf16 v[70:73], v[98:101], v[192:195], v[70:73]
	v_mfma_f32_16x16x32_bf16 v[66:69], v[114:117], v[192:195], v[66:69]
	v_mfma_f32_16x16x32_bf16 v[172:175], v[102:105], v[184:187], v[86:89]
	v_mfma_f32_16x16x32_bf16 v[176:179], v[154:157], v[184:187], v[82:85]
	v_mfma_f32_16x16x32_bf16 v[180:183], v[102:105], v[200:203], v[70:73]
	v_mfma_f32_16x16x32_bf16 v[184:187], v[154:157], v[200:203], v[66:69]
	s_setprio 0
	s_barrier
	s_nop 1
	ds_read_b128 v[66:69], v148 offset:16384
	ds_read_b128 v[70:73], v148 offset:18432
	ds_read_b128 v[82:85], v149 offset:16384
	ds_read_b128 v[86:89], v149 offset:18432
	ds_read_b128 v[188:191], v148 offset:20480
	ds_read_b128 v[192:195], v148 offset:22528
	ds_read_b128 v[196:199], v149 offset:20480
	ds_read_b128 v[200:203], v149 offset:22528
	s_waitcnt vmcnt(4)
	s_barrier
	s_waitcnt lgkmcnt(0)
	s_setprio 1
	s_waitcnt lgkmcnt(0)
	v_mfma_f32_16x16x32_bf16 v[62:65], v[140:143], v[66:69], v[62:65]
	v_mfma_f32_16x16x32_bf16 v[58:61], v[150:153], v[66:69], v[58:61]
	v_mfma_f32_16x16x32_bf16 v[46:49], v[140:143], v[188:191], v[46:49]
	v_mfma_f32_16x16x32_bf16 v[42:45], v[150:153], v[188:191], v[42:45]
	v_mfma_f32_16x16x32_bf16 v[62:65], v[144:147], v[82:85], v[62:65]
	v_mfma_f32_16x16x32_bf16 v[58:61], v[168:171], v[82:85], v[58:61]
	v_mfma_f32_16x16x32_bf16 v[54:57], v[140:143], v[70:73], v[54:57]
	v_mfma_f32_16x16x32_bf16 v[50:53], v[150:153], v[70:73], v[50:53]
	v_mfma_f32_16x16x32_bf16 v[46:49], v[144:147], v[196:199], v[46:49]
	v_mfma_f32_16x16x32_bf16 v[42:45], v[168:171], v[196:199], v[42:45]
	v_mfma_f32_16x16x32_bf16 v[38:41], v[140:143], v[192:195], v[38:41]
	v_mfma_f32_16x16x32_bf16 v[34:37], v[150:153], v[192:195], v[34:37]
	v_mfma_f32_16x16x32_bf16 v[226:229], v[144:147], v[86:89], v[54:57]
	v_mfma_f32_16x16x32_bf16 v[230:233], v[168:171], v[86:89], v[50:53]
	v_mfma_f32_16x16x32_bf16 v[138:141], v[144:147], v[200:203], v[38:41]
	v_mfma_f32_16x16x32_bf16 v[142:145], v[168:171], v[200:203], v[34:37]
	s_setprio 0
	s_setprio 1
	v_mfma_f32_16x16x32_bf16 v[30:33], v[98:101], v[66:69], v[30:33]
	v_mfma_f32_16x16x32_bf16 v[26:29], v[114:117], v[66:69], v[26:29]
	v_mfma_f32_16x16x32_bf16 v[14:17], v[98:101], v[188:191], v[14:17]
	v_mfma_f32_16x16x32_bf16 v[10:13], v[114:117], v[188:191], v[10:13]
	v_mfma_f32_16x16x32_bf16 v[30:33], v[102:105], v[82:85], v[30:33]
	v_mfma_f32_16x16x32_bf16 v[26:29], v[154:157], v[82:85], v[26:29]
	v_mfma_f32_16x16x32_bf16 v[22:25], v[98:101], v[70:73], v[22:25]
	v_mfma_f32_16x16x32_bf16 v[18:21], v[114:117], v[70:73], v[18:21]
	v_mfma_f32_16x16x32_bf16 v[14:17], v[102:105], v[196:199], v[14:17]
	v_mfma_f32_16x16x32_bf16 v[10:13], v[154:157], v[196:199], v[10:13]
	v_mfma_f32_16x16x32_bf16 v[6:9], v[98:101], v[192:195], v[6:9]
	v_mfma_f32_16x16x32_bf16 v[2:5], v[114:117], v[192:195], v[2:5]
	v_mfma_f32_16x16x32_bf16 v[150:153], v[102:105], v[86:89], v[22:25]
	v_mfma_f32_16x16x32_bf16 v[168:171], v[154:157], v[86:89], v[18:21]
	v_mfma_f32_16x16x32_bf16 v[188:191], v[102:105], v[200:203], v[6:9]
	v_mfma_f32_16x16x32_bf16 v[154:157], v[154:157], v[200:203], v[2:5]
	s_setprio 0
	s_barrier
	s_nop 1
	ds_read_b128 v[2:5], v159
	ds_read_b128 v[6:9], v160
	ds_read_b128 v[158:161], v161
	ds_read_b128 v[192:195], v162
	ds_read_b128 v[18:21], v148 offset:32768
	ds_read_b128 v[22:25], v148 offset:34816
	ds_read_b128 v[34:37], v149 offset:32768
	ds_read_b128 v[38:41], v149 offset:34816
	ds_read_b128 v[50:53], v148 offset:36864
	ds_read_b128 v[54:57], v148 offset:38912
	ds_read_b128 v[196:199], v149 offset:36864
	ds_read_b128 v[200:203], v149 offset:38912
	s_waitcnt vmcnt(2)
	s_barrier
	s_waitcnt lgkmcnt(0)
	s_setprio 1
	s_waitcnt lgkmcnt(0)
	v_mfma_f32_16x16x32_bf16 v[66:69], v[2:5], v[18:21], v[126:129]
	v_mfma_f32_16x16x32_bf16 v[126:129], v[6:9], v[34:37], v[66:69]
	v_mfma_f32_16x16x32_bf16 v[66:69], v[158:161], v[18:21], v[122:125]
	v_mfma_f32_16x16x32_bf16 v[114:117], v[192:195], v[34:37], v[66:69]
	v_mfma_f32_16x16x32_bf16 v[66:69], v[2:5], v[22:25], v[118:121]
	v_mfma_f32_16x16x32_bf16 v[102:105], v[6:9], v[38:41], v[66:69]
	v_mfma_f32_16x16x32_bf16 v[66:69], v[158:161], v[22:25], v[134:137]
	v_mfma_f32_16x16x32_bf16 v[98:101], v[192:195], v[38:41], v[66:69]
	v_mfma_f32_16x16x32_bf16 v[66:69], v[2:5], v[50:53], v[110:113]
	v_mfma_f32_16x16x32_bf16 v[86:89], v[6:9], v[196:199], v[66:69]
	v_mfma_f32_16x16x32_bf16 v[66:69], v[158:161], v[50:53], v[106:109]
	v_mfma_f32_16x16x32_bf16 v[82:85], v[192:195], v[196:199], v[66:69]
	v_mfma_f32_16x16x32_bf16 v[66:69], v[2:5], v[54:57], v[218:221]
	v_mfma_f32_16x16x32_bf16 v[70:73], v[6:9], v[200:203], v[66:69]
	v_mfma_f32_16x16x32_bf16 v[66:69], v[158:161], v[54:57], v[222:225]
	v_mfma_f32_16x16x32_bf16 v[66:69], v[192:195], v[200:203], v[66:69]
	s_setprio 0
	s_barrier
	ds_read_b128 v[134:137], v163
	ds_read_b128 v[218:221], v164
	ds_read_b128 v[162:165], v165
	ds_read_b128 v[222:225], v166
	s_waitcnt vmcnt(0)
	s_barrier
	s_waitcnt lgkmcnt(0)
	s_setprio 1
	s_waitcnt lgkmcnt(0)
	v_mfma_f32_16x16x32_bf16 v[94:97], v[134:137], v[18:21], v[94:97]
	v_mfma_f32_16x16x32_bf16 v[18:21], v[162:165], v[18:21], v[90:93]
	v_mfma_f32_16x16x32_bf16 v[118:121], v[222:225], v[34:37], v[18:21]
	v_mfma_f32_16x16x32_bf16 v[18:21], v[134:137], v[22:25], v[172:175]
	v_mfma_f32_16x16x32_bf16 v[110:113], v[218:221], v[38:41], v[18:21]
	v_mfma_f32_16x16x32_bf16 v[18:21], v[162:165], v[22:25], v[176:179]
	v_mfma_f32_16x16x32_bf16 v[106:109], v[222:225], v[38:41], v[18:21]
	v_mfma_f32_16x16x32_bf16 v[18:21], v[134:137], v[50:53], v[78:81]
	v_mfma_f32_16x16x32_bf16 v[122:125], v[218:221], v[34:37], v[94:97]
	v_mfma_f32_16x16x32_bf16 v[94:97], v[218:221], v[196:199], v[18:21]
	v_mfma_f32_16x16x32_bf16 v[18:21], v[162:165], v[50:53], v[74:77]
	v_mfma_f32_16x16x32_bf16 v[90:93], v[222:225], v[196:199], v[18:21]
	v_mfma_f32_16x16x32_bf16 v[18:21], v[134:137], v[54:57], v[180:183]
	v_mfma_f32_16x16x32_bf16 v[78:81], v[218:221], v[200:203], v[18:21]
	v_mfma_f32_16x16x32_bf16 v[18:21], v[162:165], v[54:57], v[184:187]
	v_mfma_f32_16x16x32_bf16 v[74:77], v[222:225], v[200:203], v[18:21]
	s_setprio 0
	s_barrier
	ds_read_b128 v[172:175], v148 offset:49152
	ds_read_b128 v[176:179], v148 offset:51200
	ds_read_b128 v[180:183], v149 offset:49152
	ds_read_b128 v[184:187], v149 offset:51200
	ds_read_b128 v[196:199], v148 offset:53248
	ds_read_b128 v[200:203], v148 offset:55296
	ds_read_b128 v[234:237], v149 offset:53248
	ds_read_b128 v[146:149], v149 offset:55296
	s_barrier
	s_waitcnt lgkmcnt(0)
	s_setprio 1
	s_waitcnt lgkmcnt(0)
	v_mfma_f32_16x16x32_bf16 v[18:21], v[2:5], v[172:175], v[62:65]
	v_mfma_f32_16x16x32_bf16 v[54:57], v[6:9], v[180:183], v[18:21]
	v_mfma_f32_16x16x32_bf16 v[18:21], v[158:161], v[172:175], v[58:61]
	v_mfma_f32_16x16x32_bf16 v[50:53], v[192:195], v[180:183], v[18:21]
	v_mfma_f32_16x16x32_bf16 v[18:21], v[2:5], v[176:179], v[226:229]
	v_mfma_f32_16x16x32_bf16 v[38:41], v[6:9], v[184:187], v[18:21]
	v_mfma_f32_16x16x32_bf16 v[18:21], v[158:161], v[176:179], v[230:233]
	v_mfma_f32_16x16x32_bf16 v[34:37], v[192:195], v[184:187], v[18:21]
	v_mfma_f32_16x16x32_bf16 v[18:21], v[2:5], v[196:199], v[46:49]
	v_mfma_f32_16x16x32_bf16 v[2:5], v[2:5], v[200:203], v[138:141]
	v_mfma_f32_16x16x32_bf16 v[22:25], v[6:9], v[234:237], v[18:21]
	v_mfma_f32_16x16x32_bf16 v[18:21], v[158:161], v[196:199], v[42:45]
	v_mfma_f32_16x16x32_bf16 v[6:9], v[6:9], v[146:149], v[2:5]
	v_mfma_f32_16x16x32_bf16 v[2:5], v[158:161], v[200:203], v[142:145]
	v_mfma_f32_16x16x32_bf16 v[18:21], v[192:195], v[234:237], v[18:21]
	v_mfma_f32_16x16x32_bf16 v[2:5], v[192:195], v[146:149], v[2:5]
	s_setprio 0
	s_setprio 1
	v_mfma_f32_16x16x32_bf16 v[26:29], v[162:165], v[172:175], v[26:29]
	v_mfma_f32_16x16x32_bf16 v[58:61], v[222:225], v[180:183], v[26:29]
	v_mfma_f32_16x16x32_bf16 v[26:29], v[134:137], v[176:179], v[150:153]
	v_mfma_f32_16x16x32_bf16 v[46:49], v[218:221], v[184:187], v[26:29]
	v_mfma_f32_16x16x32_bf16 v[26:29], v[162:165], v[176:179], v[168:171]
	v_mfma_f32_16x16x32_bf16 v[10:13], v[162:165], v[196:199], v[10:13]
	v_mfma_f32_16x16x32_bf16 v[30:33], v[134:137], v[172:175], v[30:33]
	v_mfma_f32_16x16x32_bf16 v[42:45], v[222:225], v[184:187], v[26:29]
	v_mfma_f32_16x16x32_bf16 v[14:17], v[134:137], v[196:199], v[14:17]
	v_mfma_f32_16x16x32_bf16 v[26:29], v[222:225], v[234:237], v[10:13]
	v_mfma_f32_16x16x32_bf16 v[10:13], v[134:137], v[200:203], v[188:191]
	v_mfma_f32_16x16x32_bf16 v[62:65], v[218:221], v[180:183], v[30:33]
	v_mfma_f32_16x16x32_bf16 v[30:33], v[218:221], v[234:237], v[14:17]
	v_mfma_f32_16x16x32_bf16 v[14:17], v[218:221], v[146:149], v[10:13]
	v_mfma_f32_16x16x32_bf16 v[10:13], v[162:165], v[200:203], v[154:157]
	v_mfma_f32_16x16x32_bf16 v[10:13], v[222:225], v[146:149], v[10:13]
	s_setprio 0
	s_cmpk_gt_u32 s0, 0xff
	s_barrier
	s_cbranch_scc1 .LBB0_329
	s_barrier
	s_branch .LBB0_329

.LBB0_491:
	s_nop 10
	v_max_f32_e32 v3, v161, v161
	v_max_f32_e32 v4, v160, v160
	v_max_f32_e32 v3, v4, v3
	v_max3_f32 v3, v3, v162, v163
	v_max3_f32 v3, v3, v164, v165
	v_max3_f32 v3, v3, v166, v167
	v_cvt_f32_i32_e32 v2, v232
	v_max3_f32 v3, v3, v168, v169
	v_max3_f32 v3, v3, v170, v171
	v_max3_f32 v3, v3, v172, v173
	v_max3_f32 v3, v3, v174, v175
	v_fma_f32 v3, -v17, v2, v3
	v_mov_b32_e32 v4, v3
	s_nop 1
	v_permlane32_swap_b32_e32 v3, v4
	v_max3_f32 v235, v15, v3, v4
	v_add_f32_e32 v3, 0x41000000, v15
	v_cmp_le_f32_e32 vcc, v235, v3
	s_cmp_eq_u64 vcc, exec
	s_cbranch_scc1 .LBB0_496
	v_sub_f32_e32 v3, v15, v235
	v_exp_f32_e32 v4, v3
	s_nop 0
	v_pk_mul_f32 v[142:143], v[142:143], v[4:5] op_sel_hi:[1,0]
	v_pk_mul_f32 v[140:141], v[140:141], v[4:5] op_sel_hi:[1,0]
	v_pk_mul_f32 v[138:139], v[138:139], v[4:5] op_sel_hi:[1,0]
	v_pk_mul_f32 v[136:137], v[136:137], v[4:5] op_sel_hi:[1,0]
	v_pk_mul_f32 v[134:135], v[134:135], v[4:5] op_sel_hi:[1,0]
	v_pk_mul_f32 v[132:133], v[132:133], v[4:5] op_sel_hi:[1,0]
	v_pk_mul_f32 v[130:131], v[130:131], v[4:5] op_sel_hi:[1,0]
	v_pk_mul_f32 v[128:129], v[128:129], v[4:5] op_sel_hi:[1,0]
	v_pk_mul_f32 v[126:127], v[126:127], v[4:5] op_sel_hi:[1,0]
	v_pk_mul_f32 v[124:125], v[124:125], v[4:5] op_sel_hi:[1,0]
	v_pk_mul_f32 v[122:123], v[122:123], v[4:5] op_sel_hi:[1,0]
	v_pk_mul_f32 v[120:121], v[120:121], v[4:5] op_sel_hi:[1,0]
	v_pk_mul_f32 v[118:119], v[118:119], v[4:5] op_sel_hi:[1,0]
	v_pk_mul_f32 v[116:117], v[116:117], v[4:5] op_sel_hi:[1,0]
	v_pk_mul_f32 v[114:115], v[114:115], v[4:5] op_sel_hi:[1,0]
	v_pk_mul_f32 v[112:113], v[112:113], v[4:5] op_sel_hi:[1,0]
	v_pk_mul_f32 v[94:95], v[94:95], v[4:5] op_sel_hi:[1,0]
	v_pk_mul_f32 v[92:93], v[92:93], v[4:5] op_sel_hi:[1,0]
	v_pk_mul_f32 v[90:91], v[90:91], v[4:5] op_sel_hi:[1,0]
	v_pk_mul_f32 v[88:89], v[88:89], v[4:5] op_sel_hi:[1,0]
	v_pk_mul_f32 v[86:87], v[86:87], v[4:5] op_sel_hi:[1,0]
	v_pk_mul_f32 v[84:85], v[84:85], v[4:5] op_sel_hi:[1,0]
	v_pk_mul_f32 v[82:83], v[82:83], v[4:5] op_sel_hi:[1,0]
	v_pk_mul_f32 v[80:81], v[80:81], v[4:5] op_sel_hi:[1,0]
	v_pk_mul_f32 v[62:63], v[62:63], v[4:5] op_sel_hi:[1,0]
	v_pk_mul_f32 v[60:61], v[60:61], v[4:5] op_sel_hi:[1,0]
	v_pk_mul_f32 v[58:59], v[58:59], v[4:5] op_sel_hi:[1,0]
	v_pk_mul_f32 v[56:57], v[56:57], v[4:5] op_sel_hi:[1,0]
	v_pk_mul_f32 v[54:55], v[54:55], v[4:5] op_sel_hi:[1,0]
	v_pk_mul_f32 v[52:53], v[52:53], v[4:5] op_sel_hi:[1,0]
	v_pk_mul_f32 v[50:51], v[50:51], v[4:5] op_sel_hi:[1,0]
	v_pk_mul_f32 v[48:49], v[48:49], v[4:5] op_sel_hi:[1,0]
	v_mul_f32_e32 v14, v14, v4
	s_branch .LBB0_497

.LBB0_499:
	s_nop 10
	v_max_f32_e32 v200, v161, v161
	v_max_f32_e32 v201, v160, v160
	v_max_f32_e32 v200, v201, v200
	v_max3_f32 v200, v200, v162, v163
	v_max3_f32 v200, v200, v164, v165
	v_max3_f32 v200, v200, v166, v167
	v_max3_f32 v200, v200, v168, v169
	v_max3_f32 v200, v200, v170, v171
	v_max3_f32 v200, v200, v172, v173
	v_max3_f32 v200, v200, v174, v175
	v_add_f32_e32 v200, v15, v200
	v_mov_b32_e32 v201, v200
	s_nop 1
	v_permlane32_swap_b32_e32 v200, v201
	v_max3_f32 v252, v233, v200, v201
	v_add_f32_e32 v200, 0x41000000, v233
	v_cmp_le_f32_e32 vcc, v252, v200
	s_mov_b64 s[70:71], 0x8254900
	s_cmp_eq_u64 vcc, exec
	s_cbranch_scc1 .LBB0_501
	v_sub_f32_e32 v200, v233, v252
	v_exp_f32_e32 v200, v200
	v_mov_b32_e32 v233, v252
	v_pk_mul_f32 v[158:159], v[158:159], v[200:201] op_sel_hi:[1,0]
	v_pk_mul_f32 v[156:157], v[156:157], v[200:201] op_sel_hi:[1,0]
	v_pk_mul_f32 v[154:155], v[154:155], v[200:201] op_sel_hi:[1,0]
	v_pk_mul_f32 v[152:153], v[152:153], v[200:201] op_sel_hi:[1,0]
	v_pk_mul_f32 v[150:151], v[150:151], v[200:201] op_sel_hi:[1,0]
	v_pk_mul_f32 v[148:149], v[148:149], v[200:201] op_sel_hi:[1,0]
	v_pk_mul_f32 v[146:147], v[146:147], v[200:201] op_sel_hi:[1,0]
	v_pk_mul_f32 v[144:145], v[144:145], v[200:201] op_sel_hi:[1,0]
	v_pk_mul_f32 v[110:111], v[110:111], v[200:201] op_sel_hi:[1,0]
	v_pk_mul_f32 v[108:109], v[108:109], v[200:201] op_sel_hi:[1,0]
	v_pk_mul_f32 v[106:107], v[106:107], v[200:201] op_sel_hi:[1,0]
	v_pk_mul_f32 v[104:105], v[104:105], v[200:201] op_sel_hi:[1,0]
	v_pk_mul_f32 v[102:103], v[102:103], v[200:201] op_sel_hi:[1,0]
	v_pk_mul_f32 v[100:101], v[100:101], v[200:201] op_sel_hi:[1,0]
	v_pk_mul_f32 v[98:99], v[98:99], v[200:201] op_sel_hi:[1,0]
	v_pk_mul_f32 v[96:97], v[96:97], v[200:201] op_sel_hi:[1,0]
	v_pk_mul_f32 v[78:79], v[78:79], v[200:201] op_sel_hi:[1,0]
	v_pk_mul_f32 v[76:77], v[76:77], v[200:201] op_sel_hi:[1,0]
	v_pk_mul_f32 v[74:75], v[74:75], v[200:201] op_sel_hi:[1,0]
	v_pk_mul_f32 v[72:73], v[72:73], v[200:201] op_sel_hi:[1,0]
	v_pk_mul_f32 v[70:71], v[70:71], v[200:201] op_sel_hi:[1,0]
	v_pk_mul_f32 v[68:69], v[68:69], v[200:201] op_sel_hi:[1,0]
	v_pk_mul_f32 v[66:67], v[66:67], v[200:201] op_sel_hi:[1,0]
	v_pk_mul_f32 v[64:65], v[64:65], v[200:201] op_sel_hi:[1,0]
	v_pk_mul_f32 v[46:47], v[46:47], v[200:201] op_sel_hi:[1,0]
	v_pk_mul_f32 v[44:45], v[44:45], v[200:201] op_sel_hi:[1,0]
	v_pk_mul_f32 v[42:43], v[42:43], v[200:201] op_sel_hi:[1,0]
	v_pk_mul_f32 v[40:41], v[40:41], v[200:201] op_sel_hi:[1,0]
	v_pk_mul_f32 v[38:39], v[38:39], v[200:201] op_sel_hi:[1,0]
	v_pk_mul_f32 v[36:37], v[36:37], v[200:201] op_sel_hi:[1,0]
	v_pk_mul_f32 v[34:35], v[34:35], v[200:201] op_sel_hi:[1,0]
	v_pk_mul_f32 v[32:33], v[32:33], v[200:201] op_sel_hi:[1,0]
	v_mul_f32_e32 v231, v231, v200
	s_branch .LBB0_502

.LBB0_505:
	s_nop 10
	v_max_f32_e32 v3, v161, v161
	v_max_f32_e32 v4, v160, v160
	v_max_f32_e32 v3, v4, v3
	v_max3_f32 v3, v3, v162, v163
	v_max3_f32 v3, v3, v164, v165
	v_max3_f32 v3, v3, v166, v167
	v_cvt_f32_i32_e32 v2, v236
	v_max3_f32 v3, v3, v168, v169
	v_max3_f32 v3, v3, v170, v171
	v_max3_f32 v3, v3, v172, v173
	v_max3_f32 v3, v3, v174, v175
	v_fma_f32 v3, -v17, v2, v3
	v_mov_b32_e32 v4, v3
	s_nop 1
	v_permlane32_swap_b32_e32 v3, v4
	v_max3_f32 v15, v235, v3, v4
	v_add_f32_e32 v3, 0x41000000, v235
	v_cmp_le_f32_e32 vcc, v15, v3
	s_cmp_eq_u64 vcc, exec
	s_cbranch_scc1 .LBB0_507
	v_sub_f32_e32 v3, v235, v15
	v_exp_f32_e32 v4, v3
	s_nop 0
	v_pk_mul_f32 v[142:143], v[142:143], v[4:5] op_sel_hi:[1,0]
	v_pk_mul_f32 v[140:141], v[140:141], v[4:5] op_sel_hi:[1,0]
	v_pk_mul_f32 v[138:139], v[138:139], v[4:5] op_sel_hi:[1,0]
	v_pk_mul_f32 v[136:137], v[136:137], v[4:5] op_sel_hi:[1,0]
	v_pk_mul_f32 v[134:135], v[134:135], v[4:5] op_sel_hi:[1,0]
	v_pk_mul_f32 v[132:133], v[132:133], v[4:5] op_sel_hi:[1,0]
	v_pk_mul_f32 v[130:131], v[130:131], v[4:5] op_sel_hi:[1,0]
	v_pk_mul_f32 v[128:129], v[128:129], v[4:5] op_sel_hi:[1,0]
	v_pk_mul_f32 v[126:127], v[126:127], v[4:5] op_sel_hi:[1,0]
	v_pk_mul_f32 v[124:125], v[124:125], v[4:5] op_sel_hi:[1,0]
	v_pk_mul_f32 v[122:123], v[122:123], v[4:5] op_sel_hi:[1,0]
	v_pk_mul_f32 v[120:121], v[120:121], v[4:5] op_sel_hi:[1,0]
	v_pk_mul_f32 v[118:119], v[118:119], v[4:5] op_sel_hi:[1,0]
	v_pk_mul_f32 v[116:117], v[116:117], v[4:5] op_sel_hi:[1,0]
	v_pk_mul_f32 v[114:115], v[114:115], v[4:5] op_sel_hi:[1,0]
	v_pk_mul_f32 v[112:113], v[112:113], v[4:5] op_sel_hi:[1,0]
	v_pk_mul_f32 v[94:95], v[94:95], v[4:5] op_sel_hi:[1,0]
	v_pk_mul_f32 v[92:93], v[92:93], v[4:5] op_sel_hi:[1,0]
	v_pk_mul_f32 v[90:91], v[90:91], v[4:5] op_sel_hi:[1,0]
	v_pk_mul_f32 v[88:89], v[88:89], v[4:5] op_sel_hi:[1,0]
	v_pk_mul_f32 v[86:87], v[86:87], v[4:5] op_sel_hi:[1,0]
	v_pk_mul_f32 v[84:85], v[84:85], v[4:5] op_sel_hi:[1,0]
	v_pk_mul_f32 v[82:83], v[82:83], v[4:5] op_sel_hi:[1,0]
	v_pk_mul_f32 v[80:81], v[80:81], v[4:5] op_sel_hi:[1,0]
	v_pk_mul_f32 v[62:63], v[62:63], v[4:5] op_sel_hi:[1,0]
	v_pk_mul_f32 v[60:61], v[60:61], v[4:5] op_sel_hi:[1,0]
	v_pk_mul_f32 v[58:59], v[58:59], v[4:5] op_sel_hi:[1,0]
	v_pk_mul_f32 v[56:57], v[56:57], v[4:5] op_sel_hi:[1,0]
	v_pk_mul_f32 v[54:55], v[54:55], v[4:5] op_sel_hi:[1,0]
	v_pk_mul_f32 v[52:53], v[52:53], v[4:5] op_sel_hi:[1,0]
	v_pk_mul_f32 v[50:51], v[50:51], v[4:5] op_sel_hi:[1,0]
	v_pk_mul_f32 v[48:49], v[48:49], v[4:5] op_sel_hi:[1,0]
	v_mul_f32_e32 v14, v14, v4
	s_branch .LBB0_508

.LBB0_510:
	s_nop 10
	v_max_f32_e32 v0, v161, v161
	v_max_f32_e32 v200, v160, v160
	v_max_f32_e32 v0, v200, v0
	v_max3_f32 v0, v0, v162, v163
	v_max3_f32 v0, v0, v164, v165
	v_max3_f32 v0, v0, v166, v167
	v_max3_f32 v0, v0, v168, v169
	v_max3_f32 v0, v0, v170, v171
	v_max3_f32 v0, v0, v172, v173
	v_max3_f32 v0, v0, v174, v175
	v_add_f32_e32 v0, v235, v0
	v_mov_b32_e32 v200, v0
	s_nop 1
	v_permlane32_swap_b32_e32 v0, v200
	v_max3_f32 v0, v233, v0, v200
	v_add_f32_e32 v200, 0x41000000, v233
	v_cmp_le_f32_e32 vcc, v0, v200
	s_mov_b64 s[70:71], 0x8254900
	s_cmp_eq_u64 vcc, exec
	s_cbranch_scc1 .LBB0_512
	v_sub_f32_e32 v200, v233, v0
	v_exp_f32_e32 v200, v200
	v_mov_b32_e32 v233, v0
	v_pk_mul_f32 v[158:159], v[158:159], v[200:201] op_sel_hi:[1,0]
	v_pk_mul_f32 v[156:157], v[156:157], v[200:201] op_sel_hi:[1,0]
	v_pk_mul_f32 v[154:155], v[154:155], v[200:201] op_sel_hi:[1,0]
	v_pk_mul_f32 v[152:153], v[152:153], v[200:201] op_sel_hi:[1,0]
	v_pk_mul_f32 v[150:151], v[150:151], v[200:201] op_sel_hi:[1,0]
	v_pk_mul_f32 v[148:149], v[148:149], v[200:201] op_sel_hi:[1,0]
	v_pk_mul_f32 v[146:147], v[146:147], v[200:201] op_sel_hi:[1,0]
	v_pk_mul_f32 v[144:145], v[144:145], v[200:201] op_sel_hi:[1,0]
	v_pk_mul_f32 v[110:111], v[110:111], v[200:201] op_sel_hi:[1,0]
	v_pk_mul_f32 v[108:109], v[108:109], v[200:201] op_sel_hi:[1,0]
	v_pk_mul_f32 v[106:107], v[106:107], v[200:201] op_sel_hi:[1,0]
	v_pk_mul_f32 v[104:105], v[104:105], v[200:201] op_sel_hi:[1,0]
	v_pk_mul_f32 v[102:103], v[102:103], v[200:201] op_sel_hi:[1,0]
	v_pk_mul_f32 v[100:101], v[100:101], v[200:201] op_sel_hi:[1,0]
	v_pk_mul_f32 v[98:99], v[98:99], v[200:201] op_sel_hi:[1,0]
	v_pk_mul_f32 v[96:97], v[96:97], v[200:201] op_sel_hi:[1,0]
	v_pk_mul_f32 v[78:79], v[78:79], v[200:201] op_sel_hi:[1,0]
	v_pk_mul_f32 v[76:77], v[76:77], v[200:201] op_sel_hi:[1,0]
	v_pk_mul_f32 v[74:75], v[74:75], v[200:201] op_sel_hi:[1,0]
	v_pk_mul_f32 v[72:73], v[72:73], v[200:201] op_sel_hi:[1,0]
	v_pk_mul_f32 v[70:71], v[70:71], v[200:201] op_sel_hi:[1,0]
	v_pk_mul_f32 v[68:69], v[68:69], v[200:201] op_sel_hi:[1,0]
	v_pk_mul_f32 v[66:67], v[66:67], v[200:201] op_sel_hi:[1,0]
	v_pk_mul_f32 v[64:65], v[64:65], v[200:201] op_sel_hi:[1,0]
	v_pk_mul_f32 v[46:47], v[46:47], v[200:201] op_sel_hi:[1,0]
	v_pk_mul_f32 v[44:45], v[44:45], v[200:201] op_sel_hi:[1,0]
	v_pk_mul_f32 v[42:43], v[42:43], v[200:201] op_sel_hi:[1,0]
	v_pk_mul_f32 v[40:41], v[40:41], v[200:201] op_sel_hi:[1,0]
	v_pk_mul_f32 v[38:39], v[38:39], v[200:201] op_sel_hi:[1,0]
	v_pk_mul_f32 v[36:37], v[36:37], v[200:201] op_sel_hi:[1,0]
	v_pk_mul_f32 v[34:35], v[34:35], v[200:201] op_sel_hi:[1,0]
	v_pk_mul_f32 v[32:33], v[32:33], v[200:201] op_sel_hi:[1,0]
	v_mul_f32_e32 v231, v231, v200
	s_branch .LBB0_513

.LBB0_597:
	v_or_b32_e32 v0, 0x10000, v154
	v_add_u32_e32 v157, 0x10800, v154
	v_or_b32_e32 v156, 0x10000, v155
	ds_read_b128 v[164:167], v0
	ds_read_b128 v[168:171], v156
	v_add_u32_e32 v158, 0x10800, v155
	ds_read_b128 v[172:175], v157
	ds_read_b128 v[176:179], v158
	v_lshl_add_u64 v[210:211], v[150:151], 0, v[144:145]
	s_add_i32 s25, s1, 0xc000
	v_lshl_add_u64 v[160:161], v[210:211], 0, s[26:27]
	s_mov_b32 m0, s25
	v_lshl_add_u64 v[214:215], v[150:151], 0, v[142:143]
	s_add_i32 s11, s1, 0xe000
	ds_read_b128 v[180:183], v152
	ds_read_b128 v[184:187], v152 offset:2048
	ds_read_b128 v[188:191], v153
	ds_read_b128 v[192:195], v153 offset:2048
	ds_read_b128 v[196:199], v152 offset:4096
	ds_read_b128 v[200:203], v152 offset:6144
	ds_read_b128 v[206:209], v153 offset:4096
	ds_read_b128 v[218:221], v153 offset:6144
	global_load_lds_dwordx4 v[160:161], off nt
	v_lshl_add_u64 v[160:161], v[214:215], 0, s[26:27]
	s_mov_b32 m0, s11
	s_nop 0
	global_load_lds_dwordx4 v[160:161], off nt
	s_waitcnt lgkmcnt(8)
	s_waitcnt vmcnt(10)
	s_barrier
	s_waitcnt lgkmcnt(0)
	s_setprio 1
	s_waitcnt lgkmcnt(0)
	v_mfma_f32_16x16x32_bf16 v[126:129], v[164:167], v[180:183], v[126:129]
	v_mfma_f32_16x16x32_bf16 v[122:125], v[172:175], v[180:183], v[122:125]
	v_mfma_f32_16x16x32_bf16 v[118:121], v[164:167], v[184:187], v[118:121]
	v_mfma_f32_16x16x32_bf16 v[114:117], v[172:175], v[184:187], v[114:117]
	v_mfma_f32_16x16x32_bf16 v[110:113], v[164:167], v[196:199], v[110:113]
	v_mfma_f32_16x16x32_bf16 v[106:109], v[172:175], v[196:199], v[106:109]
	v_mfma_f32_16x16x32_bf16 v[102:105], v[164:167], v[200:203], v[102:105]
	v_mfma_f32_16x16x32_bf16 v[98:101], v[172:175], v[200:203], v[98:101]
	v_mfma_f32_16x16x32_bf16 v[126:129], v[168:171], v[188:191], v[126:129]
	v_mfma_f32_16x16x32_bf16 v[122:125], v[176:179], v[188:191], v[122:125]
	v_mfma_f32_16x16x32_bf16 v[118:121], v[168:171], v[192:195], v[118:121]
	v_mfma_f32_16x16x32_bf16 v[114:117], v[176:179], v[192:195], v[114:117]
	v_mfma_f32_16x16x32_bf16 v[110:113], v[168:171], v[206:209], v[110:113]
	v_mfma_f32_16x16x32_bf16 v[106:109], v[176:179], v[206:209], v[106:109]
	v_mfma_f32_16x16x32_bf16 v[102:105], v[168:171], v[218:221], v[102:105]
	v_mfma_f32_16x16x32_bf16 v[98:101], v[176:179], v[218:221], v[98:101]
	s_setprio 0
	s_barrier
	v_lshl_add_u64 v[246:247], v[150:151], 0, v[148:149]
	s_mov_b32 m0, s2
	v_or_b32_e32 v159, 0x14000, v154
	v_add_u32_e32 v161, 0x14800, v154
	v_lshl_add_u64 v[238:239], v[246:247], 0, s[30:31]
	v_lshl_add_u64 v[248:249], v[150:151], 0, v[146:147]
	v_or_b32_e32 v160, 0x14000, v155
	ds_read_b128 v[222:225], v159
	ds_read_b128 v[226:229], v160
	v_add_u32_e32 v162, 0x14800, v155
	ds_read_b128 v[230:233], v161
	ds_read_b128 v[234:237], v162
	global_load_lds_dwordx4 v[238:239], off
	v_lshl_add_u64 v[238:239], v[248:249], 0, s[30:31]
	s_mov_b32 m0, s3
	s_nop 0
	global_load_lds_dwordx4 v[238:239], off
	s_waitcnt vmcnt(10)
	s_waitcnt lgkmcnt(0)
	s_barrier
	s_waitcnt lgkmcnt(0)
	s_setprio 1
	s_waitcnt lgkmcnt(0)
	v_mfma_f32_16x16x32_bf16 v[94:97], v[222:225], v[180:183], v[94:97]
	v_mfma_f32_16x16x32_bf16 v[90:93], v[230:233], v[180:183], v[90:93]
	v_mfma_f32_16x16x32_bf16 v[86:89], v[222:225], v[184:187], v[86:89]
	v_mfma_f32_16x16x32_bf16 v[82:85], v[230:233], v[184:187], v[82:85]
	v_mfma_f32_16x16x32_bf16 v[78:81], v[222:225], v[196:199], v[78:81]
	v_mfma_f32_16x16x32_bf16 v[74:77], v[230:233], v[196:199], v[74:77]
	v_mfma_f32_16x16x32_bf16 v[70:73], v[222:225], v[200:203], v[70:73]
	v_mfma_f32_16x16x32_bf16 v[66:69], v[230:233], v[200:203], v[66:69]
	v_mfma_f32_16x16x32_bf16 v[94:97], v[226:229], v[188:191], v[94:97]
	v_mfma_f32_16x16x32_bf16 v[90:93], v[234:237], v[188:191], v[90:93]
	v_mfma_f32_16x16x32_bf16 v[86:89], v[226:229], v[192:195], v[86:89]
	v_mfma_f32_16x16x32_bf16 v[82:85], v[234:237], v[192:195], v[82:85]
	v_mfma_f32_16x16x32_bf16 v[78:81], v[226:229], v[206:209], v[78:81]
	v_mfma_f32_16x16x32_bf16 v[74:77], v[234:237], v[206:209], v[74:77]
	v_mfma_f32_16x16x32_bf16 v[70:73], v[226:229], v[218:221], v[70:73]
	v_mfma_f32_16x16x32_bf16 v[66:69], v[234:237], v[218:221], v[66:69]
	s_setprio 0
	s_mov_b32 m0, s1
	v_lshl_add_u64 v[238:239], v[210:211], 0, s[34:35]
	s_barrier
	ds_read_b128 v[180:183], v152 offset:16384
	ds_read_b128 v[184:187], v152 offset:18432
	ds_read_b128 v[188:191], v153 offset:16384
	ds_read_b128 v[192:195], v153 offset:18432
	ds_read_b128 v[196:199], v152 offset:20480
	ds_read_b128 v[200:203], v152 offset:22528
	ds_read_b128 v[206:209], v153 offset:20480
	ds_read_b128 v[218:221], v153 offset:22528
	global_load_lds_dwordx4 v[238:239], off nt
	v_lshl_add_u64 v[238:239], v[214:215], 0, s[34:35]
	s_mov_b32 m0, s13
	s_nop 0
	global_load_lds_dwordx4 v[238:239], off nt
	v_lshl_add_u64 v[238:239], v[246:247], 0, s[36:37]
	s_mov_b32 m0, s15
	s_nop 0
	global_load_lds_dwordx4 v[238:239], off
	v_lshl_add_u64 v[238:239], v[248:249], 0, s[36:37]
	s_mov_b32 m0, s16
	s_nop 0
	global_load_lds_dwordx4 v[238:239], off
	s_waitcnt vmcnt(10)
	s_waitcnt lgkmcnt(0)
	s_barrier
	s_waitcnt lgkmcnt(0)
	s_setprio 1
	s_waitcnt lgkmcnt(0)
	v_mfma_f32_16x16x32_bf16 v[62:65], v[164:167], v[180:183], v[62:65]
	v_mfma_f32_16x16x32_bf16 v[58:61], v[172:175], v[180:183], v[58:61]
	v_mfma_f32_16x16x32_bf16 v[54:57], v[164:167], v[184:187], v[54:57]
	v_mfma_f32_16x16x32_bf16 v[50:53], v[172:175], v[184:187], v[50:53]
	v_mfma_f32_16x16x32_bf16 v[46:49], v[164:167], v[196:199], v[46:49]
	v_mfma_f32_16x16x32_bf16 v[42:45], v[172:175], v[196:199], v[42:45]
	v_mfma_f32_16x16x32_bf16 v[38:41], v[164:167], v[200:203], v[38:41]
	v_mfma_f32_16x16x32_bf16 v[34:37], v[172:175], v[200:203], v[34:37]
	v_mfma_f32_16x16x32_bf16 v[62:65], v[168:171], v[188:191], v[62:65]
	v_mfma_f32_16x16x32_bf16 v[58:61], v[176:179], v[188:191], v[58:61]
	v_mfma_f32_16x16x32_bf16 v[54:57], v[168:171], v[192:195], v[54:57]
	v_mfma_f32_16x16x32_bf16 v[50:53], v[176:179], v[192:195], v[50:53]
	v_mfma_f32_16x16x32_bf16 v[46:49], v[168:171], v[206:209], v[46:49]
	v_mfma_f32_16x16x32_bf16 v[42:45], v[176:179], v[206:209], v[42:45]
	v_mfma_f32_16x16x32_bf16 v[38:41], v[168:171], v[218:221], v[38:41]
	v_mfma_f32_16x16x32_bf16 v[34:37], v[176:179], v[218:221], v[34:37]
	v_mfma_f32_16x16x32_bf16 v[30:33], v[222:225], v[180:183], v[30:33]
	v_mfma_f32_16x16x32_bf16 v[26:29], v[230:233], v[180:183], v[26:29]
	v_mfma_f32_16x16x32_bf16 v[22:25], v[222:225], v[184:187], v[22:25]
	v_mfma_f32_16x16x32_bf16 v[18:21], v[230:233], v[184:187], v[18:21]
	v_mfma_f32_16x16x32_bf16 v[14:17], v[222:225], v[196:199], v[14:17]
	v_mfma_f32_16x16x32_bf16 v[10:13], v[230:233], v[196:199], v[10:13]
	v_mfma_f32_16x16x32_bf16 v[6:9], v[222:225], v[200:203], v[6:9]
	v_mfma_f32_16x16x32_bf16 v[2:5], v[230:233], v[200:203], v[2:5]
	v_mfma_f32_16x16x32_bf16 v[30:33], v[226:229], v[188:191], v[30:33]
	v_mfma_f32_16x16x32_bf16 v[26:29], v[234:237], v[188:191], v[26:29]
	v_mfma_f32_16x16x32_bf16 v[22:25], v[226:229], v[192:195], v[22:25]
	v_mfma_f32_16x16x32_bf16 v[18:21], v[234:237], v[192:195], v[18:21]
	v_mfma_f32_16x16x32_bf16 v[14:17], v[226:229], v[206:209], v[14:17]
	v_mfma_f32_16x16x32_bf16 v[10:13], v[234:237], v[206:209], v[10:13]
	v_mfma_f32_16x16x32_bf16 v[6:9], v[226:229], v[218:221], v[6:9]
	v_mfma_f32_16x16x32_bf16 v[2:5], v[234:237], v[218:221], v[2:5]
	s_setprio 0
	v_or_b32_e32 v163, 0x18000, v154
	v_add_u32_e32 v165, 0x18800, v154
	s_barrier
	v_or_b32_e32 v164, 0x18000, v155
	ds_read_b128 v[172:175], v163
	ds_read_b128 v[176:179], v164
	v_add_u32_e32 v166, 0x18800, v155
	ds_read_b128 v[180:183], v165
	ds_read_b128 v[184:187], v166
	s_mov_b32 m0, s17
	v_lshl_add_u64 v[168:169], v[210:211], 0, s[38:39]
	ds_read_b128 v[188:191], v152 offset:32768
	ds_read_b128 v[192:195], v152 offset:34816
	ds_read_b128 v[196:199], v153 offset:32768
	ds_read_b128 v[200:203], v153 offset:34816
	ds_read_b128 v[206:209], v152 offset:36864
	ds_read_b128 v[218:221], v152 offset:38912
	ds_read_b128 v[222:225], v153 offset:36864
	ds_read_b128 v[226:229], v153 offset:38912
	global_load_lds_dwordx4 v[168:169], off nt
	v_lshl_add_u64 v[168:169], v[214:215], 0, s[38:39]
	s_mov_b32 m0, s18
	s_nop 0
	global_load_lds_dwordx4 v[168:169], off nt
	s_waitcnt lgkmcnt(8)
	s_waitcnt vmcnt(10)
	s_barrier
	s_waitcnt lgkmcnt(0)
	s_setprio 1
	s_waitcnt lgkmcnt(0)
	v_mfma_f32_16x16x32_bf16 v[126:129], v[172:175], v[188:191], v[126:129]
	v_mfma_f32_16x16x32_bf16 v[122:125], v[180:183], v[188:191], v[122:125]
	v_mfma_f32_16x16x32_bf16 v[118:121], v[172:175], v[192:195], v[118:121]
	v_mfma_f32_16x16x32_bf16 v[114:117], v[180:183], v[192:195], v[114:117]
	v_mfma_f32_16x16x32_bf16 v[110:113], v[172:175], v[206:209], v[110:113]
	v_mfma_f32_16x16x32_bf16 v[106:109], v[180:183], v[206:209], v[106:109]
	v_mfma_f32_16x16x32_bf16 v[102:105], v[172:175], v[218:221], v[102:105]
	v_mfma_f32_16x16x32_bf16 v[98:101], v[180:183], v[218:221], v[98:101]
	v_mfma_f32_16x16x32_bf16 v[126:129], v[176:179], v[196:199], v[126:129]
	v_mfma_f32_16x16x32_bf16 v[122:125], v[184:187], v[196:199], v[122:125]
	v_mfma_f32_16x16x32_bf16 v[118:121], v[176:179], v[200:203], v[118:121]
	v_mfma_f32_16x16x32_bf16 v[114:117], v[184:187], v[200:203], v[114:117]
	v_mfma_f32_16x16x32_bf16 v[110:113], v[176:179], v[222:225], v[110:113]
	v_mfma_f32_16x16x32_bf16 v[106:109], v[184:187], v[222:225], v[106:109]
	v_mfma_f32_16x16x32_bf16 v[102:105], v[176:179], v[226:229], v[102:105]
	v_mfma_f32_16x16x32_bf16 v[98:101], v[184:187], v[226:229], v[98:101]
	s_setprio 0
	s_barrier
	s_mov_b32 m0, s19
	v_or_b32_e32 v167, 0x1c000, v154
	v_add_u32_e32 v169, 0x1c800, v154
	v_lshl_add_u64 v[250:251], v[246:247], 0, s[40:41]
	v_or_b32_e32 v168, 0x1c000, v155
	ds_read_b128 v[230:233], v167
	ds_read_b128 v[234:237], v168
	v_add_u32_e32 v170, 0x1c800, v155
	ds_read_b128 v[238:241], v169
	ds_read_b128 v[242:245], v170
	global_load_lds_dwordx4 v[250:251], off
	v_lshl_add_u64 v[250:251], v[248:249], 0, s[40:41]
	s_mov_b32 m0, s20
	s_nop 0
	global_load_lds_dwordx4 v[250:251], off
	s_waitcnt vmcnt(10)
	s_waitcnt lgkmcnt(0)
	s_barrier
	s_waitcnt lgkmcnt(0)
	s_setprio 1
	s_waitcnt lgkmcnt(0)
	v_mfma_f32_16x16x32_bf16 v[94:97], v[230:233], v[188:191], v[94:97]
	v_mfma_f32_16x16x32_bf16 v[90:93], v[238:241], v[188:191], v[90:93]
	v_mfma_f32_16x16x32_bf16 v[86:89], v[230:233], v[192:195], v[86:89]
	v_mfma_f32_16x16x32_bf16 v[82:85], v[238:241], v[192:195], v[82:85]
	v_mfma_f32_16x16x32_bf16 v[78:81], v[230:233], v[206:209], v[78:81]
	v_mfma_f32_16x16x32_bf16 v[74:77], v[238:241], v[206:209], v[74:77]
	v_mfma_f32_16x16x32_bf16 v[70:73], v[230:233], v[218:221], v[70:73]
	v_mfma_f32_16x16x32_bf16 v[66:69], v[238:241], v[218:221], v[66:69]
	v_mfma_f32_16x16x32_bf16 v[94:97], v[234:237], v[196:199], v[94:97]
	v_mfma_f32_16x16x32_bf16 v[90:93], v[242:245], v[196:199], v[90:93]
	v_mfma_f32_16x16x32_bf16 v[86:89], v[234:237], v[200:203], v[86:89]
	v_mfma_f32_16x16x32_bf16 v[82:85], v[242:245], v[200:203], v[82:85]
	v_mfma_f32_16x16x32_bf16 v[78:81], v[234:237], v[222:225], v[78:81]
	v_mfma_f32_16x16x32_bf16 v[74:77], v[242:245], v[222:225], v[74:77]
	v_mfma_f32_16x16x32_bf16 v[70:73], v[234:237], v[226:229], v[70:73]
	v_mfma_f32_16x16x32_bf16 v[66:69], v[242:245], v[226:229], v[66:69]
	s_setprio 0
	s_mov_b32 m0, s21
	v_lshl_add_u64 v[210:211], v[210:211], 0, s[44:45]
	s_barrier
	ds_read_b128 v[188:191], v152 offset:49152
	ds_read_b128 v[192:195], v152 offset:51200
	ds_read_b128 v[196:199], v153 offset:49152
	ds_read_b128 v[200:203], v153 offset:51200
	ds_read_b128 v[206:209], v152 offset:53248
	ds_read_b128 v[218:221], v152 offset:55296
	ds_read_b128 v[222:225], v153 offset:53248
	ds_read_b128 v[226:229], v153 offset:55296
	global_load_lds_dwordx4 v[210:211], off nt
	v_lshl_add_u64 v[210:211], v[214:215], 0, s[44:45]
	s_mov_b32 m0, s22
	s_nop 0
	global_load_lds_dwordx4 v[210:211], off nt
	v_lshl_add_u64 v[210:211], v[246:247], 0, s[48:49]
	s_mov_b32 m0, s23
	s_nop 0
	global_load_lds_dwordx4 v[210:211], off
	v_lshl_add_u64 v[210:211], v[248:249], 0, s[48:49]
	s_mov_b32 m0, s24
	s_nop 0
	global_load_lds_dwordx4 v[210:211], off
	s_waitcnt vmcnt(10)
	s_waitcnt lgkmcnt(0)
	s_barrier
	s_waitcnt lgkmcnt(0)
	s_setprio 1
	s_waitcnt lgkmcnt(0)
	v_mfma_f32_16x16x32_bf16 v[62:65], v[172:175], v[188:191], v[62:65]
	v_mfma_f32_16x16x32_bf16 v[58:61], v[180:183], v[188:191], v[58:61]
	v_mfma_f32_16x16x32_bf16 v[54:57], v[172:175], v[192:195], v[54:57]
	v_mfma_f32_16x16x32_bf16 v[50:53], v[180:183], v[192:195], v[50:53]
	v_mfma_f32_16x16x32_bf16 v[46:49], v[172:175], v[206:209], v[46:49]
	v_mfma_f32_16x16x32_bf16 v[42:45], v[180:183], v[206:209], v[42:45]
	v_mfma_f32_16x16x32_bf16 v[38:41], v[172:175], v[218:221], v[38:41]
	v_mfma_f32_16x16x32_bf16 v[34:37], v[180:183], v[218:221], v[34:37]
	v_mfma_f32_16x16x32_bf16 v[62:65], v[176:179], v[196:199], v[62:65]
	v_mfma_f32_16x16x32_bf16 v[58:61], v[184:187], v[196:199], v[58:61]
	v_mfma_f32_16x16x32_bf16 v[54:57], v[176:179], v[200:203], v[54:57]
	v_mfma_f32_16x16x32_bf16 v[50:53], v[184:187], v[200:203], v[50:53]
	v_mfma_f32_16x16x32_bf16 v[46:49], v[176:179], v[222:225], v[46:49]
	v_mfma_f32_16x16x32_bf16 v[42:45], v[184:187], v[222:225], v[42:45]
	v_mfma_f32_16x16x32_bf16 v[38:41], v[176:179], v[226:229], v[38:41]
	v_mfma_f32_16x16x32_bf16 v[34:37], v[184:187], v[226:229], v[34:37]
	v_mfma_f32_16x16x32_bf16 v[30:33], v[230:233], v[188:191], v[30:33]
	v_mfma_f32_16x16x32_bf16 v[26:29], v[238:241], v[188:191], v[26:29]
	v_mfma_f32_16x16x32_bf16 v[22:25], v[230:233], v[192:195], v[22:25]
	v_mfma_f32_16x16x32_bf16 v[18:21], v[238:241], v[192:195], v[18:21]
	v_mfma_f32_16x16x32_bf16 v[14:17], v[230:233], v[206:209], v[14:17]
	v_mfma_f32_16x16x32_bf16 v[10:13], v[238:241], v[206:209], v[10:13]
	v_mfma_f32_16x16x32_bf16 v[6:9], v[230:233], v[218:221], v[6:9]
	v_mfma_f32_16x16x32_bf16 v[2:5], v[238:241], v[218:221], v[2:5]
	v_mfma_f32_16x16x32_bf16 v[30:33], v[234:237], v[196:199], v[30:33]
	v_mfma_f32_16x16x32_bf16 v[26:29], v[242:245], v[196:199], v[26:29]
	v_mfma_f32_16x16x32_bf16 v[22:25], v[234:237], v[200:203], v[22:25]
	v_mfma_f32_16x16x32_bf16 v[18:21], v[242:245], v[200:203], v[18:21]
	v_mfma_f32_16x16x32_bf16 v[14:17], v[234:237], v[222:225], v[14:17]
	v_mfma_f32_16x16x32_bf16 v[10:13], v[242:245], v[222:225], v[10:13]
	v_mfma_f32_16x16x32_bf16 v[6:9], v[234:237], v[226:229], v[6:9]
	v_mfma_f32_16x16x32_bf16 v[2:5], v[242:245], v[226:229], v[2:5]
	s_setprio 0
	s_add_i32 s10, s10, 2
	s_cmp_lt_u32 s10, 28
	v_lshl_add_u64 v[150:151], v[150:151], 0, s[54:55]
	s_barrier
	s_cbranch_scc1 .LBB0_597
	s_waitcnt vmcnt(6)
	s_mov_b64 s[2:3], 0xf80
	s_mov_b32 m0, s25
	v_lshl_add_u64 v[140:141], v[140:141], 0, s[2:3]
	ds_read_b128 v[142:145], v0
	ds_read_b128 v[146:149], v156
	ds_read_b128 v[154:157], v157
	ds_read_b128 v[172:175], v158
	ds_read_b128 v[176:179], v152
	ds_read_b128 v[180:183], v152 offset:2048
	ds_read_b128 v[184:187], v153
	ds_read_b128 v[188:191], v153 offset:2048
	ds_read_b128 v[192:195], v152 offset:4096
	ds_read_b128 v[196:199], v152 offset:6144
	ds_read_b128 v[200:203], v153 offset:4096
	ds_read_b128 v[206:209], v153 offset:6144
	global_load_lds_dwordx4 v[140:141], off nt
	v_lshl_add_u64 v[138:139], v[138:139], 0, s[2:3]
	s_mov_b32 m0, s11
	s_nop 0
	global_load_lds_dwordx4 v[138:139], off nt
	s_barrier
	s_waitcnt lgkmcnt(0)
	s_setprio 1
	s_waitcnt lgkmcnt(0)
	v_mfma_f32_16x16x32_bf16 v[126:129], v[142:145], v[176:179], v[126:129]
	v_mfma_f32_16x16x32_bf16 v[122:125], v[154:157], v[176:179], v[122:125]
	v_mfma_f32_16x16x32_bf16 v[118:121], v[142:145], v[180:183], v[118:121]
	v_mfma_f32_16x16x32_bf16 v[114:117], v[154:157], v[180:183], v[114:117]
	v_mfma_f32_16x16x32_bf16 v[102:105], v[142:145], v[196:199], v[102:105]
	v_mfma_f32_16x16x32_bf16 v[98:101], v[154:157], v[196:199], v[98:101]
	v_mfma_f32_16x16x32_bf16 v[126:129], v[146:149], v[184:187], v[126:129]
	v_mfma_f32_16x16x32_bf16 v[122:125], v[172:175], v[184:187], v[122:125]
	v_mfma_f32_16x16x32_bf16 v[118:121], v[146:149], v[188:191], v[118:121]
	v_mfma_f32_16x16x32_bf16 v[114:117], v[172:175], v[188:191], v[114:117]
	v_mfma_f32_16x16x32_bf16 v[110:113], v[142:145], v[192:195], v[110:113]
	v_mfma_f32_16x16x32_bf16 v[106:109], v[154:157], v[192:195], v[106:109]
	v_mfma_f32_16x16x32_bf16 v[102:105], v[146:149], v[206:209], v[102:105]
	v_mfma_f32_16x16x32_bf16 v[98:101], v[172:175], v[206:209], v[98:101]
	v_mfma_f32_16x16x32_bf16 v[138:141], v[146:149], v[200:203], v[110:113]
	v_mfma_f32_16x16x32_bf16 v[218:221], v[172:175], v[200:203], v[106:109]
	s_setprio 0
	s_barrier
	s_nop 1
	ds_read_b128 v[106:109], v159
	ds_read_b128 v[110:113], v160
	ds_read_b128 v[158:161], v161
	ds_read_b128 v[222:225], v162
	s_barrier
	s_waitcnt lgkmcnt(0)
	s_setprio 1
	s_waitcnt lgkmcnt(0)
	v_mfma_f32_16x16x32_bf16 v[86:89], v[106:109], v[180:183], v[86:89]
	v_mfma_f32_16x16x32_bf16 v[82:85], v[158:161], v[180:183], v[82:85]
	v_mfma_f32_16x16x32_bf16 v[70:73], v[106:109], v[196:199], v[70:73]
	v_mfma_f32_16x16x32_bf16 v[66:69], v[158:161], v[196:199], v[66:69]
	v_mfma_f32_16x16x32_bf16 v[94:97], v[106:109], v[176:179], v[94:97]
	v_mfma_f32_16x16x32_bf16 v[90:93], v[158:161], v[176:179], v[90:93]
	v_mfma_f32_16x16x32_bf16 v[86:89], v[110:113], v[188:191], v[86:89]
	v_mfma_f32_16x16x32_bf16 v[82:85], v[222:225], v[188:191], v[82:85]
	v_mfma_f32_16x16x32_bf16 v[78:81], v[106:109], v[192:195], v[78:81]
	v_mfma_f32_16x16x32_bf16 v[74:77], v[158:161], v[192:195], v[74:77]
	v_mfma_f32_16x16x32_bf16 v[70:73], v[110:113], v[206:209], v[70:73]
	v_mfma_f32_16x16x32_bf16 v[66:69], v[222:225], v[206:209], v[66:69]
	v_mfma_f32_16x16x32_bf16 v[226:229], v[110:113], v[184:187], v[94:97]
	v_mfma_f32_16x16x32_bf16 v[176:179], v[222:225], v[184:187], v[90:93]
	v_mfma_f32_16x16x32_bf16 v[180:183], v[110:113], v[200:203], v[78:81]
	v_mfma_f32_16x16x32_bf16 v[184:187], v[222:225], v[200:203], v[74:77]
	s_setprio 0
	s_barrier
	s_nop 0
	ds_read_b128 v[74:77], v152 offset:16384
	ds_read_b128 v[78:81], v152 offset:18432
	ds_read_b128 v[90:93], v153 offset:16384
	ds_read_b128 v[94:97], v153 offset:18432
	ds_read_b128 v[188:191], v152 offset:20480
	ds_read_b128 v[192:195], v152 offset:22528
	ds_read_b128 v[196:199], v153 offset:20480
	ds_read_b128 v[200:203], v153 offset:22528
	s_waitcnt vmcnt(4)
	s_barrier
	s_waitcnt lgkmcnt(0)
	s_setprio 1
	s_waitcnt lgkmcnt(0)
	v_mfma_f32_16x16x32_bf16 v[62:65], v[142:145], v[74:77], v[62:65]
	v_mfma_f32_16x16x32_bf16 v[58:61], v[154:157], v[74:77], v[58:61]
	v_mfma_f32_16x16x32_bf16 v[54:57], v[142:145], v[78:81], v[54:57]
	v_mfma_f32_16x16x32_bf16 v[50:53], v[154:157], v[78:81], v[50:53]
	v_mfma_f32_16x16x32_bf16 v[38:41], v[142:145], v[192:195], v[38:41]
	v_mfma_f32_16x16x32_bf16 v[34:37], v[154:157], v[192:195], v[34:37]
	v_mfma_f32_16x16x32_bf16 v[62:65], v[146:149], v[90:93], v[62:65]
	v_mfma_f32_16x16x32_bf16 v[58:61], v[172:175], v[90:93], v[58:61]
	v_mfma_f32_16x16x32_bf16 v[54:57], v[146:149], v[94:97], v[54:57]
	v_mfma_f32_16x16x32_bf16 v[50:53], v[172:175], v[94:97], v[50:53]
	v_mfma_f32_16x16x32_bf16 v[46:49], v[142:145], v[188:191], v[46:49]
	v_mfma_f32_16x16x32_bf16 v[42:45], v[154:157], v[188:191], v[42:45]
	v_mfma_f32_16x16x32_bf16 v[38:41], v[146:149], v[200:203], v[38:41]
	v_mfma_f32_16x16x32_bf16 v[34:37], v[172:175], v[200:203], v[34:37]
	v_mfma_f32_16x16x32_bf16 v[206:209], v[146:149], v[196:199], v[46:49]
	v_mfma_f32_16x16x32_bf16 v[230:233], v[172:175], v[196:199], v[42:45]
	s_setprio 0
	s_setprio 1
	v_mfma_f32_16x16x32_bf16 v[22:25], v[106:109], v[78:81], v[22:25]
	v_mfma_f32_16x16x32_bf16 v[18:21], v[158:161], v[78:81], v[18:21]
	v_mfma_f32_16x16x32_bf16 v[6:9], v[106:109], v[192:195], v[6:9]
	v_mfma_f32_16x16x32_bf16 v[2:5], v[158:161], v[192:195], v[2:5]
	v_mfma_f32_16x16x32_bf16 v[30:33], v[106:109], v[74:77], v[30:33]
	v_mfma_f32_16x16x32_bf16 v[26:29], v[158:161], v[74:77], v[26:29]
	v_mfma_f32_16x16x32_bf16 v[22:25], v[110:113], v[94:97], v[22:25]
	v_mfma_f32_16x16x32_bf16 v[18:21], v[222:225], v[94:97], v[18:21]
	v_mfma_f32_16x16x32_bf16 v[14:17], v[106:109], v[188:191], v[14:17]
	v_mfma_f32_16x16x32_bf16 v[10:13], v[158:161], v[188:191], v[10:13]
	v_mfma_f32_16x16x32_bf16 v[6:9], v[110:113], v[200:203], v[6:9]
	v_mfma_f32_16x16x32_bf16 v[2:5], v[222:225], v[200:203], v[2:5]
	v_mfma_f32_16x16x32_bf16 v[142:145], v[110:113], v[90:93], v[30:33]
	v_mfma_f32_16x16x32_bf16 v[146:149], v[222:225], v[90:93], v[26:29]
	v_mfma_f32_16x16x32_bf16 v[154:157], v[110:113], v[196:199], v[14:17]
	v_mfma_f32_16x16x32_bf16 v[172:175], v[222:225], v[196:199], v[10:13]
	s_setprio 0
	s_barrier
	s_nop 0
	ds_read_b128 v[10:13], v163
	ds_read_b128 v[14:17], v164
	ds_read_b128 v[158:161], v165
	ds_read_b128 v[162:165], v166
	ds_read_b128 v[26:29], v152 offset:32768
	ds_read_b128 v[30:33], v152 offset:34816
	ds_read_b128 v[42:45], v153 offset:32768
	ds_read_b128 v[46:49], v153 offset:34816
	ds_read_b128 v[188:191], v152 offset:36864
	ds_read_b128 v[192:195], v152 offset:38912
	ds_read_b128 v[196:199], v153 offset:36864
	ds_read_b128 v[200:203], v153 offset:38912
	s_waitcnt vmcnt(2)
	s_barrier
	s_waitcnt lgkmcnt(0)
	s_setprio 1
	s_waitcnt lgkmcnt(0)
	v_mfma_f32_16x16x32_bf16 v[74:77], v[10:13], v[26:29], v[126:129]
	v_mfma_f32_16x16x32_bf16 v[126:129], v[14:17], v[42:45], v[74:77]
	v_mfma_f32_16x16x32_bf16 v[74:77], v[158:161], v[26:29], v[122:125]
	v_mfma_f32_16x16x32_bf16 v[122:125], v[162:165], v[42:45], v[74:77]
	v_mfma_f32_16x16x32_bf16 v[74:77], v[10:13], v[30:33], v[118:121]
	v_mfma_f32_16x16x32_bf16 v[110:113], v[14:17], v[46:49], v[74:77]
	v_mfma_f32_16x16x32_bf16 v[74:77], v[158:161], v[30:33], v[114:117]
	v_mfma_f32_16x16x32_bf16 v[106:109], v[162:165], v[46:49], v[74:77]
	v_mfma_f32_16x16x32_bf16 v[74:77], v[10:13], v[188:191], v[138:141]
	v_mfma_f32_16x16x32_bf16 v[94:97], v[14:17], v[196:199], v[74:77]
	v_mfma_f32_16x16x32_bf16 v[74:77], v[158:161], v[188:191], v[218:221]
	v_mfma_f32_16x16x32_bf16 v[90:93], v[162:165], v[196:199], v[74:77]
	v_mfma_f32_16x16x32_bf16 v[74:77], v[10:13], v[192:195], v[102:105]
	v_mfma_f32_16x16x32_bf16 v[78:81], v[14:17], v[200:203], v[74:77]
	v_mfma_f32_16x16x32_bf16 v[74:77], v[158:161], v[192:195], v[98:101]
	v_mfma_f32_16x16x32_bf16 v[74:77], v[162:165], v[200:203], v[74:77]
	s_setprio 0
	s_barrier
	ds_read_b128 v[138:141], v167
	ds_read_b128 v[218:221], v168
	ds_read_b128 v[166:169], v169
	ds_read_b128 v[222:225], v170
	s_waitcnt vmcnt(0)
	s_barrier
	s_waitcnt lgkmcnt(0)
	s_setprio 1
	s_waitcnt lgkmcnt(0)
	v_mfma_f32_16x16x32_bf16 v[98:101], v[138:141], v[26:29], v[226:229]
	v_mfma_f32_16x16x32_bf16 v[26:29], v[166:169], v[26:29], v[176:179]
	v_mfma_f32_16x16x32_bf16 v[114:117], v[222:225], v[42:45], v[26:29]
	v_mfma_f32_16x16x32_bf16 v[26:29], v[138:141], v[30:33], v[86:89]
	v_mfma_f32_16x16x32_bf16 v[102:105], v[218:221], v[46:49], v[26:29]
	v_mfma_f32_16x16x32_bf16 v[26:29], v[166:169], v[30:33], v[82:85]
	v_mfma_f32_16x16x32_bf16 v[118:121], v[218:221], v[42:45], v[98:101]
	v_mfma_f32_16x16x32_bf16 v[98:101], v[222:225], v[46:49], v[26:29]
	v_mfma_f32_16x16x32_bf16 v[26:29], v[138:141], v[188:191], v[180:183]
	v_mfma_f32_16x16x32_bf16 v[86:89], v[218:221], v[196:199], v[26:29]
	v_mfma_f32_16x16x32_bf16 v[26:29], v[166:169], v[188:191], v[184:187]
	v_mfma_f32_16x16x32_bf16 v[82:85], v[222:225], v[196:199], v[26:29]
	v_mfma_f32_16x16x32_bf16 v[26:29], v[138:141], v[192:195], v[70:73]
	v_mfma_f32_16x16x32_bf16 v[70:73], v[218:221], v[200:203], v[26:29]
	v_mfma_f32_16x16x32_bf16 v[26:29], v[166:169], v[192:195], v[66:69]
	v_mfma_f32_16x16x32_bf16 v[66:69], v[222:225], v[200:203], v[26:29]
	s_setprio 0
	s_barrier
	ds_read_b128 v[176:179], v152 offset:49152
	ds_read_b128 v[180:183], v152 offset:51200
	ds_read_b128 v[184:187], v153 offset:49152
	ds_read_b128 v[188:191], v153 offset:51200
	ds_read_b128 v[192:195], v152 offset:53248
	ds_read_b128 v[196:199], v152 offset:55296
	ds_read_b128 v[200:203], v153 offset:53248
	ds_read_b128 v[150:153], v153 offset:55296
	s_barrier
	s_waitcnt lgkmcnt(0)
	s_setprio 1
	s_waitcnt lgkmcnt(0)
	v_mfma_f32_16x16x32_bf16 v[26:29], v[10:13], v[176:179], v[62:65]
	v_mfma_f32_16x16x32_bf16 v[62:65], v[14:17], v[184:187], v[26:29]
	v_mfma_f32_16x16x32_bf16 v[26:29], v[158:161], v[176:179], v[58:61]
	v_mfma_f32_16x16x32_bf16 v[58:61], v[162:165], v[184:187], v[26:29]
	v_mfma_f32_16x16x32_bf16 v[26:29], v[10:13], v[180:183], v[54:57]
	v_mfma_f32_16x16x32_bf16 v[46:49], v[14:17], v[188:191], v[26:29]
	v_mfma_f32_16x16x32_bf16 v[26:29], v[158:161], v[180:183], v[50:53]
	v_mfma_f32_16x16x32_bf16 v[42:45], v[162:165], v[188:191], v[26:29]
	v_mfma_f32_16x16x32_bf16 v[26:29], v[10:13], v[192:195], v[206:209]
	v_mfma_f32_16x16x32_bf16 v[10:13], v[10:13], v[196:199], v[38:41]
	v_mfma_f32_16x16x32_bf16 v[30:33], v[14:17], v[200:203], v[26:29]
	v_mfma_f32_16x16x32_bf16 v[26:29], v[158:161], v[192:195], v[230:233]
	v_mfma_f32_16x16x32_bf16 v[14:17], v[14:17], v[150:153], v[10:13]
	v_mfma_f32_16x16x32_bf16 v[10:13], v[158:161], v[196:199], v[34:37]
	v_mfma_f32_16x16x32_bf16 v[26:29], v[162:165], v[200:203], v[26:29]
	v_mfma_f32_16x16x32_bf16 v[10:13], v[162:165], v[150:153], v[10:13]
	s_setprio 0
	s_setprio 1
	v_mfma_f32_16x16x32_bf16 v[34:37], v[138:141], v[176:179], v[142:145]
	v_mfma_f32_16x16x32_bf16 v[54:57], v[218:221], v[184:187], v[34:37]
	v_mfma_f32_16x16x32_bf16 v[34:37], v[166:169], v[176:179], v[146:149]
	v_mfma_f32_16x16x32_bf16 v[18:21], v[166:169], v[180:183], v[18:21]
	v_mfma_f32_16x16x32_bf16 v[50:53], v[222:225], v[184:187], v[34:37]
	v_mfma_f32_16x16x32_bf16 v[22:25], v[138:141], v[180:183], v[22:25]
	v_mfma_f32_16x16x32_bf16 v[34:37], v[222:225], v[188:191], v[18:21]
	v_mfma_f32_16x16x32_bf16 v[18:21], v[138:141], v[192:195], v[154:157]
	v_mfma_f32_16x16x32_bf16 v[38:41], v[218:221], v[188:191], v[22:25]
	v_mfma_f32_16x16x32_bf16 v[22:25], v[218:221], v[200:203], v[18:21]
	v_mfma_f32_16x16x32_bf16 v[18:21], v[166:169], v[192:195], v[172:175]
	v_mfma_f32_16x16x32_bf16 v[6:9], v[138:141], v[196:199], v[6:9]
	v_mfma_f32_16x16x32_bf16 v[2:5], v[166:169], v[196:199], v[2:5]
	v_mfma_f32_16x16x32_bf16 v[18:21], v[222:225], v[200:203], v[18:21]
	v_mfma_f32_16x16x32_bf16 v[6:9], v[218:221], v[150:153], v[6:9]
	v_mfma_f32_16x16x32_bf16 v[2:5], v[222:225], v[150:153], v[2:5]
	s_setprio 0
	s_cmpk_gt_u32 s0, 0xff
	s_barrier
	s_cbranch_scc1 .LBB0_600
	s_barrier

.LBB0_633:
	v_mov_b32_e32 v138, v204
	s_waitcnt vmcnt(0)
	v_and_b32_e32 v0, 15, v138
	v_ashrrev_i32_e32 v139, 2, v138
	v_and_b32_e32 v139, 0xffffffc0, v139
	v_or_b32_e32 v140, s8, v0
	v_add_u32_e32 v142, v140, v139
	v_ashrrev_i32_e32 v143, 31, v142
	v_lshl_add_u64 v[142:143], v[142:143], 3, v[132:133]
	s_barrier
	flat_load_dwordx2 v[142:143], v[142:143]
	v_or_b32_e32 v162, 16, v139
	v_add_u32_e32 v162, v162, v140
	v_ashrrev_i32_e32 v163, 31, v162
	v_lshl_add_u64 v[162:163], v[162:163], 3, v[132:133]
	flat_load_dwordx2 v[164:165], v[162:163]
	v_or_b32_e32 v162, 32, v139
	v_add_u32_e32 v162, v162, v140
	v_ashrrev_i32_e32 v163, 31, v162
	v_lshl_add_u64 v[162:163], v[162:163], 3, v[132:133]
	flat_load_dwordx2 v[166:167], v[162:163]
	v_or_b32_e32 v162, 48, v139
	v_add_u32_e32 v162, v162, v140
	v_ashrrev_i32_e32 v163, 31, v162
	v_lshl_add_u64 v[162:163], v[162:163], 3, v[132:133]
	flat_load_dwordx2 v[168:169], v[162:163]
	v_add_u32_e32 v162, 0x80, v139
	v_add_u32_e32 v162, v162, v140
	v_ashrrev_i32_e32 v163, 31, v162
	v_lshl_add_u64 v[162:163], v[162:163], 3, v[132:133]
	flat_load_dwordx2 v[170:171], v[162:163]
	v_add_u32_e32 v162, 0x90, v139
	v_add_u32_e32 v162, v162, v140
	v_ashrrev_i32_e32 v163, 31, v162
	v_lshl_add_u64 v[162:163], v[162:163], 3, v[132:133]
	flat_load_dwordx2 v[172:173], v[162:163]
	v_add_u32_e32 v162, 0xa0, v139
	v_add_u32_e32 v162, v162, v140
	v_ashrrev_i32_e32 v163, 31, v162
	v_lshl_add_u64 v[162:163], v[162:163], 3, v[132:133]
	flat_load_dwordx2 v[174:175], v[162:163]
	v_add_u32_e32 v162, 0xb0, v139
	v_add_u32_e32 v162, v162, v140
	v_ashrrev_i32_e32 v163, 31, v162
	v_lshl_add_u64 v[162:163], v[162:163], 3, v[132:133]
	flat_load_dwordx2 v[176:177], v[162:163]
	v_mov_b32_e32 v144, 0x358637bd
	s_lshl_b32 s0, s16, 2
	s_mul_i32 s1, s16, 0x20040
	s_mul_hi_i32 s2, s0, 0x8010
	s_add_u32 s0, s1, s8
	s_addc_u32 s1, s2, s9
	s_lshl_b64 s[0:1], s[0:1], 7
	v_mov_b32_e32 v253, 0x358637bd
	s_add_i32 s15, s15, s29
	s_waitcnt vmcnt(0) lgkmcnt(0)
	v_ffbh_u32_e32 v141, v143
	v_min_u32_e32 v141, 32, v141
	v_lshlrev_b64 v[142:143], v141, v[142:143]
	v_min_u32_e32 v142, 1, v142
	v_or_b32_e32 v142, v143, v142
	v_cvt_f32_u32_e32 v142, v142
	v_sub_u32_e32 v141, 32, v141
	v_ldexp_f32 v141, v142, v141
	v_fmamk_f32 v141, v141, 0x30000000, v144
	v_cmp_gt_f32_e32 vcc, s33, v141
	v_mul_f32_e32 v142, 0x4b800000, v141
	s_nop 0
	v_cndmask_b32_e32 v141, v141, v142, vcc
	v_rsq_f32_e32 v141, v141
	s_nop 0
	v_mul_f32_e32 v142, 0x45800000, v141
	v_cndmask_b32_e32 v141, v141, v142, vcc
	v_mul_f32_e32 v126, v126, v141
	v_mul_f32_e32 v127, v127, v141
	v_max_f32_e32 v126, 0, v126
	v_max_f32_e32 v127, 0, v127
	v_mul_f32_e32 v128, v128, v141
	v_max_f32_e32 v128, 0, v128
	v_mul_f32_e32 v129, v129, v141
	v_mul_f32_e32 v126, v126, v126
	v_mul_f32_e32 v127, v127, v127
	v_mul_f32_e32 v118, v118, v141
	v_mul_f32_e32 v119, v119, v141
	v_mul_f32_e32 v120, v120, v141
	v_mul_f32_e32 v121, v121, v141
	v_or_b32_e32 v142, v139, v0
	v_max_f32_e32 v129, 0, v129
	v_mul_f32_e32 v143, v128, v128
	v_cvt_pk_bf16_f32 v128, v126, v127
	v_lshrrev_b32_e32 v126, 1, v138
	v_max_f32_e32 v118, 0, v118
	v_max_f32_e32 v119, 0, v119
	v_max_f32_e32 v120, 0, v120
	v_max_f32_e32 v121, 0, v121
	v_mul_lo_u32 v142, v142, s72
	v_mul_f32_e32 v129, v129, v129
	v_and_b32_e32 v126, 24, v126
	v_and_b32_e32 v127, 0xc0, v138
	v_mul_f32_e32 v118, v118, v118
	v_mul_f32_e32 v119, v119, v119
	v_mul_f32_e32 v120, v120, v120
	v_mul_f32_e32 v121, v121, v121
	v_cvt_pk_bf16_f32 v129, v143, v129
	v_add3_u32 v142, v142, v127, v126
	v_cvt_pk_bf16_f32 v118, v118, v119
	v_cvt_pk_bf16_f32 v119, v120, v121
	ds_write2_b64 v142, v[128:129], v[118:119] offset1:4
	v_mul_f32_e32 v118, v122, v141
	v_mul_f32_e32 v119, v123, v141
	v_mul_f32_e32 v120, v124, v141
	v_mul_f32_e32 v121, v125, v141
	v_mul_f32_e32 v114, v114, v141
	v_mul_f32_e32 v115, v115, v141
	v_mul_f32_e32 v116, v116, v141
	v_mul_f32_e32 v117, v117, v141
	v_max_f32_e32 v118, 0, v118
	v_max_f32_e32 v119, 0, v119
	v_max_f32_e32 v120, 0, v120
	v_max_f32_e32 v121, 0, v121
	v_max_f32_e32 v114, 0, v114
	v_max_f32_e32 v115, 0, v115
	v_max_f32_e32 v116, 0, v116
	v_max_f32_e32 v117, 0, v117
	v_mul_f32_e32 v118, v118, v118
	v_mul_f32_e32 v119, v119, v119
	v_mul_f32_e32 v120, v120, v120
	v_mul_f32_e32 v121, v121, v121
	v_mul_f32_e32 v114, v114, v114
	v_mul_f32_e32 v115, v115, v115
	v_mul_f32_e32 v116, v116, v116
	v_mul_f32_e32 v117, v117, v117
	v_cvt_pk_bf16_f32 v118, v118, v119
	v_cvt_pk_bf16_f32 v119, v120, v121
	v_cvt_pk_bf16_f32 v114, v114, v115
	v_cvt_pk_bf16_f32 v115, v116, v117
	v_or_b32_e32 v116, 16, v139
	ds_write2_b64 v142, v[118:119], v[114:115] offset0:32 offset1:36
	v_add_u32_e32 v114, v116, v140
	v_ashrrev_i32_e32 v115, 31, v114
	v_lshl_add_u64 v[114:115], v[114:115], 3, v[132:133]
	v_mov_b32_e32 v114, v164
	v_mov_b32_e32 v115, v165
	v_ffbh_u32_e32 v117, v115
	v_min_u32_e32 v117, 32, v117
	v_lshlrev_b64 v[114:115], v117, v[114:115]
	v_min_u32_e32 v114, 1, v114
	v_or_b32_e32 v114, v115, v114
	v_cvt_f32_u32_e32 v114, v114
	v_sub_u32_e32 v115, 32, v117
	v_ldexp_f32 v114, v114, v115
	v_fmamk_f32 v114, v114, 0x30000000, v144
	v_cmp_gt_f32_e32 vcc, s33, v114
	v_mul_f32_e32 v115, 0x4b800000, v114
	s_nop 0
	v_cndmask_b32_e32 v114, v114, v115, vcc
	v_rsq_f32_e32 v114, v114
	s_nop 0
	v_mul_f32_e32 v115, 0x45800000, v114
	v_cndmask_b32_e32 v114, v114, v115, vcc
	v_mul_f32_e32 v110, v110, v114
	v_mul_f32_e32 v111, v111, v114
	v_mul_f32_e32 v112, v112, v114
	v_mul_f32_e32 v113, v113, v114
	v_mul_f32_e32 v102, v102, v114
	v_mul_f32_e32 v103, v103, v114
	v_mul_f32_e32 v104, v104, v114
	v_mul_f32_e32 v105, v105, v114
	v_or_b32_e32 v115, v116, v0
	v_max_f32_e32 v110, 0, v110
	v_max_f32_e32 v111, 0, v111
	v_max_f32_e32 v112, 0, v112
	v_max_f32_e32 v113, 0, v113
	v_max_f32_e32 v102, 0, v102
	v_max_f32_e32 v103, 0, v103
	v_max_f32_e32 v104, 0, v104
	v_max_f32_e32 v105, 0, v105
	v_mul_lo_u32 v115, v115, s72
	v_mul_f32_e32 v110, v110, v110
	v_mul_f32_e32 v111, v111, v111
	v_mul_f32_e32 v112, v112, v112
	v_mul_f32_e32 v113, v113, v113
	v_mul_f32_e32 v102, v102, v102
	v_mul_f32_e32 v103, v103, v103
	v_mul_f32_e32 v104, v104, v104
	v_mul_f32_e32 v105, v105, v105
	v_cvt_pk_bf16_f32 v110, v110, v111
	v_cvt_pk_bf16_f32 v111, v112, v113
	v_add3_u32 v112, v115, v127, v126
	v_cvt_pk_bf16_f32 v102, v102, v103
	v_cvt_pk_bf16_f32 v103, v104, v105
	ds_write2_b64 v112, v[110:111], v[102:103] offset1:4
	v_mul_f32_e32 v102, v106, v114
	v_mul_f32_e32 v103, v107, v114
	v_mul_f32_e32 v104, v108, v114
	v_mul_f32_e32 v105, v109, v114
	v_mul_f32_e32 v98, v98, v114
	v_mul_f32_e32 v99, v99, v114
	v_mul_f32_e32 v100, v100, v114
	v_mul_f32_e32 v101, v101, v114
	v_max_f32_e32 v102, 0, v102
	v_max_f32_e32 v103, 0, v103
	v_max_f32_e32 v104, 0, v104
	v_max_f32_e32 v105, 0, v105
	v_max_f32_e32 v98, 0, v98
	v_max_f32_e32 v99, 0, v99
	v_max_f32_e32 v100, 0, v100
	v_max_f32_e32 v101, 0, v101
	v_mul_f32_e32 v102, v102, v102
	v_mul_f32_e32 v103, v103, v103
	v_mul_f32_e32 v104, v104, v104
	v_mul_f32_e32 v105, v105, v105
	v_mul_f32_e32 v98, v98, v98
	v_mul_f32_e32 v99, v99, v99
	v_mul_f32_e32 v100, v100, v100
	v_mul_f32_e32 v101, v101, v101
	v_cvt_pk_bf16_f32 v102, v102, v103
	v_cvt_pk_bf16_f32 v103, v104, v105
	v_cvt_pk_bf16_f32 v98, v98, v99
	v_cvt_pk_bf16_f32 v99, v100, v101
	v_or_b32_e32 v100, 32, v139
	ds_write2_b64 v112, v[102:103], v[98:99] offset0:32 offset1:36
	v_add_u32_e32 v98, v100, v140
	v_ashrrev_i32_e32 v99, 31, v98
	v_lshl_add_u64 v[98:99], v[98:99], 3, v[132:133]
	v_mov_b32_e32 v98, v166
	v_mov_b32_e32 v99, v167
	v_ffbh_u32_e32 v101, v99
	v_min_u32_e32 v101, 32, v101
	v_lshlrev_b64 v[98:99], v101, v[98:99]
	v_min_u32_e32 v98, 1, v98
	v_or_b32_e32 v98, v99, v98
	v_cvt_f32_u32_e32 v98, v98
	v_sub_u32_e32 v99, 32, v101
	v_ldexp_f32 v98, v98, v99
	v_fmamk_f32 v98, v98, 0x30000000, v144
	v_cmp_gt_f32_e32 vcc, s33, v98
	v_mul_f32_e32 v99, 0x4b800000, v98
	s_nop 0
	v_cndmask_b32_e32 v98, v98, v99, vcc
	v_rsq_f32_e32 v98, v98
	s_nop 0
	v_mul_f32_e32 v99, 0x45800000, v98
	v_cndmask_b32_e32 v98, v98, v99, vcc
	v_mul_f32_e32 v94, v94, v98
	v_mul_f32_e32 v95, v95, v98
	v_mul_f32_e32 v96, v96, v98
	v_mul_f32_e32 v97, v97, v98
	v_mul_f32_e32 v86, v86, v98
	v_mul_f32_e32 v87, v87, v98
	v_mul_f32_e32 v88, v88, v98
	v_mul_f32_e32 v89, v89, v98
	v_or_b32_e32 v99, v100, v0
	v_max_f32_e32 v94, 0, v94
	v_max_f32_e32 v95, 0, v95
	v_max_f32_e32 v96, 0, v96
	v_max_f32_e32 v97, 0, v97
	v_max_f32_e32 v86, 0, v86
	v_max_f32_e32 v87, 0, v87
	v_max_f32_e32 v88, 0, v88
	v_max_f32_e32 v89, 0, v89
	v_mul_lo_u32 v99, v99, s72
	v_mul_f32_e32 v94, v94, v94
	v_mul_f32_e32 v95, v95, v95
	v_mul_f32_e32 v96, v96, v96
	v_mul_f32_e32 v97, v97, v97
	v_mul_f32_e32 v86, v86, v86
	v_mul_f32_e32 v87, v87, v87
	v_mul_f32_e32 v88, v88, v88
	v_mul_f32_e32 v89, v89, v89
	v_cvt_pk_bf16_f32 v94, v94, v95
	v_cvt_pk_bf16_f32 v95, v96, v97
	v_add3_u32 v96, v99, v127, v126
	v_cvt_pk_bf16_f32 v86, v86, v87
	v_cvt_pk_bf16_f32 v87, v88, v89
	ds_write2_b64 v96, v[94:95], v[86:87] offset1:4
	v_mul_f32_e32 v86, v90, v98
	v_mul_f32_e32 v87, v91, v98
	v_mul_f32_e32 v88, v92, v98
	v_mul_f32_e32 v89, v93, v98
	v_mul_f32_e32 v82, v82, v98
	v_mul_f32_e32 v83, v83, v98
	v_mul_f32_e32 v84, v84, v98
	v_mul_f32_e32 v85, v85, v98
	v_max_f32_e32 v86, 0, v86
	v_max_f32_e32 v87, 0, v87
	v_max_f32_e32 v88, 0, v88
	v_max_f32_e32 v89, 0, v89
	v_max_f32_e32 v82, 0, v82
	v_max_f32_e32 v83, 0, v83
	v_max_f32_e32 v84, 0, v84
	v_max_f32_e32 v85, 0, v85
	v_mul_f32_e32 v86, v86, v86
	v_mul_f32_e32 v87, v87, v87
	v_mul_f32_e32 v88, v88, v88
	v_mul_f32_e32 v89, v89, v89
	v_mul_f32_e32 v82, v82, v82
	v_mul_f32_e32 v83, v83, v83
	v_mul_f32_e32 v84, v84, v84
	v_mul_f32_e32 v85, v85, v85
	v_cvt_pk_bf16_f32 v86, v86, v87
	v_cvt_pk_bf16_f32 v87, v88, v89
	v_cvt_pk_bf16_f32 v82, v82, v83
	v_cvt_pk_bf16_f32 v83, v84, v85
	v_or_b32_e32 v84, 48, v139
	ds_write2_b64 v96, v[86:87], v[82:83] offset0:32 offset1:36
	v_add_u32_e32 v82, v84, v140
	v_ashrrev_i32_e32 v83, 31, v82
	v_lshl_add_u64 v[82:83], v[82:83], 3, v[132:133]
	v_mov_b32_e32 v82, v168
	v_mov_b32_e32 v83, v169
	v_ffbh_u32_e32 v85, v83
	v_min_u32_e32 v85, 32, v85
	v_lshlrev_b64 v[82:83], v85, v[82:83]
	v_min_u32_e32 v82, 1, v82
	v_or_b32_e32 v82, v83, v82
	v_cvt_f32_u32_e32 v82, v82
	v_sub_u32_e32 v83, 32, v85
	v_ldexp_f32 v82, v82, v83
	v_fmamk_f32 v82, v82, 0x30000000, v144
	v_cmp_gt_f32_e32 vcc, s33, v82
	v_mul_f32_e32 v83, 0x4b800000, v82
	s_nop 0
	v_cndmask_b32_e32 v82, v82, v83, vcc
	v_rsq_f32_e32 v82, v82
	s_nop 0
	v_mul_f32_e32 v83, 0x45800000, v82
	v_cndmask_b32_e32 v82, v82, v83, vcc
	v_mul_f32_e32 v78, v78, v82
	v_mul_f32_e32 v79, v79, v82
	v_mul_f32_e32 v80, v80, v82
	v_mul_f32_e32 v81, v81, v82
	v_mul_f32_e32 v70, v70, v82
	v_mul_f32_e32 v71, v71, v82
	v_mul_f32_e32 v72, v72, v82
	v_mul_f32_e32 v73, v73, v82
	v_or_b32_e32 v83, v84, v0
	v_max_f32_e32 v78, 0, v78
	v_max_f32_e32 v79, 0, v79
	v_max_f32_e32 v80, 0, v80
	v_max_f32_e32 v81, 0, v81
	v_max_f32_e32 v70, 0, v70
	v_max_f32_e32 v71, 0, v71
	v_max_f32_e32 v72, 0, v72
	v_max_f32_e32 v73, 0, v73
	v_mul_lo_u32 v83, v83, s72
	v_mul_f32_e32 v78, v78, v78
	v_mul_f32_e32 v79, v79, v79
	v_mul_f32_e32 v80, v80, v80
	v_mul_f32_e32 v81, v81, v81
	v_mul_f32_e32 v70, v70, v70
	v_mul_f32_e32 v71, v71, v71
	v_mul_f32_e32 v72, v72, v72
	v_mul_f32_e32 v73, v73, v73
	v_cvt_pk_bf16_f32 v78, v78, v79
	v_cvt_pk_bf16_f32 v79, v80, v81
	v_add3_u32 v80, v83, v127, v126
	v_cvt_pk_bf16_f32 v70, v70, v71
	v_cvt_pk_bf16_f32 v71, v72, v73
	ds_write2_b64 v80, v[78:79], v[70:71] offset1:4
	v_mul_f32_e32 v70, v74, v82
	v_mul_f32_e32 v71, v75, v82
	v_mul_f32_e32 v72, v76, v82
	v_mul_f32_e32 v73, v77, v82
	v_mul_f32_e32 v66, v66, v82
	v_mul_f32_e32 v67, v67, v82
	v_mul_f32_e32 v68, v68, v82
	v_mul_f32_e32 v69, v69, v82
	v_max_f32_e32 v70, 0, v70
	v_max_f32_e32 v71, 0, v71
	v_max_f32_e32 v72, 0, v72
	v_max_f32_e32 v73, 0, v73
	v_max_f32_e32 v66, 0, v66
	v_max_f32_e32 v67, 0, v67
	v_max_f32_e32 v68, 0, v68
	v_max_f32_e32 v69, 0, v69
	v_mul_f32_e32 v70, v70, v70
	v_mul_f32_e32 v71, v71, v71
	v_mul_f32_e32 v72, v72, v72
	v_mul_f32_e32 v73, v73, v73
	v_mul_f32_e32 v66, v66, v66
	v_mul_f32_e32 v67, v67, v67
	v_mul_f32_e32 v68, v68, v68
	v_mul_f32_e32 v69, v69, v69
	v_cvt_pk_bf16_f32 v70, v70, v71
	v_cvt_pk_bf16_f32 v71, v72, v73
	v_cvt_pk_bf16_f32 v66, v66, v67
	v_cvt_pk_bf16_f32 v67, v68, v69
	v_add_u32_e32 v68, 0x80, v139
	ds_write2_b64 v80, v[70:71], v[66:67] offset0:32 offset1:36
	v_add_u32_e32 v66, v68, v140
	v_ashrrev_i32_e32 v67, 31, v66
	v_lshl_add_u64 v[66:67], v[66:67], 3, v[132:133]
	v_mov_b32_e32 v66, v170
	v_mov_b32_e32 v67, v171
	v_ffbh_u32_e32 v69, v67
	v_min_u32_e32 v69, 32, v69
	v_lshlrev_b64 v[66:67], v69, v[66:67]
	v_min_u32_e32 v66, 1, v66
	v_or_b32_e32 v66, v67, v66
	v_cvt_f32_u32_e32 v66, v66
	v_sub_u32_e32 v67, 32, v69
	v_ldexp_f32 v66, v66, v67
	v_fmamk_f32 v66, v66, 0x30000000, v144
	v_cmp_gt_f32_e32 vcc, s33, v66
	v_mul_f32_e32 v67, 0x4b800000, v66
	s_nop 0
	v_cndmask_b32_e32 v66, v66, v67, vcc
	v_rsq_f32_e32 v66, v66
	s_nop 0
	v_mul_f32_e32 v67, 0x45800000, v66
	v_cndmask_b32_e32 v66, v66, v67, vcc
	v_mul_f32_e32 v62, v62, v66
	v_mul_f32_e32 v63, v63, v66
	v_mul_f32_e32 v64, v64, v66
	v_mul_f32_e32 v65, v65, v66
	v_mul_f32_e32 v54, v54, v66
	v_mul_f32_e32 v55, v55, v66
	v_mul_f32_e32 v56, v56, v66
	v_mul_f32_e32 v57, v57, v66
	v_or_b32_e32 v67, v68, v0
	v_max_f32_e32 v62, 0, v62
	v_max_f32_e32 v63, 0, v63
	v_max_f32_e32 v64, 0, v64
	v_max_f32_e32 v65, 0, v65
	v_max_f32_e32 v54, 0, v54
	v_max_f32_e32 v55, 0, v55
	v_max_f32_e32 v56, 0, v56
	v_max_f32_e32 v57, 0, v57
	v_mul_lo_u32 v67, v67, s72
	v_mul_f32_e32 v62, v62, v62
	v_mul_f32_e32 v63, v63, v63
	v_mul_f32_e32 v64, v64, v64
	v_mul_f32_e32 v65, v65, v65
	v_mul_f32_e32 v54, v54, v54
	v_mul_f32_e32 v55, v55, v55
	v_mul_f32_e32 v56, v56, v56
	v_mul_f32_e32 v57, v57, v57
	v_cvt_pk_bf16_f32 v62, v62, v63
	v_cvt_pk_bf16_f32 v63, v64, v65
	v_add3_u32 v64, v67, v127, v126
	v_cvt_pk_bf16_f32 v54, v54, v55
	v_cvt_pk_bf16_f32 v55, v56, v57
	ds_write2_b64 v64, v[62:63], v[54:55] offset1:4
	v_mul_f32_e32 v54, v58, v66
	v_mul_f32_e32 v55, v59, v66
	v_mul_f32_e32 v56, v60, v66
	v_mul_f32_e32 v57, v61, v66
	v_mul_f32_e32 v50, v50, v66
	v_mul_f32_e32 v51, v51, v66
	v_mul_f32_e32 v52, v52, v66
	v_mul_f32_e32 v53, v53, v66
	v_max_f32_e32 v54, 0, v54
	v_max_f32_e32 v55, 0, v55
	v_max_f32_e32 v56, 0, v56
	v_max_f32_e32 v57, 0, v57
	v_max_f32_e32 v50, 0, v50
	v_max_f32_e32 v51, 0, v51
	v_max_f32_e32 v52, 0, v52
	v_max_f32_e32 v53, 0, v53
	v_mul_f32_e32 v54, v54, v54
	v_mul_f32_e32 v55, v55, v55
	v_mul_f32_e32 v56, v56, v56
	v_mul_f32_e32 v57, v57, v57
	v_mul_f32_e32 v50, v50, v50
	v_mul_f32_e32 v51, v51, v51
	v_mul_f32_e32 v52, v52, v52
	v_mul_f32_e32 v53, v53, v53
	v_cvt_pk_bf16_f32 v54, v54, v55
	v_cvt_pk_bf16_f32 v55, v56, v57
	v_cvt_pk_bf16_f32 v50, v50, v51
	v_cvt_pk_bf16_f32 v51, v52, v53
	v_add_u32_e32 v52, 0x90, v139
	ds_write2_b64 v64, v[54:55], v[50:51] offset0:32 offset1:36
	v_add_u32_e32 v50, v52, v140
	v_ashrrev_i32_e32 v51, 31, v50
	v_lshl_add_u64 v[50:51], v[50:51], 3, v[132:133]
	v_mov_b32_e32 v50, v172
	v_mov_b32_e32 v51, v173
	v_ffbh_u32_e32 v53, v51
	v_min_u32_e32 v53, 32, v53
	v_lshlrev_b64 v[50:51], v53, v[50:51]
	v_min_u32_e32 v50, 1, v50
	v_or_b32_e32 v50, v51, v50
	v_cvt_f32_u32_e32 v50, v50
	v_sub_u32_e32 v51, 32, v53
	v_ldexp_f32 v50, v50, v51
	v_fmamk_f32 v50, v50, 0x30000000, v144
	v_cmp_gt_f32_e32 vcc, s33, v50
	v_mul_f32_e32 v51, 0x4b800000, v50
	s_nop 0
	v_cndmask_b32_e32 v50, v50, v51, vcc
	v_rsq_f32_e32 v50, v50
	s_nop 0
	v_mul_f32_e32 v51, 0x45800000, v50
	v_cndmask_b32_e32 v50, v50, v51, vcc
	v_mul_f32_e32 v46, v46, v50
	v_mul_f32_e32 v47, v47, v50
	v_mul_f32_e32 v48, v48, v50
	v_mul_f32_e32 v49, v49, v50
	v_mul_f32_e32 v38, v38, v50
	v_mul_f32_e32 v39, v39, v50
	v_mul_f32_e32 v40, v40, v50
	v_mul_f32_e32 v41, v41, v50
	v_or_b32_e32 v51, v52, v0
	v_max_f32_e32 v46, 0, v46
	v_max_f32_e32 v47, 0, v47
	v_max_f32_e32 v48, 0, v48
	v_max_f32_e32 v49, 0, v49
	v_max_f32_e32 v38, 0, v38
	v_max_f32_e32 v39, 0, v39
	v_max_f32_e32 v40, 0, v40
	v_max_f32_e32 v41, 0, v41
	v_mul_lo_u32 v51, v51, s72
	v_mul_f32_e32 v46, v46, v46
	v_mul_f32_e32 v47, v47, v47
	v_mul_f32_e32 v48, v48, v48
	v_mul_f32_e32 v49, v49, v49
	v_mul_f32_e32 v38, v38, v38
	v_mul_f32_e32 v39, v39, v39
	v_mul_f32_e32 v40, v40, v40
	v_mul_f32_e32 v41, v41, v41
	v_cvt_pk_bf16_f32 v46, v46, v47
	v_cvt_pk_bf16_f32 v47, v48, v49
	v_add3_u32 v48, v51, v127, v126
	v_cvt_pk_bf16_f32 v38, v38, v39
	v_cvt_pk_bf16_f32 v39, v40, v41
	ds_write2_b64 v48, v[46:47], v[38:39] offset1:4
	v_mul_f32_e32 v38, v42, v50
	v_mul_f32_e32 v39, v43, v50
	v_mul_f32_e32 v40, v44, v50
	v_mul_f32_e32 v41, v45, v50
	v_mul_f32_e32 v34, v34, v50
	v_mul_f32_e32 v35, v35, v50
	v_mul_f32_e32 v36, v36, v50
	v_mul_f32_e32 v37, v37, v50
	v_max_f32_e32 v38, 0, v38
	v_max_f32_e32 v39, 0, v39
	v_max_f32_e32 v40, 0, v40
	v_max_f32_e32 v41, 0, v41
	v_max_f32_e32 v34, 0, v34
	v_max_f32_e32 v35, 0, v35
	v_max_f32_e32 v36, 0, v36
	v_max_f32_e32 v37, 0, v37
	v_mul_f32_e32 v38, v38, v38
	v_mul_f32_e32 v39, v39, v39
	v_mul_f32_e32 v40, v40, v40
	v_mul_f32_e32 v41, v41, v41
	v_mul_f32_e32 v34, v34, v34
	v_mul_f32_e32 v35, v35, v35
	v_mul_f32_e32 v36, v36, v36
	v_mul_f32_e32 v37, v37, v37
	v_cvt_pk_bf16_f32 v38, v38, v39
	v_cvt_pk_bf16_f32 v39, v40, v41
	v_cvt_pk_bf16_f32 v34, v34, v35
	v_cvt_pk_bf16_f32 v35, v36, v37
	v_add_u32_e32 v36, 0xa0, v139
	ds_write2_b64 v48, v[38:39], v[34:35] offset0:32 offset1:36
	v_add_u32_e32 v34, v36, v140
	v_ashrrev_i32_e32 v35, 31, v34
	v_lshl_add_u64 v[34:35], v[34:35], 3, v[132:133]
	v_mov_b32_e32 v34, v174
	v_mov_b32_e32 v35, v175
	v_ffbh_u32_e32 v37, v35
	v_min_u32_e32 v37, 32, v37
	v_lshlrev_b64 v[34:35], v37, v[34:35]
	v_min_u32_e32 v34, 1, v34
	v_or_b32_e32 v34, v35, v34
	v_cvt_f32_u32_e32 v34, v34
	v_sub_u32_e32 v35, 32, v37
	v_ldexp_f32 v34, v34, v35
	v_fmamk_f32 v34, v34, 0x30000000, v144
	v_cmp_gt_f32_e32 vcc, s33, v34
	v_mul_f32_e32 v35, 0x4b800000, v34
	s_nop 0
	v_cndmask_b32_e32 v34, v34, v35, vcc
	v_rsq_f32_e32 v34, v34
	s_nop 0
	v_mul_f32_e32 v35, 0x45800000, v34
	v_cndmask_b32_e32 v34, v34, v35, vcc
	v_mul_f32_e32 v30, v30, v34
	v_mul_f32_e32 v31, v31, v34
	v_mul_f32_e32 v32, v32, v34
	v_mul_f32_e32 v33, v33, v34
	v_mul_f32_e32 v22, v22, v34
	v_mul_f32_e32 v23, v23, v34
	v_mul_f32_e32 v24, v24, v34
	v_mul_f32_e32 v25, v25, v34
	v_or_b32_e32 v35, v36, v0
	v_max_f32_e32 v30, 0, v30
	v_max_f32_e32 v31, 0, v31
	v_max_f32_e32 v32, 0, v32
	v_max_f32_e32 v33, 0, v33
	v_max_f32_e32 v22, 0, v22
	v_max_f32_e32 v23, 0, v23
	v_max_f32_e32 v24, 0, v24
	v_max_f32_e32 v25, 0, v25
	v_mul_lo_u32 v35, v35, s72
	v_mul_f32_e32 v30, v30, v30
	v_mul_f32_e32 v31, v31, v31
	v_mul_f32_e32 v32, v32, v32
	v_mul_f32_e32 v33, v33, v33
	v_mul_f32_e32 v22, v22, v22
	v_mul_f32_e32 v23, v23, v23
	v_mul_f32_e32 v24, v24, v24
	v_mul_f32_e32 v25, v25, v25
	v_cvt_pk_bf16_f32 v30, v30, v31
	v_cvt_pk_bf16_f32 v31, v32, v33
	v_add3_u32 v32, v35, v127, v126
	v_cvt_pk_bf16_f32 v22, v22, v23
	v_cvt_pk_bf16_f32 v23, v24, v25
	ds_write2_b64 v32, v[30:31], v[22:23] offset1:4
	v_mul_f32_e32 v22, v26, v34
	v_mul_f32_e32 v23, v27, v34
	v_mul_f32_e32 v24, v28, v34
	v_mul_f32_e32 v25, v29, v34
	v_mul_f32_e32 v18, v18, v34
	v_mul_f32_e32 v19, v19, v34
	v_mul_f32_e32 v20, v20, v34
	v_mul_f32_e32 v21, v21, v34
	v_max_f32_e32 v22, 0, v22
	v_max_f32_e32 v23, 0, v23
	v_max_f32_e32 v24, 0, v24
	v_max_f32_e32 v25, 0, v25
	v_max_f32_e32 v18, 0, v18
	v_max_f32_e32 v19, 0, v19
	v_max_f32_e32 v20, 0, v20
	v_max_f32_e32 v21, 0, v21
	v_mul_f32_e32 v22, v22, v22
	v_mul_f32_e32 v23, v23, v23
	v_mul_f32_e32 v24, v24, v24
	v_mul_f32_e32 v25, v25, v25
	v_mul_f32_e32 v18, v18, v18
	v_mul_f32_e32 v19, v19, v19
	v_mul_f32_e32 v20, v20, v20
	v_mul_f32_e32 v21, v21, v21
	v_cvt_pk_bf16_f32 v22, v22, v23
	v_cvt_pk_bf16_f32 v23, v24, v25
	v_cvt_pk_bf16_f32 v18, v18, v19
	v_cvt_pk_bf16_f32 v19, v20, v21
	v_add_u32_e32 v20, 0xb0, v139
	ds_write2_b64 v32, v[22:23], v[18:19] offset0:32 offset1:36
	v_add_u32_e32 v18, v20, v140
	v_ashrrev_i32_e32 v19, 31, v18
	v_lshl_add_u64 v[18:19], v[18:19], 3, v[132:133]
	v_mov_b32_e32 v18, v176
	v_mov_b32_e32 v19, v177
	v_or_b32_e32 v0, v20, v0
	v_mul_lo_u32 v0, v0, s72
	v_add3_u32 v0, v0, v127, v126
	v_ffbh_u32_e32 v21, v19
	v_min_u32_e32 v21, 32, v21
	v_lshlrev_b64 v[18:19], v21, v[18:19]
	v_min_u32_e32 v18, 1, v18
	v_or_b32_e32 v18, v19, v18
	v_cvt_f32_u32_e32 v18, v18
	v_sub_u32_e32 v19, 32, v21
	v_ldexp_f32 v18, v18, v19
	v_fmamk_f32 v18, v18, 0x30000000, v144
	v_cmp_gt_f32_e32 vcc, s33, v18
	v_mul_f32_e32 v19, 0x4b800000, v18
	s_nop 0
	v_cndmask_b32_e32 v18, v18, v19, vcc
	v_rsq_f32_e32 v18, v18
	s_nop 0
	v_mul_f32_e32 v19, 0x45800000, v18
	v_cndmask_b32_e32 v18, v18, v19, vcc
	v_mul_f32_e32 v14, v14, v18
	v_mul_f32_e32 v15, v15, v18
	v_mul_f32_e32 v16, v16, v18
	v_mul_f32_e32 v17, v17, v18
	v_mul_f32_e32 v6, v6, v18
	v_mul_f32_e32 v7, v7, v18
	v_mul_f32_e32 v8, v8, v18
	v_mul_f32_e32 v9, v9, v18
	v_max_f32_e32 v14, 0, v14
	v_max_f32_e32 v15, 0, v15
	v_max_f32_e32 v16, 0, v16
	v_max_f32_e32 v17, 0, v17
	v_max_f32_e32 v6, 0, v6
	v_max_f32_e32 v7, 0, v7
	v_max_f32_e32 v8, 0, v8
	v_max_f32_e32 v9, 0, v9
	v_mul_f32_e32 v14, v14, v14
	v_mul_f32_e32 v15, v15, v15
	v_mul_f32_e32 v16, v16, v16
	v_mul_f32_e32 v17, v17, v17
	v_mul_f32_e32 v6, v6, v6
	v_mul_f32_e32 v7, v7, v7
	v_mul_f32_e32 v8, v8, v8
	v_mul_f32_e32 v9, v9, v9
	v_cvt_pk_bf16_f32 v14, v14, v15
	v_cvt_pk_bf16_f32 v15, v16, v17
	v_cvt_pk_bf16_f32 v6, v6, v7
	v_cvt_pk_bf16_f32 v7, v8, v9
	ds_write2_b64 v0, v[14:15], v[6:7] offset1:4
	v_mul_f32_e32 v6, v10, v18
	v_mul_f32_e32 v7, v11, v18
	v_mul_f32_e32 v8, v12, v18
	v_mul_f32_e32 v9, v13, v18
	v_mul_f32_e32 v2, v2, v18
	v_mul_f32_e32 v3, v3, v18
	v_mul_f32_e32 v4, v4, v18
	v_mul_f32_e32 v5, v5, v18
	v_max_f32_e32 v6, 0, v6
	v_max_f32_e32 v7, 0, v7
	v_max_f32_e32 v8, 0, v8
	v_max_f32_e32 v9, 0, v9
	v_max_f32_e32 v2, 0, v2
	v_max_f32_e32 v3, 0, v3
	v_max_f32_e32 v4, 0, v4
	v_max_f32_e32 v5, 0, v5
	v_mul_f32_e32 v6, v6, v6
	v_mul_f32_e32 v7, v7, v7
	v_mul_f32_e32 v8, v8, v8
	v_mul_f32_e32 v9, v9, v9
	v_mul_f32_e32 v2, v2, v2
	v_mul_f32_e32 v3, v3, v3
	v_mul_f32_e32 v4, v4, v4
	v_mul_f32_e32 v5, v5, v5
	v_cvt_pk_bf16_f32 v6, v6, v7
	v_cvt_pk_bf16_f32 v7, v8, v9
	v_cvt_pk_bf16_f32 v2, v2, v3
	v_cvt_pk_bf16_f32 v3, v4, v5
	ds_write2_b64 v0, v[6:7], v[2:3] offset0:32 offset1:36
	v_lshlrev_b32_e32 v0, 4, v138
	v_lshl_add_u64 v[2:3], v[130:131], 0, s[0:1]
	v_and_b32_e32 v0, 0x70, v0
	v_lshl_add_u64 v[6:7], v[2:3], 0, v[0:1]
	v_ashrrev_i32_e32 v3, 11, v138
	v_bfe_u32 v2, v138, 3, 8
	v_mul_u32_u24_e32 v4, 0x210, v2
	v_lshlrev_b32_e32 v5, 7, v3
	v_add3_u32 v5, v4, v5, v0
	s_waitcnt lgkmcnt(0)
	s_barrier
	ds_read_b128 v[8:11], v5
	v_mul_hi_i32_i24_e32 v13, 0x8010, v3
	v_mul_i32_i24_e32 v12, 0x8010, v3
	v_mov_b32_e32 v3, v1
	v_lshl_add_u64 v[12:13], v[12:13], 0, v[2:3]
	v_lshlrev_b64 v[12:13], 7, v[12:13]
	v_lshl_add_u64 v[12:13], v[6:7], 0, v[12:13]
	v_add_u32_e32 v5, 0x200, v138
	s_waitcnt lgkmcnt(0)
	flat_store_dwordx4 v[12:13], v[8:11] nt
	v_ashrrev_i32_e32 v13, 11, v5
	v_bfe_u32 v12, v5, 3, 8
	v_mul_u32_u24_e32 v5, 0x210, v12
	v_lshlrev_b32_e32 v8, 7, v13
	v_add3_u32 v5, v5, v8, v0
	ds_read_b128 v[8:11], v5
	v_mul_hi_i32_i24_e32 v15, 0x8010, v13
	v_mul_i32_i24_e32 v14, 0x8010, v13
	v_mov_b32_e32 v13, v1
	v_lshl_add_u64 v[12:13], v[14:15], 0, v[12:13]
	v_lshlrev_b64 v[12:13], 7, v[12:13]
	v_lshl_add_u64 v[12:13], v[6:7], 0, v[12:13]
	v_add_u32_e32 v5, 0x400, v138
	s_waitcnt lgkmcnt(0)
	flat_store_dwordx4 v[12:13], v[8:11] nt
	v_ashrrev_i32_e32 v13, 11, v5
	v_bfe_u32 v12, v5, 3, 8
	v_mul_u32_u24_e32 v5, 0x210, v12
	v_lshlrev_b32_e32 v8, 7, v13
	v_add3_u32 v5, v5, v8, v0
	ds_read_b128 v[8:11], v5
	v_mul_hi_i32_i24_e32 v15, 0x8010, v13
	v_mul_i32_i24_e32 v14, 0x8010, v13
	v_mov_b32_e32 v13, v1
	v_lshl_add_u64 v[12:13], v[14:15], 0, v[12:13]
	v_lshlrev_b64 v[12:13], 7, v[12:13]
	v_lshl_add_u64 v[12:13], v[6:7], 0, v[12:13]
	v_add_u32_e32 v5, 0x600, v138
	s_waitcnt lgkmcnt(0)
	flat_store_dwordx4 v[12:13], v[8:11] nt
	v_ashrrev_i32_e32 v13, 11, v5
	v_bfe_u32 v12, v5, 3, 8
	v_mul_u32_u24_e32 v5, 0x210, v12
	v_lshlrev_b32_e32 v8, 7, v13
	v_add3_u32 v5, v5, v8, v0
	ds_read_b128 v[8:11], v5
	v_mul_hi_i32_i24_e32 v15, 0x8010, v13
	v_mul_i32_i24_e32 v14, 0x8010, v13
	v_mov_b32_e32 v13, v1
	v_lshl_add_u64 v[12:13], v[14:15], 0, v[12:13]
	v_lshlrev_b64 v[12:13], 7, v[12:13]
	v_add_u32_e32 v5, 0x800, v138
	v_lshl_add_u64 v[12:13], v[6:7], 0, v[12:13]
	v_ashrrev_i32_e32 v5, 11, v5
	s_waitcnt lgkmcnt(0)
	flat_store_dwordx4 v[12:13], v[8:11] nt
	v_mul_hi_i32_i24_e32 v13, 0x8010, v5
	v_mul_i32_i24_e32 v12, 0x8010, v5
	v_lshlrev_b32_e32 v8, 7, v5
	v_add3_u32 v8, v4, v8, v0
	ds_read_b128 v[8:11], v8
	v_lshl_add_u64 v[12:13], v[12:13], 0, v[2:3]
	v_lshlrev_b64 v[12:13], 7, v[12:13]
	v_lshl_add_u64 v[12:13], v[6:7], 0, v[12:13]
	v_add_u32_e32 v5, 0xa00, v138
	s_waitcnt lgkmcnt(0)
	flat_store_dwordx4 v[12:13], v[8:11] nt
	v_ashrrev_i32_e32 v13, 11, v5
	v_bfe_u32 v12, v5, 3, 8
	v_mul_u32_u24_e32 v5, 0x210, v12
	v_lshlrev_b32_e32 v8, 7, v13
	v_add3_u32 v5, v5, v8, v0
	ds_read_b128 v[8:11], v5
	v_mul_hi_i32_i24_e32 v15, 0x8010, v13
	v_mul_i32_i24_e32 v14, 0x8010, v13
	v_mov_b32_e32 v13, v1
	v_lshl_add_u64 v[12:13], v[14:15], 0, v[12:13]
	v_lshlrev_b64 v[12:13], 7, v[12:13]
	v_lshl_add_u64 v[12:13], v[6:7], 0, v[12:13]
	v_add_u32_e32 v5, 0xc00, v138
	s_waitcnt lgkmcnt(0)
	flat_store_dwordx4 v[12:13], v[8:11] nt
	v_ashrrev_i32_e32 v13, 11, v5
	v_bfe_u32 v12, v5, 3, 8
	v_mul_u32_u24_e32 v5, 0x210, v12
	v_lshlrev_b32_e32 v8, 7, v13
	v_add3_u32 v5, v5, v8, v0
	ds_read_b128 v[8:11], v5
	v_mul_hi_i32_i24_e32 v15, 0x8010, v13
	v_mul_i32_i24_e32 v14, 0x8010, v13
	v_mov_b32_e32 v13, v1
	v_lshl_add_u64 v[12:13], v[14:15], 0, v[12:13]
	v_lshlrev_b64 v[12:13], 7, v[12:13]
	v_lshl_add_u64 v[12:13], v[6:7], 0, v[12:13]
	v_add_u32_e32 v5, 0xe00, v138
	s_waitcnt lgkmcnt(0)
	flat_store_dwordx4 v[12:13], v[8:11] nt
	v_ashrrev_i32_e32 v13, 11, v5
	v_bfe_u32 v12, v5, 3, 8
	v_mul_u32_u24_e32 v5, 0x210, v12
	v_lshlrev_b32_e32 v8, 7, v13
	v_add3_u32 v5, v5, v8, v0
	ds_read_b128 v[8:11], v5
	v_mul_hi_i32_i24_e32 v15, 0x8010, v13
	v_mul_i32_i24_e32 v14, 0x8010, v13
	v_mov_b32_e32 v13, v1
	v_lshl_add_u64 v[12:13], v[14:15], 0, v[12:13]
	v_lshlrev_b64 v[12:13], 7, v[12:13]
	v_add_u32_e32 v5, 0x1000, v138
	v_lshl_add_u64 v[12:13], v[6:7], 0, v[12:13]
	v_ashrrev_i32_e32 v5, 11, v5
	s_waitcnt lgkmcnt(0)
	flat_store_dwordx4 v[12:13], v[8:11] nt
	v_mul_hi_i32_i24_e32 v13, 0x8010, v5
	v_mul_i32_i24_e32 v12, 0x8010, v5
	v_lshlrev_b32_e32 v8, 7, v5
	v_add3_u32 v8, v4, v8, v0
	ds_read_b128 v[8:11], v8
	v_lshl_add_u64 v[12:13], v[12:13], 0, v[2:3]
	v_lshlrev_b64 v[12:13], 7, v[12:13]
	v_lshl_add_u64 v[12:13], v[6:7], 0, v[12:13]
	v_add_u32_e32 v5, 0x1200, v138
	s_waitcnt lgkmcnt(0)
	flat_store_dwordx4 v[12:13], v[8:11] nt
	v_ashrrev_i32_e32 v13, 11, v5
	v_bfe_u32 v12, v5, 3, 8
	v_mul_u32_u24_e32 v5, 0x210, v12
	v_lshlrev_b32_e32 v8, 7, v13
	v_add3_u32 v5, v5, v8, v0
	ds_read_b128 v[8:11], v5
	v_mul_hi_i32_i24_e32 v15, 0x8010, v13
	v_mul_i32_i24_e32 v14, 0x8010, v13
	v_mov_b32_e32 v13, v1
	v_lshl_add_u64 v[12:13], v[14:15], 0, v[12:13]
	v_lshlrev_b64 v[12:13], 7, v[12:13]
	v_lshl_add_u64 v[12:13], v[6:7], 0, v[12:13]
	v_add_u32_e32 v5, 0x1400, v138
	s_waitcnt lgkmcnt(0)
	flat_store_dwordx4 v[12:13], v[8:11] nt
	v_ashrrev_i32_e32 v13, 11, v5
	v_bfe_u32 v12, v5, 3, 8
	v_mul_u32_u24_e32 v5, 0x210, v12
	v_lshlrev_b32_e32 v8, 7, v13
	v_add3_u32 v5, v5, v8, v0
	ds_read_b128 v[8:11], v5
	v_mul_hi_i32_i24_e32 v15, 0x8010, v13
	v_mul_i32_i24_e32 v14, 0x8010, v13
	v_mov_b32_e32 v13, v1
	v_lshl_add_u64 v[12:13], v[14:15], 0, v[12:13]
	v_lshlrev_b64 v[12:13], 7, v[12:13]
	v_lshl_add_u64 v[12:13], v[6:7], 0, v[12:13]
	v_add_u32_e32 v5, 0x1600, v138
	s_waitcnt lgkmcnt(0)
	flat_store_dwordx4 v[12:13], v[8:11] nt
	v_ashrrev_i32_e32 v13, 11, v5
	v_bfe_u32 v12, v5, 3, 8
	v_mul_u32_u24_e32 v5, 0x210, v12
	v_lshlrev_b32_e32 v8, 7, v13
	v_add3_u32 v5, v5, v8, v0
	ds_read_b128 v[8:11], v5
	v_mul_hi_i32_i24_e32 v15, 0x8010, v13
	v_mul_i32_i24_e32 v14, 0x8010, v13
	v_mov_b32_e32 v13, v1
	v_lshl_add_u64 v[12:13], v[14:15], 0, v[12:13]
	v_lshlrev_b64 v[12:13], 7, v[12:13]
	v_lshl_add_u64 v[12:13], v[6:7], 0, v[12:13]
	v_add_u32_e32 v5, 0x1800, v138
	s_waitcnt lgkmcnt(0)
	flat_store_dwordx4 v[12:13], v[8:11] nt
	v_ashrrev_i32_e32 v12, 11, v5
	v_lshlrev_b32_e32 v5, 7, v12
	v_add3_u32 v4, v4, v5, v0
	ds_read_b128 v[8:11], v4
	v_mul_hi_i32_i24_e32 v5, 0x8010, v12
	v_mul_i32_i24_e32 v4, 0x8010, v12
	v_lshl_add_u64 v[2:3], v[4:5], 0, v[2:3]
	v_lshlrev_b64 v[2:3], 7, v[2:3]
	v_lshl_add_u64 v[2:3], v[6:7], 0, v[2:3]
	s_waitcnt lgkmcnt(0)
	flat_store_dwordx4 v[2:3], v[8:11] nt
	v_add_u32_e32 v2, 0x1a00, v138
	s_nop 0
	v_ashrrev_i32_e32 v9, 11, v2
	v_bfe_u32 v8, v2, 3, 8
	v_mul_u32_u24_e32 v2, 0x210, v8
	v_lshlrev_b32_e32 v3, 7, v9
	v_add3_u32 v2, v2, v3, v0
	ds_read_b128 v[2:5], v2
	v_mul_hi_i32_i24_e32 v11, 0x8010, v9
	v_mul_i32_i24_e32 v10, 0x8010, v9
	v_mov_b32_e32 v9, v1
	v_lshl_add_u64 v[8:9], v[10:11], 0, v[8:9]
	v_lshlrev_b64 v[8:9], 7, v[8:9]
	v_lshl_add_u64 v[8:9], v[6:7], 0, v[8:9]
	s_waitcnt lgkmcnt(0)
	flat_store_dwordx4 v[8:9], v[2:5] nt
	s_nop 1
	v_add_u32_e32 v2, 0x1c00, v138
	v_ashrrev_i32_e32 v9, 11, v2
	v_bfe_u32 v8, v2, 3, 8
	v_mul_u32_u24_e32 v2, 0x210, v8
	v_lshlrev_b32_e32 v3, 7, v9
	v_add3_u32 v2, v2, v3, v0
	ds_read_b128 v[2:5], v2
	v_mul_hi_i32_i24_e32 v11, 0x8010, v9
	v_mul_i32_i24_e32 v10, 0x8010, v9
	v_mov_b32_e32 v9, v1
	v_lshl_add_u64 v[8:9], v[10:11], 0, v[8:9]
	v_lshlrev_b64 v[8:9], 7, v[8:9]
	v_lshl_add_u64 v[8:9], v[6:7], 0, v[8:9]
	s_waitcnt lgkmcnt(0)
	flat_store_dwordx4 v[8:9], v[2:5] nt
	s_nop 1
	v_add_u32_e32 v2, 0x1e00, v138
	v_ashrrev_i32_e32 v9, 11, v2
	v_bfe_u32 v8, v2, 3, 8
	v_mul_u32_u24_e32 v2, 0x210, v8
	v_lshlrev_b32_e32 v3, 7, v9
	v_add3_u32 v0, v2, v3, v0
	ds_read_b128 v[2:5], v0
	v_mul_hi_i32_i24_e32 v11, 0x8010, v9
	v_mul_i32_i24_e32 v10, 0x8010, v9
	v_mov_b32_e32 v9, v1
	v_lshl_add_u64 v[8:9], v[10:11], 0, v[8:9]
	v_lshlrev_b64 v[8:9], 7, v[8:9]
	v_lshl_add_u64 v[6:7], v[6:7], 0, v[8:9]
	s_waitcnt lgkmcnt(0)
	flat_store_dwordx4 v[6:7], v[2:5] nt
	s_waitcnt lgkmcnt(0)
	s_barrier

.LBB0_639:
	v_mov_b64_e32 v[2:3], s[6:7]
	v_mov_b32_e32 v2, v136
	v_mov_b32_e32 v3, v137
	v_mov_b32_e32 v16, v204
	s_lshl_b32 s2, s16, 8
	v_lshrrev_b32_e32 v20, 4, v16
	v_lshlrev_b32_e32 v0, 8, v16
	v_xor_b32_e32 v4, v16, v20
	s_lshl_b32 s8, s0, 8
	s_or_b32 s18, s2, 0x80
	v_readfirstlane_b32 s0, v16
	v_and_b32_e32 v17, 0xfffff800, v0
	v_lshlrev_b32_e32 v0, 3, v4
	s_ashr_i32 s3, s2, 31
	s_ashr_i32 s19, s18, 31
	s_ashr_i32 s22, s0, 6
	v_and_b32_e32 v18, 56, v0
	s_lshl_b64 s[10:11], s[2:3], 12
	s_lshl_b64 s[2:3], s[18:19], 12
	v_add_u32_e32 v19, 0x20000, v17
	s_lshl_b32 s1, s22, 10
	v_or_b32_e32 v0, v18, v17
	v_mov_b32_e32 v5, v1
	s_ashr_i32 s9, s8, 31
	v_lshl_add_u64 v[6:7], v[134:135], 0, s[10:11]
	v_lshl_add_u64 v[12:13], v[134:135], 0, s[2:3]
	s_add_i32 s2, s1, 0x10000
	v_or_b32_e32 v4, v18, v19
	v_lshlrev_b64 v[22:23], 1, v[0:1]
	s_lshl_b64 s[12:13], s[8:9], 12
	s_add_i32 s3, s1, 0x12000
	v_lshlrev_b64 v[24:25], 1, v[4:5]
	v_lshl_add_u64 v[10:11], v[6:7], 0, v[22:23]
	s_mov_b32 m0, s2
	v_lshl_add_u64 v[8:9], v[6:7], 0, v[24:25]
	v_lshl_add_u64 v[6:7], v[12:13], 0, v[22:23]
	v_lshl_add_u64 v[4:5], v[12:13], 0, v[24:25]
	global_load_lds_dwordx4 v[10:11], off
	s_mov_b32 m0, s3
	s_or_b32 s20, s8, 0x80
	s_add_i32 s17, s1, 0x2000
	global_load_lds_dwordx4 v[8:9], off
	s_mov_b32 m0, s1
	s_ashr_i32 s21, s20, 31
	s_add_i32 s18, s1, 0x14000
	s_lshl_b64 s[24:25], s[20:21], 12
	s_add_i32 s19, s1, 0x16000
	s_add_i32 s20, s1, 0x4000
	s_add_i32 s21, s1, 0x6000
	s_ashr_i32 s23, s0, 8
	s_cmp_lg_u32 s23, 1
	v_lshl_add_u64 v[12:13], v[2:3], 0, s[12:13]
	v_lshl_add_u64 v[14:15], v[12:13], 0, v[22:23]
	v_lshl_add_u64 v[12:13], v[12:13], 0, v[24:25]
	global_load_lds_dwordx4 v[14:15], off
	s_mov_b32 m0, s17
	v_lshl_add_u64 v[26:27], v[2:3], 0, s[24:25]
	global_load_lds_dwordx4 v[12:13], off
	s_mov_b32 m0, s18
	v_lshl_add_u64 v[140:141], v[26:27], 0, v[22:23]
	global_load_lds_dwordx4 v[6:7], off
	s_mov_b32 m0, s19
	v_lshl_add_u64 v[138:139], v[26:27], 0, v[24:25]
	global_load_lds_dwordx4 v[4:5], off
	s_mov_b32 m0, s20
	s_nop 0
	global_load_lds_dwordx4 v[140:141], off
	s_mov_b32 m0, s21
	s_nop 0
	global_load_lds_dwordx4 v[138:139], off
	s_cbranch_scc1 .LBB0_641
	s_barrier
.LBB0_641:
	s_lshl_b32 s22, s22, 5
	v_and_b32_e32 v0, 15, v16
	s_and_b32 s22, s22, 0x60
	v_lshlrev_b32_e32 v21, 7, v0
	v_or_b32_e32 v0, s22, v0
	s_add_i32 s22, s1, 0x18000
	s_mov_b64 s[30:31], 0x80
	v_lshl_or_b32 v21, s23, 13, v21
	v_lshl_add_u64 v[10:11], v[10:11], 0, s[30:31]
	s_mov_b32 m0, s22
	s_add_i32 s23, s1, 0x1a000
	s_waitcnt vmcnt(4)
	s_barrier
	global_load_lds_dwordx4 v[10:11], off
	v_lshl_add_u64 v[8:9], v[8:9], 0, s[30:31]
	s_mov_b32 m0, s23
	s_add_i32 s24, s1, 0x8000
	global_load_lds_dwordx4 v[8:9], off
	v_lshl_add_u64 v[8:9], v[14:15], 0, s[30:31]
	s_mov_b32 m0, s24
	s_add_i32 s25, s1, 0xa000
	global_load_lds_dwordx4 v[8:9], off
	v_lshl_add_u64 v[8:9], v[12:13], 0, s[30:31]
	s_mov_b32 m0, s25
	s_add_i32 s26, s1, 0x1c000
	global_load_lds_dwordx4 v[8:9], off
	v_lshl_add_u64 v[6:7], v[6:7], 0, s[30:31]
	s_mov_b32 m0, s26
	s_add_i32 s27, s1, 0x1e000
	global_load_lds_dwordx4 v[6:7], off
	v_lshl_add_u64 v[4:5], v[4:5], 0, s[30:31]
	s_mov_b32 m0, s27
	v_and_b32_e32 v22, 3, v20
	global_load_lds_dwordx4 v[4:5], off
	v_bfe_u32 v16, v16, 1, 3
	v_bitop3_b32 v20, v20, v16, 3 bitop3:0x6c
	v_bitop3_b32 v16, v22, v16, 4 bitop3:0x36
	v_lshlrev_b32_e32 v20, 4, v20
	v_lshlrev_b32_e32 v16, 4, v16
	v_lshlrev_b32_e32 v0, 7, v0
	v_or_b32_e32 v152, v0, v20
	v_or_b32_e32 v153, v0, v16
	v_add_u32_e32 v0, v19, v18
	v_lshlrev_b64 v[4:5], 1, v[0:1]
	v_lshl_add_u64 v[6:7], s[12:13], 0, v[4:5]
	v_add_u32_e32 v0, v17, v18
	v_lshl_add_u64 v[142:143], v[2:3], 0, v[6:7]
	v_lshlrev_b64 v[6:7], 1, v[0:1]
	v_lshl_add_u64 v[8:9], s[12:13], 0, v[6:7]
	v_lshl_add_u64 v[144:145], v[2:3], 0, v[8:9]
	v_lshl_add_u64 v[2:3], s[10:11], 0, v[4:5]
	s_waitcnt vmcnt(6)
	v_lshl_add_u64 v[146:147], v[136:137], 0, v[2:3]
	v_lshl_add_u64 v[2:3], s[10:11], 0, v[6:7]
	v_lshl_add_u64 v[148:149], v[136:137], 0, v[2:3]
	v_mov_b32_e32 v2, 0
	v_or_b32_e32 v150, v20, v21
	v_or_b32_e32 v151, v16, v21
	s_mov_b32 s12, -2
	s_mov_b64 s[10:11], 0
	v_mov_b32_e32 v3, v2
	v_mov_b32_e32 v4, v2
	v_mov_b32_e32 v5, v2
	v_mov_b32_e32 v6, v2
	v_mov_b32_e32 v7, v2
	v_mov_b32_e32 v8, v2
	v_mov_b32_e32 v9, v2
	v_mov_b32_e32 v10, v2
	v_mov_b32_e32 v11, v2
	v_mov_b32_e32 v12, v2
	v_mov_b32_e32 v13, v2
	v_mov_b32_e32 v14, v2
	v_mov_b32_e32 v15, v2
	v_mov_b32_e32 v16, v2
	v_mov_b32_e32 v17, v2
	v_mov_b32_e32 v18, v2
	v_mov_b32_e32 v19, v2
	v_mov_b32_e32 v20, v2
	v_mov_b32_e32 v21, v2
	v_mov_b32_e32 v22, v2
	v_mov_b32_e32 v23, v2
	v_mov_b32_e32 v24, v2
	v_mov_b32_e32 v25, v2
	v_mov_b32_e32 v26, v2
	v_mov_b32_e32 v27, v2
	v_mov_b32_e32 v28, v2
	v_mov_b32_e32 v29, v2
	v_mov_b32_e32 v30, v2
	v_mov_b32_e32 v31, v2
	v_mov_b32_e32 v32, v2
	v_mov_b32_e32 v33, v2
	v_mov_b32_e32 v34, v2
	v_mov_b32_e32 v35, v2
	v_mov_b32_e32 v36, v2
	v_mov_b32_e32 v37, v2
	v_mov_b32_e32 v38, v2
	v_mov_b32_e32 v39, v2
	v_mov_b32_e32 v40, v2
	v_mov_b32_e32 v41, v2
	v_mov_b32_e32 v42, v2
	v_mov_b32_e32 v43, v2
	v_mov_b32_e32 v44, v2
	v_mov_b32_e32 v45, v2
	v_mov_b32_e32 v46, v2
	v_mov_b32_e32 v47, v2
	v_mov_b32_e32 v48, v2
	v_mov_b32_e32 v49, v2
	v_mov_b32_e32 v50, v2
	v_mov_b32_e32 v51, v2
	v_mov_b32_e32 v52, v2
	v_mov_b32_e32 v53, v2
	v_mov_b32_e32 v54, v2
	v_mov_b32_e32 v55, v2
	v_mov_b32_e32 v56, v2
	v_mov_b32_e32 v57, v2
	v_mov_b32_e32 v58, v2
	v_mov_b32_e32 v59, v2
	v_mov_b32_e32 v60, v2
	v_mov_b32_e32 v61, v2
	v_mov_b32_e32 v62, v2
	v_mov_b32_e32 v63, v2
	v_mov_b32_e32 v64, v2
	v_mov_b32_e32 v65, v2
	v_mov_b32_e32 v66, v2
	v_mov_b32_e32 v67, v2
	v_mov_b32_e32 v68, v2
	v_mov_b32_e32 v69, v2
	v_mov_b32_e32 v70, v2
	v_mov_b32_e32 v71, v2
	v_mov_b32_e32 v72, v2
	v_mov_b32_e32 v73, v2
	v_mov_b32_e32 v74, v2
	v_mov_b32_e32 v75, v2
	v_mov_b32_e32 v76, v2
	v_mov_b32_e32 v77, v2
	v_mov_b32_e32 v78, v2
	v_mov_b32_e32 v79, v2
	v_mov_b32_e32 v80, v2
	v_mov_b32_e32 v81, v2
	v_mov_b32_e32 v82, v2
	v_mov_b32_e32 v83, v2
	v_mov_b32_e32 v84, v2
	v_mov_b32_e32 v85, v2
	v_mov_b32_e32 v86, v2
	v_mov_b32_e32 v87, v2
	v_mov_b32_e32 v88, v2
	v_mov_b32_e32 v89, v2
	v_mov_b32_e32 v90, v2
	v_mov_b32_e32 v91, v2
	v_mov_b32_e32 v92, v2
	v_mov_b32_e32 v93, v2
	v_mov_b32_e32 v94, v2
	v_mov_b32_e32 v95, v2
	v_mov_b32_e32 v96, v2
	v_mov_b32_e32 v97, v2
	v_mov_b32_e32 v98, v2
	v_mov_b32_e32 v99, v2
	v_mov_b32_e32 v100, v2
	v_mov_b32_e32 v101, v2
	v_mov_b32_e32 v102, v2
	v_mov_b32_e32 v103, v2
	v_mov_b32_e32 v104, v2
	v_mov_b32_e32 v105, v2
	v_mov_b32_e32 v106, v2
	v_mov_b32_e32 v107, v2
	v_mov_b32_e32 v108, v2
	v_mov_b32_e32 v109, v2
	v_mov_b32_e32 v110, v2
	v_mov_b32_e32 v111, v2
	v_mov_b32_e32 v112, v2
	v_mov_b32_e32 v113, v2
	v_mov_b32_e32 v114, v2
	v_mov_b32_e32 v115, v2
	v_mov_b32_e32 v116, v2
	v_mov_b32_e32 v117, v2
	v_mov_b32_e32 v118, v2
	v_mov_b32_e32 v119, v2
	v_mov_b32_e32 v120, v2
	v_mov_b32_e32 v121, v2
	v_mov_b32_e32 v122, v2
	v_mov_b32_e32 v123, v2
	v_mov_b32_e32 v124, v2
	v_mov_b32_e32 v125, v2
	v_mov_b32_e32 v126, v2
	v_mov_b32_e32 v127, v2
	v_mov_b32_e32 v128, v2
	v_mov_b32_e32 v129, v2
	s_mov_b64 s[30:31], 0xa254900
	s_mov_b64 s[34:35], 0xa2d4900
	s_mov_b64 s[36:37], 0xa254980
	s_mov_b64 s[38:39], 0xa2d4980
	v_readfirstlane_b32 s100, v136
	v_readfirstlane_b32 s101, v137
	s_mov_b64 vcc, s[100:101]
	s_add_u32 s10, s10, vcc_lo
	s_addc_u32 s11, s11, vcc_hi
	v_subrev_u32_e32 v202, vcc_lo, v144
	v_subrev_u32_e32 v210, vcc_lo, v142
	v_subrev_u32_e32 v214, vcc_lo, v148
	v_subrev_u32_e32 v246, vcc_lo, v146
	v_add_u32_e32 v248, 0x10000, v152
	v_add_u32_e32 v249, 0x10000, v153
	s_barrier
.LBB0_642:
	ds_read_b128 v[162:165], v248
	ds_read_b128 v[166:169], v249
	ds_read_b128 v[170:173], v248 offset:2048
	ds_read_b128 v[174:177], v249 offset:2048
	s_add_i32 s28, s1, 0xc000
	s_mov_b32 m0, s28
	s_add_i32 s13, s1, 0xe000
	ds_read_b128 v[178:181], v150
	ds_read_b128 v[182:185], v150 offset:2048
	ds_read_b128 v[186:189], v151
	ds_read_b128 v[190:193], v151 offset:2048
	ds_read_b128 v[194:197], v150 offset:4096
	ds_read_b128 v[198:201], v150 offset:6144
	ds_read_b128 v[206:209], v151 offset:4096
	ds_read_b128 v[218:221], v151 offset:6144
	s_add_u32 s100, s10, s50
	s_addc_u32 s101, s11, s51
	global_load_lds_dwordx4 v202, s[100:101]
	s_mov_b32 m0, s13
	s_add_u32 s100, s10, s50
	s_addc_u32 s101, s11, s51
	global_load_lds_dwordx4 v210, s[100:101]
	s_waitcnt lgkmcnt(8)
	s_waitcnt vmcnt(10)
	s_barrier
	s_waitcnt lgkmcnt(0)
	s_setprio 1
	s_waitcnt lgkmcnt(0)
	v_mfma_f32_16x16x32_bf16 v[126:129], v[162:165], v[178:181], v[126:129]
	v_mfma_f32_16x16x32_bf16 v[122:125], v[170:173], v[178:181], v[122:125]
	v_mfma_f32_16x16x32_bf16 v[118:121], v[162:165], v[182:185], v[118:121]
	v_mfma_f32_16x16x32_bf16 v[114:117], v[170:173], v[182:185], v[114:117]
	v_mfma_f32_16x16x32_bf16 v[110:113], v[162:165], v[194:197], v[110:113]
	v_mfma_f32_16x16x32_bf16 v[106:109], v[170:173], v[194:197], v[106:109]
	v_mfma_f32_16x16x32_bf16 v[102:105], v[162:165], v[198:201], v[102:105]
	v_mfma_f32_16x16x32_bf16 v[98:101], v[170:173], v[198:201], v[98:101]
	v_mfma_f32_16x16x32_bf16 v[126:129], v[166:169], v[186:189], v[126:129]
	v_mfma_f32_16x16x32_bf16 v[122:125], v[174:177], v[186:189], v[122:125]
	v_mfma_f32_16x16x32_bf16 v[118:121], v[166:169], v[190:193], v[118:121]
	v_mfma_f32_16x16x32_bf16 v[114:117], v[174:177], v[190:193], v[114:117]
	v_mfma_f32_16x16x32_bf16 v[110:113], v[166:169], v[206:209], v[110:113]
	v_mfma_f32_16x16x32_bf16 v[106:109], v[174:177], v[206:209], v[106:109]
	v_mfma_f32_16x16x32_bf16 v[102:105], v[166:169], v[218:221], v[102:105]
	v_mfma_f32_16x16x32_bf16 v[98:101], v[174:177], v[218:221], v[98:101]
	s_setprio 0
	s_barrier
	s_mov_b32 m0, s2
	ds_read_b128 v[222:225], v248 offset:16384
	ds_read_b128 v[226:229], v249 offset:16384
	ds_read_b128 v[230:233], v248 offset:18432
	ds_read_b128 v[234:237], v249 offset:18432
	s_add_u32 s100, s10, s30
	s_addc_u32 s101, s11, s31
	global_load_lds_dwordx4 v214, s[100:101]
	s_mov_b32 m0, s3
	s_add_u32 s100, s10, s30
	s_addc_u32 s101, s11, s31
	global_load_lds_dwordx4 v246, s[100:101]
	s_waitcnt vmcnt(10)
	s_waitcnt lgkmcnt(0)
	s_barrier
	s_waitcnt lgkmcnt(0)
	s_setprio 1
	s_waitcnt lgkmcnt(0)
	v_mfma_f32_16x16x32_bf16 v[94:97], v[222:225], v[178:181], v[94:97]
	v_mfma_f32_16x16x32_bf16 v[90:93], v[230:233], v[178:181], v[90:93]
	v_mfma_f32_16x16x32_bf16 v[86:89], v[222:225], v[182:185], v[86:89]
	v_mfma_f32_16x16x32_bf16 v[82:85], v[230:233], v[182:185], v[82:85]
	v_mfma_f32_16x16x32_bf16 v[78:81], v[222:225], v[194:197], v[78:81]
	v_mfma_f32_16x16x32_bf16 v[74:77], v[230:233], v[194:197], v[74:77]
	v_mfma_f32_16x16x32_bf16 v[70:73], v[222:225], v[198:201], v[70:73]
	v_mfma_f32_16x16x32_bf16 v[66:69], v[230:233], v[198:201], v[66:69]
	v_mfma_f32_16x16x32_bf16 v[94:97], v[226:229], v[186:189], v[94:97]
	v_mfma_f32_16x16x32_bf16 v[90:93], v[234:237], v[186:189], v[90:93]
	v_mfma_f32_16x16x32_bf16 v[86:89], v[226:229], v[190:193], v[86:89]
	v_mfma_f32_16x16x32_bf16 v[82:85], v[234:237], v[190:193], v[82:85]
	v_mfma_f32_16x16x32_bf16 v[78:81], v[226:229], v[206:209], v[78:81]
	v_mfma_f32_16x16x32_bf16 v[74:77], v[234:237], v[206:209], v[74:77]
	v_mfma_f32_16x16x32_bf16 v[70:73], v[226:229], v[218:221], v[70:73]
	v_mfma_f32_16x16x32_bf16 v[66:69], v[234:237], v[218:221], v[66:69]
	s_setprio 0
	s_mov_b32 m0, s1
	s_barrier
	ds_read_b128 v[178:181], v150 offset:16384
	ds_read_b128 v[182:185], v150 offset:18432
	ds_read_b128 v[186:189], v151 offset:16384
	ds_read_b128 v[190:193], v151 offset:18432
	ds_read_b128 v[194:197], v150 offset:20480
	ds_read_b128 v[198:201], v150 offset:22528
	ds_read_b128 v[206:209], v151 offset:20480
	ds_read_b128 v[218:221], v151 offset:22528
	s_add_u32 s100, s10, s54
	s_addc_u32 s101, s11, s55
	global_load_lds_dwordx4 v202, s[100:101]
	s_mov_b32 m0, s17
	s_add_u32 s100, s10, s54
	s_addc_u32 s101, s11, s55
	global_load_lds_dwordx4 v210, s[100:101]
	s_mov_b32 m0, s18
	s_add_u32 s100, s10, s34
	s_addc_u32 s101, s11, s35
	global_load_lds_dwordx4 v214, s[100:101]
	s_mov_b32 m0, s19
	s_add_u32 s100, s10, s34
	s_addc_u32 s101, s11, s35
	global_load_lds_dwordx4 v246, s[100:101]
	s_waitcnt vmcnt(10)
	s_waitcnt lgkmcnt(0)
	s_barrier
	s_waitcnt lgkmcnt(0)
	s_setprio 1
	s_waitcnt lgkmcnt(0)
	v_mfma_f32_16x16x32_bf16 v[62:65], v[162:165], v[178:181], v[62:65]
	v_mfma_f32_16x16x32_bf16 v[58:61], v[170:173], v[178:181], v[58:61]
	v_mfma_f32_16x16x32_bf16 v[54:57], v[162:165], v[182:185], v[54:57]
	v_mfma_f32_16x16x32_bf16 v[50:53], v[170:173], v[182:185], v[50:53]
	v_mfma_f32_16x16x32_bf16 v[46:49], v[162:165], v[194:197], v[46:49]
	v_mfma_f32_16x16x32_bf16 v[42:45], v[170:173], v[194:197], v[42:45]
	v_mfma_f32_16x16x32_bf16 v[38:41], v[162:165], v[198:201], v[38:41]
	v_mfma_f32_16x16x32_bf16 v[34:37], v[170:173], v[198:201], v[34:37]
	v_mfma_f32_16x16x32_bf16 v[62:65], v[166:169], v[186:189], v[62:65]
	v_mfma_f32_16x16x32_bf16 v[58:61], v[174:177], v[186:189], v[58:61]
	v_mfma_f32_16x16x32_bf16 v[54:57], v[166:169], v[190:193], v[54:57]
	v_mfma_f32_16x16x32_bf16 v[50:53], v[174:177], v[190:193], v[50:53]
	v_mfma_f32_16x16x32_bf16 v[46:49], v[166:169], v[206:209], v[46:49]
	v_mfma_f32_16x16x32_bf16 v[42:45], v[174:177], v[206:209], v[42:45]
	v_mfma_f32_16x16x32_bf16 v[38:41], v[166:169], v[218:221], v[38:41]
	v_mfma_f32_16x16x32_bf16 v[34:37], v[174:177], v[218:221], v[34:37]
	v_mfma_f32_16x16x32_bf16 v[30:33], v[222:225], v[178:181], v[30:33]
	v_mfma_f32_16x16x32_bf16 v[26:29], v[230:233], v[178:181], v[26:29]
	v_mfma_f32_16x16x32_bf16 v[22:25], v[222:225], v[182:185], v[22:25]
	v_mfma_f32_16x16x32_bf16 v[18:21], v[230:233], v[182:185], v[18:21]
	v_mfma_f32_16x16x32_bf16 v[14:17], v[222:225], v[194:197], v[14:17]
	v_mfma_f32_16x16x32_bf16 v[10:13], v[230:233], v[194:197], v[10:13]
	v_mfma_f32_16x16x32_bf16 v[6:9], v[222:225], v[198:201], v[6:9]
	v_mfma_f32_16x16x32_bf16 v[2:5], v[230:233], v[198:201], v[2:5]
	v_mfma_f32_16x16x32_bf16 v[30:33], v[226:229], v[186:189], v[30:33]
	v_mfma_f32_16x16x32_bf16 v[26:29], v[234:237], v[186:189], v[26:29]
	v_mfma_f32_16x16x32_bf16 v[22:25], v[226:229], v[190:193], v[22:25]
	v_mfma_f32_16x16x32_bf16 v[18:21], v[234:237], v[190:193], v[18:21]
	v_mfma_f32_16x16x32_bf16 v[14:17], v[226:229], v[206:209], v[14:17]
	v_mfma_f32_16x16x32_bf16 v[10:13], v[234:237], v[206:209], v[10:13]
	v_mfma_f32_16x16x32_bf16 v[6:9], v[226:229], v[218:221], v[6:9]
	v_mfma_f32_16x16x32_bf16 v[2:5], v[234:237], v[218:221], v[2:5]
	s_setprio 0
	s_barrier
	ds_read_b128 v[170:173], v248 offset:32768
	ds_read_b128 v[174:177], v249 offset:32768
	ds_read_b128 v[178:181], v248 offset:34816
	ds_read_b128 v[182:185], v249 offset:34816
	s_mov_b32 m0, s20
	ds_read_b128 v[186:189], v150 offset:32768
	ds_read_b128 v[190:193], v150 offset:34816
	ds_read_b128 v[194:197], v151 offset:32768
	ds_read_b128 v[198:201], v151 offset:34816
	ds_read_b128 v[206:209], v150 offset:36864
	ds_read_b128 v[218:221], v150 offset:38912
	ds_read_b128 v[222:225], v151 offset:36864
	ds_read_b128 v[226:229], v151 offset:38912
	s_add_u32 s100, s10, s58
	s_addc_u32 s101, s11, s59
	global_load_lds_dwordx4 v202, s[100:101]
	s_mov_b32 m0, s21
	s_add_u32 s100, s10, s58
	s_addc_u32 s101, s11, s59
	global_load_lds_dwordx4 v210, s[100:101]
	s_waitcnt lgkmcnt(8)
	s_waitcnt vmcnt(10)
	s_barrier
	s_waitcnt lgkmcnt(0)
	s_setprio 1
	s_waitcnt lgkmcnt(0)
	v_mfma_f32_16x16x32_bf16 v[126:129], v[170:173], v[186:189], v[126:129]
	v_mfma_f32_16x16x32_bf16 v[122:125], v[178:181], v[186:189], v[122:125]
	v_mfma_f32_16x16x32_bf16 v[118:121], v[170:173], v[190:193], v[118:121]
	v_mfma_f32_16x16x32_bf16 v[114:117], v[178:181], v[190:193], v[114:117]
	v_mfma_f32_16x16x32_bf16 v[110:113], v[170:173], v[206:209], v[110:113]
	v_mfma_f32_16x16x32_bf16 v[106:109], v[178:181], v[206:209], v[106:109]
	v_mfma_f32_16x16x32_bf16 v[102:105], v[170:173], v[218:221], v[102:105]
	v_mfma_f32_16x16x32_bf16 v[98:101], v[178:181], v[218:221], v[98:101]
	v_mfma_f32_16x16x32_bf16 v[126:129], v[174:177], v[194:197], v[126:129]
	v_mfma_f32_16x16x32_bf16 v[122:125], v[182:185], v[194:197], v[122:125]
	v_mfma_f32_16x16x32_bf16 v[118:121], v[174:177], v[198:201], v[118:121]
	v_mfma_f32_16x16x32_bf16 v[114:117], v[182:185], v[198:201], v[114:117]
	v_mfma_f32_16x16x32_bf16 v[110:113], v[174:177], v[222:225], v[110:113]
	v_mfma_f32_16x16x32_bf16 v[106:109], v[182:185], v[222:225], v[106:109]
	v_mfma_f32_16x16x32_bf16 v[102:105], v[174:177], v[226:229], v[102:105]
	v_mfma_f32_16x16x32_bf16 v[98:101], v[182:185], v[226:229], v[98:101]
	s_setprio 0
	s_barrier
	s_mov_b32 m0, s22
	ds_read_b128 v[230:233], v248 offset:49152
	ds_read_b128 v[234:237], v249 offset:49152
	ds_read_b128 v[238:241], v248 offset:51200
	ds_read_b128 v[242:245], v249 offset:51200
	s_add_u32 s100, s10, s36
	s_addc_u32 s101, s11, s37
	global_load_lds_dwordx4 v214, s[100:101]
	s_mov_b32 m0, s23
	s_add_u32 s100, s10, s36
	s_addc_u32 s101, s11, s37
	global_load_lds_dwordx4 v246, s[100:101]
	s_waitcnt vmcnt(10)
	s_waitcnt lgkmcnt(0)
	s_barrier
	s_waitcnt lgkmcnt(0)
	s_setprio 1
	s_waitcnt lgkmcnt(0)
	v_mfma_f32_16x16x32_bf16 v[94:97], v[230:233], v[186:189], v[94:97]
	v_mfma_f32_16x16x32_bf16 v[90:93], v[238:241], v[186:189], v[90:93]
	v_mfma_f32_16x16x32_bf16 v[86:89], v[230:233], v[190:193], v[86:89]
	v_mfma_f32_16x16x32_bf16 v[82:85], v[238:241], v[190:193], v[82:85]
	v_mfma_f32_16x16x32_bf16 v[78:81], v[230:233], v[206:209], v[78:81]
	v_mfma_f32_16x16x32_bf16 v[74:77], v[238:241], v[206:209], v[74:77]
	v_mfma_f32_16x16x32_bf16 v[70:73], v[230:233], v[218:221], v[70:73]
	v_mfma_f32_16x16x32_bf16 v[66:69], v[238:241], v[218:221], v[66:69]
	v_mfma_f32_16x16x32_bf16 v[94:97], v[234:237], v[194:197], v[94:97]
	v_mfma_f32_16x16x32_bf16 v[90:93], v[242:245], v[194:197], v[90:93]
	v_mfma_f32_16x16x32_bf16 v[86:89], v[234:237], v[198:201], v[86:89]
	v_mfma_f32_16x16x32_bf16 v[82:85], v[242:245], v[198:201], v[82:85]
	v_mfma_f32_16x16x32_bf16 v[78:81], v[234:237], v[222:225], v[78:81]
	v_mfma_f32_16x16x32_bf16 v[74:77], v[242:245], v[222:225], v[74:77]
	v_mfma_f32_16x16x32_bf16 v[70:73], v[234:237], v[226:229], v[70:73]
	v_mfma_f32_16x16x32_bf16 v[66:69], v[242:245], v[226:229], v[66:69]
	s_setprio 0
	s_mov_b32 m0, s24
	s_barrier
	ds_read_b128 v[186:189], v150 offset:49152
	ds_read_b128 v[190:193], v150 offset:51200
	ds_read_b128 v[194:197], v151 offset:49152
	ds_read_b128 v[198:201], v151 offset:51200
	ds_read_b128 v[206:209], v150 offset:53248
	ds_read_b128 v[218:221], v150 offset:55296
	ds_read_b128 v[222:225], v151 offset:53248
	ds_read_b128 v[226:229], v151 offset:55296
	s_add_u32 s100, s10, s62
	s_addc_u32 s101, s11, s63
	global_load_lds_dwordx4 v202, s[100:101]
	s_mov_b32 m0, s25
	s_add_u32 s100, s10, s62
	s_addc_u32 s101, s11, s63
	global_load_lds_dwordx4 v210, s[100:101]
	s_mov_b32 m0, s26
	s_add_u32 s100, s10, s38
	s_addc_u32 s101, s11, s39
	global_load_lds_dwordx4 v214, s[100:101]
	s_mov_b32 m0, s27
	s_add_u32 s100, s10, s38
	s_addc_u32 s101, s11, s39
	global_load_lds_dwordx4 v246, s[100:101]
	s_waitcnt vmcnt(10)
	s_waitcnt lgkmcnt(0)
	s_barrier
	s_waitcnt lgkmcnt(0)
	s_setprio 1
	s_waitcnt lgkmcnt(0)
	v_mfma_f32_16x16x32_bf16 v[62:65], v[170:173], v[186:189], v[62:65]
	v_mfma_f32_16x16x32_bf16 v[58:61], v[178:181], v[186:189], v[58:61]
	v_mfma_f32_16x16x32_bf16 v[54:57], v[170:173], v[190:193], v[54:57]
	v_mfma_f32_16x16x32_bf16 v[50:53], v[178:181], v[190:193], v[50:53]
	v_mfma_f32_16x16x32_bf16 v[46:49], v[170:173], v[206:209], v[46:49]
	v_mfma_f32_16x16x32_bf16 v[42:45], v[178:181], v[206:209], v[42:45]
	v_mfma_f32_16x16x32_bf16 v[38:41], v[170:173], v[218:221], v[38:41]
	v_mfma_f32_16x16x32_bf16 v[34:37], v[178:181], v[218:221], v[34:37]
	v_mfma_f32_16x16x32_bf16 v[62:65], v[174:177], v[194:197], v[62:65]
	v_mfma_f32_16x16x32_bf16 v[58:61], v[182:185], v[194:197], v[58:61]
	v_mfma_f32_16x16x32_bf16 v[54:57], v[174:177], v[198:201], v[54:57]
	v_mfma_f32_16x16x32_bf16 v[50:53], v[182:185], v[198:201], v[50:53]
	v_mfma_f32_16x16x32_bf16 v[46:49], v[174:177], v[222:225], v[46:49]
	v_mfma_f32_16x16x32_bf16 v[42:45], v[182:185], v[222:225], v[42:45]
	v_mfma_f32_16x16x32_bf16 v[38:41], v[174:177], v[226:229], v[38:41]
	v_mfma_f32_16x16x32_bf16 v[34:37], v[182:185], v[226:229], v[34:37]
	v_mfma_f32_16x16x32_bf16 v[30:33], v[230:233], v[186:189], v[30:33]
	v_mfma_f32_16x16x32_bf16 v[26:29], v[238:241], v[186:189], v[26:29]
	v_mfma_f32_16x16x32_bf16 v[22:25], v[230:233], v[190:193], v[22:25]
	v_mfma_f32_16x16x32_bf16 v[18:21], v[238:241], v[190:193], v[18:21]
	v_mfma_f32_16x16x32_bf16 v[14:17], v[230:233], v[206:209], v[14:17]
	v_mfma_f32_16x16x32_bf16 v[10:13], v[238:241], v[206:209], v[10:13]
	v_mfma_f32_16x16x32_bf16 v[6:9], v[230:233], v[218:221], v[6:9]
	v_mfma_f32_16x16x32_bf16 v[2:5], v[238:241], v[218:221], v[2:5]
	v_mfma_f32_16x16x32_bf16 v[30:33], v[234:237], v[194:197], v[30:33]
	v_mfma_f32_16x16x32_bf16 v[26:29], v[242:245], v[194:197], v[26:29]
	v_mfma_f32_16x16x32_bf16 v[22:25], v[234:237], v[198:201], v[22:25]
	v_mfma_f32_16x16x32_bf16 v[18:21], v[242:245], v[198:201], v[18:21]
	v_mfma_f32_16x16x32_bf16 v[14:17], v[234:237], v[222:225], v[14:17]
	v_mfma_f32_16x16x32_bf16 v[10:13], v[242:245], v[222:225], v[10:13]
	v_mfma_f32_16x16x32_bf16 v[6:9], v[234:237], v[226:229], v[6:9]
	v_mfma_f32_16x16x32_bf16 v[2:5], v[242:245], v[226:229], v[2:5]
	s_setprio 0
	s_add_i32 s12, s12, 2
	s_add_u32 s10, s10, 0x100
	s_addc_u32 s11, s11, 0
	s_cmp_lt_u32 s12, 28
	s_barrier
	s_cbranch_scc1 .LBB0_642
	s_waitcnt vmcnt(6)
	v_or_b32_e32 v0, 0x10000, v152
	v_add_u32_e32 v155, 0x10800, v152
	v_or_b32_e32 v154, 0x10000, v153
	v_add_u32_e32 v156, 0x10800, v153
	v_or_b32_e32 v157, 0x14000, v152
	v_add_u32_e32 v159, 0x14800, v152
	v_or_b32_e32 v158, 0x14000, v153
	v_add_u32_e32 v160, 0x14800, v153
	v_or_b32_e32 v161, 0x18000, v152
	v_add_u32_e32 v163, 0x18800, v152
	v_or_b32_e32 v162, 0x18000, v153
	v_add_u32_e32 v164, 0x18800, v153
	v_or_b32_e32 v165, 0x1c000, v152
	v_add_u32_e32 v167, 0x1c800, v152
	v_or_b32_e32 v166, 0x1c000, v153
	v_add_u32_e32 v168, 0x1c800, v153
	s_mov_b64 s[2:3], 0xf80
	s_mov_b32 m0, s28
	v_lshl_add_u64 v[140:141], v[140:141], 0, s[2:3]
	ds_read_b128 v[142:145], v0
	ds_read_b128 v[146:149], v154
	ds_read_b128 v[152:155], v155
	ds_read_b128 v[170:173], v156
	ds_read_b128 v[174:177], v150
	ds_read_b128 v[178:181], v150 offset:2048
	ds_read_b128 v[182:185], v151
	ds_read_b128 v[186:189], v151 offset:2048
	ds_read_b128 v[190:193], v150 offset:4096
	ds_read_b128 v[194:197], v150 offset:6144
	ds_read_b128 v[198:201], v151 offset:4096
	ds_read_b128 v[206:209], v151 offset:6144
	global_load_lds_dwordx4 v[140:141], off
	v_lshl_add_u64 v[138:139], v[138:139], 0, s[2:3]
	s_mov_b32 m0, s13
	s_nop 0
	global_load_lds_dwordx4 v[138:139], off
	s_barrier
	s_waitcnt lgkmcnt(0)
	s_setprio 1
	s_waitcnt lgkmcnt(0)
	v_mfma_f32_16x16x32_bf16 v[126:129], v[142:145], v[174:177], v[126:129]
	v_mfma_f32_16x16x32_bf16 v[122:125], v[152:155], v[174:177], v[122:125]
	v_mfma_f32_16x16x32_bf16 v[114:117], v[152:155], v[178:181], v[114:117]
	v_mfma_f32_16x16x32_bf16 v[106:109], v[152:155], v[190:193], v[106:109]
	v_mfma_f32_16x16x32_bf16 v[98:101], v[152:155], v[194:197], v[98:101]
	v_mfma_f32_16x16x32_bf16 v[126:129], v[146:149], v[182:185], v[126:129]
	v_mfma_f32_16x16x32_bf16 v[122:125], v[170:173], v[182:185], v[122:125]
	v_mfma_f32_16x16x32_bf16 v[118:121], v[142:145], v[178:181], v[118:121]
	v_mfma_f32_16x16x32_bf16 v[114:117], v[170:173], v[186:189], v[114:117]
	v_mfma_f32_16x16x32_bf16 v[110:113], v[142:145], v[190:193], v[110:113]
	v_mfma_f32_16x16x32_bf16 v[106:109], v[170:173], v[198:201], v[106:109]
	v_mfma_f32_16x16x32_bf16 v[102:105], v[142:145], v[194:197], v[102:105]
	v_mfma_f32_16x16x32_bf16 v[98:101], v[170:173], v[206:209], v[98:101]
	v_mfma_f32_16x16x32_bf16 v[138:141], v[146:149], v[186:189], v[118:121]
	v_mfma_f32_16x16x32_bf16 v[218:221], v[146:149], v[198:201], v[110:113]
	v_mfma_f32_16x16x32_bf16 v[222:225], v[146:149], v[206:209], v[102:105]
	s_setprio 0
	s_barrier
	s_nop 1
	ds_read_b128 v[102:105], v157
	ds_read_b128 v[110:113], v158
	ds_read_b128 v[118:121], v159
	ds_read_b128 v[156:159], v160
	s_barrier
	s_waitcnt lgkmcnt(0)
	s_setprio 1
	s_waitcnt lgkmcnt(0)
	v_mfma_f32_16x16x32_bf16 v[90:93], v[118:121], v[174:177], v[90:93]
	v_mfma_f32_16x16x32_bf16 v[82:85], v[118:121], v[178:181], v[82:85]
	v_mfma_f32_16x16x32_bf16 v[74:77], v[118:121], v[190:193], v[74:77]
	v_mfma_f32_16x16x32_bf16 v[66:69], v[118:121], v[194:197], v[66:69]
	v_mfma_f32_16x16x32_bf16 v[94:97], v[102:105], v[174:177], v[94:97]
	v_mfma_f32_16x16x32_bf16 v[90:93], v[156:159], v[182:185], v[90:93]
	v_mfma_f32_16x16x32_bf16 v[86:89], v[102:105], v[178:181], v[86:89]
	v_mfma_f32_16x16x32_bf16 v[82:85], v[156:159], v[186:189], v[82:85]
	v_mfma_f32_16x16x32_bf16 v[78:81], v[102:105], v[190:193], v[78:81]
	v_mfma_f32_16x16x32_bf16 v[74:77], v[156:159], v[198:201], v[74:77]
	v_mfma_f32_16x16x32_bf16 v[70:73], v[102:105], v[194:197], v[70:73]
	v_mfma_f32_16x16x32_bf16 v[66:69], v[156:159], v[206:209], v[66:69]
	v_mfma_f32_16x16x32_bf16 v[226:229], v[110:113], v[182:185], v[94:97]
	v_mfma_f32_16x16x32_bf16 v[174:177], v[110:113], v[186:189], v[86:89]
	v_mfma_f32_16x16x32_bf16 v[178:181], v[110:113], v[198:201], v[78:81]
	v_mfma_f32_16x16x32_bf16 v[182:185], v[110:113], v[206:209], v[70:73]
	s_setprio 0
	s_barrier
	s_nop 0
	ds_read_b128 v[70:73], v150 offset:16384
	ds_read_b128 v[78:81], v150 offset:18432
	ds_read_b128 v[86:89], v151 offset:16384
	ds_read_b128 v[94:97], v151 offset:18432
	ds_read_b128 v[186:189], v150 offset:20480
	ds_read_b128 v[190:193], v150 offset:22528
	ds_read_b128 v[194:197], v151 offset:20480
	ds_read_b128 v[198:201], v151 offset:22528
	s_waitcnt vmcnt(4)
	s_barrier
	s_waitcnt lgkmcnt(0)
	s_setprio 1
	s_waitcnt lgkmcnt(0)
	v_mfma_f32_16x16x32_bf16 v[62:65], v[142:145], v[70:73], v[62:65]
	v_mfma_f32_16x16x32_bf16 v[58:61], v[152:155], v[70:73], v[58:61]
	v_mfma_f32_16x16x32_bf16 v[50:53], v[152:155], v[78:81], v[50:53]
	v_mfma_f32_16x16x32_bf16 v[42:45], v[152:155], v[186:189], v[42:45]
	v_mfma_f32_16x16x32_bf16 v[34:37], v[152:155], v[190:193], v[34:37]
	v_mfma_f32_16x16x32_bf16 v[62:65], v[146:149], v[86:89], v[62:65]
	v_mfma_f32_16x16x32_bf16 v[58:61], v[170:173], v[86:89], v[58:61]
	v_mfma_f32_16x16x32_bf16 v[54:57], v[142:145], v[78:81], v[54:57]
	v_mfma_f32_16x16x32_bf16 v[50:53], v[170:173], v[94:97], v[50:53]
	v_mfma_f32_16x16x32_bf16 v[46:49], v[142:145], v[186:189], v[46:49]
	v_mfma_f32_16x16x32_bf16 v[42:45], v[170:173], v[194:197], v[42:45]
	v_mfma_f32_16x16x32_bf16 v[38:41], v[142:145], v[190:193], v[38:41]
	v_mfma_f32_16x16x32_bf16 v[34:37], v[170:173], v[198:201], v[34:37]
	v_mfma_f32_16x16x32_bf16 v[206:209], v[146:149], v[94:97], v[54:57]
	v_mfma_f32_16x16x32_bf16 v[230:233], v[146:149], v[194:197], v[46:49]
	v_mfma_f32_16x16x32_bf16 v[142:145], v[146:149], v[198:201], v[38:41]
	s_setprio 0
	s_setprio 1
	v_mfma_f32_16x16x32_bf16 v[26:29], v[118:121], v[70:73], v[26:29]
	v_mfma_f32_16x16x32_bf16 v[18:21], v[118:121], v[78:81], v[18:21]
	v_mfma_f32_16x16x32_bf16 v[10:13], v[118:121], v[186:189], v[10:13]
	v_mfma_f32_16x16x32_bf16 v[2:5], v[118:121], v[190:193], v[2:5]
	v_mfma_f32_16x16x32_bf16 v[30:33], v[102:105], v[70:73], v[30:33]
	v_mfma_f32_16x16x32_bf16 v[26:29], v[156:159], v[86:89], v[26:29]
	v_mfma_f32_16x16x32_bf16 v[22:25], v[102:105], v[78:81], v[22:25]
	v_mfma_f32_16x16x32_bf16 v[18:21], v[156:159], v[94:97], v[18:21]
	v_mfma_f32_16x16x32_bf16 v[14:17], v[102:105], v[186:189], v[14:17]
	v_mfma_f32_16x16x32_bf16 v[10:13], v[156:159], v[194:197], v[10:13]
	v_mfma_f32_16x16x32_bf16 v[6:9], v[102:105], v[190:193], v[6:9]
	v_mfma_f32_16x16x32_bf16 v[2:5], v[156:159], v[198:201], v[2:5]
	v_mfma_f32_16x16x32_bf16 v[146:149], v[110:113], v[86:89], v[30:33]
	v_mfma_f32_16x16x32_bf16 v[152:155], v[110:113], v[94:97], v[22:25]
	v_mfma_f32_16x16x32_bf16 v[170:173], v[110:113], v[194:197], v[14:17]
	v_mfma_f32_16x16x32_bf16 v[186:189], v[110:113], v[198:201], v[6:9]
	s_setprio 0
	s_barrier
	s_nop 0
	ds_read_b128 v[6:9], v161
	ds_read_b128 v[14:17], v162
	ds_read_b128 v[156:159], v163
	ds_read_b128 v[160:163], v164
	ds_read_b128 v[22:25], v150 offset:32768
	ds_read_b128 v[30:33], v150 offset:34816
	ds_read_b128 v[38:41], v151 offset:32768
	ds_read_b128 v[46:49], v151 offset:34816
	ds_read_b128 v[54:57], v150 offset:36864
	ds_read_b128 v[190:193], v150 offset:38912
	ds_read_b128 v[194:197], v151 offset:36864
	ds_read_b128 v[198:201], v151 offset:38912
	s_waitcnt vmcnt(2)
	s_barrier
	s_waitcnt lgkmcnt(0)
	s_setprio 1
	s_waitcnt lgkmcnt(0)
	v_mfma_f32_16x16x32_bf16 v[70:73], v[6:9], v[22:25], v[126:129]
	v_mfma_f32_16x16x32_bf16 v[126:129], v[14:17], v[38:41], v[70:73]
	v_mfma_f32_16x16x32_bf16 v[70:73], v[156:159], v[22:25], v[122:125]
	v_mfma_f32_16x16x32_bf16 v[118:121], v[160:163], v[38:41], v[70:73]
	v_mfma_f32_16x16x32_bf16 v[70:73], v[6:9], v[30:33], v[138:141]
	v_mfma_f32_16x16x32_bf16 v[110:113], v[14:17], v[46:49], v[70:73]
	v_mfma_f32_16x16x32_bf16 v[70:73], v[156:159], v[30:33], v[114:117]
	v_mfma_f32_16x16x32_bf16 v[102:105], v[160:163], v[46:49], v[70:73]
	v_mfma_f32_16x16x32_bf16 v[70:73], v[6:9], v[54:57], v[218:221]
	v_mfma_f32_16x16x32_bf16 v[94:97], v[14:17], v[194:197], v[70:73]
	v_mfma_f32_16x16x32_bf16 v[70:73], v[156:159], v[54:57], v[106:109]
	v_mfma_f32_16x16x32_bf16 v[86:89], v[160:163], v[194:197], v[70:73]
	v_mfma_f32_16x16x32_bf16 v[70:73], v[6:9], v[190:193], v[222:225]
	v_mfma_f32_16x16x32_bf16 v[78:81], v[14:17], v[198:201], v[70:73]
	v_mfma_f32_16x16x32_bf16 v[70:73], v[156:159], v[190:193], v[98:101]
	v_mfma_f32_16x16x32_bf16 v[70:73], v[160:163], v[198:201], v[70:73]
	s_setprio 0
	s_barrier
	ds_read_b128 v[138:141], v165
	ds_read_b128 v[218:221], v166
	ds_read_b128 v[164:167], v167
	ds_read_b128 v[222:225], v168
	s_waitcnt vmcnt(0)
	s_barrier
	s_waitcnt lgkmcnt(0)
	s_setprio 1
	s_waitcnt lgkmcnt(0)
	v_mfma_f32_16x16x32_bf16 v[98:101], v[138:141], v[22:25], v[226:229]
	v_mfma_f32_16x16x32_bf16 v[22:25], v[164:167], v[22:25], v[90:93]
	v_mfma_f32_16x16x32_bf16 v[114:117], v[222:225], v[38:41], v[22:25]
	v_mfma_f32_16x16x32_bf16 v[22:25], v[138:141], v[30:33], v[174:177]
	v_mfma_f32_16x16x32_bf16 v[106:109], v[218:221], v[46:49], v[22:25]
	v_mfma_f32_16x16x32_bf16 v[22:25], v[164:167], v[30:33], v[82:85]
	v_mfma_f32_16x16x32_bf16 v[122:125], v[218:221], v[38:41], v[98:101]
	v_mfma_f32_16x16x32_bf16 v[98:101], v[222:225], v[46:49], v[22:25]
	v_mfma_f32_16x16x32_bf16 v[22:25], v[138:141], v[54:57], v[178:181]
	v_mfma_f32_16x16x32_bf16 v[90:93], v[218:221], v[194:197], v[22:25]
	v_mfma_f32_16x16x32_bf16 v[22:25], v[164:167], v[54:57], v[74:77]
	v_mfma_f32_16x16x32_bf16 v[82:85], v[222:225], v[194:197], v[22:25]
	v_mfma_f32_16x16x32_bf16 v[22:25], v[138:141], v[190:193], v[182:185]
	v_mfma_f32_16x16x32_bf16 v[74:77], v[218:221], v[198:201], v[22:25]
	v_mfma_f32_16x16x32_bf16 v[22:25], v[164:167], v[190:193], v[66:69]
	v_mfma_f32_16x16x32_bf16 v[66:69], v[222:225], v[198:201], v[22:25]
	s_setprio 0
	s_barrier
	ds_read_b128 v[174:177], v150 offset:49152
	ds_read_b128 v[178:181], v150 offset:51200
	ds_read_b128 v[182:185], v151 offset:49152
	ds_read_b128 v[190:193], v151 offset:51200
	ds_read_b128 v[194:197], v150 offset:53248
	ds_read_b128 v[198:201], v150 offset:55296
	ds_read_b128 v[226:229], v151 offset:53248
	ds_read_b128 v[234:237], v151 offset:55296
	s_barrier
	s_waitcnt lgkmcnt(0)
	s_setprio 1
	s_waitcnt lgkmcnt(0)
	v_mfma_f32_16x16x32_bf16 v[22:25], v[6:9], v[174:177], v[62:65]
	v_mfma_f32_16x16x32_bf16 v[62:65], v[14:17], v[182:185], v[22:25]
	v_mfma_f32_16x16x32_bf16 v[22:25], v[156:159], v[174:177], v[58:61]
	v_mfma_f32_16x16x32_bf16 v[54:57], v[160:163], v[182:185], v[22:25]
	v_mfma_f32_16x16x32_bf16 v[22:25], v[6:9], v[178:181], v[206:209]
	v_mfma_f32_16x16x32_bf16 v[46:49], v[14:17], v[190:193], v[22:25]
	v_mfma_f32_16x16x32_bf16 v[22:25], v[156:159], v[178:181], v[50:53]
	v_mfma_f32_16x16x32_bf16 v[38:41], v[160:163], v[190:193], v[22:25]
	v_mfma_f32_16x16x32_bf16 v[22:25], v[6:9], v[194:197], v[230:233]
	v_mfma_f32_16x16x32_bf16 v[6:9], v[6:9], v[198:201], v[142:145]
	v_mfma_f32_16x16x32_bf16 v[30:33], v[14:17], v[226:229], v[22:25]
	v_mfma_f32_16x16x32_bf16 v[22:25], v[156:159], v[194:197], v[42:45]
	v_mfma_f32_16x16x32_bf16 v[14:17], v[14:17], v[234:237], v[6:9]
	v_mfma_f32_16x16x32_bf16 v[6:9], v[156:159], v[198:201], v[34:37]
	v_mfma_f32_16x16x32_bf16 v[22:25], v[160:163], v[226:229], v[22:25]
	v_mfma_f32_16x16x32_bf16 v[6:9], v[160:163], v[234:237], v[6:9]
	s_setprio 0
	s_setprio 1
	v_mfma_f32_16x16x32_bf16 v[34:37], v[138:141], v[174:177], v[146:149]
	v_mfma_f32_16x16x32_bf16 v[26:29], v[164:167], v[174:177], v[26:29]
	v_mfma_f32_16x16x32_bf16 v[18:21], v[164:167], v[178:181], v[18:21]
	v_mfma_f32_16x16x32_bf16 v[58:61], v[218:221], v[182:185], v[34:37]
	v_mfma_f32_16x16x32_bf16 v[50:53], v[222:225], v[182:185], v[26:29]
	v_mfma_f32_16x16x32_bf16 v[26:29], v[138:141], v[178:181], v[152:155]
	v_mfma_f32_16x16x32_bf16 v[34:37], v[222:225], v[190:193], v[18:21]
	v_mfma_f32_16x16x32_bf16 v[18:21], v[138:141], v[194:197], v[170:173]
	v_mfma_f32_16x16x32_bf16 v[10:13], v[164:167], v[194:197], v[10:13]
	v_mfma_f32_16x16x32_bf16 v[42:45], v[218:221], v[190:193], v[26:29]
	v_mfma_f32_16x16x32_bf16 v[26:29], v[218:221], v[226:229], v[18:21]
	v_mfma_f32_16x16x32_bf16 v[18:21], v[222:225], v[226:229], v[10:13]
	v_mfma_f32_16x16x32_bf16 v[10:13], v[138:141], v[198:201], v[186:189]
	v_mfma_f32_16x16x32_bf16 v[2:5], v[164:167], v[198:201], v[2:5]
	v_mfma_f32_16x16x32_bf16 v[10:13], v[218:221], v[234:237], v[10:13]
	v_mfma_f32_16x16x32_bf16 v[2:5], v[222:225], v[234:237], v[2:5]
	s_setprio 0
	s_cmpk_gt_u32 s0, 0xff
	s_barrier
	s_cbranch_scc1 .LBB0_633
	s_barrier
	s_branch .LBB0_633

.LBB0_664:
	s_lshl_b32 s20, s20, 5
	v_and_b32_e32 v19, 15, v17
	s_and_b32 s20, s20, 0x60
	v_lshlrev_b32_e32 v20, 7, v19
	v_or_b32_e32 v19, s20, v19
	s_add_i32 s20, s1, 0x18000
	s_mov_b64 s[26:27], 0x80
	v_lshl_or_b32 v20, s21, 13, v20
	v_lshl_add_u64 v[2:3], v[2:3], 0, s[26:27]
	s_mov_b32 m0, s20
	s_add_i32 s21, s1, 0x1a000
	s_waitcnt vmcnt(4)
	s_barrier
	global_load_lds_dwordx4 v[2:3], off
	v_lshl_add_u64 v[2:3], v[4:5], 0, s[26:27]
	s_mov_b32 m0, s21
	s_mov_b64 s[22:23], 0x400800
	global_load_lds_dwordx4 v[2:3], off
	v_lshl_add_u64 v[2:3], v[6:7], 0, s[22:23]
	s_add_i32 s22, s1, 0x8000
	v_lshl_add_u64 v[4:5], v[0:1], 1, v[2:3]
	s_mov_b32 m0, s22
	s_add_i32 s23, s1, 0xa000
	global_load_lds_dwordx4 v[4:5], off nt
	v_lshl_add_u64 v[2:3], v[138:139], 1, v[2:3]
	s_mov_b32 m0, s23
	s_add_i32 s24, s1, 0x1c000
	global_load_lds_dwordx4 v[2:3], off nt
	v_lshl_add_u64 v[2:3], v[10:11], 0, s[26:27]
	s_mov_b32 m0, s24
	s_add_i32 s25, s1, 0x1e000
	global_load_lds_dwordx4 v[2:3], off
	v_lshl_add_u64 v[2:3], v[8:9], 0, s[26:27]
	s_mov_b32 m0, s25
	s_add_u32 s12, s4, s12
	global_load_lds_dwordx4 v[2:3], off
	s_addc_u32 s13, 0, s13
	v_add_u32_e32 v2, v16, v12
	v_mov_b32_e32 v3, v1
	v_lshl_add_u64 v[142:143], v[2:3], 1, s[12:13]
	v_add_u32_e32 v2, v14, v12
	v_bfe_u32 v21, v17, 4, 2
	v_bfe_u32 v17, v17, 1, 3
	v_lshl_add_u64 v[144:145], v[2:3], 1, s[12:13]
	v_add_u32_e32 v2, v15, v12
	v_bitop3_b32 v18, v18, v17, 3 bitop3:0x6c
	v_bitop3_b32 v17, v21, v17, 4 bitop3:0x36
	s_waitcnt vmcnt(6)
	v_lshl_add_u64 v[146:147], v[2:3], 1, s[10:11]
	v_add_u32_e32 v2, v13, v12
	v_lshlrev_b32_e32 v18, 4, v18
	v_lshlrev_b32_e32 v17, 4, v17
	v_lshlrev_b32_e32 v19, 7, v19
	v_lshl_add_u64 v[148:149], v[2:3], 1, s[10:11]
	v_mov_b32_e32 v2, 0
	v_or_b32_e32 v150, v18, v20
	v_or_b32_e32 v152, v19, v18
	v_or_b32_e32 v153, v19, v17
	v_or_b32_e32 v151, v17, v20
	s_mov_b32 s10, -2
	v_mov_b32_e32 v3, v2
	v_mov_b32_e32 v4, v2
	v_mov_b32_e32 v5, v2
	v_mov_b32_e32 v6, v2
	v_mov_b32_e32 v7, v2
	v_mov_b32_e32 v8, v2
	v_mov_b32_e32 v9, v2
	v_mov_b32_e32 v10, v2
	v_mov_b32_e32 v11, v2
	v_mov_b32_e32 v12, v2
	v_mov_b32_e32 v13, v2
	v_mov_b32_e32 v14, v2
	v_mov_b32_e32 v15, v2
	v_mov_b32_e32 v16, v2
	v_mov_b32_e32 v17, v2
	v_mov_b32_e32 v18, v2
	v_mov_b32_e32 v19, v2
	v_mov_b32_e32 v20, v2
	v_mov_b32_e32 v21, v2
	v_mov_b32_e32 v22, v2
	v_mov_b32_e32 v23, v2
	v_mov_b32_e32 v24, v2
	v_mov_b32_e32 v25, v2
	v_mov_b32_e32 v26, v2
	v_mov_b32_e32 v27, v2
	v_mov_b32_e32 v28, v2
	v_mov_b32_e32 v29, v2
	v_mov_b32_e32 v30, v2
	v_mov_b32_e32 v31, v2
	v_mov_b32_e32 v32, v2
	v_mov_b32_e32 v33, v2
	v_mov_b32_e32 v34, v2
	v_mov_b32_e32 v35, v2
	v_mov_b32_e32 v36, v2
	v_mov_b32_e32 v37, v2
	v_mov_b32_e32 v38, v2
	v_mov_b32_e32 v39, v2
	v_mov_b32_e32 v40, v2
	v_mov_b32_e32 v41, v2
	v_mov_b32_e32 v42, v2
	v_mov_b32_e32 v43, v2
	v_mov_b32_e32 v44, v2
	v_mov_b32_e32 v45, v2
	v_mov_b32_e32 v46, v2
	v_mov_b32_e32 v47, v2
	v_mov_b32_e32 v48, v2
	v_mov_b32_e32 v49, v2
	v_mov_b32_e32 v50, v2
	v_mov_b32_e32 v51, v2
	v_mov_b32_e32 v52, v2
	v_mov_b32_e32 v53, v2
	v_mov_b32_e32 v54, v2
	v_mov_b32_e32 v55, v2
	v_mov_b32_e32 v56, v2
	v_mov_b32_e32 v57, v2
	v_mov_b32_e32 v58, v2
	v_mov_b32_e32 v59, v2
	v_mov_b32_e32 v60, v2
	v_mov_b32_e32 v61, v2
	v_mov_b32_e32 v62, v2
	v_mov_b32_e32 v63, v2
	v_mov_b32_e32 v64, v2
	v_mov_b32_e32 v65, v2
	v_mov_b32_e32 v66, v2
	v_mov_b32_e32 v67, v2
	v_mov_b32_e32 v68, v2
	v_mov_b32_e32 v69, v2
	v_mov_b32_e32 v70, v2
	v_mov_b32_e32 v71, v2
	v_mov_b32_e32 v72, v2
	v_mov_b32_e32 v73, v2
	v_mov_b32_e32 v74, v2
	v_mov_b32_e32 v75, v2
	v_mov_b32_e32 v76, v2
	v_mov_b32_e32 v77, v2
	v_mov_b32_e32 v78, v2
	v_mov_b32_e32 v79, v2
	v_mov_b32_e32 v80, v2
	v_mov_b32_e32 v81, v2
	v_mov_b32_e32 v82, v2
	v_mov_b32_e32 v83, v2
	v_mov_b32_e32 v84, v2
	v_mov_b32_e32 v85, v2
	v_mov_b32_e32 v86, v2
	v_mov_b32_e32 v87, v2
	v_mov_b32_e32 v88, v2
	v_mov_b32_e32 v89, v2
	v_mov_b32_e32 v90, v2
	v_mov_b32_e32 v91, v2
	v_mov_b32_e32 v92, v2
	v_mov_b32_e32 v93, v2
	v_mov_b32_e32 v94, v2
	v_mov_b32_e32 v95, v2
	v_mov_b32_e32 v96, v2
	v_mov_b32_e32 v97, v2
	v_mov_b32_e32 v98, v2
	v_mov_b32_e32 v99, v2
	v_mov_b32_e32 v100, v2
	v_mov_b32_e32 v101, v2
	v_mov_b32_e32 v102, v2
	v_mov_b32_e32 v103, v2
	v_mov_b32_e32 v104, v2
	v_mov_b32_e32 v105, v2
	v_mov_b32_e32 v106, v2
	v_mov_b32_e32 v107, v2
	v_mov_b32_e32 v108, v2
	v_mov_b32_e32 v109, v2
	v_mov_b32_e32 v110, v2
	v_mov_b32_e32 v111, v2
	v_mov_b32_e32 v112, v2
	v_mov_b32_e32 v113, v2
	v_mov_b32_e32 v114, v2
	v_mov_b32_e32 v115, v2
	v_mov_b32_e32 v116, v2
	v_mov_b32_e32 v117, v2
	v_mov_b32_e32 v118, v2
	v_mov_b32_e32 v119, v2
	v_mov_b32_e32 v120, v2
	v_mov_b32_e32 v121, v2
	v_mov_b32_e32 v122, v2
	v_mov_b32_e32 v123, v2
	v_mov_b32_e32 v124, v2
	v_mov_b32_e32 v125, v2
	v_mov_b32_e32 v126, v2
	v_mov_b32_e32 v127, v2
	v_mov_b32_e32 v128, v2
	v_mov_b32_e32 v129, v2
	s_mov_b64 s[26:27], 0x404800
	s_mov_b64 s[30:31], 0xc254900
	s_mov_b64 s[34:35], 0xc454900
	s_mov_b64 s[36:37], 0x805000
	v_readfirstlane_b32 s100, v130
	v_readfirstlane_b32 s101, v131
	s_mov_b64 vcc, s[100:101]
	s_mov_b32 s11, s100
	s_mov_b32 s12, s101
	v_add_u32_e32 v202, 0x10000, v152
	v_add_u32_e32 v203, 0x10000, v153
	s_barrier
.LBB0_665:
	ds_read_b128 v[162:165], v202
	ds_read_b128 v[166:169], v203
	ds_read_b128 v[170:173], v202 offset:2048
	ds_read_b128 v[174:177], v203 offset:2048
	s_add_i32 m0, s1, 0xc000
	ds_read_b128 v[178:181], v150
	ds_read_b128 v[182:185], v150 offset:2048
	ds_read_b128 v[186:189], v151
	ds_read_b128 v[190:193], v151 offset:2048
	ds_read_b128 v[194:197], v150 offset:4096
	ds_read_b128 v[198:201], v150 offset:6144
	ds_read_b128 v[206:209], v151 offset:4096
	ds_read_b128 v[218:221], v151 offset:6144
	s_add_u32 s100, vcc_lo, s26
	s_addc_u32 s101, vcc_hi, s27
	global_load_lds_dwordx4 v144, s[100:101] nt
	s_add_i32 m0, s1, 0xe000
	s_add_u32 s100, vcc_lo, s26
	s_addc_u32 s101, vcc_hi, s27
	global_load_lds_dwordx4 v142, s[100:101] nt
	s_waitcnt lgkmcnt(8)
	s_waitcnt vmcnt(10)
	s_barrier
	s_waitcnt lgkmcnt(0)
	s_setprio 1
	s_waitcnt lgkmcnt(0)
	v_mfma_f32_16x16x32_bf16 v[126:129], v[162:165], v[178:181], v[126:129]
	v_mfma_f32_16x16x32_bf16 v[122:125], v[170:173], v[178:181], v[122:125]
	v_mfma_f32_16x16x32_bf16 v[118:121], v[162:165], v[182:185], v[118:121]
	v_mfma_f32_16x16x32_bf16 v[114:117], v[170:173], v[182:185], v[114:117]
	v_mfma_f32_16x16x32_bf16 v[110:113], v[162:165], v[194:197], v[110:113]
	v_mfma_f32_16x16x32_bf16 v[106:109], v[170:173], v[194:197], v[106:109]
	v_mfma_f32_16x16x32_bf16 v[102:105], v[162:165], v[198:201], v[102:105]
	v_mfma_f32_16x16x32_bf16 v[98:101], v[170:173], v[198:201], v[98:101]
	v_mfma_f32_16x16x32_bf16 v[126:129], v[166:169], v[186:189], v[126:129]
	v_mfma_f32_16x16x32_bf16 v[122:125], v[174:177], v[186:189], v[122:125]
	v_mfma_f32_16x16x32_bf16 v[118:121], v[166:169], v[190:193], v[118:121]
	v_mfma_f32_16x16x32_bf16 v[114:117], v[174:177], v[190:193], v[114:117]
	v_mfma_f32_16x16x32_bf16 v[110:113], v[166:169], v[206:209], v[110:113]
	v_mfma_f32_16x16x32_bf16 v[106:109], v[174:177], v[206:209], v[106:109]
	v_mfma_f32_16x16x32_bf16 v[102:105], v[166:169], v[218:221], v[102:105]
	v_mfma_f32_16x16x32_bf16 v[98:101], v[174:177], v[218:221], v[98:101]
	s_setprio 0
	s_barrier
	s_mov_b32 m0, s2
	ds_read_b128 v[222:225], v202 offset:16384
	ds_read_b128 v[226:229], v203 offset:16384
	ds_read_b128 v[230:233], v202 offset:18432
	ds_read_b128 v[234:237], v203 offset:18432
	s_add_u32 s100, s11, s30
	s_addc_u32 s101, s12, s31
	global_load_lds_dwordx4 v148, s[100:101]
	s_mov_b32 m0, s3
	s_add_u32 s100, s11, s30
	s_addc_u32 s101, s12, s31
	global_load_lds_dwordx4 v146, s[100:101]
	s_waitcnt vmcnt(10)
	s_waitcnt lgkmcnt(0)
	s_barrier
	s_waitcnt lgkmcnt(0)
	s_setprio 1
	s_waitcnt lgkmcnt(0)
	v_mfma_f32_16x16x32_bf16 v[94:97], v[222:225], v[178:181], v[94:97]
	v_mfma_f32_16x16x32_bf16 v[90:93], v[230:233], v[178:181], v[90:93]
	v_mfma_f32_16x16x32_bf16 v[86:89], v[222:225], v[182:185], v[86:89]
	v_mfma_f32_16x16x32_bf16 v[82:85], v[230:233], v[182:185], v[82:85]
	v_mfma_f32_16x16x32_bf16 v[78:81], v[222:225], v[194:197], v[78:81]
	v_mfma_f32_16x16x32_bf16 v[74:77], v[230:233], v[194:197], v[74:77]
	v_mfma_f32_16x16x32_bf16 v[70:73], v[222:225], v[198:201], v[70:73]
	v_mfma_f32_16x16x32_bf16 v[66:69], v[230:233], v[198:201], v[66:69]
	v_mfma_f32_16x16x32_bf16 v[94:97], v[226:229], v[186:189], v[94:97]
	v_mfma_f32_16x16x32_bf16 v[90:93], v[234:237], v[186:189], v[90:93]
	v_mfma_f32_16x16x32_bf16 v[86:89], v[226:229], v[190:193], v[86:89]
	v_mfma_f32_16x16x32_bf16 v[82:85], v[234:237], v[190:193], v[82:85]
	v_mfma_f32_16x16x32_bf16 v[78:81], v[226:229], v[206:209], v[78:81]
	v_mfma_f32_16x16x32_bf16 v[74:77], v[234:237], v[206:209], v[74:77]
	v_mfma_f32_16x16x32_bf16 v[70:73], v[226:229], v[218:221], v[70:73]
	v_mfma_f32_16x16x32_bf16 v[66:69], v[234:237], v[218:221], v[66:69]
	s_setprio 0
	s_mov_b32 m0, s1
	s_barrier
	ds_read_b128 v[178:181], v150 offset:16384
	ds_read_b128 v[182:185], v150 offset:18432
	ds_read_b128 v[186:189], v151 offset:16384
	ds_read_b128 v[190:193], v151 offset:18432
	ds_read_b128 v[194:197], v150 offset:20480
	ds_read_b128 v[198:201], v150 offset:22528
	ds_read_b128 v[206:209], v151 offset:20480
	ds_read_b128 v[218:221], v151 offset:22528
	s_add_u32 s100, vcc_lo, s42
	s_addc_u32 s101, vcc_hi, s43
	global_load_lds_dwordx4 v144, s[100:101] nt
	s_mov_b32 m0, s5
	s_add_u32 s100, vcc_lo, s42
	s_addc_u32 s101, vcc_hi, s43
	global_load_lds_dwordx4 v142, s[100:101] nt
	s_mov_b32 m0, s15
	s_add_u32 s100, s11, s34
	s_addc_u32 s101, s12, s35
	global_load_lds_dwordx4 v148, s[100:101]
	s_mov_b32 m0, s17
	s_add_u32 s100, s11, s34
	s_addc_u32 s101, s12, s35
	global_load_lds_dwordx4 v146, s[100:101]
	s_waitcnt vmcnt(10)
	s_waitcnt lgkmcnt(0)
	s_barrier
	s_waitcnt lgkmcnt(0)
	s_setprio 1
	s_waitcnt lgkmcnt(0)
	v_mfma_f32_16x16x32_bf16 v[62:65], v[162:165], v[178:181], v[62:65]
	v_mfma_f32_16x16x32_bf16 v[58:61], v[170:173], v[178:181], v[58:61]
	v_mfma_f32_16x16x32_bf16 v[54:57], v[162:165], v[182:185], v[54:57]
	v_mfma_f32_16x16x32_bf16 v[50:53], v[170:173], v[182:185], v[50:53]
	v_mfma_f32_16x16x32_bf16 v[46:49], v[162:165], v[194:197], v[46:49]
	v_mfma_f32_16x16x32_bf16 v[42:45], v[170:173], v[194:197], v[42:45]
	v_mfma_f32_16x16x32_bf16 v[38:41], v[162:165], v[198:201], v[38:41]
	v_mfma_f32_16x16x32_bf16 v[34:37], v[170:173], v[198:201], v[34:37]
	v_mfma_f32_16x16x32_bf16 v[62:65], v[166:169], v[186:189], v[62:65]
	v_mfma_f32_16x16x32_bf16 v[58:61], v[174:177], v[186:189], v[58:61]
	v_mfma_f32_16x16x32_bf16 v[54:57], v[166:169], v[190:193], v[54:57]
	v_mfma_f32_16x16x32_bf16 v[50:53], v[174:177], v[190:193], v[50:53]
	v_mfma_f32_16x16x32_bf16 v[46:49], v[166:169], v[206:209], v[46:49]
	v_mfma_f32_16x16x32_bf16 v[42:45], v[174:177], v[206:209], v[42:45]
	v_mfma_f32_16x16x32_bf16 v[38:41], v[166:169], v[218:221], v[38:41]
	v_mfma_f32_16x16x32_bf16 v[34:37], v[174:177], v[218:221], v[34:37]
	v_mfma_f32_16x16x32_bf16 v[30:33], v[222:225], v[178:181], v[30:33]
	v_mfma_f32_16x16x32_bf16 v[26:29], v[230:233], v[178:181], v[26:29]
	v_mfma_f32_16x16x32_bf16 v[22:25], v[222:225], v[182:185], v[22:25]
	v_mfma_f32_16x16x32_bf16 v[18:21], v[230:233], v[182:185], v[18:21]
	v_mfma_f32_16x16x32_bf16 v[14:17], v[222:225], v[194:197], v[14:17]
	v_mfma_f32_16x16x32_bf16 v[10:13], v[230:233], v[194:197], v[10:13]
	v_mfma_f32_16x16x32_bf16 v[6:9], v[222:225], v[198:201], v[6:9]
	v_mfma_f32_16x16x32_bf16 v[2:5], v[230:233], v[198:201], v[2:5]
	v_mfma_f32_16x16x32_bf16 v[30:33], v[226:229], v[186:189], v[30:33]
	v_mfma_f32_16x16x32_bf16 v[26:29], v[234:237], v[186:189], v[26:29]
	v_mfma_f32_16x16x32_bf16 v[22:25], v[226:229], v[190:193], v[22:25]
	v_mfma_f32_16x16x32_bf16 v[18:21], v[234:237], v[190:193], v[18:21]
	v_mfma_f32_16x16x32_bf16 v[14:17], v[226:229], v[206:209], v[14:17]
	v_mfma_f32_16x16x32_bf16 v[10:13], v[234:237], v[206:209], v[10:13]
	v_mfma_f32_16x16x32_bf16 v[6:9], v[226:229], v[218:221], v[6:9]
	v_mfma_f32_16x16x32_bf16 v[2:5], v[234:237], v[218:221], v[2:5]
	s_setprio 0
	s_barrier
	ds_read_b128 v[170:173], v202 offset:32768
	ds_read_b128 v[174:177], v203 offset:32768
	ds_read_b128 v[178:181], v202 offset:34816
	ds_read_b128 v[182:185], v203 offset:34816
	s_mov_b32 m0, s18
	ds_read_b128 v[186:189], v150 offset:32768
	ds_read_b128 v[190:193], v150 offset:34816
	ds_read_b128 v[194:197], v151 offset:32768
	ds_read_b128 v[198:201], v151 offset:34816
	ds_read_b128 v[206:209], v150 offset:36864
	ds_read_b128 v[218:221], v150 offset:38912
	ds_read_b128 v[222:225], v151 offset:36864
	ds_read_b128 v[226:229], v151 offset:38912
	s_add_u32 s100, vcc_lo, s36
	s_addc_u32 s101, vcc_hi, s37
	global_load_lds_dwordx4 v144, s[100:101] nt
	s_mov_b32 m0, s19
	s_add_u32 s100, vcc_lo, s36
	s_addc_u32 s101, vcc_hi, s37
	global_load_lds_dwordx4 v142, s[100:101] nt
	s_waitcnt lgkmcnt(8)
	s_waitcnt vmcnt(10)
	s_barrier
	s_waitcnt lgkmcnt(0)
	s_setprio 1
	s_waitcnt lgkmcnt(0)
	v_mfma_f32_16x16x32_bf16 v[126:129], v[170:173], v[186:189], v[126:129]
	v_mfma_f32_16x16x32_bf16 v[122:125], v[178:181], v[186:189], v[122:125]
	v_mfma_f32_16x16x32_bf16 v[118:121], v[170:173], v[190:193], v[118:121]
	v_mfma_f32_16x16x32_bf16 v[114:117], v[178:181], v[190:193], v[114:117]
	v_mfma_f32_16x16x32_bf16 v[110:113], v[170:173], v[206:209], v[110:113]
	v_mfma_f32_16x16x32_bf16 v[106:109], v[178:181], v[206:209], v[106:109]
	v_mfma_f32_16x16x32_bf16 v[102:105], v[170:173], v[218:221], v[102:105]
	v_mfma_f32_16x16x32_bf16 v[98:101], v[178:181], v[218:221], v[98:101]
	v_mfma_f32_16x16x32_bf16 v[126:129], v[174:177], v[194:197], v[126:129]
	v_mfma_f32_16x16x32_bf16 v[122:125], v[182:185], v[194:197], v[122:125]
	v_mfma_f32_16x16x32_bf16 v[118:121], v[174:177], v[198:201], v[118:121]
	v_mfma_f32_16x16x32_bf16 v[114:117], v[182:185], v[198:201], v[114:117]
	v_mfma_f32_16x16x32_bf16 v[110:113], v[174:177], v[222:225], v[110:113]
	v_mfma_f32_16x16x32_bf16 v[106:109], v[182:185], v[222:225], v[106:109]
	v_mfma_f32_16x16x32_bf16 v[102:105], v[174:177], v[226:229], v[102:105]
	v_mfma_f32_16x16x32_bf16 v[98:101], v[182:185], v[226:229], v[98:101]
	s_setprio 0
	s_barrier
	s_mov_b32 m0, s20
	ds_read_b128 v[230:233], v202 offset:49152
	ds_read_b128 v[234:237], v203 offset:49152
	ds_read_b128 v[238:241], v202 offset:51200
	ds_read_b128 v[242:245], v203 offset:51200
	s_add_u32 s100, s11, s46
	s_addc_u32 s101, s12, s47
	global_load_lds_dwordx4 v148, s[100:101]
	s_mov_b32 m0, s21
	s_add_u32 s100, s11, s46
	s_addc_u32 s101, s12, s47
	global_load_lds_dwordx4 v146, s[100:101]
	s_waitcnt vmcnt(10)
	s_waitcnt lgkmcnt(0)
	s_barrier
	s_waitcnt lgkmcnt(0)
	s_setprio 1
	s_waitcnt lgkmcnt(0)
	v_mfma_f32_16x16x32_bf16 v[94:97], v[230:233], v[186:189], v[94:97]
	v_mfma_f32_16x16x32_bf16 v[90:93], v[238:241], v[186:189], v[90:93]
	v_mfma_f32_16x16x32_bf16 v[86:89], v[230:233], v[190:193], v[86:89]
	v_mfma_f32_16x16x32_bf16 v[82:85], v[238:241], v[190:193], v[82:85]
	v_mfma_f32_16x16x32_bf16 v[78:81], v[230:233], v[206:209], v[78:81]
	v_mfma_f32_16x16x32_bf16 v[74:77], v[238:241], v[206:209], v[74:77]
	v_mfma_f32_16x16x32_bf16 v[70:73], v[230:233], v[218:221], v[70:73]
	v_mfma_f32_16x16x32_bf16 v[66:69], v[238:241], v[218:221], v[66:69]
	v_mfma_f32_16x16x32_bf16 v[94:97], v[234:237], v[194:197], v[94:97]
	v_mfma_f32_16x16x32_bf16 v[90:93], v[242:245], v[194:197], v[90:93]
	v_mfma_f32_16x16x32_bf16 v[86:89], v[234:237], v[198:201], v[86:89]
	v_mfma_f32_16x16x32_bf16 v[82:85], v[242:245], v[198:201], v[82:85]
	v_mfma_f32_16x16x32_bf16 v[78:81], v[234:237], v[222:225], v[78:81]
	v_mfma_f32_16x16x32_bf16 v[74:77], v[242:245], v[222:225], v[74:77]
	v_mfma_f32_16x16x32_bf16 v[70:73], v[234:237], v[226:229], v[70:73]
	v_mfma_f32_16x16x32_bf16 v[66:69], v[242:245], v[226:229], v[66:69]
	s_setprio 0
	s_mov_b32 m0, s22
	s_barrier
	ds_read_b128 v[186:189], v150 offset:49152
	ds_read_b128 v[190:193], v150 offset:51200
	ds_read_b128 v[194:197], v151 offset:49152
	ds_read_b128 v[198:201], v151 offset:51200
	ds_read_b128 v[206:209], v150 offset:53248
	ds_read_b128 v[218:221], v150 offset:55296
	ds_read_b128 v[222:225], v151 offset:53248
	ds_read_b128 v[226:229], v151 offset:55296
	s_add_u32 s100, vcc_lo, s96
	s_addc_u32 s101, vcc_hi, s97
	global_load_lds_dwordx4 v144, s[100:101] nt
	s_mov_b32 m0, s23
	s_add_u32 s100, vcc_lo, s96
	s_addc_u32 s101, vcc_hi, s97
	global_load_lds_dwordx4 v142, s[100:101] nt
	s_mov_b32 m0, s24
	s_add_u32 s100, s11, s68
	s_addc_u32 s101, s12, s69
	global_load_lds_dwordx4 v148, s[100:101]
	s_mov_b32 m0, s25
	s_add_u32 s100, s11, s68
	s_addc_u32 s101, s12, s69
	global_load_lds_dwordx4 v146, s[100:101]
	s_waitcnt vmcnt(10)
	s_waitcnt lgkmcnt(0)
	s_barrier
	s_waitcnt lgkmcnt(0)
	s_setprio 1
	s_waitcnt lgkmcnt(0)
	v_mfma_f32_16x16x32_bf16 v[62:65], v[170:173], v[186:189], v[62:65]
	v_mfma_f32_16x16x32_bf16 v[58:61], v[178:181], v[186:189], v[58:61]
	v_mfma_f32_16x16x32_bf16 v[54:57], v[170:173], v[190:193], v[54:57]
	v_mfma_f32_16x16x32_bf16 v[50:53], v[178:181], v[190:193], v[50:53]
	v_mfma_f32_16x16x32_bf16 v[46:49], v[170:173], v[206:209], v[46:49]
	v_mfma_f32_16x16x32_bf16 v[42:45], v[178:181], v[206:209], v[42:45]
	v_mfma_f32_16x16x32_bf16 v[38:41], v[170:173], v[218:221], v[38:41]
	v_mfma_f32_16x16x32_bf16 v[34:37], v[178:181], v[218:221], v[34:37]
	v_mfma_f32_16x16x32_bf16 v[62:65], v[174:177], v[194:197], v[62:65]
	v_mfma_f32_16x16x32_bf16 v[58:61], v[182:185], v[194:197], v[58:61]
	v_mfma_f32_16x16x32_bf16 v[54:57], v[174:177], v[198:201], v[54:57]
	v_mfma_f32_16x16x32_bf16 v[50:53], v[182:185], v[198:201], v[50:53]
	v_mfma_f32_16x16x32_bf16 v[46:49], v[174:177], v[222:225], v[46:49]
	v_mfma_f32_16x16x32_bf16 v[42:45], v[182:185], v[222:225], v[42:45]
	v_mfma_f32_16x16x32_bf16 v[38:41], v[174:177], v[226:229], v[38:41]
	v_mfma_f32_16x16x32_bf16 v[34:37], v[182:185], v[226:229], v[34:37]
	v_mfma_f32_16x16x32_bf16 v[30:33], v[230:233], v[186:189], v[30:33]
	v_mfma_f32_16x16x32_bf16 v[26:29], v[238:241], v[186:189], v[26:29]
	v_mfma_f32_16x16x32_bf16 v[22:25], v[230:233], v[190:193], v[22:25]
	v_mfma_f32_16x16x32_bf16 v[18:21], v[238:241], v[190:193], v[18:21]
	v_mfma_f32_16x16x32_bf16 v[14:17], v[230:233], v[206:209], v[14:17]
	v_mfma_f32_16x16x32_bf16 v[10:13], v[238:241], v[206:209], v[10:13]
	v_mfma_f32_16x16x32_bf16 v[6:9], v[230:233], v[218:221], v[6:9]
	v_mfma_f32_16x16x32_bf16 v[2:5], v[238:241], v[218:221], v[2:5]
	v_mfma_f32_16x16x32_bf16 v[30:33], v[234:237], v[194:197], v[30:33]
	v_mfma_f32_16x16x32_bf16 v[26:29], v[242:245], v[194:197], v[26:29]
	v_mfma_f32_16x16x32_bf16 v[22:25], v[234:237], v[198:201], v[22:25]
	v_mfma_f32_16x16x32_bf16 v[18:21], v[242:245], v[198:201], v[18:21]
	v_mfma_f32_16x16x32_bf16 v[14:17], v[234:237], v[222:225], v[14:17]
	v_mfma_f32_16x16x32_bf16 v[10:13], v[242:245], v[222:225], v[10:13]
	v_mfma_f32_16x16x32_bf16 v[6:9], v[234:237], v[226:229], v[6:9]
	v_mfma_f32_16x16x32_bf16 v[2:5], v[242:245], v[226:229], v[2:5]
	s_setprio 0
	s_add_u32 vcc_lo, vcc_lo, s42
	s_addc_u32 vcc_hi, vcc_hi, s43
	s_add_u32 s11, s11, s54
	s_addc_u32 s12, s12, s55
	s_add_i32 s10, s10, 2
	s_cmpk_lt_u32 s10, 0x7c
	s_barrier
	s_cbranch_scc1 .LBB0_665
	s_waitcnt vmcnt(6)
	v_or_b32_e32 v154, 0x10000, v152
	v_add_u32_e32 v156, 0x10800, v152
	v_or_b32_e32 v155, 0x10000, v153
	v_add_u32_e32 v157, 0x10800, v153
	s_add_i32 s12, s1, 0xc000
	s_add_i32 s11, s1, 0xe000
	v_or_b32_e32 v158, 0x14000, v152
	v_add_u32_e32 v160, 0x14800, v152
	v_or_b32_e32 v159, 0x14000, v153
	v_add_u32_e32 v161, 0x14800, v153
	v_or_b32_e32 v162, 0x18000, v152
	v_add_u32_e32 v164, 0x18800, v152
	v_or_b32_e32 v163, 0x18000, v153
	v_add_u32_e32 v165, 0x18800, v153
	v_or_b32_e32 v166, 0x1c000, v152
	v_add_u32_e32 v168, 0x1c800, v152
	v_or_b32_e32 v167, 0x1c000, v153
	v_add_u32_e32 v169, 0x1c800, v153
	s_mov_b64 s[2:3], 0x1fc3f800
	v_lshl_add_u64 v[140:141], v[140:141], 0, s[2:3]
	s_mov_b32 m0, s12
	ds_read_b128 v[142:145], v154
	ds_read_b128 v[146:149], v155
	ds_read_b128 v[152:155], v156
	ds_read_b128 v[170:173], v157
	ds_read_b128 v[174:177], v150
	ds_read_b128 v[178:181], v150 offset:2048
	ds_read_b128 v[182:185], v151
	ds_read_b128 v[186:189], v151 offset:2048
	ds_read_b128 v[190:193], v150 offset:4096
	ds_read_b128 v[194:197], v150 offset:6144
	ds_read_b128 v[198:201], v151 offset:4096
	ds_read_b128 v[206:209], v151 offset:6144
	v_lshl_add_u64 v[156:157], v[0:1], 1, v[140:141]
	global_load_lds_dwordx4 v[156:157], off nt
	v_lshl_add_u64 v[138:139], v[138:139], 1, v[140:141]
	s_mov_b32 m0, s11
	s_nop 0
	global_load_lds_dwordx4 v[138:139], off nt
	s_barrier
	s_waitcnt lgkmcnt(0)
	s_setprio 1
	s_waitcnt lgkmcnt(0)
	v_mfma_f32_16x16x32_bf16 v[126:129], v[142:145], v[174:177], v[126:129]
	v_mfma_f32_16x16x32_bf16 v[122:125], v[152:155], v[174:177], v[122:125]
	v_mfma_f32_16x16x32_bf16 v[118:121], v[142:145], v[178:181], v[118:121]
	v_mfma_f32_16x16x32_bf16 v[114:117], v[152:155], v[178:181], v[114:117]
	v_mfma_f32_16x16x32_bf16 v[102:105], v[142:145], v[194:197], v[102:105]
	v_mfma_f32_16x16x32_bf16 v[98:101], v[152:155], v[194:197], v[98:101]
	v_mfma_f32_16x16x32_bf16 v[126:129], v[146:149], v[182:185], v[126:129]
	v_mfma_f32_16x16x32_bf16 v[122:125], v[170:173], v[182:185], v[122:125]
	v_mfma_f32_16x16x32_bf16 v[118:121], v[146:149], v[186:189], v[118:121]
	v_mfma_f32_16x16x32_bf16 v[114:117], v[170:173], v[186:189], v[114:117]
	v_mfma_f32_16x16x32_bf16 v[110:113], v[142:145], v[190:193], v[110:113]
	v_mfma_f32_16x16x32_bf16 v[106:109], v[152:155], v[190:193], v[106:109]
	v_mfma_f32_16x16x32_bf16 v[102:105], v[146:149], v[206:209], v[102:105]
	v_mfma_f32_16x16x32_bf16 v[98:101], v[170:173], v[206:209], v[98:101]
	v_mfma_f32_16x16x32_bf16 v[138:141], v[146:149], v[198:201], v[110:113]
	v_mfma_f32_16x16x32_bf16 v[218:221], v[170:173], v[198:201], v[106:109]
	s_setprio 0
	s_barrier
	s_nop 1
	ds_read_b128 v[106:109], v158
	ds_read_b128 v[110:113], v159
	ds_read_b128 v[156:159], v160
	ds_read_b128 v[222:225], v161
	s_barrier
	s_waitcnt lgkmcnt(0)
	s_setprio 1
	s_waitcnt lgkmcnt(0)
	v_mfma_f32_16x16x32_bf16 v[86:89], v[106:109], v[178:181], v[86:89]
	v_mfma_f32_16x16x32_bf16 v[82:85], v[156:159], v[178:181], v[82:85]
	v_mfma_f32_16x16x32_bf16 v[70:73], v[106:109], v[194:197], v[70:73]
	v_mfma_f32_16x16x32_bf16 v[66:69], v[156:159], v[194:197], v[66:69]
	v_mfma_f32_16x16x32_bf16 v[94:97], v[106:109], v[174:177], v[94:97]
	v_mfma_f32_16x16x32_bf16 v[90:93], v[156:159], v[174:177], v[90:93]
	v_mfma_f32_16x16x32_bf16 v[86:89], v[110:113], v[186:189], v[86:89]
	v_mfma_f32_16x16x32_bf16 v[82:85], v[222:225], v[186:189], v[82:85]
	v_mfma_f32_16x16x32_bf16 v[78:81], v[106:109], v[190:193], v[78:81]
	v_mfma_f32_16x16x32_bf16 v[74:77], v[156:159], v[190:193], v[74:77]
	v_mfma_f32_16x16x32_bf16 v[70:73], v[110:113], v[206:209], v[70:73]
	v_mfma_f32_16x16x32_bf16 v[66:69], v[222:225], v[206:209], v[66:69]
	v_mfma_f32_16x16x32_bf16 v[226:229], v[110:113], v[182:185], v[94:97]
	v_mfma_f32_16x16x32_bf16 v[174:177], v[222:225], v[182:185], v[90:93]
	v_mfma_f32_16x16x32_bf16 v[178:181], v[110:113], v[198:201], v[78:81]
	v_mfma_f32_16x16x32_bf16 v[182:185], v[222:225], v[198:201], v[74:77]
	s_setprio 0
	s_barrier
	s_nop 0
	ds_read_b128 v[74:77], v150 offset:16384
	ds_read_b128 v[78:81], v150 offset:18432
	ds_read_b128 v[90:93], v151 offset:16384
	ds_read_b128 v[94:97], v151 offset:18432
	ds_read_b128 v[186:189], v150 offset:20480
	ds_read_b128 v[190:193], v150 offset:22528
	ds_read_b128 v[194:197], v151 offset:20480
	ds_read_b128 v[198:201], v151 offset:22528
	s_waitcnt vmcnt(4)
	s_barrier
	s_waitcnt lgkmcnt(0)
	s_setprio 1
	s_waitcnt lgkmcnt(0)
	v_mfma_f32_16x16x32_bf16 v[62:65], v[142:145], v[74:77], v[62:65]
	v_mfma_f32_16x16x32_bf16 v[58:61], v[152:155], v[74:77], v[58:61]
	v_mfma_f32_16x16x32_bf16 v[54:57], v[142:145], v[78:81], v[54:57]
	v_mfma_f32_16x16x32_bf16 v[50:53], v[152:155], v[78:81], v[50:53]
	v_mfma_f32_16x16x32_bf16 v[38:41], v[142:145], v[190:193], v[38:41]
	v_mfma_f32_16x16x32_bf16 v[34:37], v[152:155], v[190:193], v[34:37]
	v_mfma_f32_16x16x32_bf16 v[62:65], v[146:149], v[90:93], v[62:65]
	v_mfma_f32_16x16x32_bf16 v[58:61], v[170:173], v[90:93], v[58:61]
	v_mfma_f32_16x16x32_bf16 v[54:57], v[146:149], v[94:97], v[54:57]
	v_mfma_f32_16x16x32_bf16 v[50:53], v[170:173], v[94:97], v[50:53]
	v_mfma_f32_16x16x32_bf16 v[46:49], v[142:145], v[186:189], v[46:49]
	v_mfma_f32_16x16x32_bf16 v[42:45], v[152:155], v[186:189], v[42:45]
	v_mfma_f32_16x16x32_bf16 v[38:41], v[146:149], v[198:201], v[38:41]
	v_mfma_f32_16x16x32_bf16 v[34:37], v[170:173], v[198:201], v[34:37]
	v_mfma_f32_16x16x32_bf16 v[206:209], v[146:149], v[194:197], v[46:49]
	v_mfma_f32_16x16x32_bf16 v[230:233], v[170:173], v[194:197], v[42:45]
	s_setprio 0
	s_setprio 1
	v_mfma_f32_16x16x32_bf16 v[22:25], v[106:109], v[78:81], v[22:25]
	v_mfma_f32_16x16x32_bf16 v[18:21], v[156:159], v[78:81], v[18:21]
	v_mfma_f32_16x16x32_bf16 v[6:9], v[106:109], v[190:193], v[6:9]
	v_mfma_f32_16x16x32_bf16 v[2:5], v[156:159], v[190:193], v[2:5]
	v_mfma_f32_16x16x32_bf16 v[30:33], v[106:109], v[74:77], v[30:33]
	v_mfma_f32_16x16x32_bf16 v[26:29], v[156:159], v[74:77], v[26:29]
	v_mfma_f32_16x16x32_bf16 v[22:25], v[110:113], v[94:97], v[22:25]
	v_mfma_f32_16x16x32_bf16 v[18:21], v[222:225], v[94:97], v[18:21]
	v_mfma_f32_16x16x32_bf16 v[14:17], v[106:109], v[186:189], v[14:17]
	v_mfma_f32_16x16x32_bf16 v[10:13], v[156:159], v[186:189], v[10:13]
	v_mfma_f32_16x16x32_bf16 v[6:9], v[110:113], v[198:201], v[6:9]
	v_mfma_f32_16x16x32_bf16 v[2:5], v[222:225], v[198:201], v[2:5]
	v_mfma_f32_16x16x32_bf16 v[142:145], v[110:113], v[90:93], v[30:33]
	v_mfma_f32_16x16x32_bf16 v[146:149], v[222:225], v[90:93], v[26:29]
	v_mfma_f32_16x16x32_bf16 v[152:155], v[110:113], v[194:197], v[14:17]
	v_mfma_f32_16x16x32_bf16 v[170:173], v[222:225], v[194:197], v[10:13]
	s_setprio 0
	s_barrier
	s_nop 0
	ds_read_b128 v[10:13], v162
	ds_read_b128 v[14:17], v163
	ds_read_b128 v[156:159], v164
	ds_read_b128 v[160:163], v165
	ds_read_b128 v[26:29], v150 offset:32768
	ds_read_b128 v[30:33], v150 offset:34816
	ds_read_b128 v[42:45], v151 offset:32768
	ds_read_b128 v[46:49], v151 offset:34816
	ds_read_b128 v[186:189], v150 offset:36864
	ds_read_b128 v[190:193], v150 offset:38912
	ds_read_b128 v[194:197], v151 offset:36864
	ds_read_b128 v[198:201], v151 offset:38912
	s_waitcnt vmcnt(2)
	s_barrier
	s_waitcnt lgkmcnt(0)
	s_setprio 1
	s_waitcnt lgkmcnt(0)
	v_mfma_f32_16x16x32_bf16 v[74:77], v[10:13], v[26:29], v[126:129]
	v_mfma_f32_16x16x32_bf16 v[126:129], v[14:17], v[42:45], v[74:77]
	v_mfma_f32_16x16x32_bf16 v[74:77], v[156:159], v[26:29], v[122:125]
	v_mfma_f32_16x16x32_bf16 v[122:125], v[160:163], v[42:45], v[74:77]
	v_mfma_f32_16x16x32_bf16 v[74:77], v[10:13], v[30:33], v[118:121]
	v_mfma_f32_16x16x32_bf16 v[110:113], v[14:17], v[46:49], v[74:77]
	v_mfma_f32_16x16x32_bf16 v[74:77], v[156:159], v[30:33], v[114:117]
	v_mfma_f32_16x16x32_bf16 v[106:109], v[160:163], v[46:49], v[74:77]
	v_mfma_f32_16x16x32_bf16 v[74:77], v[10:13], v[186:189], v[138:141]
	v_mfma_f32_16x16x32_bf16 v[94:97], v[14:17], v[194:197], v[74:77]
	v_mfma_f32_16x16x32_bf16 v[74:77], v[156:159], v[186:189], v[218:221]
	v_mfma_f32_16x16x32_bf16 v[90:93], v[160:163], v[194:197], v[74:77]
	v_mfma_f32_16x16x32_bf16 v[74:77], v[10:13], v[190:193], v[102:105]
	v_mfma_f32_16x16x32_bf16 v[78:81], v[14:17], v[198:201], v[74:77]
	v_mfma_f32_16x16x32_bf16 v[74:77], v[156:159], v[190:193], v[98:101]
	v_mfma_f32_16x16x32_bf16 v[74:77], v[160:163], v[198:201], v[74:77]
	s_setprio 0
	s_barrier
	ds_read_b128 v[138:141], v166
	ds_read_b128 v[164:167], v167
	ds_read_b128 v[218:221], v168
	ds_read_b128 v[222:225], v169
	s_waitcnt vmcnt(0)
	s_barrier
	s_waitcnt lgkmcnt(0)
	s_setprio 1
	s_waitcnt lgkmcnt(0)
	v_mfma_f32_16x16x32_bf16 v[98:101], v[138:141], v[26:29], v[226:229]
	v_mfma_f32_16x16x32_bf16 v[26:29], v[218:221], v[26:29], v[174:177]
	v_mfma_f32_16x16x32_bf16 v[114:117], v[222:225], v[42:45], v[26:29]
	v_mfma_f32_16x16x32_bf16 v[26:29], v[138:141], v[30:33], v[86:89]
	v_mfma_f32_16x16x32_bf16 v[102:105], v[164:167], v[46:49], v[26:29]
	v_mfma_f32_16x16x32_bf16 v[26:29], v[218:221], v[30:33], v[82:85]
	v_mfma_f32_16x16x32_bf16 v[118:121], v[164:167], v[42:45], v[98:101]
	v_mfma_f32_16x16x32_bf16 v[98:101], v[222:225], v[46:49], v[26:29]
	v_mfma_f32_16x16x32_bf16 v[26:29], v[138:141], v[186:189], v[178:181]
	v_mfma_f32_16x16x32_bf16 v[86:89], v[164:167], v[194:197], v[26:29]
	v_mfma_f32_16x16x32_bf16 v[26:29], v[218:221], v[186:189], v[182:185]
	v_mfma_f32_16x16x32_bf16 v[82:85], v[222:225], v[194:197], v[26:29]
	v_mfma_f32_16x16x32_bf16 v[26:29], v[138:141], v[190:193], v[70:73]
	v_mfma_f32_16x16x32_bf16 v[70:73], v[164:167], v[198:201], v[26:29]
	v_mfma_f32_16x16x32_bf16 v[26:29], v[218:221], v[190:193], v[66:69]
	v_mfma_f32_16x16x32_bf16 v[66:69], v[222:225], v[198:201], v[26:29]
	s_setprio 0
	s_barrier
	ds_read_b128 v[174:177], v150 offset:49152
	ds_read_b128 v[178:181], v150 offset:51200
	ds_read_b128 v[182:185], v151 offset:49152
	ds_read_b128 v[186:189], v151 offset:51200
	ds_read_b128 v[190:193], v150 offset:53248
	ds_read_b128 v[194:197], v150 offset:55296
	ds_read_b128 v[198:201], v151 offset:53248
	ds_read_b128 v[226:229], v151 offset:55296
	s_barrier
	s_waitcnt lgkmcnt(0)
	s_setprio 1
	s_waitcnt lgkmcnt(0)
	v_mfma_f32_16x16x32_bf16 v[26:29], v[10:13], v[174:177], v[62:65]
	v_mfma_f32_16x16x32_bf16 v[62:65], v[14:17], v[182:185], v[26:29]
	v_mfma_f32_16x16x32_bf16 v[26:29], v[156:159], v[174:177], v[58:61]
	v_mfma_f32_16x16x32_bf16 v[58:61], v[160:163], v[182:185], v[26:29]
	v_mfma_f32_16x16x32_bf16 v[26:29], v[10:13], v[178:181], v[54:57]
	v_mfma_f32_16x16x32_bf16 v[46:49], v[14:17], v[186:189], v[26:29]
	v_mfma_f32_16x16x32_bf16 v[26:29], v[156:159], v[178:181], v[50:53]
	v_mfma_f32_16x16x32_bf16 v[42:45], v[160:163], v[186:189], v[26:29]
	v_mfma_f32_16x16x32_bf16 v[26:29], v[10:13], v[190:193], v[206:209]
	v_mfma_f32_16x16x32_bf16 v[10:13], v[10:13], v[194:197], v[38:41]
	v_mfma_f32_16x16x32_bf16 v[30:33], v[14:17], v[198:201], v[26:29]
	v_mfma_f32_16x16x32_bf16 v[26:29], v[156:159], v[190:193], v[230:233]
	v_mfma_f32_16x16x32_bf16 v[14:17], v[14:17], v[226:229], v[10:13]
	v_mfma_f32_16x16x32_bf16 v[10:13], v[156:159], v[194:197], v[34:37]
	v_mfma_f32_16x16x32_bf16 v[26:29], v[160:163], v[198:201], v[26:29]
	v_mfma_f32_16x16x32_bf16 v[10:13], v[160:163], v[226:229], v[10:13]
	s_setprio 0
	s_setprio 1
	v_mfma_f32_16x16x32_bf16 v[34:37], v[138:141], v[174:177], v[142:145]
	v_mfma_f32_16x16x32_bf16 v[54:57], v[164:167], v[182:185], v[34:37]
	v_mfma_f32_16x16x32_bf16 v[34:37], v[218:221], v[174:177], v[146:149]
	v_mfma_f32_16x16x32_bf16 v[18:21], v[218:221], v[178:181], v[18:21]
	v_mfma_f32_16x16x32_bf16 v[50:53], v[222:225], v[182:185], v[34:37]
	v_mfma_f32_16x16x32_bf16 v[22:25], v[138:141], v[178:181], v[22:25]
	v_mfma_f32_16x16x32_bf16 v[34:37], v[222:225], v[186:189], v[18:21]
	v_mfma_f32_16x16x32_bf16 v[18:21], v[138:141], v[190:193], v[152:155]
	v_mfma_f32_16x16x32_bf16 v[38:41], v[164:167], v[186:189], v[22:25]
	v_mfma_f32_16x16x32_bf16 v[22:25], v[164:167], v[198:201], v[18:21]
	v_mfma_f32_16x16x32_bf16 v[18:21], v[218:221], v[190:193], v[170:173]
	v_mfma_f32_16x16x32_bf16 v[6:9], v[138:141], v[194:197], v[6:9]
	v_mfma_f32_16x16x32_bf16 v[2:5], v[218:221], v[194:197], v[2:5]
	v_mfma_f32_16x16x32_bf16 v[18:21], v[222:225], v[198:201], v[18:21]
	v_mfma_f32_16x16x32_bf16 v[6:9], v[164:167], v[226:229], v[6:9]
	v_mfma_f32_16x16x32_bf16 v[2:5], v[222:225], v[226:229], v[2:5]
	s_setprio 0
	s_cmpk_gt_u32 s0, 0xff
	s_barrier
	s_cbranch_scc1 .LBB0_668
	s_barrier

	.amdhsa_kernel _Z12yoco_forward6Params
		.amdhsa_group_segment_fixed_size 141568
		.amdhsa_private_segment_fixed_size 0
		.amdhsa_kernarg_size 424
		.amdhsa_user_sgpr_count 2
		.amdhsa_user_sgpr_dispatch_ptr 0
		.amdhsa_user_sgpr_queue_ptr 0
		.amdhsa_user_sgpr_kernarg_segment_ptr 1
		.amdhsa_user_sgpr_dispatch_id 0
		.amdhsa_user_sgpr_kernarg_preload_length 0
		.amdhsa_user_sgpr_kernarg_preload_offset 0
		.amdhsa_user_sgpr_private_segment_size 0
		.amdhsa_uses_dynamic_stack 0
		.amdhsa_enable_private_segment 0
		.amdhsa_system_sgpr_workgroup_id_x 1
		.amdhsa_system_sgpr_workgroup_id_y 0
		.amdhsa_system_sgpr_workgroup_id_z 0
		.amdhsa_system_sgpr_workgroup_info 0
		.amdhsa_system_vgpr_workitem_id 2
		.amdhsa_next_free_vgpr 256
		.amdhsa_next_free_sgpr 102
		.amdhsa_accum_offset 256
		.amdhsa_reserve_vcc 1
		.amdhsa_float_round_mode_32 0
		.amdhsa_float_round_mode_16_64 0
		.amdhsa_float_denorm_mode_32 3
		.amdhsa_float_denorm_mode_16_64 3
		.amdhsa_dx10_clamp 1
		.amdhsa_ieee_mode 1
		.amdhsa_fp16_overflow 0
		.amdhsa_tg_split 0
		.amdhsa_exception_fp_ieee_invalid_op 0
		.amdhsa_exception_fp_denorm_src 0
		.amdhsa_exception_fp_ieee_div_zero 0
		.amdhsa_exception_fp_ieee_overflow 0
		.amdhsa_exception_fp_ieee_underflow 0
		.amdhsa_exception_fp_ieee_inexact 0
		.amdhsa_exception_int_div_zero 0
	.end_amdhsa_kernel

amdhsa.kernels:
  - .agpr_count:     0
    .args:
      - .offset:         0
        .size:           168
        .value_kind:     by_value
      - .offset:         168
        .size:           4
        .value_kind:     hidden_block_count_x
      - .offset:         172
        .size:           4
        .value_kind:     hidden_block_count_y
      - .offset:         176
        .size:           4
        .value_kind:     hidden_block_count_z
      - .offset:         180
        .size:           2
        .value_kind:     hidden_group_size_x
      - .offset:         182
        .size:           2
        .value_kind:     hidden_group_size_y
      - .offset:         184
        .size:           2
        .value_kind:     hidden_group_size_z
      - .offset:         186
        .size:           2
        .value_kind:     hidden_remainder_x
      - .offset:         188
        .size:           2
        .value_kind:     hidden_remainder_y
      - .offset:         190
        .size:           2
        .value_kind:     hidden_remainder_z
      - .offset:         208
        .size:           8
        .value_kind:     hidden_global_offset_x
      - .offset:         216
        .size:           8
        .value_kind:     hidden_global_offset_y
      - .offset:         224
        .size:           8
        .value_kind:     hidden_global_offset_z
      - .offset:         232
        .size:           2
        .value_kind:     hidden_grid_dims
      - .offset:         256
        .size:           8
        .value_kind:     hidden_multigrid_sync_arg
    .group_segment_fixed_size: 141568
    .kernarg_segment_align: 8
    .kernarg_segment_size: 424
    .language:       OpenCL C
    .language_version:
      - 2
      - 0
    .max_flat_workgroup_size: 512
    .name:           _Z12yoco_forward6Params
    .private_segment_fixed_size: 0
    .sgpr_count:     108
    .sgpr_spill_count: 22
    .symbol:         _Z12yoco_forward6Params.kd
    .uniform_work_group_size: 1
    .uses_dynamic_stack: false
    .vgpr_count:     256
    .vgpr_spill_count: 0
    .wavefront_size: 64
